# static s_setprio 1 for waves 4-7 at kernel entry, all per-segment s_setprio flips in the GEMM K-loops removed; on v26
# speedup vs baseline: 1.0074x; 1.0074x over previous
; #define LAS __attribute__((address_space(3)))
; __global__ void __launch_bounds__(NT, 2) fwd(const Args args) {
;     extern __shared__ __attribute__((aligned(16))) unsigned char lds_raw[];
;     Frame F0;
;     F0.lds = (LAS unsigned char*)lds_raw; F0.LW = (volatile LAS unsigned*)(F0.lds + LDSCTL_OFF);
;     F0.tid = threadIdx.x; F0.lane = F0.tid & 63; F0.wave = __builtin_amdgcn_readfirstlane(F0.tid >> 6); F0.G = gridDim.x; F0.bid = blockIdx.x; F0.gw = blockIdx.x * NW + F0.wave; F0.NGW = F0.G * NW;
;     F0.out = nullptr; F0.ws = nullptr; F0.ctl = nullptr;
;     for (int u = F0.tid; u < (LDS_BYTES - LDSCTL_OFF) / 4; u += NT) F0.LW[u] = 0u;
;     __syncthreads();
;     const int lo = args.ph_lo, hi = args.ph_hi;
;     const bool multi = (hi - lo) > 1;
;     XcdBarrier bar; bar.bar = (unsigned*)(args.ws + WS_CTL) + CW_BAR; bar.x = 0; bar.st = F0.LW + LW_XB;
;     if (multi) bar = xcd_barrier_post((unsigned*)(args.ws + WS_CTL) + CW_BAR, F0.LW + LW_XB);
_Z3fwd4Args:
	s_load_dwordx4 s[4:7], s[0:1], 0xe8
	s_load_dword s94, s[0:1], 0xf8
	v_lshl_add_u32 v2, v0, 2, 0
	v_writelane_b32 v253, s2, 0
	s_add_u32 s2, s0, 0xf8
	s_waitcnt lgkmcnt(0)
	v_writelane_b32 v253, s4, 1
	v_or_b32_e32 v1, 0xfffffe00, v0
	v_add_u32_e32 v2, 0x25800, v2
	v_writelane_b32 v253, s5, 2
	v_writelane_b32 v253, s6, 3
	v_writelane_b32 v253, s7, 4
	v_writelane_b32 v253, s0, 5
	s_addc_u32 s3, s1, 0
	v_readfirstlane_b32 s4, v0
	v_writelane_b32 v253, s1, 6
	v_writelane_b32 v253, s2, 7
	s_mov_b64 s[0:1], 0
	v_mov_b32_e32 v3, 0
	v_writelane_b32 v253, s3, 8
	s_cmp_ge_u32 s4, 0x100
	s_cbranch_scc0 .Lprio_done
	s_setprio 1
.Lprio_done:
.LBB0_1:
	v_add_co_u32_e32 v1, vcc, 0x200, v1
	s_xor_b64 s[2:3], vcc, -1
	s_and_b64 s[2:3], exec, s[2:3]
	ds_write_b32 v2, v3
	s_or_b64 s[0:1], s[2:3], s[0:1]
	v_add_u32_e32 v2, 0x800, v2
	s_andn2_b64 exec, exec, s[0:1]
	s_cbranch_execnz .LBB0_1
	s_or_b64 exec, exec, s[0:1]
	v_readlane_b32 s8, v253, 1
	v_readlane_b32 s10, v253, 3
	v_readlane_b32 s11, v253, 4
	s_sub_i32 s0, s11, s10
	v_readlane_b32 s9, v253, 2
	s_add_u32 s2, s8, 0x4000
	s_addc_u32 s3, s9, 0
	v_writelane_b32 v253, s2, 9
	s_cmp_gt_i32 s0, 1
	s_mov_b32 s33, 0
	v_writelane_b32 v253, s3, 10
	v_cmp_eq_u32_e32 vcc, 0, v0
	s_waitcnt lgkmcnt(0)
	s_barrier
	s_cbranch_scc0 .LBB0_7
	s_getreg_b32 s0, hwreg(HW_REG_XCC_ID, 0, 4)
	s_and_b32 s33, s0, 15
	s_and_saveexec_b64 s[0:1], vcc
	s_cbranch_execz .LBB0_6
	s_mov_b64 s[2:3], exec
	v_mbcnt_lo_u32_b32 v1, s2, 0
	v_mbcnt_hi_u32_b32 v1, s3, v1
	v_cmp_eq_u32_e32 vcc, 0, v1
	s_and_b64 s[6:7], exec, vcc
	s_mov_b64 exec, s[6:7]
	s_cbranch_execz .LBB0_6
	s_bcnt1_i32_b64 s2, s[2:3]
	s_lshl_b32 s5, s33, 8
	v_mov_b32_e32 v2, s2
	v_readlane_b32 s2, v253, 9
	v_mov_b32_e32 v1, s5
	v_readlane_b32 s3, v253, 10
	s_nop 4
	global_atomic_add v1, v2, s[2:3] offset:1024

; #define LAS __attribute__((address_space(3)))
;     __device__ bool next(int i, Unit& u) const { if (!so.next(i >> 1, u)) return false; u.sel = i & 1; return true; }
;     __device__ bool next(int i, Unit& u) const { const int L = i * nw + r; if (L >= nu) return false; u.pm = L >> 2; u.pn = L & 3; u.pb = u.pn; u.sel = 0; return true; }
; #define PG8_STAGE(bufoff, gbase, voff) do { _Pragma("unroll") for (int _i = 0; _i < 2; ++_i) \
;         __builtin_amdgcn_global_load_lds((const unsigned*)((const char*)(gbase) + (voff)[_i]), (LAS unsigned*)(lds + (bufoff) + ldsw + _i * 8192), 16, 0, 0); } while (0)
; template <class Epi, class Sched>
; __device__ __forceinline__ void gemm_phase(const int tid, LAS unsigned char* lds, const bf16* Aop, const bf16* Bop, const int K_, const Sched& S, const Epi& E, const bf16* Aop1 = nullptr, const bf16* Bop1 = nullptr) {
;     ...
;     for (;;) {
;         const bool has_next = S.next(ui + 1, nxt);
;         if (Epi::GATHER && has_next && wid < 4) E.tok_dma(nxt.pm * 256 + wid * 64, (LAS unsigned*)(lds + 8 * HTB) + ((ui + 1) & 1) * 256 + wid * 64, lane);
;         const char* nA = has_next ? (const char*)((Aop1 && nxt.sel) ? Aop1 : Aop) + (Epi::GATHER ? (size_t)0 : (size_t)nxt.pm * tstep) : cA; const char* nB = has_next ? (const char*)((Bop1 && nxt.sel) ? Bop1 : Bop) + (size_t)nxt.pb * tstep : cB;
;         for (int t = 0; t < nt; t += 2) {
;             const bool last = (t == nt - 2);
;             const char* a1 = cA + (size_t)(t + 1) * kstep;
;             const char* a2 = last ? nA : cA + (size_t)(t + 2) * kstep; const char* b2 = last ? nB : cB + (size_t)(t + 2) * kstep;
;             const char* a3 = a2 + kstep; const char* b3 = b2 + kstep;
;             PG8_LDB(B0, 0, 0); PG8_LDB(B1, 0, 1); PG8_SCHED; PG8_LDA(At, 0, 0); PG8_STAGE_A1(PG8_SA(1, 1), a1);
;             PG8_WAIT_V(8); PG8_WAIT_L(0); PG8_BAR; PG8_MMA(0, 0, At, B0); PG8_MMA(0, 1, At, B1); PG8_BAR; PG8_SCHED;
;             PG8_LDA(At, 0, 1); PG8_STAGE(PG8_SB(0, 0), b2, voffB); PG8_STAGE(PG8_SB(0, 1), b2 + hstep, voffB); if (Epi::GATHER && last && has_next) PG8_GOFFS((ui + 1) & 1); PG8_STAGE(PG8_SA(0, 0), a2, voffA[0]);
;             PG8_WAIT_V(8); PG8_WAIT_L(0); PG8_BAR; PG8_MMA(1, 0, At, B0); PG8_MMA(1, 1, At, B1); PG8_BAR; PG8_SCHED;
;             PG8_LDB(B0, 1, 0); PG8_LDB(B1, 1, 1); PG8_SCHED; PG8_LDA(At, 1, 0); PG8_STAGE_A1(PG8_SA(0, 1), a2);
.LBB0_129:
	v_mov_b32_e32 v143, 0
	s_andn2_b64 vcc, exec, s[18:19]
	s_cbranch_vccnz .LBB0_133
	s_add_u32 s26, s26, 0x80
	s_addc_u32 s27, s27, 0
	s_add_u32 s11, s42, 0x100
	v_mov_b64_e32 v[180:181], v[178:179]
	v_mov_b64_e32 v[178:179], v[176:177]
	v_mov_b64_e32 v[176:177], v[190:191]
	v_mov_b32_e32 v205, 0x7f800000
	v_mov_b32_e32 v203, 0x3ecc95a3
	v_mov_b32_e32 v200, 1
	v_mov_b64_e32 v[226:227], 0x100
	s_addc_u32 s42, s43, 0
	s_mov_b32 s40, 0
	s_add_i32 s43, s40, 2
	s_add_u32 s44, s26, 0x80
	s_addc_u32 s41, s27, 0
	s_add_i32 s48, 0, 0x10000
	s_cmp_eq_u32 s77, s40
	s_cselect_b32 s41, s35, s41
	s_cselect_b32 s40, s34, s44
	s_cselect_b32 s45, s37, s42
	s_cselect_b32 s44, s36, s11
	s_add_i32 s49, 0, 0x14000
	v_add_u32_e32 v80, s48, v3
	v_add_u32_e32 v160, s49, v3
	ds_read_b128 v[60:63], v80
	ds_read_b128 v[68:71], v80 offset:1024
	ds_read_b128 v[76:79], v80 offset:2048
	ds_read_b128 v[80:83], v80 offset:3072
	ds_read_b128 v[148:151], v160
	ds_read_b128 v[152:155], v160 offset:1024
	ds_read_b128 v[156:159], v160 offset:2048
	ds_read_b128 v[160:163], v160 offset:3072
	v_lshl_add_u64 v[164:165], s[26:27], 0, v[192:193]
	s_add_i32 m0, s70, 0xc000
	ds_read_b128 v[206:209], v175
	ds_read_b128 v[210:213], v175 offset:1024
	ds_read_b128 v[214:217], v175 offset:2048
	ds_read_b128 v[218:221], v175 offset:3072
	ds_read_b128 v[238:241], v175 offset:4096
	ds_read_b128 v[242:245], v175 offset:5120
	ds_read_b128 v[246:249], v175 offset:6144
	ds_read_b128 v[230:233], v175 offset:7168
	global_load_lds_dwordx4 v[164:165], off
	v_lshl_add_u64 v[164:165], s[26:27], 0, v[194:195]
	s_add_i32 m0, s70, 0xe000
	s_nop 0
	global_load_lds_dwordx4 v[164:165], off
	s_waitcnt vmcnt(8)
	s_waitcnt lgkmcnt(0)
	s_barrier
	s_nop 0
	s_waitcnt lgkmcnt(0)
	v_mfma_f32_16x16x32_bf16 v[140:143], v[60:63], v[206:209], 0
	v_mfma_f32_16x16x32_bf16 v[144:147], v[76:79], v[206:209], 0
	v_mfma_f32_16x16x32_bf16 v[128:131], v[60:63], v[214:217], 0
	v_mfma_f32_16x16x32_bf16 v[124:127], v[76:79], v[214:217], 0
	v_mfma_f32_16x16x32_bf16 v[112:115], v[60:63], v[238:241], 0
	v_mfma_f32_16x16x32_bf16 v[108:111], v[76:79], v[238:241], 0
	v_mfma_f32_16x16x32_bf16 v[96:99], v[60:63], v[246:249], 0
	v_mfma_f32_16x16x32_bf16 v[92:95], v[76:79], v[246:249], 0
	v_mfma_f32_16x16x32_bf16 v[140:143], v[68:71], v[210:213], v[140:143]
	v_mfma_f32_16x16x32_bf16 v[144:147], v[80:83], v[210:213], v[144:147]
	v_mfma_f32_16x16x32_bf16 v[128:131], v[68:71], v[218:221], v[128:131]
	v_mfma_f32_16x16x32_bf16 v[124:127], v[80:83], v[218:221], v[124:127]
	v_mfma_f32_16x16x32_bf16 v[112:115], v[68:71], v[242:245], v[112:115]
	v_mfma_f32_16x16x32_bf16 v[108:111], v[80:83], v[242:245], v[108:111]
	v_mfma_f32_16x16x32_bf16 v[96:99], v[68:71], v[230:233], v[96:99]
	v_mfma_f32_16x16x32_bf16 v[92:95], v[80:83], v[230:233], v[92:95]
	s_nop 0
	s_nop 0
	v_mfma_f32_16x16x32_bf16 v[136:139], v[148:151], v[206:209], 0
	v_mfma_f32_16x16x32_bf16 v[132:135], v[156:159], v[206:209], 0
	v_mfma_f32_16x16x32_bf16 v[120:123], v[148:151], v[214:217], 0
	v_mfma_f32_16x16x32_bf16 v[116:119], v[156:159], v[214:217], 0
	v_mfma_f32_16x16x32_bf16 v[104:107], v[148:151], v[238:241], 0
	v_mfma_f32_16x16x32_bf16 v[100:103], v[156:159], v[238:241], 0
	v_mfma_f32_16x16x32_bf16 v[88:91], v[148:151], v[246:249], 0
	v_mfma_f32_16x16x32_bf16 v[84:87], v[156:159], v[246:249], 0
	v_mfma_f32_16x16x32_bf16 v[136:139], v[152:155], v[210:213], v[136:139]
	v_mfma_f32_16x16x32_bf16 v[132:135], v[160:163], v[210:213], v[132:135]
	v_mfma_f32_16x16x32_bf16 v[120:123], v[152:155], v[218:221], v[120:123]
	v_mfma_f32_16x16x32_bf16 v[116:119], v[160:163], v[218:221], v[116:119]
	v_mfma_f32_16x16x32_bf16 v[104:107], v[152:155], v[242:245], v[104:107]
	v_mfma_f32_16x16x32_bf16 v[100:103], v[160:163], v[242:245], v[100:103]
	v_mfma_f32_16x16x32_bf16 v[88:91], v[152:155], v[230:233], v[88:91]
	v_mfma_f32_16x16x32_bf16 v[84:87], v[160:163], v[230:233], v[84:87]
	s_nop 0
	s_barrier
	s_add_i32 s48, s48, s69
	v_lshl_add_u64 v[164:165], s[44:45], 0, v[166:167]
	s_mov_b32 m0, s48
	ds_read_b128 v[206:209], v175 offset:16384
	ds_read_b128 v[210:213], v175 offset:17408
	ds_read_b128 v[214:217], v175 offset:18432
	ds_read_b128 v[218:221], v175 offset:19456
	ds_read_b128 v[230:233], v175 offset:20480
	ds_read_b128 v[238:241], v175 offset:21504
	ds_read_b128 v[242:245], v175 offset:22528
	ds_read_b128 v[246:249], v175 offset:23552
	global_load_lds_dwordx4 v[164:165], off
	s_add_i32 m0, s48, 0x2000
	v_lshl_add_u64 v[222:223], s[44:45], 0, v[170:171]
	s_add_u32 s44, s44, s6
	s_addc_u32 s45, s45, s7
	s_add_i32 s48, s49, s69
	global_load_lds_dwordx4 v[222:223], off
	v_lshl_add_u64 v[250:251], s[44:45], 0, v[166:167]
	s_mov_b32 m0, s48
	v_lshl_add_u64 v[196:197], s[44:45], 0, v[170:171]
	global_load_lds_dwordx4 v[250:251], off
	s_add_i32 m0, s48, 0x2000
	v_lshl_add_u64 v[198:199], s[40:41], 0, v[0:1]
	global_load_lds_dwordx4 v[196:197], off
	s_mov_b32 m0, s70
	v_lshl_add_u64 v[224:225], s[40:41], 0, v[168:169]
	global_load_lds_dwordx4 v[198:199], off
	s_mov_b32 m0, s71
	s_nop 0
	global_load_lds_dwordx4 v[224:225], off
	s_waitcnt vmcnt(8)
	s_waitcnt lgkmcnt(0)
	s_barrier
; #define PG8_STAGE_A1(bufoff, gbase) do { if (Epi::GATHER) PG8_STAGE(bufoff, gbase, voffA[1]); else PG8_STAGE(bufoff, (gbase) + hstep, voffA[0]); } while (0)
; #define PG8_LDA(dst, b, h) do { _Pragma("unroll") for (int m = 0; m < 4; ++m) _Pragma("unroll") for (int k = 0; k < 2; ++k) dst[m][k] = *(const LAS bf16x8*)(lds + PG8_SA(b, h) + aoff + m * 2048 + k * 1024); } while (0)
; #define PG8_LDB(dst, b, h) do { _Pragma("unroll") for (int n = 0; n < 2; ++n) _Pragma("unroll") for (int k = 0; k < 2; ++k) dst[n][k] = *(const LAS bf16x8*)(lds + PG8_SB(b, h) + boff + n * 2048 + k * 1024); } while (0)
; #define PG8_MMA(ai, bj, At, Bt) do { __builtin_amdgcn_s_setprio(1); _Pragma("unroll") for (int m = 0; m < 4; ++m) _Pragma("unroll") for (int n = 0; n < 2; ++n) _Pragma("unroll") for (int k = 0; k < 2; ++k) \
;         acc[ai][bj][m][n] = __builtin_amdgcn_mfma_f32_16x16x32_bf16(Bt[n][k], At[m][k], acc[ai][bj][m][n], 0, 0, 0); __builtin_amdgcn_s_setprio(0); } while (0)
; #define PG8_WAIT_V(n) asm volatile("s_waitcnt vmcnt(" #n ")" ::: "memory")
; #define PG8_WAIT_L(n) asm volatile("s_waitcnt lgkmcnt(" #n ")" ::: "memory")
; #define PG8_BAR __builtin_amdgcn_s_barrier()
; #define PG8_SCHED __builtin_amdgcn_sched_barrier(0)
; template <class Epi, class Sched>
; __device__ __forceinline__ void gemm_phase(const int tid, LAS unsigned char* lds, const bf16* Aop, const bf16* Bop, const int K_, const Sched& S, const Epi& E, const bf16* Aop1 = nullptr, const bf16* Bop1 = nullptr) {
;     ...
;             PG8_WAIT_V(8); PG8_WAIT_L(0); PG8_BAR; PG8_MMA(1, 0, At, B0); PG8_MMA(1, 1, At, B1); PG8_BAR; PG8_SCHED;
;             PG8_LDB(B0, 1, 0); PG8_LDB(B1, 1, 1); PG8_SCHED; PG8_LDA(At, 1, 0); PG8_STAGE_A1(PG8_SA(0, 1), a2);
;             PG8_WAIT_V(8); PG8_WAIT_L(0); PG8_BAR; PG8_MMA(0, 0, At, B0); PG8_MMA(0, 1, At, B1); PG8_BAR; PG8_SCHED;
	s_nop 0
	s_waitcnt lgkmcnt(0)
	v_mfma_f32_16x16x32_bf16 v[72:75], v[60:63], v[206:209], 0
	v_mfma_f32_16x16x32_bf16 v[64:67], v[76:79], v[206:209], 0
	v_mfma_f32_16x16x32_bf16 v[48:51], v[60:63], v[214:217], 0
	v_mfma_f32_16x16x32_bf16 v[44:47], v[76:79], v[214:217], 0
	v_mfma_f32_16x16x32_bf16 v[32:35], v[60:63], v[230:233], 0
	v_mfma_f32_16x16x32_bf16 v[28:31], v[76:79], v[230:233], 0
	v_mfma_f32_16x16x32_bf16 v[16:19], v[60:63], v[242:245], 0
	v_mfma_f32_16x16x32_bf16 v[12:15], v[76:79], v[242:245], 0
	v_mfma_f32_16x16x32_bf16 v[72:75], v[68:71], v[210:213], v[72:75]
	v_mfma_f32_16x16x32_bf16 v[64:67], v[80:83], v[210:213], v[64:67]
	v_mfma_f32_16x16x32_bf16 v[48:51], v[68:71], v[218:221], v[48:51]
	v_mfma_f32_16x16x32_bf16 v[44:47], v[80:83], v[218:221], v[44:47]
	v_mfma_f32_16x16x32_bf16 v[32:35], v[68:71], v[238:241], v[32:35]
	v_mfma_f32_16x16x32_bf16 v[28:31], v[80:83], v[238:241], v[28:31]
	v_mfma_f32_16x16x32_bf16 v[16:19], v[68:71], v[246:249], v[16:19]
	v_mfma_f32_16x16x32_bf16 v[12:15], v[80:83], v[246:249], v[12:15]
	s_nop 0
	s_nop 0
	v_mfma_f32_16x16x32_bf16 v[56:59], v[148:151], v[206:209], 0
	v_mfma_f32_16x16x32_bf16 v[52:55], v[156:159], v[206:209], 0
	v_mfma_f32_16x16x32_bf16 v[40:43], v[148:151], v[214:217], 0
	v_mfma_f32_16x16x32_bf16 v[36:39], v[156:159], v[214:217], 0
	v_mfma_f32_16x16x32_bf16 v[24:27], v[148:151], v[230:233], 0
	v_mfma_f32_16x16x32_bf16 v[20:23], v[156:159], v[230:233], 0
	v_mfma_f32_16x16x32_bf16 v[8:11], v[148:151], v[242:245], 0
	v_mfma_f32_16x16x32_bf16 v[4:7], v[156:159], v[242:245], 0
	v_mfma_f32_16x16x32_bf16 v[56:59], v[152:155], v[210:213], v[56:59]
	v_mfma_f32_16x16x32_bf16 v[52:55], v[160:163], v[210:213], v[52:55]
	v_mfma_f32_16x16x32_bf16 v[40:43], v[152:155], v[218:221], v[40:43]
	v_mfma_f32_16x16x32_bf16 v[36:39], v[160:163], v[218:221], v[36:39]
	v_mfma_f32_16x16x32_bf16 v[24:27], v[152:155], v[238:241], v[24:27]
	v_mfma_f32_16x16x32_bf16 v[20:23], v[160:163], v[238:241], v[20:23]
	v_mfma_f32_16x16x32_bf16 v[8:11], v[152:155], v[246:249], v[8:11]
	v_mfma_f32_16x16x32_bf16 v[4:7], v[160:163], v[246:249], v[4:7]
	s_nop 0
	s_barrier
	s_add_i32 s44, 0, 0x18000
	s_add_i32 s45, 0, 0x1c000
	v_add_u32_e32 v80, s44, v3
	v_add_u32_e32 v160, s45, v3
	ds_read_b128 v[60:63], v80
	ds_read_b128 v[68:71], v80 offset:1024
	ds_read_b128 v[76:79], v80 offset:2048
	ds_read_b128 v[80:83], v80 offset:3072
	ds_read_b128 v[148:151], v160
	ds_read_b128 v[152:155], v160 offset:1024
	ds_read_b128 v[156:159], v160 offset:2048
	ds_read_b128 v[160:163], v160 offset:3072
	s_add_u32 s40, s40, s6
	s_addc_u32 s41, s41, s7
	s_mov_b32 m0, s72
	v_lshl_add_u64 v[190:191], s[40:41], 0, v[0:1]
	ds_read_b128 v[206:209], v175 offset:32768
	ds_read_b128 v[210:213], v175 offset:33792
	ds_read_b128 v[214:217], v175 offset:34816
	ds_read_b128 v[218:221], v175 offset:35840
	ds_read_b128 v[230:233], v175 offset:36864
	ds_read_b128 v[238:241], v175 offset:37888
	ds_read_b128 v[242:245], v175 offset:38912
	ds_read_b128 v[246:249], v175 offset:39936
	global_load_lds_dwordx4 v[190:191], off
	v_lshl_add_u64 v[190:191], s[40:41], 0, v[168:169]
	s_mov_b32 m0, s73
	s_nop 0
	global_load_lds_dwordx4 v[190:191], off
	s_waitcnt vmcnt(8)
	s_waitcnt lgkmcnt(0)
	s_barrier
	s_nop 0
	s_waitcnt lgkmcnt(0)
	v_mfma_f32_16x16x32_bf16 v[140:143], v[60:63], v[206:209], v[140:143]
	v_mfma_f32_16x16x32_bf16 v[144:147], v[76:79], v[206:209], v[144:147]
	v_mfma_f32_16x16x32_bf16 v[128:131], v[60:63], v[214:217], v[128:131]
	v_mfma_f32_16x16x32_bf16 v[124:127], v[76:79], v[214:217], v[124:127]
	v_mfma_f32_16x16x32_bf16 v[112:115], v[60:63], v[230:233], v[112:115]
	v_mfma_f32_16x16x32_bf16 v[108:111], v[76:79], v[230:233], v[108:111]
	v_mfma_f32_16x16x32_bf16 v[96:99], v[60:63], v[242:245], v[96:99]
	v_mfma_f32_16x16x32_bf16 v[92:95], v[76:79], v[242:245], v[92:95]
	v_mfma_f32_16x16x32_bf16 v[140:143], v[68:71], v[210:213], v[140:143]
	v_mfma_f32_16x16x32_bf16 v[144:147], v[80:83], v[210:213], v[144:147]
	v_mfma_f32_16x16x32_bf16 v[128:131], v[68:71], v[218:221], v[128:131]
	v_mfma_f32_16x16x32_bf16 v[124:127], v[80:83], v[218:221], v[124:127]
	v_mfma_f32_16x16x32_bf16 v[112:115], v[68:71], v[238:241], v[112:115]
	v_mfma_f32_16x16x32_bf16 v[108:111], v[80:83], v[238:241], v[108:111]
	v_mfma_f32_16x16x32_bf16 v[96:99], v[68:71], v[246:249], v[96:99]
	v_mfma_f32_16x16x32_bf16 v[92:95], v[80:83], v[246:249], v[92:95]
	s_nop 0
	s_nop 0
	v_mfma_f32_16x16x32_bf16 v[136:139], v[148:151], v[206:209], v[136:139]
	v_mfma_f32_16x16x32_bf16 v[132:135], v[156:159], v[206:209], v[132:135]
	v_mfma_f32_16x16x32_bf16 v[120:123], v[148:151], v[214:217], v[120:123]
	v_mfma_f32_16x16x32_bf16 v[116:119], v[156:159], v[214:217], v[116:119]
	v_mfma_f32_16x16x32_bf16 v[104:107], v[148:151], v[230:233], v[104:107]
	v_mfma_f32_16x16x32_bf16 v[100:103], v[156:159], v[230:233], v[100:103]
	v_mfma_f32_16x16x32_bf16 v[88:91], v[148:151], v[242:245], v[88:91]
	v_mfma_f32_16x16x32_bf16 v[84:87], v[156:159], v[242:245], v[84:87]
	v_mfma_f32_16x16x32_bf16 v[136:139], v[152:155], v[210:213], v[136:139]
	v_mfma_f32_16x16x32_bf16 v[132:135], v[160:163], v[210:213], v[132:135]
	v_mfma_f32_16x16x32_bf16 v[120:123], v[152:155], v[218:221], v[120:123]
	v_mfma_f32_16x16x32_bf16 v[116:119], v[160:163], v[218:221], v[116:119]
	v_mfma_f32_16x16x32_bf16 v[104:107], v[152:155], v[238:241], v[104:107]
	v_mfma_f32_16x16x32_bf16 v[100:103], v[160:163], v[238:241], v[100:103]
	v_mfma_f32_16x16x32_bf16 v[88:91], v[152:155], v[246:249], v[88:91]
	v_mfma_f32_16x16x32_bf16 v[84:87], v[160:163], v[246:249], v[84:87]
	s_nop 0
	s_barrier
; #define PG8_STAGE(bufoff, gbase, voff) do { _Pragma("unroll") for (int _i = 0; _i < 2; ++_i) \
;         __builtin_amdgcn_global_load_lds((const unsigned*)((const char*)(gbase) + (voff)[_i]), (LAS unsigned*)(lds + (bufoff) + ldsw + _i * 8192), 16, 0, 0); } while (0)
; #define PG8_STAGE_A1(bufoff, gbase) do { if (Epi::GATHER) PG8_STAGE(bufoff, gbase, voffA[1]); else PG8_STAGE(bufoff, (gbase) + hstep, voffA[0]); } while (0)
; #define PG8_LDA(dst, b, h) do { _Pragma("unroll") for (int m = 0; m < 4; ++m) _Pragma("unroll") for (int k = 0; k < 2; ++k) dst[m][k] = *(const LAS bf16x8*)(lds + PG8_SA(b, h) + aoff + m * 2048 + k * 1024); } while (0)
; #define PG8_LDB(dst, b, h) do { _Pragma("unroll") for (int n = 0; n < 2; ++n) _Pragma("unroll") for (int k = 0; k < 2; ++k) dst[n][k] = *(const LAS bf16x8*)(lds + PG8_SB(b, h) + boff + n * 2048 + k * 1024); } while (0)
; #define PG8_MMA(ai, bj, At, Bt) do { __builtin_amdgcn_s_setprio(1); _Pragma("unroll") for (int m = 0; m < 4; ++m) _Pragma("unroll") for (int n = 0; n < 2; ++n) _Pragma("unroll") for (int k = 0; k < 2; ++k) \
;         acc[ai][bj][m][n] = __builtin_amdgcn_mfma_f32_16x16x32_bf16(Bt[n][k], At[m][k], acc[ai][bj][m][n], 0, 0, 0); __builtin_amdgcn_s_setprio(0); } while (0)
; #define PG8_WAIT_V(n) asm volatile("s_waitcnt vmcnt(" #n ")" ::: "memory")
; #define PG8_WAIT_L(n) asm volatile("s_waitcnt lgkmcnt(" #n ")" ::: "memory")
; template <class Epi, class Sched>
; __device__ __forceinline__ void gemm_phase(const int tid, LAS unsigned char* lds, const bf16* Aop, const bf16* Bop, const int K_, const Sched& S, const Epi& E, const bf16* Aop1 = nullptr, const bf16* Bop1 = nullptr) {
;     ...
;         for (int t = 0; t < nt; t += 2) {
;             const bool last = (t == nt - 2);
;             const char* a1 = cA + (size_t)(t + 1) * kstep;
;             const char* a2 = last ? nA : cA + (size_t)(t + 2) * kstep; const char* b2 = last ? nB : cB + (size_t)(t + 2) * kstep;
;             const char* a3 = a2 + kstep; const char* b3 = b2 + kstep;
;             PG8_LDB(B0, 0, 0); PG8_LDB(B1, 0, 1); PG8_SCHED; PG8_LDA(At, 0, 0); PG8_STAGE_A1(PG8_SA(1, 1), a1);
;     ...
;             PG8_LDA(At, 1, 1); PG8_STAGE(PG8_SB(1, 0), b3, voffB); PG8_STAGE(PG8_SB(1, 1), b3 + hstep, voffB); PG8_STAGE(PG8_SA(1, 0), a3, voffA[0]);
;             PG8_WAIT_V(8); PG8_WAIT_L(0); PG8_BAR; PG8_MMA(1, 0, At, B0); PG8_MMA(1, 1, At, B1); PG8_BAR; PG8_SCHED;
	s_add_i32 s40, s44, s69
	v_lshl_add_u64 v[164:165], v[164:165], 0, s[20:21]
	s_mov_b32 m0, s40
	ds_read_b128 v[206:209], v175 offset:49152
	ds_read_b128 v[210:213], v175 offset:50176
	ds_read_b128 v[214:217], v175 offset:51200
	ds_read_b128 v[218:221], v175 offset:52224
	ds_read_b128 v[230:233], v175 offset:53248
	ds_read_b128 v[238:241], v175 offset:54272
	ds_read_b128 v[242:245], v175 offset:55296
	ds_read_b128 v[246:249], v175 offset:56320
	global_load_lds_dwordx4 v[164:165], off
	v_lshl_add_u64 v[164:165], v[222:223], 0, s[20:21]
	s_add_i32 m0, s40, 0x2000
	s_add_i32 s40, s45, s69
	global_load_lds_dwordx4 v[164:165], off
	v_lshl_add_u64 v[164:165], v[250:251], 0, s[20:21]
	s_mov_b32 m0, s40
	s_nop 0
	global_load_lds_dwordx4 v[164:165], off
	v_lshl_add_u64 v[164:165], v[196:197], 0, s[20:21]
	s_add_i32 m0, s40, 0x2000
	s_nop 0
	global_load_lds_dwordx4 v[164:165], off
	v_lshl_add_u64 v[164:165], v[198:199], 0, s[20:21]
	s_mov_b32 m0, s75
	s_nop 0
	global_load_lds_dwordx4 v[164:165], off
	v_lshl_add_u64 v[164:165], v[224:225], 0, s[20:21]
	s_mov_b32 m0, s76
	s_nop 0
	global_load_lds_dwordx4 v[164:165], off
	s_waitcnt vmcnt(8)
	s_waitcnt lgkmcnt(0)
	s_barrier
	s_nop 0
	s_waitcnt lgkmcnt(0)
	v_mfma_f32_16x16x32_bf16 v[72:75], v[60:63], v[206:209], v[72:75]
	v_mfma_f32_16x16x32_bf16 v[64:67], v[76:79], v[206:209], v[64:67]
	v_mfma_f32_16x16x32_bf16 v[48:51], v[60:63], v[214:217], v[48:51]
	v_mfma_f32_16x16x32_bf16 v[44:47], v[76:79], v[214:217], v[44:47]
	v_mfma_f32_16x16x32_bf16 v[32:35], v[60:63], v[230:233], v[32:35]
	v_mfma_f32_16x16x32_bf16 v[28:31], v[76:79], v[230:233], v[28:31]
	v_mfma_f32_16x16x32_bf16 v[16:19], v[60:63], v[242:245], v[16:19]
	v_mfma_f32_16x16x32_bf16 v[12:15], v[76:79], v[242:245], v[12:15]
	v_mfma_f32_16x16x32_bf16 v[72:75], v[68:71], v[210:213], v[72:75]
	v_mfma_f32_16x16x32_bf16 v[64:67], v[80:83], v[210:213], v[64:67]
	v_mfma_f32_16x16x32_bf16 v[48:51], v[68:71], v[218:221], v[48:51]
	v_mfma_f32_16x16x32_bf16 v[44:47], v[80:83], v[218:221], v[44:47]
	v_mfma_f32_16x16x32_bf16 v[32:35], v[68:71], v[238:241], v[32:35]
	v_mfma_f32_16x16x32_bf16 v[28:31], v[80:83], v[238:241], v[28:31]
	v_mfma_f32_16x16x32_bf16 v[16:19], v[68:71], v[246:249], v[16:19]
	v_mfma_f32_16x16x32_bf16 v[12:15], v[80:83], v[246:249], v[12:15]
	s_nop 0
	s_nop 0
	v_mfma_f32_16x16x32_bf16 v[56:59], v[148:151], v[206:209], v[56:59]
	v_mfma_f32_16x16x32_bf16 v[52:55], v[156:159], v[206:209], v[52:55]
	v_mfma_f32_16x16x32_bf16 v[40:43], v[148:151], v[214:217], v[40:43]
	v_mfma_f32_16x16x32_bf16 v[36:39], v[156:159], v[214:217], v[36:39]
	v_mfma_f32_16x16x32_bf16 v[24:27], v[148:151], v[230:233], v[24:27]
	v_mfma_f32_16x16x32_bf16 v[20:23], v[156:159], v[230:233], v[20:23]
	v_mfma_f32_16x16x32_bf16 v[8:11], v[148:151], v[242:245], v[8:11]
	v_mfma_f32_16x16x32_bf16 v[4:7], v[156:159], v[242:245], v[4:7]
	v_mfma_f32_16x16x32_bf16 v[56:59], v[152:155], v[210:213], v[56:59]
	v_mfma_f32_16x16x32_bf16 v[52:55], v[160:163], v[210:213], v[52:55]
	v_mfma_f32_16x16x32_bf16 v[40:43], v[152:155], v[218:221], v[40:43]
	v_mfma_f32_16x16x32_bf16 v[36:39], v[160:163], v[218:221], v[36:39]
	v_mfma_f32_16x16x32_bf16 v[24:27], v[152:155], v[238:241], v[24:27]
	v_mfma_f32_16x16x32_bf16 v[20:23], v[160:163], v[238:241], v[20:23]
	v_mfma_f32_16x16x32_bf16 v[8:11], v[152:155], v[246:249], v[8:11]
	v_mfma_f32_16x16x32_bf16 v[4:7], v[160:163], v[246:249], v[4:7]
	s_nop 0
	s_barrier
	s_add_u32 s26, s26, 0x100
	s_addc_u32 s27, s27, 0
	s_add_u32 s11, s11, 0x100
	s_addc_u32 s42, s42, 0
	s_cmp_ge_i32 s43, s74
	s_mov_b32 s40, s43
	s_cbranch_scc0 .LBB0_131
	s_branch .Lpeel_exit_131
.LBB0_131:
	s_add_i32 s43, s40, 2
	s_add_u32 s44, s26, 0x80
	s_addc_u32 s41, s27, 0
	s_add_i32 s48, 0, 0x10000
	s_cmp_eq_u32 s77, s40
	s_cselect_b32 s41, s35, s41
	s_cselect_b32 s40, s34, s44
	s_cselect_b32 s45, s37, s42
	s_cselect_b32 s44, s36, s11
	s_add_i32 s49, 0, 0x14000
	v_add_u32_e32 v80, s48, v3
	v_add_u32_e32 v160, s49, v3
	ds_read_b128 v[60:63], v80
	ds_read_b128 v[68:71], v80 offset:1024
	ds_read_b128 v[76:79], v80 offset:2048
	ds_read_b128 v[80:83], v80 offset:3072
	ds_read_b128 v[148:151], v160
	ds_read_b128 v[152:155], v160 offset:1024
	ds_read_b128 v[156:159], v160 offset:2048
	ds_read_b128 v[160:163], v160 offset:3072
	v_lshl_add_u64 v[164:165], s[26:27], 0, v[192:193]
	s_add_i32 m0, s70, 0xc000
	ds_read_b128 v[206:209], v175
	ds_read_b128 v[210:213], v175 offset:1024
	ds_read_b128 v[214:217], v175 offset:2048
	ds_read_b128 v[218:221], v175 offset:3072
	ds_read_b128 v[238:241], v175 offset:4096
	ds_read_b128 v[242:245], v175 offset:5120
	ds_read_b128 v[246:249], v175 offset:6144
	ds_read_b128 v[230:233], v175 offset:7168
	global_load_lds_dwordx4 v[164:165], off
	v_lshl_add_u64 v[164:165], s[26:27], 0, v[194:195]
	s_add_i32 m0, s70, 0xe000
	s_nop 0
	global_load_lds_dwordx4 v[164:165], off
	s_waitcnt vmcnt(8)
	s_waitcnt lgkmcnt(0)
	s_barrier
; #define PG8_GOFFS(slot_) do { _Pragma("unroll") for (int _i = 0; _i < 2; ++_i) { int R, C; stage_rc(tid * 16 + _i * 8192, R, C); _Pragma("unroll") for (int _h = 0; _h < 2; ++_h) { \
;         unsigned t_ = gtab[(slot_) * 256 + R + 128 * _h]; t_ = t_ < (unsigned)(T - 1) ? t_ : (unsigned)(T - 1); voffA[_h][_i] = (t_ * (unsigned)K + (unsigned)C) * 2u; } } } while (0)
; #define PG8_STAGE(bufoff, gbase, voff) do { _Pragma("unroll") for (int _i = 0; _i < 2; ++_i) \
;         __builtin_amdgcn_global_load_lds((const unsigned*)((const char*)(gbase) + (voff)[_i]), (LAS unsigned*)(lds + (bufoff) + ldsw + _i * 8192), 16, 0, 0); } while (0)
; #define PG8_LDA(dst, b, h) do { _Pragma("unroll") for (int m = 0; m < 4; ++m) _Pragma("unroll") for (int k = 0; k < 2; ++k) dst[m][k] = *(const LAS bf16x8*)(lds + PG8_SA(b, h) + aoff + m * 2048 + k * 1024); } while (0)
; #define PG8_MMA(ai, bj, At, Bt) do { __builtin_amdgcn_s_setprio(1); _Pragma("unroll") for (int m = 0; m < 4; ++m) _Pragma("unroll") for (int n = 0; n < 2; ++n) _Pragma("unroll") for (int k = 0; k < 2; ++k) \
;         acc[ai][bj][m][n] = __builtin_amdgcn_mfma_f32_16x16x32_bf16(Bt[n][k], At[m][k], acc[ai][bj][m][n], 0, 0, 0); __builtin_amdgcn_s_setprio(0); } while (0)
; #define PG8_WAIT_V(n) asm volatile("s_waitcnt vmcnt(" #n ")" ::: "memory")
; #define PG8_WAIT_L(n) asm volatile("s_waitcnt lgkmcnt(" #n ")" ::: "memory")
; #define PG8_BAR __builtin_amdgcn_s_barrier()
; #define PG8_SCHED __builtin_amdgcn_sched_barrier(0)
; template <class Epi, class Sched>
; __device__ __forceinline__ void gemm_phase(const int tid, LAS unsigned char* lds, const bf16* Aop, const bf16* Bop, const int K_, const Sched& S, const Epi& E, const bf16* Aop1 = nullptr, const bf16* Bop1 = nullptr) {
;     ...
;             PG8_WAIT_V(8); PG8_WAIT_L(0); PG8_BAR; PG8_MMA(0, 0, At, B0); PG8_MMA(0, 1, At, B1); PG8_BAR; PG8_SCHED;
;             PG8_LDA(At, 0, 1); PG8_STAGE(PG8_SB(0, 0), b2, voffB); PG8_STAGE(PG8_SB(0, 1), b2 + hstep, voffB); if (Epi::GATHER && last && has_next) PG8_GOFFS((ui + 1) & 1); PG8_STAGE(PG8_SA(0, 0), a2, voffA[0]);
;             PG8_WAIT_V(8); PG8_WAIT_L(0); PG8_BAR; PG8_MMA(1, 0, At, B0); PG8_MMA(1, 1, At, B1); PG8_BAR; PG8_SCHED;
	s_nop 0
	s_waitcnt lgkmcnt(0)
	v_mfma_f32_16x16x32_bf16 v[140:143], v[60:63], v[206:209], v[140:143]
	v_mfma_f32_16x16x32_bf16 v[144:147], v[76:79], v[206:209], v[144:147]
	v_mfma_f32_16x16x32_bf16 v[128:131], v[60:63], v[214:217], v[128:131]
	v_mfma_f32_16x16x32_bf16 v[124:127], v[76:79], v[214:217], v[124:127]
	v_mfma_f32_16x16x32_bf16 v[112:115], v[60:63], v[238:241], v[112:115]
	v_mfma_f32_16x16x32_bf16 v[108:111], v[76:79], v[238:241], v[108:111]
	v_mfma_f32_16x16x32_bf16 v[96:99], v[60:63], v[246:249], v[96:99]
	v_mfma_f32_16x16x32_bf16 v[92:95], v[76:79], v[246:249], v[92:95]
	v_mfma_f32_16x16x32_bf16 v[140:143], v[68:71], v[210:213], v[140:143]
	v_mfma_f32_16x16x32_bf16 v[144:147], v[80:83], v[210:213], v[144:147]
	v_mfma_f32_16x16x32_bf16 v[128:131], v[68:71], v[218:221], v[128:131]
	v_mfma_f32_16x16x32_bf16 v[124:127], v[80:83], v[218:221], v[124:127]
	v_mfma_f32_16x16x32_bf16 v[112:115], v[68:71], v[242:245], v[112:115]
	v_mfma_f32_16x16x32_bf16 v[108:111], v[80:83], v[242:245], v[108:111]
	v_mfma_f32_16x16x32_bf16 v[96:99], v[68:71], v[230:233], v[96:99]
	v_mfma_f32_16x16x32_bf16 v[92:95], v[80:83], v[230:233], v[92:95]
	s_nop 0
	s_nop 0
	v_mfma_f32_16x16x32_bf16 v[136:139], v[148:151], v[206:209], v[136:139]
	v_mfma_f32_16x16x32_bf16 v[132:135], v[156:159], v[206:209], v[132:135]
	v_mfma_f32_16x16x32_bf16 v[120:123], v[148:151], v[214:217], v[120:123]
	v_mfma_f32_16x16x32_bf16 v[116:119], v[156:159], v[214:217], v[116:119]
	v_mfma_f32_16x16x32_bf16 v[104:107], v[148:151], v[238:241], v[104:107]
	v_mfma_f32_16x16x32_bf16 v[100:103], v[156:159], v[238:241], v[100:103]
	v_mfma_f32_16x16x32_bf16 v[88:91], v[148:151], v[246:249], v[88:91]
	v_mfma_f32_16x16x32_bf16 v[84:87], v[156:159], v[246:249], v[84:87]
	v_mfma_f32_16x16x32_bf16 v[136:139], v[152:155], v[210:213], v[136:139]
	v_mfma_f32_16x16x32_bf16 v[132:135], v[160:163], v[210:213], v[132:135]
	v_mfma_f32_16x16x32_bf16 v[120:123], v[152:155], v[218:221], v[120:123]
	v_mfma_f32_16x16x32_bf16 v[116:119], v[160:163], v[218:221], v[116:119]
	v_mfma_f32_16x16x32_bf16 v[104:107], v[152:155], v[242:245], v[104:107]
	v_mfma_f32_16x16x32_bf16 v[100:103], v[160:163], v[242:245], v[100:103]
	v_mfma_f32_16x16x32_bf16 v[88:91], v[152:155], v[230:233], v[88:91]
	v_mfma_f32_16x16x32_bf16 v[84:87], v[160:163], v[230:233], v[84:87]
	s_nop 0
	s_barrier
	s_add_i32 s48, s48, s69
	v_lshl_add_u64 v[164:165], s[44:45], 0, v[166:167]
	s_mov_b32 m0, s48
	ds_read_b128 v[206:209], v175 offset:16384
	ds_read_b128 v[210:213], v175 offset:17408
	ds_read_b128 v[214:217], v175 offset:18432
	ds_read_b128 v[218:221], v175 offset:19456
	ds_read_b128 v[230:233], v175 offset:20480
	ds_read_b128 v[238:241], v175 offset:21504
	ds_read_b128 v[242:245], v175 offset:22528
	ds_read_b128 v[246:249], v175 offset:23552
	global_load_lds_dwordx4 v[164:165], off
	s_add_i32 m0, s48, 0x2000
	v_lshl_add_u64 v[222:223], s[44:45], 0, v[170:171]
	s_add_u32 s44, s44, s6
	s_addc_u32 s45, s45, s7
	s_add_i32 s48, s49, s69
	global_load_lds_dwordx4 v[222:223], off
	v_lshl_add_u64 v[250:251], s[44:45], 0, v[166:167]
	s_mov_b32 m0, s48
	v_lshl_add_u64 v[196:197], s[44:45], 0, v[170:171]
	global_load_lds_dwordx4 v[250:251], off
	s_add_i32 m0, s48, 0x2000
	v_lshl_add_u64 v[198:199], s[40:41], 0, v[0:1]
	global_load_lds_dwordx4 v[196:197], off
	s_mov_b32 m0, s70
	v_lshl_add_u64 v[224:225], s[40:41], 0, v[168:169]
	global_load_lds_dwordx4 v[198:199], off
	s_mov_b32 m0, s71
	s_nop 0
	global_load_lds_dwordx4 v[224:225], off
	s_waitcnt vmcnt(8)
	s_waitcnt lgkmcnt(0)
	s_barrier
	s_nop 0
	s_waitcnt lgkmcnt(0)
	v_mfma_f32_16x16x32_bf16 v[72:75], v[60:63], v[206:209], v[72:75]
	v_mfma_f32_16x16x32_bf16 v[64:67], v[76:79], v[206:209], v[64:67]
	v_mfma_f32_16x16x32_bf16 v[48:51], v[60:63], v[214:217], v[48:51]
	v_mfma_f32_16x16x32_bf16 v[44:47], v[76:79], v[214:217], v[44:47]
	v_mfma_f32_16x16x32_bf16 v[32:35], v[60:63], v[230:233], v[32:35]
	v_mfma_f32_16x16x32_bf16 v[28:31], v[76:79], v[230:233], v[28:31]
	v_mfma_f32_16x16x32_bf16 v[16:19], v[60:63], v[242:245], v[16:19]
	v_mfma_f32_16x16x32_bf16 v[12:15], v[76:79], v[242:245], v[12:15]
	v_mfma_f32_16x16x32_bf16 v[72:75], v[68:71], v[210:213], v[72:75]
	v_mfma_f32_16x16x32_bf16 v[64:67], v[80:83], v[210:213], v[64:67]
	v_mfma_f32_16x16x32_bf16 v[48:51], v[68:71], v[218:221], v[48:51]
	v_mfma_f32_16x16x32_bf16 v[44:47], v[80:83], v[218:221], v[44:47]
	v_mfma_f32_16x16x32_bf16 v[32:35], v[68:71], v[238:241], v[32:35]
	v_mfma_f32_16x16x32_bf16 v[28:31], v[80:83], v[238:241], v[28:31]
	v_mfma_f32_16x16x32_bf16 v[16:19], v[68:71], v[246:249], v[16:19]
	v_mfma_f32_16x16x32_bf16 v[12:15], v[80:83], v[246:249], v[12:15]
	s_nop 0
	s_nop 0
	v_mfma_f32_16x16x32_bf16 v[56:59], v[148:151], v[206:209], v[56:59]
	v_mfma_f32_16x16x32_bf16 v[52:55], v[156:159], v[206:209], v[52:55]
	v_mfma_f32_16x16x32_bf16 v[40:43], v[148:151], v[214:217], v[40:43]
	v_mfma_f32_16x16x32_bf16 v[36:39], v[156:159], v[214:217], v[36:39]
	v_mfma_f32_16x16x32_bf16 v[24:27], v[148:151], v[230:233], v[24:27]
	v_mfma_f32_16x16x32_bf16 v[20:23], v[156:159], v[230:233], v[20:23]
	v_mfma_f32_16x16x32_bf16 v[8:11], v[148:151], v[242:245], v[8:11]
	v_mfma_f32_16x16x32_bf16 v[4:7], v[156:159], v[242:245], v[4:7]
	v_mfma_f32_16x16x32_bf16 v[56:59], v[152:155], v[210:213], v[56:59]
	v_mfma_f32_16x16x32_bf16 v[52:55], v[160:163], v[210:213], v[52:55]
	v_mfma_f32_16x16x32_bf16 v[40:43], v[152:155], v[218:221], v[40:43]
	v_mfma_f32_16x16x32_bf16 v[36:39], v[160:163], v[218:221], v[36:39]
	v_mfma_f32_16x16x32_bf16 v[24:27], v[152:155], v[238:241], v[24:27]
	v_mfma_f32_16x16x32_bf16 v[20:23], v[160:163], v[238:241], v[20:23]
	v_mfma_f32_16x16x32_bf16 v[8:11], v[152:155], v[246:249], v[8:11]
	v_mfma_f32_16x16x32_bf16 v[4:7], v[160:163], v[246:249], v[4:7]
	s_nop 0
	s_barrier
; #define PG8_STAGE(bufoff, gbase, voff) do { _Pragma("unroll") for (int _i = 0; _i < 2; ++_i) \
;         __builtin_amdgcn_global_load_lds((const unsigned*)((const char*)(gbase) + (voff)[_i]), (LAS unsigned*)(lds + (bufoff) + ldsw + _i * 8192), 16, 0, 0); } while (0)
; #define PG8_STAGE_A1(bufoff, gbase) do { if (Epi::GATHER) PG8_STAGE(bufoff, gbase, voffA[1]); else PG8_STAGE(bufoff, (gbase) + hstep, voffA[0]); } while (0)
; #define PG8_LDA(dst, b, h) do { _Pragma("unroll") for (int m = 0; m < 4; ++m) _Pragma("unroll") for (int k = 0; k < 2; ++k) dst[m][k] = *(const LAS bf16x8*)(lds + PG8_SA(b, h) + aoff + m * 2048 + k * 1024); } while (0)
; #define PG8_LDB(dst, b, h) do { _Pragma("unroll") for (int n = 0; n < 2; ++n) _Pragma("unroll") for (int k = 0; k < 2; ++k) dst[n][k] = *(const LAS bf16x8*)(lds + PG8_SB(b, h) + boff + n * 2048 + k * 1024); } while (0)
; #define PG8_MMA(ai, bj, At, Bt) do { __builtin_amdgcn_s_setprio(1); _Pragma("unroll") for (int m = 0; m < 4; ++m) _Pragma("unroll") for (int n = 0; n < 2; ++n) _Pragma("unroll") for (int k = 0; k < 2; ++k) \
;         acc[ai][bj][m][n] = __builtin_amdgcn_mfma_f32_16x16x32_bf16(Bt[n][k], At[m][k], acc[ai][bj][m][n], 0, 0, 0); __builtin_amdgcn_s_setprio(0); } while (0)
; #define PG8_WAIT_V(n) asm volatile("s_waitcnt vmcnt(" #n ")" ::: "memory")
; #define PG8_WAIT_L(n) asm volatile("s_waitcnt lgkmcnt(" #n ")" ::: "memory")
; #define PG8_BAR __builtin_amdgcn_s_barrier()
; #define PG8_SCHED __builtin_amdgcn_sched_barrier(0)
; template <class Epi, class Sched>
; __device__ __forceinline__ void gemm_phase(const int tid, LAS unsigned char* lds, const bf16* Aop, const bf16* Bop, const int K_, const Sched& S, const Epi& E, const bf16* Aop1 = nullptr, const bf16* Bop1 = nullptr) {
;     ...
;             PG8_LDB(B0, 1, 0); PG8_LDB(B1, 1, 1); PG8_SCHED; PG8_LDA(At, 1, 0); PG8_STAGE_A1(PG8_SA(0, 1), a2);
;             PG8_WAIT_V(8); PG8_WAIT_L(0); PG8_BAR; PG8_MMA(0, 0, At, B0); PG8_MMA(0, 1, At, B1); PG8_BAR; PG8_SCHED;
;             PG8_LDA(At, 1, 1); PG8_STAGE(PG8_SB(1, 0), b3, voffB); PG8_STAGE(PG8_SB(1, 1), b3 + hstep, voffB); PG8_STAGE(PG8_SA(1, 0), a3, voffA[0]);
;             PG8_WAIT_V(8); PG8_WAIT_L(0); PG8_BAR; PG8_MMA(1, 0, At, B0); PG8_MMA(1, 1, At, B1); PG8_BAR; PG8_SCHED;
;         }
	s_add_i32 s44, 0, 0x18000
	s_add_i32 s45, 0, 0x1c000
	v_add_u32_e32 v80, s44, v3
	v_add_u32_e32 v160, s45, v3
	ds_read_b128 v[60:63], v80
	ds_read_b128 v[68:71], v80 offset:1024
	ds_read_b128 v[76:79], v80 offset:2048
	ds_read_b128 v[80:83], v80 offset:3072
	ds_read_b128 v[148:151], v160
	ds_read_b128 v[152:155], v160 offset:1024
	ds_read_b128 v[156:159], v160 offset:2048
	ds_read_b128 v[160:163], v160 offset:3072
	s_add_u32 s40, s40, s6
	s_addc_u32 s41, s41, s7
	s_mov_b32 m0, s72
	v_lshl_add_u64 v[190:191], s[40:41], 0, v[0:1]
	ds_read_b128 v[206:209], v175 offset:32768
	ds_read_b128 v[210:213], v175 offset:33792
	ds_read_b128 v[214:217], v175 offset:34816
	ds_read_b128 v[218:221], v175 offset:35840
	ds_read_b128 v[230:233], v175 offset:36864
	ds_read_b128 v[238:241], v175 offset:37888
	ds_read_b128 v[242:245], v175 offset:38912
	ds_read_b128 v[246:249], v175 offset:39936
	global_load_lds_dwordx4 v[190:191], off
	v_lshl_add_u64 v[190:191], s[40:41], 0, v[168:169]
	s_mov_b32 m0, s73
	s_nop 0
	global_load_lds_dwordx4 v[190:191], off
	s_waitcnt vmcnt(8)
	s_waitcnt lgkmcnt(0)
	s_barrier
	s_nop 0
	s_waitcnt lgkmcnt(0)
	v_mfma_f32_16x16x32_bf16 v[140:143], v[60:63], v[206:209], v[140:143]
	v_mfma_f32_16x16x32_bf16 v[144:147], v[76:79], v[206:209], v[144:147]
	v_mfma_f32_16x16x32_bf16 v[128:131], v[60:63], v[214:217], v[128:131]
	v_mfma_f32_16x16x32_bf16 v[124:127], v[76:79], v[214:217], v[124:127]
	v_mfma_f32_16x16x32_bf16 v[112:115], v[60:63], v[230:233], v[112:115]
	v_mfma_f32_16x16x32_bf16 v[108:111], v[76:79], v[230:233], v[108:111]
	v_mfma_f32_16x16x32_bf16 v[96:99], v[60:63], v[242:245], v[96:99]
	v_mfma_f32_16x16x32_bf16 v[92:95], v[76:79], v[242:245], v[92:95]
	v_mfma_f32_16x16x32_bf16 v[140:143], v[68:71], v[210:213], v[140:143]
	v_mfma_f32_16x16x32_bf16 v[144:147], v[80:83], v[210:213], v[144:147]
	v_mfma_f32_16x16x32_bf16 v[128:131], v[68:71], v[218:221], v[128:131]
	v_mfma_f32_16x16x32_bf16 v[124:127], v[80:83], v[218:221], v[124:127]
	v_mfma_f32_16x16x32_bf16 v[112:115], v[68:71], v[238:241], v[112:115]
	v_mfma_f32_16x16x32_bf16 v[108:111], v[80:83], v[238:241], v[108:111]
	v_mfma_f32_16x16x32_bf16 v[96:99], v[68:71], v[246:249], v[96:99]
	v_mfma_f32_16x16x32_bf16 v[92:95], v[80:83], v[246:249], v[92:95]
	s_nop 0
	s_nop 0
	v_mfma_f32_16x16x32_bf16 v[136:139], v[148:151], v[206:209], v[136:139]
	v_mfma_f32_16x16x32_bf16 v[132:135], v[156:159], v[206:209], v[132:135]
	v_mfma_f32_16x16x32_bf16 v[120:123], v[148:151], v[214:217], v[120:123]
	v_mfma_f32_16x16x32_bf16 v[116:119], v[156:159], v[214:217], v[116:119]
	v_mfma_f32_16x16x32_bf16 v[104:107], v[148:151], v[230:233], v[104:107]
	v_mfma_f32_16x16x32_bf16 v[100:103], v[156:159], v[230:233], v[100:103]
	v_mfma_f32_16x16x32_bf16 v[88:91], v[148:151], v[242:245], v[88:91]
	v_mfma_f32_16x16x32_bf16 v[84:87], v[156:159], v[242:245], v[84:87]
	v_mfma_f32_16x16x32_bf16 v[136:139], v[152:155], v[210:213], v[136:139]
	v_mfma_f32_16x16x32_bf16 v[132:135], v[160:163], v[210:213], v[132:135]
	v_mfma_f32_16x16x32_bf16 v[120:123], v[152:155], v[218:221], v[120:123]
	v_mfma_f32_16x16x32_bf16 v[116:119], v[160:163], v[218:221], v[116:119]
	v_mfma_f32_16x16x32_bf16 v[104:107], v[152:155], v[238:241], v[104:107]
	v_mfma_f32_16x16x32_bf16 v[100:103], v[160:163], v[238:241], v[100:103]
	v_mfma_f32_16x16x32_bf16 v[88:91], v[152:155], v[246:249], v[88:91]
	v_mfma_f32_16x16x32_bf16 v[84:87], v[160:163], v[246:249], v[84:87]
	s_nop 0
	s_barrier
	s_add_i32 s40, s44, s69
	v_lshl_add_u64 v[164:165], v[164:165], 0, s[20:21]
	s_mov_b32 m0, s40
	ds_read_b128 v[206:209], v175 offset:49152
	ds_read_b128 v[210:213], v175 offset:50176
	ds_read_b128 v[214:217], v175 offset:51200
	ds_read_b128 v[218:221], v175 offset:52224
	ds_read_b128 v[230:233], v175 offset:53248
	ds_read_b128 v[238:241], v175 offset:54272
	ds_read_b128 v[242:245], v175 offset:55296
	ds_read_b128 v[246:249], v175 offset:56320
	global_load_lds_dwordx4 v[164:165], off
	v_lshl_add_u64 v[164:165], v[222:223], 0, s[20:21]
	s_add_i32 m0, s40, 0x2000
	s_add_i32 s40, s45, s69
	global_load_lds_dwordx4 v[164:165], off
	v_lshl_add_u64 v[164:165], v[250:251], 0, s[20:21]
	s_mov_b32 m0, s40
	s_nop 0
	global_load_lds_dwordx4 v[164:165], off
	v_lshl_add_u64 v[164:165], v[196:197], 0, s[20:21]
	s_add_i32 m0, s40, 0x2000
	s_nop 0
	global_load_lds_dwordx4 v[164:165], off
	v_lshl_add_u64 v[164:165], v[198:199], 0, s[20:21]
	s_mov_b32 m0, s75
	s_nop 0
	global_load_lds_dwordx4 v[164:165], off
	v_lshl_add_u64 v[164:165], v[224:225], 0, s[20:21]
	s_mov_b32 m0, s76
	s_nop 0
	global_load_lds_dwordx4 v[164:165], off
	s_waitcnt vmcnt(8)
	s_waitcnt lgkmcnt(0)
	s_barrier
	s_nop 0
	s_waitcnt lgkmcnt(0)
	v_mfma_f32_16x16x32_bf16 v[72:75], v[60:63], v[206:209], v[72:75]
	v_mfma_f32_16x16x32_bf16 v[64:67], v[76:79], v[206:209], v[64:67]
	v_mfma_f32_16x16x32_bf16 v[48:51], v[60:63], v[214:217], v[48:51]
	v_mfma_f32_16x16x32_bf16 v[44:47], v[76:79], v[214:217], v[44:47]
	v_mfma_f32_16x16x32_bf16 v[32:35], v[60:63], v[230:233], v[32:35]
	v_mfma_f32_16x16x32_bf16 v[28:31], v[76:79], v[230:233], v[28:31]
	v_mfma_f32_16x16x32_bf16 v[16:19], v[60:63], v[242:245], v[16:19]
	v_mfma_f32_16x16x32_bf16 v[12:15], v[76:79], v[242:245], v[12:15]
	v_mfma_f32_16x16x32_bf16 v[72:75], v[68:71], v[210:213], v[72:75]
	v_mfma_f32_16x16x32_bf16 v[64:67], v[80:83], v[210:213], v[64:67]
	v_mfma_f32_16x16x32_bf16 v[48:51], v[68:71], v[218:221], v[48:51]
	v_mfma_f32_16x16x32_bf16 v[44:47], v[80:83], v[218:221], v[44:47]
	v_mfma_f32_16x16x32_bf16 v[32:35], v[68:71], v[238:241], v[32:35]
	v_mfma_f32_16x16x32_bf16 v[28:31], v[80:83], v[238:241], v[28:31]
	v_mfma_f32_16x16x32_bf16 v[16:19], v[68:71], v[246:249], v[16:19]
	v_mfma_f32_16x16x32_bf16 v[12:15], v[80:83], v[246:249], v[12:15]
	s_nop 0
	s_nop 0
	v_mfma_f32_16x16x32_bf16 v[56:59], v[148:151], v[206:209], v[56:59]
	v_mfma_f32_16x16x32_bf16 v[52:55], v[156:159], v[206:209], v[52:55]
	v_mfma_f32_16x16x32_bf16 v[40:43], v[148:151], v[214:217], v[40:43]
	v_mfma_f32_16x16x32_bf16 v[36:39], v[156:159], v[214:217], v[36:39]
	v_mfma_f32_16x16x32_bf16 v[24:27], v[148:151], v[230:233], v[24:27]
	v_mfma_f32_16x16x32_bf16 v[20:23], v[156:159], v[230:233], v[20:23]
	v_mfma_f32_16x16x32_bf16 v[8:11], v[148:151], v[242:245], v[8:11]
	v_mfma_f32_16x16x32_bf16 v[4:7], v[156:159], v[242:245], v[4:7]
	v_mfma_f32_16x16x32_bf16 v[56:59], v[152:155], v[210:213], v[56:59]
	v_mfma_f32_16x16x32_bf16 v[52:55], v[160:163], v[210:213], v[52:55]
	v_mfma_f32_16x16x32_bf16 v[40:43], v[152:155], v[218:221], v[40:43]
	v_mfma_f32_16x16x32_bf16 v[36:39], v[160:163], v[218:221], v[36:39]
	v_mfma_f32_16x16x32_bf16 v[24:27], v[152:155], v[238:241], v[24:27]
	v_mfma_f32_16x16x32_bf16 v[20:23], v[160:163], v[238:241], v[20:23]
	v_mfma_f32_16x16x32_bf16 v[8:11], v[152:155], v[246:249], v[8:11]
	v_mfma_f32_16x16x32_bf16 v[4:7], v[160:163], v[246:249], v[4:7]
	s_nop 0
	s_barrier
	s_add_u32 s26, s26, 0x100
	s_addc_u32 s27, s27, 0
	s_add_u32 s11, s11, 0x100
	s_addc_u32 s42, s42, 0
	s_cmp_ge_i32 s43, s74
	s_mov_b32 s40, s43
	s_cbranch_scc0 .LBB0_131

; #define LAS __attribute__((address_space(3)))
;     __device__ bool next(int i, Unit& u) const { if (!so.next(i >> 1, u)) return false; u.sel = i & 1; return true; }
;     __device__ bool next(int i, Unit& u) const { const int L = i * nw + r; if (L >= nu) return false; u.pm = L >> 2; u.pn = L & 3; u.pb = u.pn; u.sel = 0; return true; }
; #define PG8_STAGE(bufoff, gbase, voff) do { _Pragma("unroll") for (int _i = 0; _i < 2; ++_i) \
;         __builtin_amdgcn_global_load_lds((const unsigned*)((const char*)(gbase) + (voff)[_i]), (LAS unsigned*)(lds + (bufoff) + ldsw + _i * 8192), 16, 0, 0); } while (0)
; template <class Epi, class Sched>
; __device__ __forceinline__ void gemm_phase(const int tid, LAS unsigned char* lds, const bf16* Aop, const bf16* Bop, const int K_, const Sched& S, const Epi& E, const bf16* Aop1 = nullptr, const bf16* Bop1 = nullptr) {
;     ...
;     for (;;) {
;         const bool has_next = S.next(ui + 1, nxt);
;         if (Epi::GATHER && has_next && wid < 4) E.tok_dma(nxt.pm * 256 + wid * 64, (LAS unsigned*)(lds + 8 * HTB) + ((ui + 1) & 1) * 256 + wid * 64, lane);
;         const char* nA = has_next ? (const char*)((Aop1 && nxt.sel) ? Aop1 : Aop) + (Epi::GATHER ? (size_t)0 : (size_t)nxt.pm * tstep) : cA; const char* nB = has_next ? (const char*)((Bop1 && nxt.sel) ? Bop1 : Bop) + (size_t)nxt.pb * tstep : cB;
;         for (int t = 0; t < nt; t += 2) {
;             const bool last = (t == nt - 2);
;             const char* a1 = cA + (size_t)(t + 1) * kstep;
;             const char* a2 = last ? nA : cA + (size_t)(t + 2) * kstep; const char* b2 = last ? nB : cB + (size_t)(t + 2) * kstep;
;             const char* a3 = a2 + kstep; const char* b3 = b2 + kstep;
;             PG8_LDB(B0, 0, 0); PG8_LDB(B1, 0, 1); PG8_SCHED; PG8_LDA(At, 0, 0); PG8_STAGE_A1(PG8_SA(1, 1), a1);
;             PG8_WAIT_V(8); PG8_WAIT_L(0); PG8_BAR; PG8_MMA(0, 0, At, B0); PG8_MMA(0, 1, At, B1); PG8_BAR; PG8_SCHED;
;             PG8_LDA(At, 0, 1); PG8_STAGE(PG8_SB(0, 0), b2, voffB); PG8_STAGE(PG8_SB(0, 1), b2 + hstep, voffB); if (Epi::GATHER && last && has_next) PG8_GOFFS((ui + 1) & 1); PG8_STAGE(PG8_SA(0, 0), a2, voffA[0]);
;             PG8_WAIT_V(8); PG8_WAIT_L(0); PG8_BAR; PG8_MMA(1, 0, At, B0); PG8_MMA(1, 1, At, B1); PG8_BAR; PG8_SCHED;
;             PG8_LDB(B0, 1, 0); PG8_LDB(B1, 1, 1); PG8_SCHED; PG8_LDA(At, 1, 0); PG8_STAGE_A1(PG8_SA(0, 1), a2);
.LBB0_998:
	v_mov_b32_e32 v131, 0
	s_andn2_b64 vcc, exec, s[44:45]
	s_cbranch_vccnz .LBB0_1001
	s_add_u32 s12, s12, 0x80
	s_addc_u32 s13, s13, 0
	s_add_u32 s11, s26, 0x100
	s_addc_u32 s71, s27, 0
	s_mov_b32 s26, 0
	s_add_i32 s72, s26, 2
	s_add_u32 s73, s12, 0x80
	s_addc_u32 s27, s13, 0
	s_add_i32 s76, 0, 0x10000
	s_cmp_eq_u32 s64, s26
	s_cselect_b32 s27, s7, s27
	s_cselect_b32 s26, s6, s73
	s_cselect_b32 s75, s41, s71
	s_cselect_b32 s74, s40, s11
	s_add_i32 s73, 0, 0x14000
	v_add_u32_e32 v156, s76, v171
	v_add_u32_e32 v178, s73, v171
	ds_read_b128 v[132:135], v156
	ds_read_b128 v[148:151], v156 offset:1024
	ds_read_b128 v[152:155], v156 offset:2048
	ds_read_b128 v[156:159], v156 offset:3072
	ds_read_b128 v[160:163], v178
	ds_read_b128 v[164:167], v178 offset:1024
	ds_read_b128 v[174:177], v178 offset:2048
	ds_read_b128 v[178:181], v178 offset:3072
	v_lshl_add_u64 v[194:195], s[12:13], 0, v[144:145]
	s_add_i32 m0, s56, 0xc000
	ds_read_b128 v[182:185], v173
	ds_read_b128 v[186:189], v173 offset:1024
	ds_read_b128 v[190:193], v173 offset:2048
	ds_read_b128 v[202:205], v173 offset:3072
	ds_read_b128 v[206:209], v173 offset:4096
	ds_read_b128 v[210:213], v173 offset:5120
	ds_read_b128 v[214:217], v173 offset:6144
	ds_read_b128 v[218:221], v173 offset:7168
	global_load_lds_dwordx4 v[194:195], off
	v_lshl_add_u64 v[194:195], s[12:13], 0, v[146:147]
	s_add_i32 m0, s56, 0xe000
	s_nop 0
	global_load_lds_dwordx4 v[194:195], off
	s_waitcnt vmcnt(8)
	s_waitcnt lgkmcnt(0)
	s_barrier
	s_nop 0
	s_waitcnt lgkmcnt(0)
	v_mfma_f32_16x16x32_bf16 v[128:131], v[132:135], v[182:185], 0
	v_mfma_f32_16x16x32_bf16 v[124:127], v[152:155], v[182:185], 0
	v_mfma_f32_16x16x32_bf16 v[112:115], v[132:135], v[190:193], 0
	v_mfma_f32_16x16x32_bf16 v[108:111], v[152:155], v[190:193], 0
	v_mfma_f32_16x16x32_bf16 v[96:99], v[132:135], v[206:209], 0
	v_mfma_f32_16x16x32_bf16 v[92:95], v[152:155], v[206:209], 0
	v_mfma_f32_16x16x32_bf16 v[80:83], v[132:135], v[214:217], 0
	v_mfma_f32_16x16x32_bf16 v[76:79], v[152:155], v[214:217], 0
	v_mfma_f32_16x16x32_bf16 v[128:131], v[148:151], v[186:189], v[128:131]
	v_mfma_f32_16x16x32_bf16 v[124:127], v[156:159], v[186:189], v[124:127]
	v_mfma_f32_16x16x32_bf16 v[112:115], v[148:151], v[202:205], v[112:115]
	v_mfma_f32_16x16x32_bf16 v[108:111], v[156:159], v[202:205], v[108:111]
	v_mfma_f32_16x16x32_bf16 v[96:99], v[148:151], v[210:213], v[96:99]
	v_mfma_f32_16x16x32_bf16 v[92:95], v[156:159], v[210:213], v[92:95]
	v_mfma_f32_16x16x32_bf16 v[80:83], v[148:151], v[218:221], v[80:83]
	v_mfma_f32_16x16x32_bf16 v[76:79], v[156:159], v[218:221], v[76:79]
	s_nop 0
	s_nop 0
	v_mfma_f32_16x16x32_bf16 v[120:123], v[160:163], v[182:185], 0
	v_mfma_f32_16x16x32_bf16 v[116:119], v[174:177], v[182:185], 0
	v_mfma_f32_16x16x32_bf16 v[104:107], v[160:163], v[190:193], 0
	v_mfma_f32_16x16x32_bf16 v[100:103], v[174:177], v[190:193], 0
	v_mfma_f32_16x16x32_bf16 v[88:91], v[160:163], v[206:209], 0
	v_mfma_f32_16x16x32_bf16 v[84:87], v[174:177], v[206:209], 0
	v_mfma_f32_16x16x32_bf16 v[72:75], v[160:163], v[214:217], 0
	v_mfma_f32_16x16x32_bf16 v[68:71], v[174:177], v[214:217], 0
	v_mfma_f32_16x16x32_bf16 v[120:123], v[164:167], v[186:189], v[120:123]
	v_mfma_f32_16x16x32_bf16 v[116:119], v[178:181], v[186:189], v[116:119]
	v_mfma_f32_16x16x32_bf16 v[104:107], v[164:167], v[202:205], v[104:107]
	v_mfma_f32_16x16x32_bf16 v[100:103], v[178:181], v[202:205], v[100:103]
	v_mfma_f32_16x16x32_bf16 v[88:91], v[164:167], v[210:213], v[88:91]
	v_mfma_f32_16x16x32_bf16 v[84:87], v[178:181], v[210:213], v[84:87]
	v_mfma_f32_16x16x32_bf16 v[72:75], v[164:167], v[218:221], v[72:75]
	v_mfma_f32_16x16x32_bf16 v[68:71], v[178:181], v[218:221], v[68:71]
	s_nop 0
	s_barrier
	s_add_i32 s76, s76, s55
	v_lshl_add_u64 v[194:195], s[74:75], 0, v[136:137]
	s_mov_b32 m0, s76
	ds_read_b128 v[182:185], v173 offset:16384
	ds_read_b128 v[186:189], v173 offset:17408
	ds_read_b128 v[190:193], v173 offset:18432
	ds_read_b128 v[202:205], v173 offset:19456
	ds_read_b128 v[206:209], v173 offset:20480
	ds_read_b128 v[210:213], v173 offset:21504
	ds_read_b128 v[214:217], v173 offset:22528
	ds_read_b128 v[218:221], v173 offset:23552
	global_load_lds_dwordx4 v[194:195], off
	s_add_i32 m0, s76, 0x2000
	v_lshl_add_u64 v[196:197], s[74:75], 0, v[140:141]
	s_add_u32 s74, s74, s18
	s_addc_u32 s75, s75, s19
	s_add_i32 s73, s73, s55
	global_load_lds_dwordx4 v[196:197], off
	v_lshl_add_u64 v[198:199], s[74:75], 0, v[136:137]
	s_mov_b32 m0, s73
	v_lshl_add_u64 v[222:223], s[74:75], 0, v[140:141]
	global_load_lds_dwordx4 v[198:199], off
	s_add_i32 m0, s73, 0x2000
	v_lshl_add_u64 v[224:225], s[26:27], 0, v[0:1]
	global_load_lds_dwordx4 v[222:223], off
	s_mov_b32 m0, s56
	v_lshl_add_u64 v[230:231], s[26:27], 0, v[138:139]
	global_load_lds_dwordx4 v[224:225], off
	s_mov_b32 m0, s57
	s_nop 0
	global_load_lds_dwordx4 v[230:231], off
	s_waitcnt vmcnt(8)
	s_waitcnt lgkmcnt(0)
	s_barrier
; #define PG8_STAGE_A1(bufoff, gbase) do { if (Epi::GATHER) PG8_STAGE(bufoff, gbase, voffA[1]); else PG8_STAGE(bufoff, (gbase) + hstep, voffA[0]); } while (0)
; #define PG8_LDA(dst, b, h) do { _Pragma("unroll") for (int m = 0; m < 4; ++m) _Pragma("unroll") for (int k = 0; k < 2; ++k) dst[m][k] = *(const LAS bf16x8*)(lds + PG8_SA(b, h) + aoff + m * 2048 + k * 1024); } while (0)
; #define PG8_LDB(dst, b, h) do { _Pragma("unroll") for (int n = 0; n < 2; ++n) _Pragma("unroll") for (int k = 0; k < 2; ++k) dst[n][k] = *(const LAS bf16x8*)(lds + PG8_SB(b, h) + boff + n * 2048 + k * 1024); } while (0)
; #define PG8_MMA(ai, bj, At, Bt) do { __builtin_amdgcn_s_setprio(1); _Pragma("unroll") for (int m = 0; m < 4; ++m) _Pragma("unroll") for (int n = 0; n < 2; ++n) _Pragma("unroll") for (int k = 0; k < 2; ++k) \
;         acc[ai][bj][m][n] = __builtin_amdgcn_mfma_f32_16x16x32_bf16(Bt[n][k], At[m][k], acc[ai][bj][m][n], 0, 0, 0); __builtin_amdgcn_s_setprio(0); } while (0)
; #define PG8_WAIT_V(n) asm volatile("s_waitcnt vmcnt(" #n ")" ::: "memory")
; #define PG8_WAIT_L(n) asm volatile("s_waitcnt lgkmcnt(" #n ")" ::: "memory")
; #define PG8_BAR __builtin_amdgcn_s_barrier()
; #define PG8_SCHED __builtin_amdgcn_sched_barrier(0)
; template <class Epi, class Sched>
; __device__ __forceinline__ void gemm_phase(const int tid, LAS unsigned char* lds, const bf16* Aop, const bf16* Bop, const int K_, const Sched& S, const Epi& E, const bf16* Aop1 = nullptr, const bf16* Bop1 = nullptr) {
;     ...
;             PG8_WAIT_V(8); PG8_WAIT_L(0); PG8_BAR; PG8_MMA(1, 0, At, B0); PG8_MMA(1, 1, At, B1); PG8_BAR; PG8_SCHED;
;             PG8_LDB(B0, 1, 0); PG8_LDB(B1, 1, 1); PG8_SCHED; PG8_LDA(At, 1, 0); PG8_STAGE_A1(PG8_SA(0, 1), a2);
;             PG8_WAIT_V(8); PG8_WAIT_L(0); PG8_BAR; PG8_MMA(0, 0, At, B0); PG8_MMA(0, 1, At, B1); PG8_BAR; PG8_SCHED;
	s_nop 0
	s_waitcnt lgkmcnt(0)
	v_mfma_f32_16x16x32_bf16 v[64:67], v[132:135], v[182:185], 0
	v_mfma_f32_16x16x32_bf16 v[60:63], v[152:155], v[182:185], 0
	v_mfma_f32_16x16x32_bf16 v[48:51], v[132:135], v[190:193], 0
	v_mfma_f32_16x16x32_bf16 v[44:47], v[152:155], v[190:193], 0
	v_mfma_f32_16x16x32_bf16 v[32:35], v[132:135], v[206:209], 0
	v_mfma_f32_16x16x32_bf16 v[28:31], v[152:155], v[206:209], 0
	v_mfma_f32_16x16x32_bf16 v[16:19], v[132:135], v[214:217], 0
	v_mfma_f32_16x16x32_bf16 v[12:15], v[152:155], v[214:217], 0
	v_mfma_f32_16x16x32_bf16 v[64:67], v[148:151], v[186:189], v[64:67]
	v_mfma_f32_16x16x32_bf16 v[60:63], v[156:159], v[186:189], v[60:63]
	v_mfma_f32_16x16x32_bf16 v[48:51], v[148:151], v[202:205], v[48:51]
	v_mfma_f32_16x16x32_bf16 v[44:47], v[156:159], v[202:205], v[44:47]
	v_mfma_f32_16x16x32_bf16 v[32:35], v[148:151], v[210:213], v[32:35]
	v_mfma_f32_16x16x32_bf16 v[28:31], v[156:159], v[210:213], v[28:31]
	v_mfma_f32_16x16x32_bf16 v[16:19], v[148:151], v[218:221], v[16:19]
	v_mfma_f32_16x16x32_bf16 v[12:15], v[156:159], v[218:221], v[12:15]
	s_nop 0
	s_nop 0
	v_mfma_f32_16x16x32_bf16 v[56:59], v[160:163], v[182:185], 0
	v_mfma_f32_16x16x32_bf16 v[52:55], v[174:177], v[182:185], 0
	v_mfma_f32_16x16x32_bf16 v[40:43], v[160:163], v[190:193], 0
	v_mfma_f32_16x16x32_bf16 v[36:39], v[174:177], v[190:193], 0
	v_mfma_f32_16x16x32_bf16 v[24:27], v[160:163], v[206:209], 0
	v_mfma_f32_16x16x32_bf16 v[20:23], v[174:177], v[206:209], 0
	v_mfma_f32_16x16x32_bf16 v[8:11], v[160:163], v[214:217], 0
	v_mfma_f32_16x16x32_bf16 v[4:7], v[174:177], v[214:217], 0
	v_mfma_f32_16x16x32_bf16 v[56:59], v[164:167], v[186:189], v[56:59]
	v_mfma_f32_16x16x32_bf16 v[52:55], v[178:181], v[186:189], v[52:55]
	v_mfma_f32_16x16x32_bf16 v[40:43], v[164:167], v[202:205], v[40:43]
	v_mfma_f32_16x16x32_bf16 v[36:39], v[178:181], v[202:205], v[36:39]
	v_mfma_f32_16x16x32_bf16 v[24:27], v[164:167], v[210:213], v[24:27]
	v_mfma_f32_16x16x32_bf16 v[20:23], v[178:181], v[210:213], v[20:23]
	v_mfma_f32_16x16x32_bf16 v[8:11], v[164:167], v[218:221], v[8:11]
	v_mfma_f32_16x16x32_bf16 v[4:7], v[178:181], v[218:221], v[4:7]
	s_nop 0
	s_barrier
	s_add_i32 s73, 0, 0x18000
	s_add_i32 s74, 0, 0x1c000
	v_add_u32_e32 v156, s73, v171
	v_add_u32_e32 v178, s74, v171
	ds_read_b128 v[132:135], v156
	ds_read_b128 v[148:151], v156 offset:1024
	ds_read_b128 v[152:155], v156 offset:2048
	ds_read_b128 v[156:159], v156 offset:3072
	ds_read_b128 v[160:163], v178
	ds_read_b128 v[164:167], v178 offset:1024
	ds_read_b128 v[174:177], v178 offset:2048
	ds_read_b128 v[178:181], v178 offset:3072
	s_add_u32 s26, s26, s18
	s_addc_u32 s27, s27, s19
	s_mov_b32 m0, s58
	v_lshl_add_u64 v[232:233], s[26:27], 0, v[0:1]
	ds_read_b128 v[182:185], v173 offset:32768
	ds_read_b128 v[186:189], v173 offset:33792
	ds_read_b128 v[190:193], v173 offset:34816
	ds_read_b128 v[202:205], v173 offset:35840
	ds_read_b128 v[206:209], v173 offset:36864
	ds_read_b128 v[210:213], v173 offset:37888
	ds_read_b128 v[214:217], v173 offset:38912
	ds_read_b128 v[218:221], v173 offset:39936
	global_load_lds_dwordx4 v[232:233], off
	v_lshl_add_u64 v[232:233], s[26:27], 0, v[138:139]
	s_mov_b32 m0, s59
	s_nop 0
	global_load_lds_dwordx4 v[232:233], off
	s_waitcnt vmcnt(8)
	s_waitcnt lgkmcnt(0)
	s_barrier
	s_nop 0
	s_waitcnt lgkmcnt(0)
	v_mfma_f32_16x16x32_bf16 v[128:131], v[132:135], v[182:185], v[128:131]
	v_mfma_f32_16x16x32_bf16 v[124:127], v[152:155], v[182:185], v[124:127]
	v_mfma_f32_16x16x32_bf16 v[112:115], v[132:135], v[190:193], v[112:115]
	v_mfma_f32_16x16x32_bf16 v[108:111], v[152:155], v[190:193], v[108:111]
	v_mfma_f32_16x16x32_bf16 v[96:99], v[132:135], v[206:209], v[96:99]
	v_mfma_f32_16x16x32_bf16 v[92:95], v[152:155], v[206:209], v[92:95]
	v_mfma_f32_16x16x32_bf16 v[80:83], v[132:135], v[214:217], v[80:83]
	v_mfma_f32_16x16x32_bf16 v[76:79], v[152:155], v[214:217], v[76:79]
	v_mfma_f32_16x16x32_bf16 v[128:131], v[148:151], v[186:189], v[128:131]
	v_mfma_f32_16x16x32_bf16 v[124:127], v[156:159], v[186:189], v[124:127]
	v_mfma_f32_16x16x32_bf16 v[112:115], v[148:151], v[202:205], v[112:115]
	v_mfma_f32_16x16x32_bf16 v[108:111], v[156:159], v[202:205], v[108:111]
	v_mfma_f32_16x16x32_bf16 v[96:99], v[148:151], v[210:213], v[96:99]
	v_mfma_f32_16x16x32_bf16 v[92:95], v[156:159], v[210:213], v[92:95]
	v_mfma_f32_16x16x32_bf16 v[80:83], v[148:151], v[218:221], v[80:83]
	v_mfma_f32_16x16x32_bf16 v[76:79], v[156:159], v[218:221], v[76:79]
	s_nop 0
	s_nop 0
	v_mfma_f32_16x16x32_bf16 v[120:123], v[160:163], v[182:185], v[120:123]
	v_mfma_f32_16x16x32_bf16 v[116:119], v[174:177], v[182:185], v[116:119]
	v_mfma_f32_16x16x32_bf16 v[104:107], v[160:163], v[190:193], v[104:107]
	v_mfma_f32_16x16x32_bf16 v[100:103], v[174:177], v[190:193], v[100:103]
	v_mfma_f32_16x16x32_bf16 v[88:91], v[160:163], v[206:209], v[88:91]
	v_mfma_f32_16x16x32_bf16 v[84:87], v[174:177], v[206:209], v[84:87]
	v_mfma_f32_16x16x32_bf16 v[72:75], v[160:163], v[214:217], v[72:75]
	v_mfma_f32_16x16x32_bf16 v[68:71], v[174:177], v[214:217], v[68:71]
	v_mfma_f32_16x16x32_bf16 v[120:123], v[164:167], v[186:189], v[120:123]
	v_mfma_f32_16x16x32_bf16 v[116:119], v[178:181], v[186:189], v[116:119]
	v_mfma_f32_16x16x32_bf16 v[104:107], v[164:167], v[202:205], v[104:107]
	v_mfma_f32_16x16x32_bf16 v[100:103], v[178:181], v[202:205], v[100:103]
	v_mfma_f32_16x16x32_bf16 v[88:91], v[164:167], v[210:213], v[88:91]
	v_mfma_f32_16x16x32_bf16 v[84:87], v[178:181], v[210:213], v[84:87]
	v_mfma_f32_16x16x32_bf16 v[72:75], v[164:167], v[218:221], v[72:75]
	v_mfma_f32_16x16x32_bf16 v[68:71], v[178:181], v[218:221], v[68:71]
	s_nop 0
	s_barrier
; #define PG8_STAGE(bufoff, gbase, voff) do { _Pragma("unroll") for (int _i = 0; _i < 2; ++_i) \
;         __builtin_amdgcn_global_load_lds((const unsigned*)((const char*)(gbase) + (voff)[_i]), (LAS unsigned*)(lds + (bufoff) + ldsw + _i * 8192), 16, 0, 0); } while (0)
; #define PG8_STAGE_A1(bufoff, gbase) do { if (Epi::GATHER) PG8_STAGE(bufoff, gbase, voffA[1]); else PG8_STAGE(bufoff, (gbase) + hstep, voffA[0]); } while (0)
; #define PG8_LDA(dst, b, h) do { _Pragma("unroll") for (int m = 0; m < 4; ++m) _Pragma("unroll") for (int k = 0; k < 2; ++k) dst[m][k] = *(const LAS bf16x8*)(lds + PG8_SA(b, h) + aoff + m * 2048 + k * 1024); } while (0)
; #define PG8_LDB(dst, b, h) do { _Pragma("unroll") for (int n = 0; n < 2; ++n) _Pragma("unroll") for (int k = 0; k < 2; ++k) dst[n][k] = *(const LAS bf16x8*)(lds + PG8_SB(b, h) + boff + n * 2048 + k * 1024); } while (0)
; #define PG8_MMA(ai, bj, At, Bt) do { __builtin_amdgcn_s_setprio(1); _Pragma("unroll") for (int m = 0; m < 4; ++m) _Pragma("unroll") for (int n = 0; n < 2; ++n) _Pragma("unroll") for (int k = 0; k < 2; ++k) \
;         acc[ai][bj][m][n] = __builtin_amdgcn_mfma_f32_16x16x32_bf16(Bt[n][k], At[m][k], acc[ai][bj][m][n], 0, 0, 0); __builtin_amdgcn_s_setprio(0); } while (0)
; #define PG8_WAIT_V(n) asm volatile("s_waitcnt vmcnt(" #n ")" ::: "memory")
; #define PG8_WAIT_L(n) asm volatile("s_waitcnt lgkmcnt(" #n ")" ::: "memory")
; template <class Epi, class Sched>
; __device__ __forceinline__ void gemm_phase(const int tid, LAS unsigned char* lds, const bf16* Aop, const bf16* Bop, const int K_, const Sched& S, const Epi& E, const bf16* Aop1 = nullptr, const bf16* Bop1 = nullptr) {
;     ...
;         for (int t = 0; t < nt; t += 2) {
;             const bool last = (t == nt - 2);
;             const char* a1 = cA + (size_t)(t + 1) * kstep;
;             const char* a2 = last ? nA : cA + (size_t)(t + 2) * kstep; const char* b2 = last ? nB : cB + (size_t)(t + 2) * kstep;
;             const char* a3 = a2 + kstep; const char* b3 = b2 + kstep;
;             PG8_LDB(B0, 0, 0); PG8_LDB(B1, 0, 1); PG8_SCHED; PG8_LDA(At, 0, 0); PG8_STAGE_A1(PG8_SA(1, 1), a1);
;     ...
;             PG8_LDA(At, 1, 1); PG8_STAGE(PG8_SB(1, 0), b3, voffB); PG8_STAGE(PG8_SB(1, 1), b3 + hstep, voffB); PG8_STAGE(PG8_SA(1, 0), a3, voffA[0]);
;             PG8_WAIT_V(8); PG8_WAIT_L(0); PG8_BAR; PG8_MMA(1, 0, At, B0); PG8_MMA(1, 1, At, B1); PG8_BAR; PG8_SCHED;
	s_add_i32 s26, s73, s55
	v_lshl_add_u64 v[194:195], v[194:195], 0, s[20:21]
	s_mov_b32 m0, s26
	ds_read_b128 v[182:185], v173 offset:49152
	ds_read_b128 v[186:189], v173 offset:50176
	ds_read_b128 v[190:193], v173 offset:51200
	ds_read_b128 v[202:205], v173 offset:52224
	ds_read_b128 v[206:209], v173 offset:53248
	ds_read_b128 v[210:213], v173 offset:54272
	ds_read_b128 v[214:217], v173 offset:55296
	ds_read_b128 v[218:221], v173 offset:56320
	global_load_lds_dwordx4 v[194:195], off
	v_lshl_add_u64 v[194:195], v[196:197], 0, s[20:21]
	s_add_i32 m0, s26, 0x2000
	s_add_i32 s26, s74, s55
	global_load_lds_dwordx4 v[194:195], off
	v_lshl_add_u64 v[194:195], v[198:199], 0, s[20:21]
	s_mov_b32 m0, s26
	s_nop 0
	global_load_lds_dwordx4 v[194:195], off
	v_lshl_add_u64 v[194:195], v[222:223], 0, s[20:21]
	s_add_i32 m0, s26, 0x2000
	s_nop 0
	global_load_lds_dwordx4 v[194:195], off
	v_lshl_add_u64 v[194:195], v[224:225], 0, s[20:21]
	s_mov_b32 m0, s60
	s_nop 0
	global_load_lds_dwordx4 v[194:195], off
	v_lshl_add_u64 v[194:195], v[230:231], 0, s[20:21]
	s_mov_b32 m0, s61
	s_nop 0
	global_load_lds_dwordx4 v[194:195], off
	s_waitcnt vmcnt(8)
	s_waitcnt lgkmcnt(0)
	s_barrier
	s_nop 0
	s_waitcnt lgkmcnt(0)
	v_mfma_f32_16x16x32_bf16 v[64:67], v[132:135], v[182:185], v[64:67]
	v_mfma_f32_16x16x32_bf16 v[60:63], v[152:155], v[182:185], v[60:63]
	v_mfma_f32_16x16x32_bf16 v[48:51], v[132:135], v[190:193], v[48:51]
	v_mfma_f32_16x16x32_bf16 v[44:47], v[152:155], v[190:193], v[44:47]
	v_mfma_f32_16x16x32_bf16 v[32:35], v[132:135], v[206:209], v[32:35]
	v_mfma_f32_16x16x32_bf16 v[28:31], v[152:155], v[206:209], v[28:31]
	v_mfma_f32_16x16x32_bf16 v[16:19], v[132:135], v[214:217], v[16:19]
	v_mfma_f32_16x16x32_bf16 v[12:15], v[152:155], v[214:217], v[12:15]
	v_mfma_f32_16x16x32_bf16 v[64:67], v[148:151], v[186:189], v[64:67]
	v_mfma_f32_16x16x32_bf16 v[60:63], v[156:159], v[186:189], v[60:63]
	v_mfma_f32_16x16x32_bf16 v[48:51], v[148:151], v[202:205], v[48:51]
	v_mfma_f32_16x16x32_bf16 v[44:47], v[156:159], v[202:205], v[44:47]
	v_mfma_f32_16x16x32_bf16 v[32:35], v[148:151], v[210:213], v[32:35]
	v_mfma_f32_16x16x32_bf16 v[28:31], v[156:159], v[210:213], v[28:31]
	v_mfma_f32_16x16x32_bf16 v[16:19], v[148:151], v[218:221], v[16:19]
	v_mfma_f32_16x16x32_bf16 v[12:15], v[156:159], v[218:221], v[12:15]
	s_nop 0
	s_nop 0
	v_mfma_f32_16x16x32_bf16 v[56:59], v[160:163], v[182:185], v[56:59]
	v_mfma_f32_16x16x32_bf16 v[52:55], v[174:177], v[182:185], v[52:55]
	v_mfma_f32_16x16x32_bf16 v[40:43], v[160:163], v[190:193], v[40:43]
	v_mfma_f32_16x16x32_bf16 v[36:39], v[174:177], v[190:193], v[36:39]
	v_mfma_f32_16x16x32_bf16 v[24:27], v[160:163], v[206:209], v[24:27]
	v_mfma_f32_16x16x32_bf16 v[20:23], v[174:177], v[206:209], v[20:23]
	v_mfma_f32_16x16x32_bf16 v[8:11], v[160:163], v[214:217], v[8:11]
	v_mfma_f32_16x16x32_bf16 v[4:7], v[174:177], v[214:217], v[4:7]
	v_mfma_f32_16x16x32_bf16 v[56:59], v[164:167], v[186:189], v[56:59]
	v_mfma_f32_16x16x32_bf16 v[52:55], v[178:181], v[186:189], v[52:55]
	v_mfma_f32_16x16x32_bf16 v[40:43], v[164:167], v[202:205], v[40:43]
	v_mfma_f32_16x16x32_bf16 v[36:39], v[178:181], v[202:205], v[36:39]
	v_mfma_f32_16x16x32_bf16 v[24:27], v[164:167], v[210:213], v[24:27]
	v_mfma_f32_16x16x32_bf16 v[20:23], v[178:181], v[210:213], v[20:23]
	v_mfma_f32_16x16x32_bf16 v[8:11], v[164:167], v[218:221], v[8:11]
	v_mfma_f32_16x16x32_bf16 v[4:7], v[178:181], v[218:221], v[4:7]
	s_nop 0
	s_barrier
	s_add_u32 s12, s12, 0x100
	s_addc_u32 s13, s13, 0
	s_add_u32 s11, s11, 0x100
	s_addc_u32 s71, s71, 0
	s_cmp_ge_i32 s72, s8
	s_mov_b32 s26, s72
	s_cbranch_scc0 .LBB0_1000
	s_branch .LBB0_1001
.LBB0_1000:
	s_add_i32 s72, s26, 2
	s_add_u32 s73, s12, 0x80
	s_addc_u32 s27, s13, 0
	s_add_i32 s76, 0, 0x10000
	s_cmp_eq_u32 s64, s26
	s_cselect_b32 s27, s7, s27
	s_cselect_b32 s26, s6, s73
	s_cselect_b32 s75, s41, s71
	s_cselect_b32 s74, s40, s11
	s_add_i32 s73, 0, 0x14000
	v_add_u32_e32 v156, s76, v171
	v_add_u32_e32 v178, s73, v171
	ds_read_b128 v[132:135], v156
	ds_read_b128 v[148:151], v156 offset:1024
	ds_read_b128 v[152:155], v156 offset:2048
	ds_read_b128 v[156:159], v156 offset:3072
	ds_read_b128 v[160:163], v178
	ds_read_b128 v[164:167], v178 offset:1024
	ds_read_b128 v[174:177], v178 offset:2048
	ds_read_b128 v[178:181], v178 offset:3072
	v_lshl_add_u64 v[194:195], s[12:13], 0, v[144:145]
	s_add_i32 m0, s56, 0xc000
	ds_read_b128 v[182:185], v173
	ds_read_b128 v[186:189], v173 offset:1024
	ds_read_b128 v[190:193], v173 offset:2048
	ds_read_b128 v[202:205], v173 offset:3072
	ds_read_b128 v[206:209], v173 offset:4096
	ds_read_b128 v[210:213], v173 offset:5120
	ds_read_b128 v[214:217], v173 offset:6144
	ds_read_b128 v[218:221], v173 offset:7168
	global_load_lds_dwordx4 v[194:195], off
	v_lshl_add_u64 v[194:195], s[12:13], 0, v[146:147]
	s_add_i32 m0, s56, 0xe000
	s_nop 0
	global_load_lds_dwordx4 v[194:195], off
	s_waitcnt vmcnt(8)
	s_waitcnt lgkmcnt(0)
	s_barrier
; #define PG8_GOFFS(slot_) do { _Pragma("unroll") for (int _i = 0; _i < 2; ++_i) { int R, C; stage_rc(tid * 16 + _i * 8192, R, C); _Pragma("unroll") for (int _h = 0; _h < 2; ++_h) { \
;         unsigned t_ = gtab[(slot_) * 256 + R + 128 * _h]; t_ = t_ < (unsigned)(T - 1) ? t_ : (unsigned)(T - 1); voffA[_h][_i] = (t_ * (unsigned)K + (unsigned)C) * 2u; } } } while (0)
; #define PG8_STAGE(bufoff, gbase, voff) do { _Pragma("unroll") for (int _i = 0; _i < 2; ++_i) \
;         __builtin_amdgcn_global_load_lds((const unsigned*)((const char*)(gbase) + (voff)[_i]), (LAS unsigned*)(lds + (bufoff) + ldsw + _i * 8192), 16, 0, 0); } while (0)
; #define PG8_LDA(dst, b, h) do { _Pragma("unroll") for (int m = 0; m < 4; ++m) _Pragma("unroll") for (int k = 0; k < 2; ++k) dst[m][k] = *(const LAS bf16x8*)(lds + PG8_SA(b, h) + aoff + m * 2048 + k * 1024); } while (0)
; #define PG8_MMA(ai, bj, At, Bt) do { __builtin_amdgcn_s_setprio(1); _Pragma("unroll") for (int m = 0; m < 4; ++m) _Pragma("unroll") for (int n = 0; n < 2; ++n) _Pragma("unroll") for (int k = 0; k < 2; ++k) \
;         acc[ai][bj][m][n] = __builtin_amdgcn_mfma_f32_16x16x32_bf16(Bt[n][k], At[m][k], acc[ai][bj][m][n], 0, 0, 0); __builtin_amdgcn_s_setprio(0); } while (0)
; #define PG8_WAIT_V(n) asm volatile("s_waitcnt vmcnt(" #n ")" ::: "memory")
; #define PG8_WAIT_L(n) asm volatile("s_waitcnt lgkmcnt(" #n ")" ::: "memory")
; #define PG8_BAR __builtin_amdgcn_s_barrier()
; #define PG8_SCHED __builtin_amdgcn_sched_barrier(0)
; template <class Epi, class Sched>
; __device__ __forceinline__ void gemm_phase(const int tid, LAS unsigned char* lds, const bf16* Aop, const bf16* Bop, const int K_, const Sched& S, const Epi& E, const bf16* Aop1 = nullptr, const bf16* Bop1 = nullptr) {
;     ...
;             PG8_WAIT_V(8); PG8_WAIT_L(0); PG8_BAR; PG8_MMA(0, 0, At, B0); PG8_MMA(0, 1, At, B1); PG8_BAR; PG8_SCHED;
;             PG8_LDA(At, 0, 1); PG8_STAGE(PG8_SB(0, 0), b2, voffB); PG8_STAGE(PG8_SB(0, 1), b2 + hstep, voffB); if (Epi::GATHER && last && has_next) PG8_GOFFS((ui + 1) & 1); PG8_STAGE(PG8_SA(0, 0), a2, voffA[0]);
;             PG8_WAIT_V(8); PG8_WAIT_L(0); PG8_BAR; PG8_MMA(1, 0, At, B0); PG8_MMA(1, 1, At, B1); PG8_BAR; PG8_SCHED;
	s_nop 0
	s_waitcnt lgkmcnt(0)
	v_mfma_f32_16x16x32_bf16 v[128:131], v[132:135], v[182:185], v[128:131]
	v_mfma_f32_16x16x32_bf16 v[124:127], v[152:155], v[182:185], v[124:127]
	v_mfma_f32_16x16x32_bf16 v[112:115], v[132:135], v[190:193], v[112:115]
	v_mfma_f32_16x16x32_bf16 v[108:111], v[152:155], v[190:193], v[108:111]
	v_mfma_f32_16x16x32_bf16 v[96:99], v[132:135], v[206:209], v[96:99]
	v_mfma_f32_16x16x32_bf16 v[92:95], v[152:155], v[206:209], v[92:95]
	v_mfma_f32_16x16x32_bf16 v[80:83], v[132:135], v[214:217], v[80:83]
	v_mfma_f32_16x16x32_bf16 v[76:79], v[152:155], v[214:217], v[76:79]
	v_mfma_f32_16x16x32_bf16 v[128:131], v[148:151], v[186:189], v[128:131]
	v_mfma_f32_16x16x32_bf16 v[124:127], v[156:159], v[186:189], v[124:127]
	v_mfma_f32_16x16x32_bf16 v[112:115], v[148:151], v[202:205], v[112:115]
	v_mfma_f32_16x16x32_bf16 v[108:111], v[156:159], v[202:205], v[108:111]
	v_mfma_f32_16x16x32_bf16 v[96:99], v[148:151], v[210:213], v[96:99]
	v_mfma_f32_16x16x32_bf16 v[92:95], v[156:159], v[210:213], v[92:95]
	v_mfma_f32_16x16x32_bf16 v[80:83], v[148:151], v[218:221], v[80:83]
	v_mfma_f32_16x16x32_bf16 v[76:79], v[156:159], v[218:221], v[76:79]
	s_nop 0
	s_nop 0
	v_mfma_f32_16x16x32_bf16 v[120:123], v[160:163], v[182:185], v[120:123]
	v_mfma_f32_16x16x32_bf16 v[116:119], v[174:177], v[182:185], v[116:119]
	v_mfma_f32_16x16x32_bf16 v[104:107], v[160:163], v[190:193], v[104:107]
	v_mfma_f32_16x16x32_bf16 v[100:103], v[174:177], v[190:193], v[100:103]
	v_mfma_f32_16x16x32_bf16 v[88:91], v[160:163], v[206:209], v[88:91]
	v_mfma_f32_16x16x32_bf16 v[84:87], v[174:177], v[206:209], v[84:87]
	v_mfma_f32_16x16x32_bf16 v[72:75], v[160:163], v[214:217], v[72:75]
	v_mfma_f32_16x16x32_bf16 v[68:71], v[174:177], v[214:217], v[68:71]
	v_mfma_f32_16x16x32_bf16 v[120:123], v[164:167], v[186:189], v[120:123]
	v_mfma_f32_16x16x32_bf16 v[116:119], v[178:181], v[186:189], v[116:119]
	v_mfma_f32_16x16x32_bf16 v[104:107], v[164:167], v[202:205], v[104:107]
	v_mfma_f32_16x16x32_bf16 v[100:103], v[178:181], v[202:205], v[100:103]
	v_mfma_f32_16x16x32_bf16 v[88:91], v[164:167], v[210:213], v[88:91]
	v_mfma_f32_16x16x32_bf16 v[84:87], v[178:181], v[210:213], v[84:87]
	v_mfma_f32_16x16x32_bf16 v[72:75], v[164:167], v[218:221], v[72:75]
	v_mfma_f32_16x16x32_bf16 v[68:71], v[178:181], v[218:221], v[68:71]
	s_nop 0
	s_barrier
	s_add_i32 s76, s76, s55
	v_lshl_add_u64 v[194:195], s[74:75], 0, v[136:137]
	s_mov_b32 m0, s76
	ds_read_b128 v[182:185], v173 offset:16384
	ds_read_b128 v[186:189], v173 offset:17408
	ds_read_b128 v[190:193], v173 offset:18432
	ds_read_b128 v[202:205], v173 offset:19456
	ds_read_b128 v[206:209], v173 offset:20480
	ds_read_b128 v[210:213], v173 offset:21504
	ds_read_b128 v[214:217], v173 offset:22528
	ds_read_b128 v[218:221], v173 offset:23552
	global_load_lds_dwordx4 v[194:195], off
	s_add_i32 m0, s76, 0x2000
	v_lshl_add_u64 v[196:197], s[74:75], 0, v[140:141]
	s_add_u32 s74, s74, s18
	s_addc_u32 s75, s75, s19
	s_add_i32 s73, s73, s55
	global_load_lds_dwordx4 v[196:197], off
	v_lshl_add_u64 v[198:199], s[74:75], 0, v[136:137]
	s_mov_b32 m0, s73
	v_lshl_add_u64 v[222:223], s[74:75], 0, v[140:141]
	global_load_lds_dwordx4 v[198:199], off
	s_add_i32 m0, s73, 0x2000
	v_lshl_add_u64 v[224:225], s[26:27], 0, v[0:1]
	global_load_lds_dwordx4 v[222:223], off
	s_mov_b32 m0, s56
	v_lshl_add_u64 v[230:231], s[26:27], 0, v[138:139]
	global_load_lds_dwordx4 v[224:225], off
	s_mov_b32 m0, s57
	s_nop 0
	global_load_lds_dwordx4 v[230:231], off
	s_waitcnt vmcnt(8)
	s_waitcnt lgkmcnt(0)
	s_barrier
	s_nop 0
	s_waitcnt lgkmcnt(0)
	v_mfma_f32_16x16x32_bf16 v[64:67], v[132:135], v[182:185], v[64:67]
	v_mfma_f32_16x16x32_bf16 v[60:63], v[152:155], v[182:185], v[60:63]
	v_mfma_f32_16x16x32_bf16 v[48:51], v[132:135], v[190:193], v[48:51]
	v_mfma_f32_16x16x32_bf16 v[44:47], v[152:155], v[190:193], v[44:47]
	v_mfma_f32_16x16x32_bf16 v[32:35], v[132:135], v[206:209], v[32:35]
	v_mfma_f32_16x16x32_bf16 v[28:31], v[152:155], v[206:209], v[28:31]
	v_mfma_f32_16x16x32_bf16 v[16:19], v[132:135], v[214:217], v[16:19]
	v_mfma_f32_16x16x32_bf16 v[12:15], v[152:155], v[214:217], v[12:15]
	v_mfma_f32_16x16x32_bf16 v[64:67], v[148:151], v[186:189], v[64:67]
	v_mfma_f32_16x16x32_bf16 v[60:63], v[156:159], v[186:189], v[60:63]
	v_mfma_f32_16x16x32_bf16 v[48:51], v[148:151], v[202:205], v[48:51]
	v_mfma_f32_16x16x32_bf16 v[44:47], v[156:159], v[202:205], v[44:47]
	v_mfma_f32_16x16x32_bf16 v[32:35], v[148:151], v[210:213], v[32:35]
	v_mfma_f32_16x16x32_bf16 v[28:31], v[156:159], v[210:213], v[28:31]
	v_mfma_f32_16x16x32_bf16 v[16:19], v[148:151], v[218:221], v[16:19]
	v_mfma_f32_16x16x32_bf16 v[12:15], v[156:159], v[218:221], v[12:15]
	s_nop 0
	s_nop 0
	v_mfma_f32_16x16x32_bf16 v[56:59], v[160:163], v[182:185], v[56:59]
	v_mfma_f32_16x16x32_bf16 v[52:55], v[174:177], v[182:185], v[52:55]
	v_mfma_f32_16x16x32_bf16 v[40:43], v[160:163], v[190:193], v[40:43]
	v_mfma_f32_16x16x32_bf16 v[36:39], v[174:177], v[190:193], v[36:39]
	v_mfma_f32_16x16x32_bf16 v[24:27], v[160:163], v[206:209], v[24:27]
	v_mfma_f32_16x16x32_bf16 v[20:23], v[174:177], v[206:209], v[20:23]
	v_mfma_f32_16x16x32_bf16 v[8:11], v[160:163], v[214:217], v[8:11]
	v_mfma_f32_16x16x32_bf16 v[4:7], v[174:177], v[214:217], v[4:7]
	v_mfma_f32_16x16x32_bf16 v[56:59], v[164:167], v[186:189], v[56:59]
	v_mfma_f32_16x16x32_bf16 v[52:55], v[178:181], v[186:189], v[52:55]
	v_mfma_f32_16x16x32_bf16 v[40:43], v[164:167], v[202:205], v[40:43]
	v_mfma_f32_16x16x32_bf16 v[36:39], v[178:181], v[202:205], v[36:39]
	v_mfma_f32_16x16x32_bf16 v[24:27], v[164:167], v[210:213], v[24:27]
	v_mfma_f32_16x16x32_bf16 v[20:23], v[178:181], v[210:213], v[20:23]
	v_mfma_f32_16x16x32_bf16 v[8:11], v[164:167], v[218:221], v[8:11]
	v_mfma_f32_16x16x32_bf16 v[4:7], v[178:181], v[218:221], v[4:7]
	s_nop 0
	s_barrier
; #define PG8_STAGE_A1(bufoff, gbase) do { if (Epi::GATHER) PG8_STAGE(bufoff, gbase, voffA[1]); else PG8_STAGE(bufoff, (gbase) + hstep, voffA[0]); } while (0)
; #define PG8_LDA(dst, b, h) do { _Pragma("unroll") for (int m = 0; m < 4; ++m) _Pragma("unroll") for (int k = 0; k < 2; ++k) dst[m][k] = *(const LAS bf16x8*)(lds + PG8_SA(b, h) + aoff + m * 2048 + k * 1024); } while (0)
; #define PG8_LDB(dst, b, h) do { _Pragma("unroll") for (int n = 0; n < 2; ++n) _Pragma("unroll") for (int k = 0; k < 2; ++k) dst[n][k] = *(const LAS bf16x8*)(lds + PG8_SB(b, h) + boff + n * 2048 + k * 1024); } while (0)
; #define PG8_MMA(ai, bj, At, Bt) do { __builtin_amdgcn_s_setprio(1); _Pragma("unroll") for (int m = 0; m < 4; ++m) _Pragma("unroll") for (int n = 0; n < 2; ++n) _Pragma("unroll") for (int k = 0; k < 2; ++k) \
;         acc[ai][bj][m][n] = __builtin_amdgcn_mfma_f32_16x16x32_bf16(Bt[n][k], At[m][k], acc[ai][bj][m][n], 0, 0, 0); __builtin_amdgcn_s_setprio(0); } while (0)
; #define PG8_WAIT_V(n) asm volatile("s_waitcnt vmcnt(" #n ")" ::: "memory")
; #define PG8_WAIT_L(n) asm volatile("s_waitcnt lgkmcnt(" #n ")" ::: "memory")
; #define PG8_BAR __builtin_amdgcn_s_barrier()
; #define PG8_SCHED __builtin_amdgcn_sched_barrier(0)
; template <class Epi, class Sched>
; __device__ __forceinline__ void gemm_phase(const int tid, LAS unsigned char* lds, const bf16* Aop, const bf16* Bop, const int K_, const Sched& S, const Epi& E, const bf16* Aop1 = nullptr, const bf16* Bop1 = nullptr) {
;     ...
;             PG8_LDB(B0, 1, 0); PG8_LDB(B1, 1, 1); PG8_SCHED; PG8_LDA(At, 1, 0); PG8_STAGE_A1(PG8_SA(0, 1), a2);
;             PG8_WAIT_V(8); PG8_WAIT_L(0); PG8_BAR; PG8_MMA(0, 0, At, B0); PG8_MMA(0, 1, At, B1); PG8_BAR; PG8_SCHED;
	s_add_i32 s73, 0, 0x18000
	s_add_i32 s74, 0, 0x1c000
	v_add_u32_e32 v156, s73, v171
	v_add_u32_e32 v178, s74, v171
	ds_read_b128 v[132:135], v156
	ds_read_b128 v[148:151], v156 offset:1024
	ds_read_b128 v[152:155], v156 offset:2048
	ds_read_b128 v[156:159], v156 offset:3072
	ds_read_b128 v[160:163], v178
	ds_read_b128 v[164:167], v178 offset:1024
	ds_read_b128 v[174:177], v178 offset:2048
	ds_read_b128 v[178:181], v178 offset:3072
	s_add_u32 s26, s26, s18
	s_addc_u32 s27, s27, s19
	s_mov_b32 m0, s58
	v_lshl_add_u64 v[232:233], s[26:27], 0, v[0:1]
	ds_read_b128 v[182:185], v173 offset:32768
	ds_read_b128 v[186:189], v173 offset:33792
	ds_read_b128 v[190:193], v173 offset:34816
	ds_read_b128 v[202:205], v173 offset:35840
	ds_read_b128 v[206:209], v173 offset:36864
	ds_read_b128 v[210:213], v173 offset:37888
	ds_read_b128 v[214:217], v173 offset:38912
	ds_read_b128 v[218:221], v173 offset:39936
	global_load_lds_dwordx4 v[232:233], off
	v_lshl_add_u64 v[232:233], s[26:27], 0, v[138:139]
	s_mov_b32 m0, s59
	s_nop 0
	global_load_lds_dwordx4 v[232:233], off
	s_waitcnt vmcnt(8)
	s_waitcnt lgkmcnt(0)
	s_barrier
	s_nop 0
	s_waitcnt lgkmcnt(0)
	v_mfma_f32_16x16x32_bf16 v[128:131], v[132:135], v[182:185], v[128:131]
	v_mfma_f32_16x16x32_bf16 v[124:127], v[152:155], v[182:185], v[124:127]
	v_mfma_f32_16x16x32_bf16 v[112:115], v[132:135], v[190:193], v[112:115]
	v_mfma_f32_16x16x32_bf16 v[108:111], v[152:155], v[190:193], v[108:111]
	v_mfma_f32_16x16x32_bf16 v[96:99], v[132:135], v[206:209], v[96:99]
	v_mfma_f32_16x16x32_bf16 v[92:95], v[152:155], v[206:209], v[92:95]
	v_mfma_f32_16x16x32_bf16 v[80:83], v[132:135], v[214:217], v[80:83]
	v_mfma_f32_16x16x32_bf16 v[76:79], v[152:155], v[214:217], v[76:79]
	v_mfma_f32_16x16x32_bf16 v[128:131], v[148:151], v[186:189], v[128:131]
	v_mfma_f32_16x16x32_bf16 v[124:127], v[156:159], v[186:189], v[124:127]
	v_mfma_f32_16x16x32_bf16 v[112:115], v[148:151], v[202:205], v[112:115]
	v_mfma_f32_16x16x32_bf16 v[108:111], v[156:159], v[202:205], v[108:111]
	v_mfma_f32_16x16x32_bf16 v[96:99], v[148:151], v[210:213], v[96:99]
	v_mfma_f32_16x16x32_bf16 v[92:95], v[156:159], v[210:213], v[92:95]
	v_mfma_f32_16x16x32_bf16 v[80:83], v[148:151], v[218:221], v[80:83]
	v_mfma_f32_16x16x32_bf16 v[76:79], v[156:159], v[218:221], v[76:79]
	s_nop 0
	s_nop 0
	v_mfma_f32_16x16x32_bf16 v[120:123], v[160:163], v[182:185], v[120:123]
	v_mfma_f32_16x16x32_bf16 v[116:119], v[174:177], v[182:185], v[116:119]
	v_mfma_f32_16x16x32_bf16 v[104:107], v[160:163], v[190:193], v[104:107]
	v_mfma_f32_16x16x32_bf16 v[100:103], v[174:177], v[190:193], v[100:103]
	v_mfma_f32_16x16x32_bf16 v[88:91], v[160:163], v[206:209], v[88:91]
	v_mfma_f32_16x16x32_bf16 v[84:87], v[174:177], v[206:209], v[84:87]
	v_mfma_f32_16x16x32_bf16 v[72:75], v[160:163], v[214:217], v[72:75]
	v_mfma_f32_16x16x32_bf16 v[68:71], v[174:177], v[214:217], v[68:71]
	v_mfma_f32_16x16x32_bf16 v[120:123], v[164:167], v[186:189], v[120:123]
	v_mfma_f32_16x16x32_bf16 v[116:119], v[178:181], v[186:189], v[116:119]
	v_mfma_f32_16x16x32_bf16 v[104:107], v[164:167], v[202:205], v[104:107]
	v_mfma_f32_16x16x32_bf16 v[100:103], v[178:181], v[202:205], v[100:103]
	v_mfma_f32_16x16x32_bf16 v[88:91], v[164:167], v[210:213], v[88:91]
	v_mfma_f32_16x16x32_bf16 v[84:87], v[178:181], v[210:213], v[84:87]
	v_mfma_f32_16x16x32_bf16 v[72:75], v[164:167], v[218:221], v[72:75]
	v_mfma_f32_16x16x32_bf16 v[68:71], v[178:181], v[218:221], v[68:71]
	s_nop 0
	s_barrier
; #define PG8_STAGE(bufoff, gbase, voff) do { _Pragma("unroll") for (int _i = 0; _i < 2; ++_i) \
;         __builtin_amdgcn_global_load_lds((const unsigned*)((const char*)(gbase) + (voff)[_i]), (LAS unsigned*)(lds + (bufoff) + ldsw + _i * 8192), 16, 0, 0); } while (0)
; #define PG8_LDA(dst, b, h) do { _Pragma("unroll") for (int m = 0; m < 4; ++m) _Pragma("unroll") for (int k = 0; k < 2; ++k) dst[m][k] = *(const LAS bf16x8*)(lds + PG8_SA(b, h) + aoff + m * 2048 + k * 1024); } while (0)
; #define PG8_MMA(ai, bj, At, Bt) do { __builtin_amdgcn_s_setprio(1); _Pragma("unroll") for (int m = 0; m < 4; ++m) _Pragma("unroll") for (int n = 0; n < 2; ++n) _Pragma("unroll") for (int k = 0; k < 2; ++k) \
;         acc[ai][bj][m][n] = __builtin_amdgcn_mfma_f32_16x16x32_bf16(Bt[n][k], At[m][k], acc[ai][bj][m][n], 0, 0, 0); __builtin_amdgcn_s_setprio(0); } while (0)
; #define PG8_WAIT_V(n) asm volatile("s_waitcnt vmcnt(" #n ")" ::: "memory")
; #define PG8_WAIT_L(n) asm volatile("s_waitcnt lgkmcnt(" #n ")" ::: "memory")
; #define PG8_BAR __builtin_amdgcn_s_barrier()
; #define PG8_SCHED __builtin_amdgcn_sched_barrier(0)
; template <class Epi, class Sched>
; __device__ __forceinline__ void gemm_phase(const int tid, LAS unsigned char* lds, const bf16* Aop, const bf16* Bop, const int K_, const Sched& S, const Epi& E, const bf16* Aop1 = nullptr, const bf16* Bop1 = nullptr) {
;     ...
;             PG8_LDA(At, 1, 1); PG8_STAGE(PG8_SB(1, 0), b3, voffB); PG8_STAGE(PG8_SB(1, 1), b3 + hstep, voffB); PG8_STAGE(PG8_SA(1, 0), a3, voffA[0]);
;             PG8_WAIT_V(8); PG8_WAIT_L(0); PG8_BAR; PG8_MMA(1, 0, At, B0); PG8_MMA(1, 1, At, B1); PG8_BAR; PG8_SCHED;
;         }
	s_add_i32 s26, s73, s55
	v_lshl_add_u64 v[194:195], v[194:195], 0, s[20:21]
	s_mov_b32 m0, s26
	ds_read_b128 v[182:185], v173 offset:49152
	ds_read_b128 v[186:189], v173 offset:50176
	ds_read_b128 v[190:193], v173 offset:51200
	ds_read_b128 v[202:205], v173 offset:52224
	ds_read_b128 v[206:209], v173 offset:53248
	ds_read_b128 v[210:213], v173 offset:54272
	ds_read_b128 v[214:217], v173 offset:55296
	ds_read_b128 v[218:221], v173 offset:56320
	global_load_lds_dwordx4 v[194:195], off
	v_lshl_add_u64 v[194:195], v[196:197], 0, s[20:21]
	s_add_i32 m0, s26, 0x2000
	s_add_i32 s26, s74, s55
	global_load_lds_dwordx4 v[194:195], off
	v_lshl_add_u64 v[194:195], v[198:199], 0, s[20:21]
	s_mov_b32 m0, s26
	s_nop 0
	global_load_lds_dwordx4 v[194:195], off
	v_lshl_add_u64 v[194:195], v[222:223], 0, s[20:21]
	s_add_i32 m0, s26, 0x2000
	s_nop 0
	global_load_lds_dwordx4 v[194:195], off
	v_lshl_add_u64 v[194:195], v[224:225], 0, s[20:21]
	s_mov_b32 m0, s60
	s_nop 0
	global_load_lds_dwordx4 v[194:195], off
	v_lshl_add_u64 v[194:195], v[230:231], 0, s[20:21]
	s_mov_b32 m0, s61
	s_nop 0
	global_load_lds_dwordx4 v[194:195], off
	s_waitcnt vmcnt(8)
	s_waitcnt lgkmcnt(0)
	s_barrier
	s_nop 0
	s_waitcnt lgkmcnt(0)
	v_mfma_f32_16x16x32_bf16 v[64:67], v[132:135], v[182:185], v[64:67]
	v_mfma_f32_16x16x32_bf16 v[60:63], v[152:155], v[182:185], v[60:63]
	v_mfma_f32_16x16x32_bf16 v[48:51], v[132:135], v[190:193], v[48:51]
	v_mfma_f32_16x16x32_bf16 v[44:47], v[152:155], v[190:193], v[44:47]
	v_mfma_f32_16x16x32_bf16 v[32:35], v[132:135], v[206:209], v[32:35]
	v_mfma_f32_16x16x32_bf16 v[28:31], v[152:155], v[206:209], v[28:31]
	v_mfma_f32_16x16x32_bf16 v[16:19], v[132:135], v[214:217], v[16:19]
	v_mfma_f32_16x16x32_bf16 v[12:15], v[152:155], v[214:217], v[12:15]
	v_mfma_f32_16x16x32_bf16 v[64:67], v[148:151], v[186:189], v[64:67]
	v_mfma_f32_16x16x32_bf16 v[60:63], v[156:159], v[186:189], v[60:63]
	v_mfma_f32_16x16x32_bf16 v[48:51], v[148:151], v[202:205], v[48:51]
	v_mfma_f32_16x16x32_bf16 v[44:47], v[156:159], v[202:205], v[44:47]
	v_mfma_f32_16x16x32_bf16 v[32:35], v[148:151], v[210:213], v[32:35]
	v_mfma_f32_16x16x32_bf16 v[28:31], v[156:159], v[210:213], v[28:31]
	v_mfma_f32_16x16x32_bf16 v[16:19], v[148:151], v[218:221], v[16:19]
	v_mfma_f32_16x16x32_bf16 v[12:15], v[156:159], v[218:221], v[12:15]
	s_nop 0
	s_nop 0
	v_mfma_f32_16x16x32_bf16 v[56:59], v[160:163], v[182:185], v[56:59]
	v_mfma_f32_16x16x32_bf16 v[52:55], v[174:177], v[182:185], v[52:55]
	v_mfma_f32_16x16x32_bf16 v[40:43], v[160:163], v[190:193], v[40:43]
	v_mfma_f32_16x16x32_bf16 v[36:39], v[174:177], v[190:193], v[36:39]
	v_mfma_f32_16x16x32_bf16 v[24:27], v[160:163], v[206:209], v[24:27]
	v_mfma_f32_16x16x32_bf16 v[20:23], v[174:177], v[206:209], v[20:23]
	v_mfma_f32_16x16x32_bf16 v[8:11], v[160:163], v[214:217], v[8:11]
	v_mfma_f32_16x16x32_bf16 v[4:7], v[174:177], v[214:217], v[4:7]
	v_mfma_f32_16x16x32_bf16 v[56:59], v[164:167], v[186:189], v[56:59]
	v_mfma_f32_16x16x32_bf16 v[52:55], v[178:181], v[186:189], v[52:55]
	v_mfma_f32_16x16x32_bf16 v[40:43], v[164:167], v[202:205], v[40:43]
	v_mfma_f32_16x16x32_bf16 v[36:39], v[178:181], v[202:205], v[36:39]
	v_mfma_f32_16x16x32_bf16 v[24:27], v[164:167], v[210:213], v[24:27]
	v_mfma_f32_16x16x32_bf16 v[20:23], v[178:181], v[210:213], v[20:23]
	v_mfma_f32_16x16x32_bf16 v[8:11], v[164:167], v[218:221], v[8:11]
	v_mfma_f32_16x16x32_bf16 v[4:7], v[178:181], v[218:221], v[4:7]
	s_nop 0
	s_barrier
	s_add_u32 s12, s12, 0x100
	s_addc_u32 s13, s13, 0
	s_add_u32 s11, s11, 0x100
	s_addc_u32 s71, s71, 0
	s_cmp_ge_i32 s72, s8
	s_mov_b32 s26, s72
	s_cbranch_scc0 .LBB0_1000

; #define LAS __attribute__((address_space(3)))
;     __device__ bool next(int i, Unit& u) const { if (!so.next(i >> 1, u)) return false; u.sel = i & 1; return true; }
;     __device__ bool next(int i, Unit& u) const { const int L = i * nw + r; if (L >= nu) return false; u.pm = L >> 2; u.pn = L & 3; u.pb = u.pn; u.sel = 0; return true; }
; #define PG8_STAGE(bufoff, gbase, voff) do { _Pragma("unroll") for (int _i = 0; _i < 2; ++_i) \
;         __builtin_amdgcn_global_load_lds((const unsigned*)((const char*)(gbase) + (voff)[_i]), (LAS unsigned*)(lds + (bufoff) + ldsw + _i * 8192), 16, 0, 0); } while (0)
; template <class Epi, class Sched>
; __device__ __forceinline__ void gemm_phase(const int tid, LAS unsigned char* lds, const bf16* Aop, const bf16* Bop, const int K_, const Sched& S, const Epi& E, const bf16* Aop1 = nullptr, const bf16* Bop1 = nullptr) {
;     ...
;     for (;;) {
;         const bool has_next = S.next(ui + 1, nxt);
;         if (Epi::GATHER && has_next && wid < 4) E.tok_dma(nxt.pm * 256 + wid * 64, (LAS unsigned*)(lds + 8 * HTB) + ((ui + 1) & 1) * 256 + wid * 64, lane);
;         const char* nA = has_next ? (const char*)((Aop1 && nxt.sel) ? Aop1 : Aop) + (Epi::GATHER ? (size_t)0 : (size_t)nxt.pm * tstep) : cA; const char* nB = has_next ? (const char*)((Bop1 && nxt.sel) ? Bop1 : Bop) + (size_t)nxt.pb * tstep : cB;
;         for (int t = 0; t < nt; t += 2) {
;             const bool last = (t == nt - 2);
;             const char* a1 = cA + (size_t)(t + 1) * kstep;
;             const char* a2 = last ? nA : cA + (size_t)(t + 2) * kstep; const char* b2 = last ? nB : cB + (size_t)(t + 2) * kstep;
;             const char* a3 = a2 + kstep; const char* b3 = b2 + kstep;
;             PG8_LDB(B0, 0, 0); PG8_LDB(B1, 0, 1); PG8_SCHED; PG8_LDA(At, 0, 0); PG8_STAGE_A1(PG8_SA(1, 1), a1);
;             PG8_WAIT_V(8); PG8_WAIT_L(0); PG8_BAR; PG8_MMA(0, 0, At, B0); PG8_MMA(0, 1, At, B1); PG8_BAR; PG8_SCHED;
;             PG8_LDA(At, 0, 1); PG8_STAGE(PG8_SB(0, 0), b2, voffB); PG8_STAGE(PG8_SB(0, 1), b2 + hstep, voffB); if (Epi::GATHER && last && has_next) PG8_GOFFS((ui + 1) & 1); PG8_STAGE(PG8_SA(0, 0), a2, voffA[0]);
;             PG8_WAIT_V(8); PG8_WAIT_L(0); PG8_BAR; PG8_MMA(1, 0, At, B0); PG8_MMA(1, 1, At, B1); PG8_BAR; PG8_SCHED;
;             PG8_LDB(B0, 1, 0); PG8_LDB(B1, 1, 1); PG8_SCHED; PG8_LDA(At, 1, 0); PG8_STAGE_A1(PG8_SA(0, 1), a2);
.LBB0_1092:
	v_mov_b32_e32 v127, 0
	s_andn2_b64 vcc, exec, s[14:15]
	s_cbranch_vccnz .LBB0_1095
	s_add_u32 s34, s34, 0x80
	s_addc_u32 s35, s35, 0
	s_add_u32 s40, s36, 0x100
	s_addc_u32 s41, s37, 0
	s_mov_b32 s36, 0
	s_add_i32 s60, s36, 2
	s_add_u32 s61, s34, 0x80
	s_addc_u32 s37, s35, 0
	s_add_i32 s66, 0, 0x10000
	s_cmp_eq_u32 s56, s36
	s_cselect_b32 s37, s19, s37
	s_cselect_b32 s36, s18, s61
	v_add_u32_e32 v144, s66, v149
	s_cselect_b32 s65, s27, s41
	s_cselect_b32 s64, s26, s40
	s_add_i32 s61, 0, 0x14000
	ds_read_b128 v[152:155], v144
	ds_read_b128 v[156:159], v144 offset:1024
	ds_read_b128 v[160:163], v144 offset:2048
	ds_read_b128 v[164:167], v144 offset:3072
	v_add_u32_e32 v144, s61, v149
	ds_read_b128 v[168:171], v144
	ds_read_b128 v[172:175], v144 offset:1024
	ds_read_b128 v[176:179], v144 offset:2048
	ds_read_b128 v[180:183], v144 offset:3072
	v_lshl_add_u64 v[144:145], s[34:35], 0, v[140:141]
	s_add_i32 m0, s50, 0xc000
	ds_read_b128 v[184:187], v151
	ds_read_b128 v[188:191], v151 offset:1024
	ds_read_b128 v[192:195], v151 offset:2048
	ds_read_b128 v[202:205], v151 offset:3072
	ds_read_b128 v[206:209], v151 offset:4096
	ds_read_b128 v[210:213], v151 offset:5120
	ds_read_b128 v[214:217], v151 offset:6144
	ds_read_b128 v[218:221], v151 offset:7168
	global_load_lds_dwordx4 v[144:145], off
	v_lshl_add_u64 v[144:145], s[34:35], 0, v[142:143]
	s_add_i32 m0, s50, 0xe000
	s_nop 0
	global_load_lds_dwordx4 v[144:145], off
	s_waitcnt vmcnt(8)
	s_waitcnt lgkmcnt(0)
	s_barrier
	s_nop 0
	s_waitcnt lgkmcnt(0)
	v_mfma_f32_16x16x32_bf16 v[124:127], v[152:155], v[184:187], 0
	v_mfma_f32_16x16x32_bf16 v[128:131], v[160:163], v[184:187], 0
	v_mfma_f32_16x16x32_bf16 v[112:115], v[152:155], v[192:195], 0
	v_mfma_f32_16x16x32_bf16 v[108:111], v[160:163], v[192:195], 0
	v_mfma_f32_16x16x32_bf16 v[96:99], v[152:155], v[206:209], 0
	v_mfma_f32_16x16x32_bf16 v[92:95], v[160:163], v[206:209], 0
	v_mfma_f32_16x16x32_bf16 v[80:83], v[152:155], v[214:217], 0
	v_mfma_f32_16x16x32_bf16 v[76:79], v[160:163], v[214:217], 0
	v_mfma_f32_16x16x32_bf16 v[124:127], v[156:159], v[188:191], v[124:127]
	v_mfma_f32_16x16x32_bf16 v[128:131], v[164:167], v[188:191], v[128:131]
	v_mfma_f32_16x16x32_bf16 v[112:115], v[156:159], v[202:205], v[112:115]
	v_mfma_f32_16x16x32_bf16 v[108:111], v[164:167], v[202:205], v[108:111]
	v_mfma_f32_16x16x32_bf16 v[96:99], v[156:159], v[210:213], v[96:99]
	v_mfma_f32_16x16x32_bf16 v[92:95], v[164:167], v[210:213], v[92:95]
	v_mfma_f32_16x16x32_bf16 v[80:83], v[156:159], v[218:221], v[80:83]
	v_mfma_f32_16x16x32_bf16 v[76:79], v[164:167], v[218:221], v[76:79]
	s_nop 0
	s_nop 0
	v_mfma_f32_16x16x32_bf16 v[120:123], v[168:171], v[184:187], 0
	v_mfma_f32_16x16x32_bf16 v[116:119], v[176:179], v[184:187], 0
	v_mfma_f32_16x16x32_bf16 v[104:107], v[168:171], v[192:195], 0
	v_mfma_f32_16x16x32_bf16 v[100:103], v[176:179], v[192:195], 0
	v_mfma_f32_16x16x32_bf16 v[88:91], v[168:171], v[206:209], 0
	v_mfma_f32_16x16x32_bf16 v[84:87], v[176:179], v[206:209], 0
	v_mfma_f32_16x16x32_bf16 v[72:75], v[168:171], v[214:217], 0
	v_mfma_f32_16x16x32_bf16 v[68:71], v[176:179], v[214:217], 0
	v_mfma_f32_16x16x32_bf16 v[120:123], v[172:175], v[188:191], v[120:123]
	v_mfma_f32_16x16x32_bf16 v[116:119], v[180:183], v[188:191], v[116:119]
	v_mfma_f32_16x16x32_bf16 v[104:107], v[172:175], v[202:205], v[104:107]
	v_mfma_f32_16x16x32_bf16 v[100:103], v[180:183], v[202:205], v[100:103]
	v_mfma_f32_16x16x32_bf16 v[88:91], v[172:175], v[210:213], v[88:91]
	v_mfma_f32_16x16x32_bf16 v[84:87], v[180:183], v[210:213], v[84:87]
	v_mfma_f32_16x16x32_bf16 v[72:75], v[172:175], v[218:221], v[72:75]
	v_mfma_f32_16x16x32_bf16 v[68:71], v[180:183], v[218:221], v[68:71]
	s_nop 0
	s_barrier
	s_add_i32 s66, s66, s49
	v_lshl_add_u64 v[144:145], s[64:65], 0, v[132:133]
	s_mov_b32 m0, s66
	ds_read_b128 v[184:187], v151 offset:16384
	ds_read_b128 v[188:191], v151 offset:17408
	ds_read_b128 v[192:195], v151 offset:18432
	ds_read_b128 v[202:205], v151 offset:19456
	ds_read_b128 v[206:209], v151 offset:20480
	ds_read_b128 v[210:213], v151 offset:21504
	ds_read_b128 v[214:217], v151 offset:22528
	ds_read_b128 v[218:221], v151 offset:23552
	global_load_lds_dwordx4 v[144:145], off
	s_add_i32 m0, s66, 0x2000
	v_lshl_add_u64 v[196:197], s[64:65], 0, v[136:137]
	s_add_u32 s64, s64, s6
	s_addc_u32 s65, s65, s7
	s_add_i32 s61, s61, s49
	global_load_lds_dwordx4 v[196:197], off
	v_lshl_add_u64 v[198:199], s[64:65], 0, v[132:133]
	s_mov_b32 m0, s61
	v_lshl_add_u64 v[222:223], s[64:65], 0, v[136:137]
	global_load_lds_dwordx4 v[198:199], off
	s_add_i32 m0, s61, 0x2000
	v_lshl_add_u64 v[224:225], s[36:37], 0, v[0:1]
	global_load_lds_dwordx4 v[222:223], off
	s_mov_b32 m0, s50
	v_lshl_add_u64 v[230:231], s[36:37], 0, v[134:135]
	global_load_lds_dwordx4 v[224:225], off
	s_mov_b32 m0, s51
	s_nop 0
	global_load_lds_dwordx4 v[230:231], off
	s_waitcnt vmcnt(8)
	s_waitcnt lgkmcnt(0)
	s_barrier
; #define PG8_STAGE_A1(bufoff, gbase) do { if (Epi::GATHER) PG8_STAGE(bufoff, gbase, voffA[1]); else PG8_STAGE(bufoff, (gbase) + hstep, voffA[0]); } while (0)
; #define PG8_LDA(dst, b, h) do { _Pragma("unroll") for (int m = 0; m < 4; ++m) _Pragma("unroll") for (int k = 0; k < 2; ++k) dst[m][k] = *(const LAS bf16x8*)(lds + PG8_SA(b, h) + aoff + m * 2048 + k * 1024); } while (0)
; #define PG8_LDB(dst, b, h) do { _Pragma("unroll") for (int n = 0; n < 2; ++n) _Pragma("unroll") for (int k = 0; k < 2; ++k) dst[n][k] = *(const LAS bf16x8*)(lds + PG8_SB(b, h) + boff + n * 2048 + k * 1024); } while (0)
; #define PG8_MMA(ai, bj, At, Bt) do { __builtin_amdgcn_s_setprio(1); _Pragma("unroll") for (int m = 0; m < 4; ++m) _Pragma("unroll") for (int n = 0; n < 2; ++n) _Pragma("unroll") for (int k = 0; k < 2; ++k) \
;         acc[ai][bj][m][n] = __builtin_amdgcn_mfma_f32_16x16x32_bf16(Bt[n][k], At[m][k], acc[ai][bj][m][n], 0, 0, 0); __builtin_amdgcn_s_setprio(0); } while (0)
; #define PG8_WAIT_V(n) asm volatile("s_waitcnt vmcnt(" #n ")" ::: "memory")
; #define PG8_WAIT_L(n) asm volatile("s_waitcnt lgkmcnt(" #n ")" ::: "memory")
; #define PG8_BAR __builtin_amdgcn_s_barrier()
; #define PG8_SCHED __builtin_amdgcn_sched_barrier(0)
; template <class Epi, class Sched>
; __device__ __forceinline__ void gemm_phase(const int tid, LAS unsigned char* lds, const bf16* Aop, const bf16* Bop, const int K_, const Sched& S, const Epi& E, const bf16* Aop1 = nullptr, const bf16* Bop1 = nullptr) {
;     ...
;             PG8_WAIT_V(8); PG8_WAIT_L(0); PG8_BAR; PG8_MMA(1, 0, At, B0); PG8_MMA(1, 1, At, B1); PG8_BAR; PG8_SCHED;
;             PG8_LDB(B0, 1, 0); PG8_LDB(B1, 1, 1); PG8_SCHED; PG8_LDA(At, 1, 0); PG8_STAGE_A1(PG8_SA(0, 1), a2);
;             PG8_WAIT_V(8); PG8_WAIT_L(0); PG8_BAR; PG8_MMA(0, 0, At, B0); PG8_MMA(0, 1, At, B1); PG8_BAR; PG8_SCHED;
	s_nop 0
	s_waitcnt lgkmcnt(0)
	v_mfma_f32_16x16x32_bf16 v[64:67], v[152:155], v[184:187], 0
	v_mfma_f32_16x16x32_bf16 v[60:63], v[160:163], v[184:187], 0
	v_mfma_f32_16x16x32_bf16 v[48:51], v[152:155], v[192:195], 0
	v_mfma_f32_16x16x32_bf16 v[44:47], v[160:163], v[192:195], 0
	v_mfma_f32_16x16x32_bf16 v[32:35], v[152:155], v[206:209], 0
	v_mfma_f32_16x16x32_bf16 v[28:31], v[160:163], v[206:209], 0
	v_mfma_f32_16x16x32_bf16 v[16:19], v[152:155], v[214:217], 0
	v_mfma_f32_16x16x32_bf16 v[12:15], v[160:163], v[214:217], 0
	v_mfma_f32_16x16x32_bf16 v[64:67], v[156:159], v[188:191], v[64:67]
	v_mfma_f32_16x16x32_bf16 v[60:63], v[164:167], v[188:191], v[60:63]
	v_mfma_f32_16x16x32_bf16 v[48:51], v[156:159], v[202:205], v[48:51]
	v_mfma_f32_16x16x32_bf16 v[44:47], v[164:167], v[202:205], v[44:47]
	v_mfma_f32_16x16x32_bf16 v[32:35], v[156:159], v[210:213], v[32:35]
	v_mfma_f32_16x16x32_bf16 v[28:31], v[164:167], v[210:213], v[28:31]
	v_mfma_f32_16x16x32_bf16 v[16:19], v[156:159], v[218:221], v[16:19]
	v_mfma_f32_16x16x32_bf16 v[12:15], v[164:167], v[218:221], v[12:15]
	s_nop 0
	s_nop 0
	v_mfma_f32_16x16x32_bf16 v[56:59], v[168:171], v[184:187], 0
	v_mfma_f32_16x16x32_bf16 v[52:55], v[176:179], v[184:187], 0
	v_mfma_f32_16x16x32_bf16 v[40:43], v[168:171], v[192:195], 0
	v_mfma_f32_16x16x32_bf16 v[36:39], v[176:179], v[192:195], 0
	v_mfma_f32_16x16x32_bf16 v[24:27], v[168:171], v[206:209], 0
	v_mfma_f32_16x16x32_bf16 v[20:23], v[176:179], v[206:209], 0
	v_mfma_f32_16x16x32_bf16 v[8:11], v[168:171], v[214:217], 0
	v_mfma_f32_16x16x32_bf16 v[4:7], v[176:179], v[214:217], 0
	v_mfma_f32_16x16x32_bf16 v[56:59], v[172:175], v[188:191], v[56:59]
	v_mfma_f32_16x16x32_bf16 v[52:55], v[180:183], v[188:191], v[52:55]
	v_mfma_f32_16x16x32_bf16 v[40:43], v[172:175], v[202:205], v[40:43]
	v_mfma_f32_16x16x32_bf16 v[36:39], v[180:183], v[202:205], v[36:39]
	v_mfma_f32_16x16x32_bf16 v[24:27], v[172:175], v[210:213], v[24:27]
	v_mfma_f32_16x16x32_bf16 v[20:23], v[180:183], v[210:213], v[20:23]
	v_mfma_f32_16x16x32_bf16 v[8:11], v[172:175], v[218:221], v[8:11]
	v_mfma_f32_16x16x32_bf16 v[4:7], v[180:183], v[218:221], v[4:7]
	s_nop 0
	s_barrier
	s_add_i32 s61, 0, 0x18000
	s_add_i32 s64, 0, 0x1c000
	v_add_u32_e32 v164, s61, v149
	v_add_u32_e32 v180, s64, v149
	ds_read_b128 v[152:155], v164
	ds_read_b128 v[156:159], v164 offset:1024
	ds_read_b128 v[160:163], v164 offset:2048
	ds_read_b128 v[164:167], v164 offset:3072
	ds_read_b128 v[168:171], v180
	ds_read_b128 v[172:175], v180 offset:1024
	ds_read_b128 v[176:179], v180 offset:2048
	ds_read_b128 v[180:183], v180 offset:3072
	s_add_u32 s36, s36, s6
	s_addc_u32 s37, s37, s7
	s_mov_b32 m0, s52
	v_lshl_add_u64 v[232:233], s[36:37], 0, v[0:1]
	ds_read_b128 v[184:187], v151 offset:32768
	ds_read_b128 v[188:191], v151 offset:33792
	ds_read_b128 v[192:195], v151 offset:34816
	ds_read_b128 v[202:205], v151 offset:35840
	ds_read_b128 v[206:209], v151 offset:36864
	ds_read_b128 v[210:213], v151 offset:37888
	ds_read_b128 v[214:217], v151 offset:38912
	ds_read_b128 v[218:221], v151 offset:39936
	global_load_lds_dwordx4 v[232:233], off
	v_lshl_add_u64 v[232:233], s[36:37], 0, v[134:135]
	s_mov_b32 m0, s53
	s_nop 0
	global_load_lds_dwordx4 v[232:233], off
	s_waitcnt vmcnt(8)
	s_waitcnt lgkmcnt(0)
	s_barrier
	s_nop 0
	s_waitcnt lgkmcnt(0)
	v_mfma_f32_16x16x32_bf16 v[124:127], v[152:155], v[184:187], v[124:127]
	v_mfma_f32_16x16x32_bf16 v[128:131], v[160:163], v[184:187], v[128:131]
	v_mfma_f32_16x16x32_bf16 v[112:115], v[152:155], v[192:195], v[112:115]
	v_mfma_f32_16x16x32_bf16 v[108:111], v[160:163], v[192:195], v[108:111]
	v_mfma_f32_16x16x32_bf16 v[96:99], v[152:155], v[206:209], v[96:99]
	v_mfma_f32_16x16x32_bf16 v[92:95], v[160:163], v[206:209], v[92:95]
	v_mfma_f32_16x16x32_bf16 v[80:83], v[152:155], v[214:217], v[80:83]
	v_mfma_f32_16x16x32_bf16 v[76:79], v[160:163], v[214:217], v[76:79]
	v_mfma_f32_16x16x32_bf16 v[124:127], v[156:159], v[188:191], v[124:127]
	v_mfma_f32_16x16x32_bf16 v[128:131], v[164:167], v[188:191], v[128:131]
	v_mfma_f32_16x16x32_bf16 v[112:115], v[156:159], v[202:205], v[112:115]
	v_mfma_f32_16x16x32_bf16 v[108:111], v[164:167], v[202:205], v[108:111]
	v_mfma_f32_16x16x32_bf16 v[96:99], v[156:159], v[210:213], v[96:99]
	v_mfma_f32_16x16x32_bf16 v[92:95], v[164:167], v[210:213], v[92:95]
	v_mfma_f32_16x16x32_bf16 v[80:83], v[156:159], v[218:221], v[80:83]
	v_mfma_f32_16x16x32_bf16 v[76:79], v[164:167], v[218:221], v[76:79]
	s_nop 0
	s_nop 0
	v_mfma_f32_16x16x32_bf16 v[120:123], v[168:171], v[184:187], v[120:123]
	v_mfma_f32_16x16x32_bf16 v[116:119], v[176:179], v[184:187], v[116:119]
	v_mfma_f32_16x16x32_bf16 v[104:107], v[168:171], v[192:195], v[104:107]
	v_mfma_f32_16x16x32_bf16 v[100:103], v[176:179], v[192:195], v[100:103]
	v_mfma_f32_16x16x32_bf16 v[88:91], v[168:171], v[206:209], v[88:91]
	v_mfma_f32_16x16x32_bf16 v[84:87], v[176:179], v[206:209], v[84:87]
	v_mfma_f32_16x16x32_bf16 v[72:75], v[168:171], v[214:217], v[72:75]
	v_mfma_f32_16x16x32_bf16 v[68:71], v[176:179], v[214:217], v[68:71]
	v_mfma_f32_16x16x32_bf16 v[120:123], v[172:175], v[188:191], v[120:123]
	v_mfma_f32_16x16x32_bf16 v[116:119], v[180:183], v[188:191], v[116:119]
	v_mfma_f32_16x16x32_bf16 v[104:107], v[172:175], v[202:205], v[104:107]
	v_mfma_f32_16x16x32_bf16 v[100:103], v[180:183], v[202:205], v[100:103]
	v_mfma_f32_16x16x32_bf16 v[88:91], v[172:175], v[210:213], v[88:91]
	v_mfma_f32_16x16x32_bf16 v[84:87], v[180:183], v[210:213], v[84:87]
	v_mfma_f32_16x16x32_bf16 v[72:75], v[172:175], v[218:221], v[72:75]
	v_mfma_f32_16x16x32_bf16 v[68:71], v[180:183], v[218:221], v[68:71]
	s_nop 0
	s_barrier
; #define PG8_STAGE(bufoff, gbase, voff) do { _Pragma("unroll") for (int _i = 0; _i < 2; ++_i) \
;         __builtin_amdgcn_global_load_lds((const unsigned*)((const char*)(gbase) + (voff)[_i]), (LAS unsigned*)(lds + (bufoff) + ldsw + _i * 8192), 16, 0, 0); } while (0)
; #define PG8_STAGE_A1(bufoff, gbase) do { if (Epi::GATHER) PG8_STAGE(bufoff, gbase, voffA[1]); else PG8_STAGE(bufoff, (gbase) + hstep, voffA[0]); } while (0)
; #define PG8_LDA(dst, b, h) do { _Pragma("unroll") for (int m = 0; m < 4; ++m) _Pragma("unroll") for (int k = 0; k < 2; ++k) dst[m][k] = *(const LAS bf16x8*)(lds + PG8_SA(b, h) + aoff + m * 2048 + k * 1024); } while (0)
; #define PG8_LDB(dst, b, h) do { _Pragma("unroll") for (int n = 0; n < 2; ++n) _Pragma("unroll") for (int k = 0; k < 2; ++k) dst[n][k] = *(const LAS bf16x8*)(lds + PG8_SB(b, h) + boff + n * 2048 + k * 1024); } while (0)
; #define PG8_MMA(ai, bj, At, Bt) do { __builtin_amdgcn_s_setprio(1); _Pragma("unroll") for (int m = 0; m < 4; ++m) _Pragma("unroll") for (int n = 0; n < 2; ++n) _Pragma("unroll") for (int k = 0; k < 2; ++k) \
;         acc[ai][bj][m][n] = __builtin_amdgcn_mfma_f32_16x16x32_bf16(Bt[n][k], At[m][k], acc[ai][bj][m][n], 0, 0, 0); __builtin_amdgcn_s_setprio(0); } while (0)
; #define PG8_WAIT_V(n) asm volatile("s_waitcnt vmcnt(" #n ")" ::: "memory")
; #define PG8_WAIT_L(n) asm volatile("s_waitcnt lgkmcnt(" #n ")" ::: "memory")
; template <class Epi, class Sched>
; __device__ __forceinline__ void gemm_phase(const int tid, LAS unsigned char* lds, const bf16* Aop, const bf16* Bop, const int K_, const Sched& S, const Epi& E, const bf16* Aop1 = nullptr, const bf16* Bop1 = nullptr) {
;     ...
;         for (int t = 0; t < nt; t += 2) {
;             const bool last = (t == nt - 2);
;             const char* a1 = cA + (size_t)(t + 1) * kstep;
;             const char* a2 = last ? nA : cA + (size_t)(t + 2) * kstep; const char* b2 = last ? nB : cB + (size_t)(t + 2) * kstep;
;             const char* a3 = a2 + kstep; const char* b3 = b2 + kstep;
;             PG8_LDB(B0, 0, 0); PG8_LDB(B1, 0, 1); PG8_SCHED; PG8_LDA(At, 0, 0); PG8_STAGE_A1(PG8_SA(1, 1), a1);
;     ...
;             PG8_LDA(At, 1, 1); PG8_STAGE(PG8_SB(1, 0), b3, voffB); PG8_STAGE(PG8_SB(1, 1), b3 + hstep, voffB); PG8_STAGE(PG8_SA(1, 0), a3, voffA[0]);
;             PG8_WAIT_V(8); PG8_WAIT_L(0); PG8_BAR; PG8_MMA(1, 0, At, B0); PG8_MMA(1, 1, At, B1); PG8_BAR; PG8_SCHED;
	s_add_i32 s36, s61, s49
	v_lshl_add_u64 v[144:145], v[144:145], 0, s[20:21]
	s_mov_b32 m0, s36
	ds_read_b128 v[184:187], v151 offset:49152
	ds_read_b128 v[188:191], v151 offset:50176
	ds_read_b128 v[192:195], v151 offset:51200
	ds_read_b128 v[202:205], v151 offset:52224
	ds_read_b128 v[206:209], v151 offset:53248
	ds_read_b128 v[210:213], v151 offset:54272
	ds_read_b128 v[214:217], v151 offset:55296
	ds_read_b128 v[218:221], v151 offset:56320
	global_load_lds_dwordx4 v[144:145], off
	v_lshl_add_u64 v[144:145], v[196:197], 0, s[20:21]
	s_add_i32 m0, s36, 0x2000
	s_add_i32 s36, s64, s49
	global_load_lds_dwordx4 v[144:145], off
	v_lshl_add_u64 v[144:145], v[198:199], 0, s[20:21]
	s_mov_b32 m0, s36
	s_nop 0
	global_load_lds_dwordx4 v[144:145], off
	v_lshl_add_u64 v[144:145], v[222:223], 0, s[20:21]
	s_add_i32 m0, s36, 0x2000
	s_nop 0
	global_load_lds_dwordx4 v[144:145], off
	v_lshl_add_u64 v[144:145], v[224:225], 0, s[20:21]
	s_mov_b32 m0, s54
	s_nop 0
	global_load_lds_dwordx4 v[144:145], off
	v_lshl_add_u64 v[144:145], v[230:231], 0, s[20:21]
	s_mov_b32 m0, s55
	s_nop 0
	global_load_lds_dwordx4 v[144:145], off
	s_waitcnt vmcnt(8)
	s_waitcnt lgkmcnt(0)
	s_barrier
	s_nop 0
	s_waitcnt lgkmcnt(0)
	v_mfma_f32_16x16x32_bf16 v[64:67], v[152:155], v[184:187], v[64:67]
	v_mfma_f32_16x16x32_bf16 v[60:63], v[160:163], v[184:187], v[60:63]
	v_mfma_f32_16x16x32_bf16 v[48:51], v[152:155], v[192:195], v[48:51]
	v_mfma_f32_16x16x32_bf16 v[44:47], v[160:163], v[192:195], v[44:47]
	v_mfma_f32_16x16x32_bf16 v[32:35], v[152:155], v[206:209], v[32:35]
	v_mfma_f32_16x16x32_bf16 v[28:31], v[160:163], v[206:209], v[28:31]
	v_mfma_f32_16x16x32_bf16 v[16:19], v[152:155], v[214:217], v[16:19]
	v_mfma_f32_16x16x32_bf16 v[12:15], v[160:163], v[214:217], v[12:15]
	v_mfma_f32_16x16x32_bf16 v[64:67], v[156:159], v[188:191], v[64:67]
	v_mfma_f32_16x16x32_bf16 v[60:63], v[164:167], v[188:191], v[60:63]
	v_mfma_f32_16x16x32_bf16 v[48:51], v[156:159], v[202:205], v[48:51]
	v_mfma_f32_16x16x32_bf16 v[44:47], v[164:167], v[202:205], v[44:47]
	v_mfma_f32_16x16x32_bf16 v[32:35], v[156:159], v[210:213], v[32:35]
	v_mfma_f32_16x16x32_bf16 v[28:31], v[164:167], v[210:213], v[28:31]
	v_mfma_f32_16x16x32_bf16 v[16:19], v[156:159], v[218:221], v[16:19]
	v_mfma_f32_16x16x32_bf16 v[12:15], v[164:167], v[218:221], v[12:15]
	s_nop 0
	s_nop 0
	v_mfma_f32_16x16x32_bf16 v[56:59], v[168:171], v[184:187], v[56:59]
	v_mfma_f32_16x16x32_bf16 v[52:55], v[176:179], v[184:187], v[52:55]
	v_mfma_f32_16x16x32_bf16 v[40:43], v[168:171], v[192:195], v[40:43]
	v_mfma_f32_16x16x32_bf16 v[36:39], v[176:179], v[192:195], v[36:39]
	v_mfma_f32_16x16x32_bf16 v[24:27], v[168:171], v[206:209], v[24:27]
	v_mfma_f32_16x16x32_bf16 v[20:23], v[176:179], v[206:209], v[20:23]
	v_mfma_f32_16x16x32_bf16 v[8:11], v[168:171], v[214:217], v[8:11]
	v_mfma_f32_16x16x32_bf16 v[4:7], v[176:179], v[214:217], v[4:7]
	v_mfma_f32_16x16x32_bf16 v[56:59], v[172:175], v[188:191], v[56:59]
	v_mfma_f32_16x16x32_bf16 v[52:55], v[180:183], v[188:191], v[52:55]
	v_mfma_f32_16x16x32_bf16 v[40:43], v[172:175], v[202:205], v[40:43]
	v_mfma_f32_16x16x32_bf16 v[36:39], v[180:183], v[202:205], v[36:39]
	v_mfma_f32_16x16x32_bf16 v[24:27], v[172:175], v[210:213], v[24:27]
	v_mfma_f32_16x16x32_bf16 v[20:23], v[180:183], v[210:213], v[20:23]
	v_mfma_f32_16x16x32_bf16 v[8:11], v[172:175], v[218:221], v[8:11]
	v_mfma_f32_16x16x32_bf16 v[4:7], v[180:183], v[218:221], v[4:7]
	s_nop 0
	s_barrier
	s_add_u32 s34, s34, 0x100
	s_addc_u32 s35, s35, 0
	s_add_u32 s40, s40, 0x100
	s_addc_u32 s41, s41, 0
	s_cmp_ge_i32 s60, s8
	s_mov_b32 s36, s60
	s_cbranch_scc0 .LBB0_1094
	s_branch .LBB0_1095
.LBB0_1094:
	s_add_i32 s60, s36, 2
	s_add_u32 s61, s34, 0x80
	s_addc_u32 s37, s35, 0
	s_add_i32 s66, 0, 0x10000
	s_cmp_eq_u32 s56, s36
	s_cselect_b32 s37, s19, s37
	s_cselect_b32 s36, s18, s61
	v_add_u32_e32 v144, s66, v149
	s_cselect_b32 s65, s27, s41
	s_cselect_b32 s64, s26, s40
	s_add_i32 s61, 0, 0x14000
	ds_read_b128 v[152:155], v144
	ds_read_b128 v[156:159], v144 offset:1024
	ds_read_b128 v[160:163], v144 offset:2048
	ds_read_b128 v[164:167], v144 offset:3072
	v_add_u32_e32 v144, s61, v149
	ds_read_b128 v[168:171], v144
	ds_read_b128 v[172:175], v144 offset:1024
	ds_read_b128 v[176:179], v144 offset:2048
	ds_read_b128 v[180:183], v144 offset:3072
	v_lshl_add_u64 v[144:145], s[34:35], 0, v[140:141]
	s_add_i32 m0, s50, 0xc000
	ds_read_b128 v[184:187], v151
	ds_read_b128 v[188:191], v151 offset:1024
	ds_read_b128 v[192:195], v151 offset:2048
	ds_read_b128 v[202:205], v151 offset:3072
	ds_read_b128 v[206:209], v151 offset:4096
	ds_read_b128 v[210:213], v151 offset:5120
	ds_read_b128 v[214:217], v151 offset:6144
	ds_read_b128 v[218:221], v151 offset:7168
	global_load_lds_dwordx4 v[144:145], off
	v_lshl_add_u64 v[144:145], s[34:35], 0, v[142:143]
	s_add_i32 m0, s50, 0xe000
	s_nop 0
	global_load_lds_dwordx4 v[144:145], off
	s_waitcnt vmcnt(8)
	s_waitcnt lgkmcnt(0)
	s_barrier
; #define PG8_GOFFS(slot_) do { _Pragma("unroll") for (int _i = 0; _i < 2; ++_i) { int R, C; stage_rc(tid * 16 + _i * 8192, R, C); _Pragma("unroll") for (int _h = 0; _h < 2; ++_h) { \
;         unsigned t_ = gtab[(slot_) * 256 + R + 128 * _h]; t_ = t_ < (unsigned)(T - 1) ? t_ : (unsigned)(T - 1); voffA[_h][_i] = (t_ * (unsigned)K + (unsigned)C) * 2u; } } } while (0)
; #define PG8_STAGE(bufoff, gbase, voff) do { _Pragma("unroll") for (int _i = 0; _i < 2; ++_i) \
;         __builtin_amdgcn_global_load_lds((const unsigned*)((const char*)(gbase) + (voff)[_i]), (LAS unsigned*)(lds + (bufoff) + ldsw + _i * 8192), 16, 0, 0); } while (0)
; #define PG8_LDA(dst, b, h) do { _Pragma("unroll") for (int m = 0; m < 4; ++m) _Pragma("unroll") for (int k = 0; k < 2; ++k) dst[m][k] = *(const LAS bf16x8*)(lds + PG8_SA(b, h) + aoff + m * 2048 + k * 1024); } while (0)
; #define PG8_MMA(ai, bj, At, Bt) do { __builtin_amdgcn_s_setprio(1); _Pragma("unroll") for (int m = 0; m < 4; ++m) _Pragma("unroll") for (int n = 0; n < 2; ++n) _Pragma("unroll") for (int k = 0; k < 2; ++k) \
;         acc[ai][bj][m][n] = __builtin_amdgcn_mfma_f32_16x16x32_bf16(Bt[n][k], At[m][k], acc[ai][bj][m][n], 0, 0, 0); __builtin_amdgcn_s_setprio(0); } while (0)
; #define PG8_WAIT_V(n) asm volatile("s_waitcnt vmcnt(" #n ")" ::: "memory")
; #define PG8_WAIT_L(n) asm volatile("s_waitcnt lgkmcnt(" #n ")" ::: "memory")
; #define PG8_BAR __builtin_amdgcn_s_barrier()
; #define PG8_SCHED __builtin_amdgcn_sched_barrier(0)
; template <class Epi, class Sched>
; __device__ __forceinline__ void gemm_phase(const int tid, LAS unsigned char* lds, const bf16* Aop, const bf16* Bop, const int K_, const Sched& S, const Epi& E, const bf16* Aop1 = nullptr, const bf16* Bop1 = nullptr) {
;     ...
;             PG8_WAIT_V(8); PG8_WAIT_L(0); PG8_BAR; PG8_MMA(0, 0, At, B0); PG8_MMA(0, 1, At, B1); PG8_BAR; PG8_SCHED;
;             PG8_LDA(At, 0, 1); PG8_STAGE(PG8_SB(0, 0), b2, voffB); PG8_STAGE(PG8_SB(0, 1), b2 + hstep, voffB); if (Epi::GATHER && last && has_next) PG8_GOFFS((ui + 1) & 1); PG8_STAGE(PG8_SA(0, 0), a2, voffA[0]);
;             PG8_WAIT_V(8); PG8_WAIT_L(0); PG8_BAR; PG8_MMA(1, 0, At, B0); PG8_MMA(1, 1, At, B1); PG8_BAR; PG8_SCHED;
	s_nop 0
	s_waitcnt lgkmcnt(0)
	v_mfma_f32_16x16x32_bf16 v[124:127], v[152:155], v[184:187], v[124:127]
	v_mfma_f32_16x16x32_bf16 v[128:131], v[160:163], v[184:187], v[128:131]
	v_mfma_f32_16x16x32_bf16 v[112:115], v[152:155], v[192:195], v[112:115]
	v_mfma_f32_16x16x32_bf16 v[108:111], v[160:163], v[192:195], v[108:111]
	v_mfma_f32_16x16x32_bf16 v[96:99], v[152:155], v[206:209], v[96:99]
	v_mfma_f32_16x16x32_bf16 v[92:95], v[160:163], v[206:209], v[92:95]
	v_mfma_f32_16x16x32_bf16 v[80:83], v[152:155], v[214:217], v[80:83]
	v_mfma_f32_16x16x32_bf16 v[76:79], v[160:163], v[214:217], v[76:79]
	v_mfma_f32_16x16x32_bf16 v[124:127], v[156:159], v[188:191], v[124:127]
	v_mfma_f32_16x16x32_bf16 v[128:131], v[164:167], v[188:191], v[128:131]
	v_mfma_f32_16x16x32_bf16 v[112:115], v[156:159], v[202:205], v[112:115]
	v_mfma_f32_16x16x32_bf16 v[108:111], v[164:167], v[202:205], v[108:111]
	v_mfma_f32_16x16x32_bf16 v[96:99], v[156:159], v[210:213], v[96:99]
	v_mfma_f32_16x16x32_bf16 v[92:95], v[164:167], v[210:213], v[92:95]
	v_mfma_f32_16x16x32_bf16 v[80:83], v[156:159], v[218:221], v[80:83]
	v_mfma_f32_16x16x32_bf16 v[76:79], v[164:167], v[218:221], v[76:79]
	s_nop 0
	s_nop 0
	v_mfma_f32_16x16x32_bf16 v[120:123], v[168:171], v[184:187], v[120:123]
	v_mfma_f32_16x16x32_bf16 v[116:119], v[176:179], v[184:187], v[116:119]
	v_mfma_f32_16x16x32_bf16 v[104:107], v[168:171], v[192:195], v[104:107]
	v_mfma_f32_16x16x32_bf16 v[100:103], v[176:179], v[192:195], v[100:103]
	v_mfma_f32_16x16x32_bf16 v[88:91], v[168:171], v[206:209], v[88:91]
	v_mfma_f32_16x16x32_bf16 v[84:87], v[176:179], v[206:209], v[84:87]
	v_mfma_f32_16x16x32_bf16 v[72:75], v[168:171], v[214:217], v[72:75]
	v_mfma_f32_16x16x32_bf16 v[68:71], v[176:179], v[214:217], v[68:71]
	v_mfma_f32_16x16x32_bf16 v[120:123], v[172:175], v[188:191], v[120:123]
	v_mfma_f32_16x16x32_bf16 v[116:119], v[180:183], v[188:191], v[116:119]
	v_mfma_f32_16x16x32_bf16 v[104:107], v[172:175], v[202:205], v[104:107]
	v_mfma_f32_16x16x32_bf16 v[100:103], v[180:183], v[202:205], v[100:103]
	v_mfma_f32_16x16x32_bf16 v[88:91], v[172:175], v[210:213], v[88:91]
	v_mfma_f32_16x16x32_bf16 v[84:87], v[180:183], v[210:213], v[84:87]
	v_mfma_f32_16x16x32_bf16 v[72:75], v[172:175], v[218:221], v[72:75]
	v_mfma_f32_16x16x32_bf16 v[68:71], v[180:183], v[218:221], v[68:71]
	s_nop 0
	s_barrier
	s_add_i32 s66, s66, s49
	v_lshl_add_u64 v[144:145], s[64:65], 0, v[132:133]
	s_mov_b32 m0, s66
	ds_read_b128 v[184:187], v151 offset:16384
	ds_read_b128 v[188:191], v151 offset:17408
	ds_read_b128 v[192:195], v151 offset:18432
	ds_read_b128 v[202:205], v151 offset:19456
	ds_read_b128 v[206:209], v151 offset:20480
	ds_read_b128 v[210:213], v151 offset:21504
	ds_read_b128 v[214:217], v151 offset:22528
	ds_read_b128 v[218:221], v151 offset:23552
	global_load_lds_dwordx4 v[144:145], off
	s_add_i32 m0, s66, 0x2000
	v_lshl_add_u64 v[196:197], s[64:65], 0, v[136:137]
	s_add_u32 s64, s64, s6
	s_addc_u32 s65, s65, s7
	s_add_i32 s61, s61, s49
	global_load_lds_dwordx4 v[196:197], off
	v_lshl_add_u64 v[198:199], s[64:65], 0, v[132:133]
	s_mov_b32 m0, s61
	v_lshl_add_u64 v[222:223], s[64:65], 0, v[136:137]
	global_load_lds_dwordx4 v[198:199], off
	s_add_i32 m0, s61, 0x2000
	v_lshl_add_u64 v[224:225], s[36:37], 0, v[0:1]
	global_load_lds_dwordx4 v[222:223], off
	s_mov_b32 m0, s50
	v_lshl_add_u64 v[230:231], s[36:37], 0, v[134:135]
	global_load_lds_dwordx4 v[224:225], off
	s_mov_b32 m0, s51
	s_nop 0
	global_load_lds_dwordx4 v[230:231], off
	s_waitcnt vmcnt(8)
	s_waitcnt lgkmcnt(0)
	s_barrier
	s_nop 0
	s_waitcnt lgkmcnt(0)
	v_mfma_f32_16x16x32_bf16 v[64:67], v[152:155], v[184:187], v[64:67]
	v_mfma_f32_16x16x32_bf16 v[60:63], v[160:163], v[184:187], v[60:63]
	v_mfma_f32_16x16x32_bf16 v[48:51], v[152:155], v[192:195], v[48:51]
	v_mfma_f32_16x16x32_bf16 v[44:47], v[160:163], v[192:195], v[44:47]
	v_mfma_f32_16x16x32_bf16 v[32:35], v[152:155], v[206:209], v[32:35]
	v_mfma_f32_16x16x32_bf16 v[28:31], v[160:163], v[206:209], v[28:31]
	v_mfma_f32_16x16x32_bf16 v[16:19], v[152:155], v[214:217], v[16:19]
	v_mfma_f32_16x16x32_bf16 v[12:15], v[160:163], v[214:217], v[12:15]
	v_mfma_f32_16x16x32_bf16 v[64:67], v[156:159], v[188:191], v[64:67]
	v_mfma_f32_16x16x32_bf16 v[60:63], v[164:167], v[188:191], v[60:63]
	v_mfma_f32_16x16x32_bf16 v[48:51], v[156:159], v[202:205], v[48:51]
	v_mfma_f32_16x16x32_bf16 v[44:47], v[164:167], v[202:205], v[44:47]
	v_mfma_f32_16x16x32_bf16 v[32:35], v[156:159], v[210:213], v[32:35]
	v_mfma_f32_16x16x32_bf16 v[28:31], v[164:167], v[210:213], v[28:31]
	v_mfma_f32_16x16x32_bf16 v[16:19], v[156:159], v[218:221], v[16:19]
	v_mfma_f32_16x16x32_bf16 v[12:15], v[164:167], v[218:221], v[12:15]
	s_nop 0
	s_nop 0
	v_mfma_f32_16x16x32_bf16 v[56:59], v[168:171], v[184:187], v[56:59]
	v_mfma_f32_16x16x32_bf16 v[52:55], v[176:179], v[184:187], v[52:55]
	v_mfma_f32_16x16x32_bf16 v[40:43], v[168:171], v[192:195], v[40:43]
	v_mfma_f32_16x16x32_bf16 v[36:39], v[176:179], v[192:195], v[36:39]
	v_mfma_f32_16x16x32_bf16 v[24:27], v[168:171], v[206:209], v[24:27]
	v_mfma_f32_16x16x32_bf16 v[20:23], v[176:179], v[206:209], v[20:23]
	v_mfma_f32_16x16x32_bf16 v[8:11], v[168:171], v[214:217], v[8:11]
	v_mfma_f32_16x16x32_bf16 v[4:7], v[176:179], v[214:217], v[4:7]
	v_mfma_f32_16x16x32_bf16 v[56:59], v[172:175], v[188:191], v[56:59]
	v_mfma_f32_16x16x32_bf16 v[52:55], v[180:183], v[188:191], v[52:55]
	v_mfma_f32_16x16x32_bf16 v[40:43], v[172:175], v[202:205], v[40:43]
	v_mfma_f32_16x16x32_bf16 v[36:39], v[180:183], v[202:205], v[36:39]
	v_mfma_f32_16x16x32_bf16 v[24:27], v[172:175], v[210:213], v[24:27]
	v_mfma_f32_16x16x32_bf16 v[20:23], v[180:183], v[210:213], v[20:23]
	v_mfma_f32_16x16x32_bf16 v[8:11], v[172:175], v[218:221], v[8:11]
	v_mfma_f32_16x16x32_bf16 v[4:7], v[180:183], v[218:221], v[4:7]
	s_nop 0
	s_barrier
; #define PG8_STAGE_A1(bufoff, gbase) do { if (Epi::GATHER) PG8_STAGE(bufoff, gbase, voffA[1]); else PG8_STAGE(bufoff, (gbase) + hstep, voffA[0]); } while (0)
; #define PG8_LDA(dst, b, h) do { _Pragma("unroll") for (int m = 0; m < 4; ++m) _Pragma("unroll") for (int k = 0; k < 2; ++k) dst[m][k] = *(const LAS bf16x8*)(lds + PG8_SA(b, h) + aoff + m * 2048 + k * 1024); } while (0)
; #define PG8_LDB(dst, b, h) do { _Pragma("unroll") for (int n = 0; n < 2; ++n) _Pragma("unroll") for (int k = 0; k < 2; ++k) dst[n][k] = *(const LAS bf16x8*)(lds + PG8_SB(b, h) + boff + n * 2048 + k * 1024); } while (0)
; #define PG8_MMA(ai, bj, At, Bt) do { __builtin_amdgcn_s_setprio(1); _Pragma("unroll") for (int m = 0; m < 4; ++m) _Pragma("unroll") for (int n = 0; n < 2; ++n) _Pragma("unroll") for (int k = 0; k < 2; ++k) \
;         acc[ai][bj][m][n] = __builtin_amdgcn_mfma_f32_16x16x32_bf16(Bt[n][k], At[m][k], acc[ai][bj][m][n], 0, 0, 0); __builtin_amdgcn_s_setprio(0); } while (0)
; #define PG8_WAIT_V(n) asm volatile("s_waitcnt vmcnt(" #n ")" ::: "memory")
; #define PG8_WAIT_L(n) asm volatile("s_waitcnt lgkmcnt(" #n ")" ::: "memory")
; #define PG8_BAR __builtin_amdgcn_s_barrier()
; #define PG8_SCHED __builtin_amdgcn_sched_barrier(0)
; template <class Epi, class Sched>
; __device__ __forceinline__ void gemm_phase(const int tid, LAS unsigned char* lds, const bf16* Aop, const bf16* Bop, const int K_, const Sched& S, const Epi& E, const bf16* Aop1 = nullptr, const bf16* Bop1 = nullptr) {
;     ...
;             PG8_LDB(B0, 1, 0); PG8_LDB(B1, 1, 1); PG8_SCHED; PG8_LDA(At, 1, 0); PG8_STAGE_A1(PG8_SA(0, 1), a2);
;             PG8_WAIT_V(8); PG8_WAIT_L(0); PG8_BAR; PG8_MMA(0, 0, At, B0); PG8_MMA(0, 1, At, B1); PG8_BAR; PG8_SCHED;
	s_add_i32 s61, 0, 0x18000
	s_add_i32 s64, 0, 0x1c000
	v_add_u32_e32 v164, s61, v149
	v_add_u32_e32 v180, s64, v149
	ds_read_b128 v[152:155], v164
	ds_read_b128 v[156:159], v164 offset:1024
	ds_read_b128 v[160:163], v164 offset:2048
	ds_read_b128 v[164:167], v164 offset:3072
	ds_read_b128 v[168:171], v180
	ds_read_b128 v[172:175], v180 offset:1024
	ds_read_b128 v[176:179], v180 offset:2048
	ds_read_b128 v[180:183], v180 offset:3072
	s_add_u32 s36, s36, s6
	s_addc_u32 s37, s37, s7
	s_mov_b32 m0, s52
	v_lshl_add_u64 v[232:233], s[36:37], 0, v[0:1]
	ds_read_b128 v[184:187], v151 offset:32768
	ds_read_b128 v[188:191], v151 offset:33792
	ds_read_b128 v[192:195], v151 offset:34816
	ds_read_b128 v[202:205], v151 offset:35840
	ds_read_b128 v[206:209], v151 offset:36864
	ds_read_b128 v[210:213], v151 offset:37888
	ds_read_b128 v[214:217], v151 offset:38912
	ds_read_b128 v[218:221], v151 offset:39936
	global_load_lds_dwordx4 v[232:233], off
	v_lshl_add_u64 v[232:233], s[36:37], 0, v[134:135]
	s_mov_b32 m0, s53
	s_nop 0
	global_load_lds_dwordx4 v[232:233], off
	s_waitcnt vmcnt(8)
	s_waitcnt lgkmcnt(0)
	s_barrier
	s_nop 0
	s_waitcnt lgkmcnt(0)
	v_mfma_f32_16x16x32_bf16 v[124:127], v[152:155], v[184:187], v[124:127]
	v_mfma_f32_16x16x32_bf16 v[128:131], v[160:163], v[184:187], v[128:131]
	v_mfma_f32_16x16x32_bf16 v[112:115], v[152:155], v[192:195], v[112:115]
	v_mfma_f32_16x16x32_bf16 v[108:111], v[160:163], v[192:195], v[108:111]
	v_mfma_f32_16x16x32_bf16 v[96:99], v[152:155], v[206:209], v[96:99]
	v_mfma_f32_16x16x32_bf16 v[92:95], v[160:163], v[206:209], v[92:95]
	v_mfma_f32_16x16x32_bf16 v[80:83], v[152:155], v[214:217], v[80:83]
	v_mfma_f32_16x16x32_bf16 v[76:79], v[160:163], v[214:217], v[76:79]
	v_mfma_f32_16x16x32_bf16 v[124:127], v[156:159], v[188:191], v[124:127]
	v_mfma_f32_16x16x32_bf16 v[128:131], v[164:167], v[188:191], v[128:131]
	v_mfma_f32_16x16x32_bf16 v[112:115], v[156:159], v[202:205], v[112:115]
	v_mfma_f32_16x16x32_bf16 v[108:111], v[164:167], v[202:205], v[108:111]
	v_mfma_f32_16x16x32_bf16 v[96:99], v[156:159], v[210:213], v[96:99]
	v_mfma_f32_16x16x32_bf16 v[92:95], v[164:167], v[210:213], v[92:95]
	v_mfma_f32_16x16x32_bf16 v[80:83], v[156:159], v[218:221], v[80:83]
	v_mfma_f32_16x16x32_bf16 v[76:79], v[164:167], v[218:221], v[76:79]
	s_nop 0
	s_nop 0
	v_mfma_f32_16x16x32_bf16 v[120:123], v[168:171], v[184:187], v[120:123]
	v_mfma_f32_16x16x32_bf16 v[116:119], v[176:179], v[184:187], v[116:119]
	v_mfma_f32_16x16x32_bf16 v[104:107], v[168:171], v[192:195], v[104:107]
	v_mfma_f32_16x16x32_bf16 v[100:103], v[176:179], v[192:195], v[100:103]
	v_mfma_f32_16x16x32_bf16 v[88:91], v[168:171], v[206:209], v[88:91]
	v_mfma_f32_16x16x32_bf16 v[84:87], v[176:179], v[206:209], v[84:87]
	v_mfma_f32_16x16x32_bf16 v[72:75], v[168:171], v[214:217], v[72:75]
	v_mfma_f32_16x16x32_bf16 v[68:71], v[176:179], v[214:217], v[68:71]
	v_mfma_f32_16x16x32_bf16 v[120:123], v[172:175], v[188:191], v[120:123]
	v_mfma_f32_16x16x32_bf16 v[116:119], v[180:183], v[188:191], v[116:119]
	v_mfma_f32_16x16x32_bf16 v[104:107], v[172:175], v[202:205], v[104:107]
	v_mfma_f32_16x16x32_bf16 v[100:103], v[180:183], v[202:205], v[100:103]
	v_mfma_f32_16x16x32_bf16 v[88:91], v[172:175], v[210:213], v[88:91]
	v_mfma_f32_16x16x32_bf16 v[84:87], v[180:183], v[210:213], v[84:87]
	v_mfma_f32_16x16x32_bf16 v[72:75], v[172:175], v[218:221], v[72:75]
	v_mfma_f32_16x16x32_bf16 v[68:71], v[180:183], v[218:221], v[68:71]
	s_nop 0
	s_barrier
; #define PG8_STAGE(bufoff, gbase, voff) do { _Pragma("unroll") for (int _i = 0; _i < 2; ++_i) \
;         __builtin_amdgcn_global_load_lds((const unsigned*)((const char*)(gbase) + (voff)[_i]), (LAS unsigned*)(lds + (bufoff) + ldsw + _i * 8192), 16, 0, 0); } while (0)
; #define PG8_LDA(dst, b, h) do { _Pragma("unroll") for (int m = 0; m < 4; ++m) _Pragma("unroll") for (int k = 0; k < 2; ++k) dst[m][k] = *(const LAS bf16x8*)(lds + PG8_SA(b, h) + aoff + m * 2048 + k * 1024); } while (0)
; #define PG8_MMA(ai, bj, At, Bt) do { __builtin_amdgcn_s_setprio(1); _Pragma("unroll") for (int m = 0; m < 4; ++m) _Pragma("unroll") for (int n = 0; n < 2; ++n) _Pragma("unroll") for (int k = 0; k < 2; ++k) \
;         acc[ai][bj][m][n] = __builtin_amdgcn_mfma_f32_16x16x32_bf16(Bt[n][k], At[m][k], acc[ai][bj][m][n], 0, 0, 0); __builtin_amdgcn_s_setprio(0); } while (0)
; #define PG8_WAIT_V(n) asm volatile("s_waitcnt vmcnt(" #n ")" ::: "memory")
; #define PG8_WAIT_L(n) asm volatile("s_waitcnt lgkmcnt(" #n ")" ::: "memory")
; #define PG8_BAR __builtin_amdgcn_s_barrier()
; #define PG8_SCHED __builtin_amdgcn_sched_barrier(0)
; template <class Epi, class Sched>
; __device__ __forceinline__ void gemm_phase(const int tid, LAS unsigned char* lds, const bf16* Aop, const bf16* Bop, const int K_, const Sched& S, const Epi& E, const bf16* Aop1 = nullptr, const bf16* Bop1 = nullptr) {
;     ...
;             PG8_LDA(At, 1, 1); PG8_STAGE(PG8_SB(1, 0), b3, voffB); PG8_STAGE(PG8_SB(1, 1), b3 + hstep, voffB); PG8_STAGE(PG8_SA(1, 0), a3, voffA[0]);
;             PG8_WAIT_V(8); PG8_WAIT_L(0); PG8_BAR; PG8_MMA(1, 0, At, B0); PG8_MMA(1, 1, At, B1); PG8_BAR; PG8_SCHED;
;         }
	s_add_i32 s36, s61, s49
	v_lshl_add_u64 v[144:145], v[144:145], 0, s[20:21]
	s_mov_b32 m0, s36
	ds_read_b128 v[184:187], v151 offset:49152
	ds_read_b128 v[188:191], v151 offset:50176
	ds_read_b128 v[192:195], v151 offset:51200
	ds_read_b128 v[202:205], v151 offset:52224
	ds_read_b128 v[206:209], v151 offset:53248
	ds_read_b128 v[210:213], v151 offset:54272
	ds_read_b128 v[214:217], v151 offset:55296
	ds_read_b128 v[218:221], v151 offset:56320
	global_load_lds_dwordx4 v[144:145], off
	v_lshl_add_u64 v[144:145], v[196:197], 0, s[20:21]
	s_add_i32 m0, s36, 0x2000
	s_add_i32 s36, s64, s49
	global_load_lds_dwordx4 v[144:145], off
	v_lshl_add_u64 v[144:145], v[198:199], 0, s[20:21]
	s_mov_b32 m0, s36
	s_nop 0
	global_load_lds_dwordx4 v[144:145], off
	v_lshl_add_u64 v[144:145], v[222:223], 0, s[20:21]
	s_add_i32 m0, s36, 0x2000
	s_nop 0
	global_load_lds_dwordx4 v[144:145], off
	v_lshl_add_u64 v[144:145], v[224:225], 0, s[20:21]
	s_mov_b32 m0, s54
	s_nop 0
	global_load_lds_dwordx4 v[144:145], off
	v_lshl_add_u64 v[144:145], v[230:231], 0, s[20:21]
	s_mov_b32 m0, s55
	s_nop 0
	global_load_lds_dwordx4 v[144:145], off
	s_waitcnt vmcnt(8)
	s_waitcnt lgkmcnt(0)
	s_barrier
	s_nop 0
	s_waitcnt lgkmcnt(0)
	v_mfma_f32_16x16x32_bf16 v[64:67], v[152:155], v[184:187], v[64:67]
	v_mfma_f32_16x16x32_bf16 v[60:63], v[160:163], v[184:187], v[60:63]
	v_mfma_f32_16x16x32_bf16 v[48:51], v[152:155], v[192:195], v[48:51]
	v_mfma_f32_16x16x32_bf16 v[44:47], v[160:163], v[192:195], v[44:47]
	v_mfma_f32_16x16x32_bf16 v[32:35], v[152:155], v[206:209], v[32:35]
	v_mfma_f32_16x16x32_bf16 v[28:31], v[160:163], v[206:209], v[28:31]
	v_mfma_f32_16x16x32_bf16 v[16:19], v[152:155], v[214:217], v[16:19]
	v_mfma_f32_16x16x32_bf16 v[12:15], v[160:163], v[214:217], v[12:15]
	v_mfma_f32_16x16x32_bf16 v[64:67], v[156:159], v[188:191], v[64:67]
	v_mfma_f32_16x16x32_bf16 v[60:63], v[164:167], v[188:191], v[60:63]
	v_mfma_f32_16x16x32_bf16 v[48:51], v[156:159], v[202:205], v[48:51]
	v_mfma_f32_16x16x32_bf16 v[44:47], v[164:167], v[202:205], v[44:47]
	v_mfma_f32_16x16x32_bf16 v[32:35], v[156:159], v[210:213], v[32:35]
	v_mfma_f32_16x16x32_bf16 v[28:31], v[164:167], v[210:213], v[28:31]
	v_mfma_f32_16x16x32_bf16 v[16:19], v[156:159], v[218:221], v[16:19]
	v_mfma_f32_16x16x32_bf16 v[12:15], v[164:167], v[218:221], v[12:15]
	s_nop 0
	s_nop 0
	v_mfma_f32_16x16x32_bf16 v[56:59], v[168:171], v[184:187], v[56:59]
	v_mfma_f32_16x16x32_bf16 v[52:55], v[176:179], v[184:187], v[52:55]
	v_mfma_f32_16x16x32_bf16 v[40:43], v[168:171], v[192:195], v[40:43]
	v_mfma_f32_16x16x32_bf16 v[36:39], v[176:179], v[192:195], v[36:39]
	v_mfma_f32_16x16x32_bf16 v[24:27], v[168:171], v[206:209], v[24:27]
	v_mfma_f32_16x16x32_bf16 v[20:23], v[176:179], v[206:209], v[20:23]
	v_mfma_f32_16x16x32_bf16 v[8:11], v[168:171], v[214:217], v[8:11]
	v_mfma_f32_16x16x32_bf16 v[4:7], v[176:179], v[214:217], v[4:7]
	v_mfma_f32_16x16x32_bf16 v[56:59], v[172:175], v[188:191], v[56:59]
	v_mfma_f32_16x16x32_bf16 v[52:55], v[180:183], v[188:191], v[52:55]
	v_mfma_f32_16x16x32_bf16 v[40:43], v[172:175], v[202:205], v[40:43]
	v_mfma_f32_16x16x32_bf16 v[36:39], v[180:183], v[202:205], v[36:39]
	v_mfma_f32_16x16x32_bf16 v[24:27], v[172:175], v[210:213], v[24:27]
	v_mfma_f32_16x16x32_bf16 v[20:23], v[180:183], v[210:213], v[20:23]
	v_mfma_f32_16x16x32_bf16 v[8:11], v[172:175], v[218:221], v[8:11]
	v_mfma_f32_16x16x32_bf16 v[4:7], v[180:183], v[218:221], v[4:7]
	s_nop 0
	s_barrier
	s_add_u32 s34, s34, 0x100
	s_addc_u32 s35, s35, 0
	s_add_u32 s40, s40, 0x100
	s_addc_u32 s41, s41, 0
	s_cmp_ge_i32 s60, s8
	s_mov_b32 s36, s60
	s_cbranch_scc0 .LBB0_1094

; #define PG8_GOFFS(slot_) do { _Pragma("unroll") for (int _i = 0; _i < 2; ++_i) { int R, C; stage_rc(tid * 16 + _i * 8192, R, C); _Pragma("unroll") for (int _h = 0; _h < 2; ++_h) { \
;         unsigned t_ = gtab[(slot_) * 256 + R + 128 * _h]; t_ = t_ < (unsigned)(T - 1) ? t_ : (unsigned)(T - 1); voffA[_h][_i] = (t_ * (unsigned)K + (unsigned)C) * 2u; } } } while (0)
; #define PG8_STAGE(bufoff, gbase, voff) do { _Pragma("unroll") for (int _i = 0; _i < 2; ++_i) \
;         __builtin_amdgcn_global_load_lds((const unsigned*)((const char*)(gbase) + (voff)[_i]), (LAS unsigned*)(lds + (bufoff) + ldsw + _i * 8192), 16, 0, 0); } while (0)
; #define PG8_STAGE_A1(bufoff, gbase) do { if (Epi::GATHER) PG8_STAGE(bufoff, gbase, voffA[1]); else PG8_STAGE(bufoff, (gbase) + hstep, voffA[0]); } while (0)
; #define PG8_LDA(dst, b, h) do { _Pragma("unroll") for (int m = 0; m < 4; ++m) _Pragma("unroll") for (int k = 0; k < 2; ++k) dst[m][k] = *(const LAS bf16x8*)(lds + PG8_SA(b, h) + aoff + m * 2048 + k * 1024); } while (0)
; #define PG8_BAR __builtin_amdgcn_s_barrier()
; template <class Epi, class Sched>
; __device__ __forceinline__ void gemm_phase(const int tid, LAS unsigned char* lds, const bf16* Aop, const bf16* Bop, const int K_, const Sched& S, const Epi& E, const bf16* Aop1 = nullptr, const bf16* Bop1 = nullptr) {
;     ...
;             PG8_LDB(B0, 0, 0); PG8_LDB(B1, 0, 1); PG8_SCHED; PG8_LDA(At, 0, 0); PG8_STAGE_A1(PG8_SA(1, 1), a1);
;             PG8_WAIT_V(8); PG8_WAIT_L(0); PG8_BAR; PG8_MMA(0, 0, At, B0); PG8_MMA(0, 1, At, B1); PG8_BAR; PG8_SCHED;
;             PG8_LDA(At, 0, 1); PG8_STAGE(PG8_SB(0, 0), b2, voffB); PG8_STAGE(PG8_SB(0, 1), b2 + hstep, voffB); if (Epi::GATHER && last && has_next) PG8_GOFFS((ui + 1) & 1); PG8_STAGE(PG8_SA(0, 0), a2, voffA[0]);
;             PG8_WAIT_V(8); PG8_WAIT_L(0); PG8_BAR; PG8_MMA(1, 0, At, B0); PG8_MMA(1, 1, At, B1); PG8_BAR; PG8_SCHED;
;             PG8_LDB(B0, 1, 0); PG8_LDB(B1, 1, 1); PG8_SCHED; PG8_LDA(At, 1, 0); PG8_STAGE_A1(PG8_SA(0, 1), a2);
;             PG8_WAIT_V(8); PG8_WAIT_L(0); PG8_BAR; PG8_MMA(0, 0, At, B0); PG8_MMA(0, 1, At, B1); PG8_BAR; PG8_SCHED;
;             PG8_LDA(At, 1, 1); PG8_STAGE(PG8_SB(1, 0), b3, voffB); PG8_STAGE(PG8_SB(1, 1), b3 + hstep, voffB); PG8_STAGE(PG8_SA(1, 0), a3, voffA[0]);
;             PG8_WAIT_V(8); PG8_WAIT_L(0); PG8_BAR; PG8_MMA(1, 0, At, B0); PG8_MMA(1, 1, At, B1); PG8_BAR; PG8_SCHED;
.LBB0_1314:
	s_add_i32 s69, s69, 2
	s_add_u32 s40, s40, 0x100
	s_addc_u32 s41, s41, 0
	s_and_b64 s[42:43], s[42:43], exec
	s_cselect_b32 s42, 0, s40
	s_cselect_b32 s43, 0, s41
	s_add_u32 s42, s4, s42
	s_mov_b32 m0, s52
	s_addc_u32 s43, s5, s43
	global_load_lds_dwordx4 v204, s[42:43]
	s_mov_b32 m0, s53
	v_mov_b32_e32 v205, v2
	global_load_lds_dwordx4 v208, s[42:43]
	s_waitcnt vmcnt(8)
	s_waitcnt lgkmcnt(0)
	v_mov_b32_e32 v209, v2
	v_mov_b32_e32 v207, v2
	v_mov_b32_e32 v211, v2
	v_lshl_add_u64 v[196:197], s[42:43], 0, v[204:205]
	v_lshl_add_u64 v[198:199], s[42:43], 0, v[208:209]
	s_barrier
	s_nop 0
	s_waitcnt lgkmcnt(0)
	v_mfma_f32_16x16x32_bf16 v[64:67], v[148:151], v[188:191], v[64:67]
	v_mfma_f32_16x16x32_bf16 v[56:59], v[156:159], v[188:191], v[56:59]
	v_mfma_f32_16x16x32_bf16 v[48:51], v[148:151], v[180:183], v[48:51]
	v_mfma_f32_16x16x32_bf16 v[40:43], v[156:159], v[180:183], v[40:43]
	v_mfma_f32_16x16x32_bf16 v[32:35], v[148:151], v[172:175], v[32:35]
	v_mfma_f32_16x16x32_bf16 v[24:27], v[156:159], v[172:175], v[24:27]
	v_mfma_f32_16x16x32_bf16 v[16:19], v[148:151], v[164:167], v[16:19]
	v_mfma_f32_16x16x32_bf16 v[8:11], v[156:159], v[164:167], v[8:11]
	v_mfma_f32_16x16x32_bf16 v[64:67], v[152:155], v[192:195], v[64:67]
	v_mfma_f32_16x16x32_bf16 v[56:59], v[160:163], v[192:195], v[56:59]
	v_mfma_f32_16x16x32_bf16 v[48:51], v[152:155], v[184:187], v[48:51]
	v_mfma_f32_16x16x32_bf16 v[40:43], v[160:163], v[184:187], v[40:43]
	v_mfma_f32_16x16x32_bf16 v[32:35], v[152:155], v[176:179], v[32:35]
	v_mfma_f32_16x16x32_bf16 v[24:27], v[160:163], v[176:179], v[24:27]
	v_mfma_f32_16x16x32_bf16 v[16:19], v[152:155], v[168:171], v[16:19]
	v_mfma_f32_16x16x32_bf16 v[8:11], v[160:163], v[168:171], v[8:11]
	s_nop 0
	s_nop 0
	v_mfma_f32_16x16x32_bf16 v[60:63], v[132:135], v[188:191], v[60:63]
	v_mfma_f32_16x16x32_bf16 v[52:55], v[140:143], v[188:191], v[52:55]
	v_mfma_f32_16x16x32_bf16 v[44:47], v[132:135], v[180:183], v[44:47]
	v_mfma_f32_16x16x32_bf16 v[36:39], v[140:143], v[180:183], v[36:39]
	v_mfma_f32_16x16x32_bf16 v[28:31], v[132:135], v[172:175], v[28:31]
	v_mfma_f32_16x16x32_bf16 v[20:23], v[140:143], v[172:175], v[20:23]
	v_mfma_f32_16x16x32_bf16 v[12:15], v[132:135], v[164:167], v[12:15]
	v_mfma_f32_16x16x32_bf16 v[4:7], v[140:143], v[164:167], v[4:7]
	v_mfma_f32_16x16x32_bf16 v[60:63], v[136:139], v[192:195], v[60:63]
	v_mfma_f32_16x16x32_bf16 v[52:55], v[144:147], v[192:195], v[52:55]
	v_mfma_f32_16x16x32_bf16 v[44:47], v[136:139], v[184:187], v[44:47]
	v_mfma_f32_16x16x32_bf16 v[36:39], v[144:147], v[184:187], v[36:39]
	v_mfma_f32_16x16x32_bf16 v[28:31], v[136:139], v[176:179], v[28:31]
	v_mfma_f32_16x16x32_bf16 v[20:23], v[144:147], v[176:179], v[20:23]
	v_mfma_f32_16x16x32_bf16 v[12:15], v[136:139], v[168:171], v[12:15]
	v_mfma_f32_16x16x32_bf16 v[4:7], v[144:147], v[168:171], v[4:7]
	s_nop 0
	s_barrier
	s_add_i32 s70, 0, 0x18000
	s_add_i32 s71, 0, 0x1c000
	v_add_u32_e32 v144, s70, v242
	v_add_u32_e32 v160, s71, v242
	ds_read_b128 v[132:135], v144
	ds_read_b128 v[136:139], v144 offset:1024
	ds_read_b128 v[140:143], v144 offset:2048
	ds_read_b128 v[144:147], v144 offset:3072
	ds_read_b128 v[148:151], v160
	ds_read_b128 v[152:155], v160 offset:1024
	ds_read_b128 v[156:159], v160 offset:2048
	ds_read_b128 v[160:163], v160 offset:3072
	s_mov_b32 m0, s54
	v_lshl_add_u64 v[224:225], s[42:43], 0, v[206:207]
	ds_read_b128 v[164:167], v244 offset:32768
	ds_read_b128 v[168:171], v244 offset:33792
	ds_read_b128 v[172:175], v244 offset:34816
	ds_read_b128 v[176:179], v244 offset:35840
	ds_read_b128 v[180:183], v244 offset:36864
	ds_read_b128 v[184:187], v244 offset:37888
	ds_read_b128 v[188:191], v244 offset:38912
	ds_read_b128 v[192:195], v244 offset:39936
	global_load_lds_dwordx4 v[224:225], off
	v_lshl_add_u64 v[224:225], s[42:43], 0, v[210:211]
	s_mov_b32 m0, s55
	s_nop 0
	global_load_lds_dwordx4 v[224:225], off
	s_waitcnt vmcnt(8)
	s_waitcnt lgkmcnt(0)
	s_barrier
	s_nop 0
	s_waitcnt lgkmcnt(0)
	v_mfma_f32_16x16x32_bf16 v[124:127], v[132:135], v[164:167], v[124:127]
	v_mfma_f32_16x16x32_bf16 v[120:123], v[140:143], v[164:167], v[120:123]
	v_mfma_f32_16x16x32_bf16 v[112:115], v[132:135], v[172:175], v[112:115]
	v_mfma_f32_16x16x32_bf16 v[104:107], v[140:143], v[172:175], v[104:107]
	v_mfma_f32_16x16x32_bf16 v[96:99], v[132:135], v[180:183], v[96:99]
	v_mfma_f32_16x16x32_bf16 v[88:91], v[140:143], v[180:183], v[88:91]
	v_mfma_f32_16x16x32_bf16 v[80:83], v[132:135], v[188:191], v[80:83]
	v_mfma_f32_16x16x32_bf16 v[72:75], v[140:143], v[188:191], v[72:75]
	v_mfma_f32_16x16x32_bf16 v[124:127], v[136:139], v[168:171], v[124:127]
	v_mfma_f32_16x16x32_bf16 v[120:123], v[144:147], v[168:171], v[120:123]
	v_mfma_f32_16x16x32_bf16 v[112:115], v[136:139], v[176:179], v[112:115]
	v_mfma_f32_16x16x32_bf16 v[104:107], v[144:147], v[176:179], v[104:107]
	v_mfma_f32_16x16x32_bf16 v[96:99], v[136:139], v[184:187], v[96:99]
	v_mfma_f32_16x16x32_bf16 v[88:91], v[144:147], v[184:187], v[88:91]
	v_mfma_f32_16x16x32_bf16 v[80:83], v[136:139], v[192:195], v[80:83]
	v_mfma_f32_16x16x32_bf16 v[72:75], v[144:147], v[192:195], v[72:75]
	s_nop 0
	s_nop 0
	v_mfma_f32_16x16x32_bf16 v[128:131], v[148:151], v[164:167], v[128:131]
	v_mfma_f32_16x16x32_bf16 v[116:119], v[156:159], v[164:167], v[116:119]
	v_mfma_f32_16x16x32_bf16 v[108:111], v[148:151], v[172:175], v[108:111]
	v_mfma_f32_16x16x32_bf16 v[100:103], v[156:159], v[172:175], v[100:103]
	v_mfma_f32_16x16x32_bf16 v[92:95], v[148:151], v[180:183], v[92:95]
	v_mfma_f32_16x16x32_bf16 v[84:87], v[156:159], v[180:183], v[84:87]
	v_mfma_f32_16x16x32_bf16 v[76:79], v[148:151], v[188:191], v[76:79]
	v_mfma_f32_16x16x32_bf16 v[68:71], v[156:159], v[188:191], v[68:71]
	v_mfma_f32_16x16x32_bf16 v[128:131], v[152:155], v[168:171], v[128:131]
	v_mfma_f32_16x16x32_bf16 v[116:119], v[160:163], v[168:171], v[116:119]
	v_mfma_f32_16x16x32_bf16 v[108:111], v[152:155], v[176:179], v[108:111]
	v_mfma_f32_16x16x32_bf16 v[100:103], v[160:163], v[176:179], v[100:103]
	v_mfma_f32_16x16x32_bf16 v[92:95], v[152:155], v[184:187], v[92:95]
	v_mfma_f32_16x16x32_bf16 v[84:87], v[160:163], v[184:187], v[84:87]
	v_mfma_f32_16x16x32_bf16 v[76:79], v[152:155], v[192:195], v[76:79]
	v_mfma_f32_16x16x32_bf16 v[68:71], v[160:163], v[192:195], v[68:71]
	s_nop 0
	s_barrier
; #define PG8_GOFFS(slot_) do { _Pragma("unroll") for (int _i = 0; _i < 2; ++_i) { int R, C; stage_rc(tid * 16 + _i * 8192, R, C); _Pragma("unroll") for (int _h = 0; _h < 2; ++_h) { \
;         unsigned t_ = gtab[(slot_) * 256 + R + 128 * _h]; t_ = t_ < (unsigned)(T - 1) ? t_ : (unsigned)(T - 1); voffA[_h][_i] = (t_ * (unsigned)K + (unsigned)C) * 2u; } } } while (0)
; #define PG8_STAGE(bufoff, gbase, voff) do { _Pragma("unroll") for (int _i = 0; _i < 2; ++_i) \
;         __builtin_amdgcn_global_load_lds((const unsigned*)((const char*)(gbase) + (voff)[_i]), (LAS unsigned*)(lds + (bufoff) + ldsw + _i * 8192), 16, 0, 0); } while (0)
; #define PG8_STAGE_A1(bufoff, gbase) do { if (Epi::GATHER) PG8_STAGE(bufoff, gbase, voffA[1]); else PG8_STAGE(bufoff, (gbase) + hstep, voffA[0]); } while (0)
; #define PG8_LDA(dst, b, h) do { _Pragma("unroll") for (int m = 0; m < 4; ++m) _Pragma("unroll") for (int k = 0; k < 2; ++k) dst[m][k] = *(const LAS bf16x8*)(lds + PG8_SA(b, h) + aoff + m * 2048 + k * 1024); } while (0)
; #define PG8_LDB(dst, b, h) do { _Pragma("unroll") for (int n = 0; n < 2; ++n) _Pragma("unroll") for (int k = 0; k < 2; ++k) dst[n][k] = *(const LAS bf16x8*)(lds + PG8_SB(b, h) + boff + n * 2048 + k * 1024); } while (0)
; #define PG8_BAR __builtin_amdgcn_s_barrier()
; template <class Epi, class Sched>
; __device__ __forceinline__ void gemm_phase(const int tid, LAS unsigned char* lds, const bf16* Aop, const bf16* Bop, const int K_, const Sched& S, const Epi& E, const bf16* Aop1 = nullptr, const bf16* Bop1 = nullptr) {
;     ...
;             PG8_LDA(At, 0, 1); PG8_STAGE(PG8_SB(0, 0), b2, voffB); PG8_STAGE(PG8_SB(0, 1), b2 + hstep, voffB); if (Epi::GATHER && last && has_next) PG8_GOFFS((ui + 1) & 1); PG8_STAGE(PG8_SA(0, 0), a2, voffA[0]);
;             PG8_WAIT_V(8); PG8_WAIT_L(0); PG8_BAR; PG8_MMA(1, 0, At, B0); PG8_MMA(1, 1, At, B1); PG8_BAR; PG8_SCHED;
;             PG8_LDB(B0, 1, 0); PG8_LDB(B1, 1, 1); PG8_SCHED; PG8_LDA(At, 1, 0); PG8_STAGE_A1(PG8_SA(0, 1), a2);
;             PG8_WAIT_V(8); PG8_WAIT_L(0); PG8_BAR; PG8_MMA(0, 0, At, B0); PG8_MMA(0, 1, At, B1); PG8_BAR; PG8_SCHED;
;             PG8_LDA(At, 1, 1); PG8_STAGE(PG8_SB(1, 0), b3, voffB); PG8_STAGE(PG8_SB(1, 1), b3 + hstep, voffB); PG8_STAGE(PG8_SA(1, 0), a3, voffA[0]);
;             PG8_WAIT_V(8); PG8_WAIT_L(0); PG8_BAR; PG8_MMA(1, 0, At, B0); PG8_MMA(1, 1, At, B1); PG8_BAR; PG8_SCHED;
;         }
	s_add_i32 s42, s70, s51
	v_lshl_add_u64 v[216:217], v[216:217], 0, s[20:21]
	s_mov_b32 m0, s42
	ds_read_b128 v[164:167], v244 offset:49152
	ds_read_b128 v[168:171], v244 offset:50176
	ds_read_b128 v[172:175], v244 offset:51200
	ds_read_b128 v[176:179], v244 offset:52224
	ds_read_b128 v[180:183], v244 offset:53248
	ds_read_b128 v[184:187], v244 offset:54272
	ds_read_b128 v[188:191], v244 offset:55296
	ds_read_b128 v[192:195], v244 offset:56320
	global_load_lds_dwordx4 v[216:217], off
	v_lshl_add_u64 v[216:217], v[218:219], 0, s[20:21]
	s_add_i32 m0, s42, 0x2000
	s_add_i32 s42, s71, s51
	global_load_lds_dwordx4 v[216:217], off
	v_lshl_add_u64 v[216:217], v[220:221], 0, s[20:21]
	s_mov_b32 m0, s42
	v_lshl_add_u64 v[196:197], v[196:197], 0, s[20:21]
	global_load_lds_dwordx4 v[216:217], off
	v_lshl_add_u64 v[216:217], v[222:223], 0, s[20:21]
	s_add_i32 m0, s42, 0x2000
	s_nop 0
	global_load_lds_dwordx4 v[216:217], off
	s_mov_b32 m0, s56
	s_nop 0
	global_load_lds_dwordx4 v[196:197], off
	v_lshl_add_u64 v[196:197], v[198:199], 0, s[20:21]
	s_mov_b32 m0, s57
	s_nop 0
	global_load_lds_dwordx4 v[196:197], off
	s_waitcnt vmcnt(8)
	s_waitcnt lgkmcnt(0)
	s_barrier
	s_nop 0
	s_waitcnt lgkmcnt(0)
	v_mfma_f32_16x16x32_bf16 v[64:67], v[132:135], v[164:167], v[64:67]
	v_mfma_f32_16x16x32_bf16 v[56:59], v[140:143], v[164:167], v[56:59]
	v_mfma_f32_16x16x32_bf16 v[48:51], v[132:135], v[172:175], v[48:51]
	v_mfma_f32_16x16x32_bf16 v[40:43], v[140:143], v[172:175], v[40:43]
	v_mfma_f32_16x16x32_bf16 v[32:35], v[132:135], v[180:183], v[32:35]
	v_mfma_f32_16x16x32_bf16 v[24:27], v[140:143], v[180:183], v[24:27]
	v_mfma_f32_16x16x32_bf16 v[16:19], v[132:135], v[188:191], v[16:19]
	v_mfma_f32_16x16x32_bf16 v[8:11], v[140:143], v[188:191], v[8:11]
	v_mfma_f32_16x16x32_bf16 v[64:67], v[136:139], v[168:171], v[64:67]
	v_mfma_f32_16x16x32_bf16 v[56:59], v[144:147], v[168:171], v[56:59]
	v_mfma_f32_16x16x32_bf16 v[48:51], v[136:139], v[176:179], v[48:51]
	v_mfma_f32_16x16x32_bf16 v[40:43], v[144:147], v[176:179], v[40:43]
	v_mfma_f32_16x16x32_bf16 v[32:35], v[136:139], v[184:187], v[32:35]
	v_mfma_f32_16x16x32_bf16 v[24:27], v[144:147], v[184:187], v[24:27]
	v_mfma_f32_16x16x32_bf16 v[16:19], v[136:139], v[192:195], v[16:19]
	v_mfma_f32_16x16x32_bf16 v[8:11], v[144:147], v[192:195], v[8:11]
	s_nop 0
	s_nop 0
	v_mfma_f32_16x16x32_bf16 v[60:63], v[148:151], v[164:167], v[60:63]
	v_mfma_f32_16x16x32_bf16 v[52:55], v[156:159], v[164:167], v[52:55]
	v_mfma_f32_16x16x32_bf16 v[44:47], v[148:151], v[172:175], v[44:47]
	v_mfma_f32_16x16x32_bf16 v[36:39], v[156:159], v[172:175], v[36:39]
	v_mfma_f32_16x16x32_bf16 v[28:31], v[148:151], v[180:183], v[28:31]
	v_mfma_f32_16x16x32_bf16 v[20:23], v[156:159], v[180:183], v[20:23]
	v_mfma_f32_16x16x32_bf16 v[12:15], v[148:151], v[188:191], v[12:15]
	v_mfma_f32_16x16x32_bf16 v[4:7], v[156:159], v[188:191], v[4:7]
	v_mfma_f32_16x16x32_bf16 v[60:63], v[152:155], v[168:171], v[60:63]
	v_mfma_f32_16x16x32_bf16 v[52:55], v[160:163], v[168:171], v[52:55]
	v_mfma_f32_16x16x32_bf16 v[44:47], v[152:155], v[176:179], v[44:47]
	v_mfma_f32_16x16x32_bf16 v[36:39], v[160:163], v[176:179], v[36:39]
	v_mfma_f32_16x16x32_bf16 v[28:31], v[152:155], v[184:187], v[28:31]
	v_mfma_f32_16x16x32_bf16 v[20:23], v[160:163], v[184:187], v[20:23]
	v_mfma_f32_16x16x32_bf16 v[12:15], v[152:155], v[192:195], v[12:15]
	v_mfma_f32_16x16x32_bf16 v[4:7], v[160:163], v[192:195], v[4:7]
	s_nop 0
	s_barrier
	s_cmp_ge_i32 s69, s3
	s_cbranch_scc1 .LBB0_1318
; #define PG8_GOFFS(slot_) do { _Pragma("unroll") for (int _i = 0; _i < 2; ++_i) { int R, C; stage_rc(tid * 16 + _i * 8192, R, C); _Pragma("unroll") for (int _h = 0; _h < 2; ++_h) { \
;         unsigned t_ = gtab[(slot_) * 256 + R + 128 * _h]; t_ = t_ < (unsigned)(T - 1) ? t_ : (unsigned)(T - 1); voffA[_h][_i] = (t_ * (unsigned)K + (unsigned)C) * 2u; } } } while (0)
; #define PG8_STAGE(bufoff, gbase, voff) do { _Pragma("unroll") for (int _i = 0; _i < 2; ++_i) \
;         __builtin_amdgcn_global_load_lds((const unsigned*)((const char*)(gbase) + (voff)[_i]), (LAS unsigned*)(lds + (bufoff) + ldsw + _i * 8192), 16, 0, 0); } while (0)
; #define PG8_STAGE_A1(bufoff, gbase) do { if (Epi::GATHER) PG8_STAGE(bufoff, gbase, voffA[1]); else PG8_STAGE(bufoff, (gbase) + hstep, voffA[0]); } while (0)
; #define PG8_LDA(dst, b, h) do { _Pragma("unroll") for (int m = 0; m < 4; ++m) _Pragma("unroll") for (int k = 0; k < 2; ++k) dst[m][k] = *(const LAS bf16x8*)(lds + PG8_SA(b, h) + aoff + m * 2048 + k * 1024); } while (0)
; #define PG8_LDB(dst, b, h) do { _Pragma("unroll") for (int n = 0; n < 2; ++n) _Pragma("unroll") for (int k = 0; k < 2; ++k) dst[n][k] = *(const LAS bf16x8*)(lds + PG8_SB(b, h) + boff + n * 2048 + k * 1024); } while (0)
; #define PG8_WAIT_V(n) asm volatile("s_waitcnt vmcnt(" #n ")" ::: "memory")
; #define PG8_WAIT_L(n) asm volatile("s_waitcnt lgkmcnt(" #n ")" ::: "memory")
; #define PG8_BAR __builtin_amdgcn_s_barrier()
; template <class Epi, class Sched>
; __device__ __forceinline__ void gemm_phase(const int tid, LAS unsigned char* lds, const bf16* Aop, const bf16* Bop, const int K_, const Sched& S, const Epi& E, const bf16* Aop1 = nullptr, const bf16* Bop1 = nullptr) {
;     ...
;             PG8_LDB(B0, 0, 0); PG8_LDB(B1, 0, 1); PG8_SCHED; PG8_LDA(At, 0, 0); PG8_STAGE_A1(PG8_SA(1, 1), a1);
;             PG8_WAIT_V(8); PG8_WAIT_L(0); PG8_BAR; PG8_MMA(0, 0, At, B0); PG8_MMA(0, 1, At, B1); PG8_BAR; PG8_SCHED;
;             PG8_LDA(At, 0, 1); PG8_STAGE(PG8_SB(0, 0), b2, voffB); PG8_STAGE(PG8_SB(0, 1), b2 + hstep, voffB); if (Epi::GATHER && last && has_next) PG8_GOFFS((ui + 1) & 1); PG8_STAGE(PG8_SA(0, 0), a2, voffA[0]);
;             PG8_WAIT_V(8); PG8_WAIT_L(0); PG8_BAR; PG8_MMA(1, 0, At, B0); PG8_MMA(1, 1, At, B1); PG8_BAR; PG8_SCHED;
;             PG8_LDB(B0, 1, 0); PG8_LDB(B1, 1, 1); PG8_SCHED; PG8_LDA(At, 1, 0); PG8_STAGE_A1(PG8_SA(0, 1), a2);
.LBB0_1315:
	s_cmp_eq_u32 s60, s69
	s_cselect_b64 s[42:43], -1, 0
	s_add_u32 s72, s67, s40
	s_addc_u32 s73, s68, s41
	s_add_i32 s74, 0, 0x10000
	s_and_b64 s[70:71], s[42:43], exec
	s_cselect_b32 s71, s29, s73
	s_cselect_b32 s70, s28, s72
	s_add_i32 s75, 0, 0x14000
	v_add_u32_e32 v132, s74, v242
	v_add_u32_e32 v144, s75, v242
	ds_read_b128 v[148:151], v132
	ds_read_b128 v[152:155], v132 offset:1024
	ds_read_b128 v[156:159], v132 offset:2048
	ds_read_b128 v[160:163], v132 offset:3072
	ds_read_b128 v[132:135], v144
	ds_read_b128 v[136:139], v144 offset:1024
	ds_read_b128 v[140:143], v144 offset:2048
	ds_read_b128 v[144:147], v144 offset:3072
	s_add_i32 m0, s52, 0xc000
	s_add_u32 s72, s14, s40
	s_addc_u32 s73, s15, s41
	ds_read_b128 v[164:167], v244
	ds_read_b128 v[168:171], v244 offset:1024
	ds_read_b128 v[172:175], v244 offset:2048
	ds_read_b128 v[176:179], v244 offset:3072
	ds_read_b128 v[180:183], v244 offset:4096
	ds_read_b128 v[184:187], v244 offset:5120
	ds_read_b128 v[188:191], v244 offset:6144
	ds_read_b128 v[192:195], v244 offset:7168
	global_load_lds_dwordx4 v206, s[72:73]
	s_add_i32 m0, s52, 0xe000
	s_nop 0
	global_load_lds_dwordx4 v210, s[72:73]
	s_waitcnt vmcnt(8)
	s_waitcnt lgkmcnt(0)
	s_barrier
	s_nop 0
	s_waitcnt lgkmcnt(0)
	v_mfma_f32_16x16x32_bf16 v[124:127], v[148:151], v[164:167], v[124:127]
	v_mfma_f32_16x16x32_bf16 v[120:123], v[156:159], v[164:167], v[120:123]
	v_mfma_f32_16x16x32_bf16 v[112:115], v[148:151], v[172:175], v[112:115]
	v_mfma_f32_16x16x32_bf16 v[104:107], v[156:159], v[172:175], v[104:107]
	v_mfma_f32_16x16x32_bf16 v[96:99], v[148:151], v[180:183], v[96:99]
	v_mfma_f32_16x16x32_bf16 v[88:91], v[156:159], v[180:183], v[88:91]
	v_mfma_f32_16x16x32_bf16 v[80:83], v[148:151], v[188:191], v[80:83]
	v_mfma_f32_16x16x32_bf16 v[72:75], v[156:159], v[188:191], v[72:75]
	v_mfma_f32_16x16x32_bf16 v[124:127], v[152:155], v[168:171], v[124:127]
	v_mfma_f32_16x16x32_bf16 v[120:123], v[160:163], v[168:171], v[120:123]
	v_mfma_f32_16x16x32_bf16 v[112:115], v[152:155], v[176:179], v[112:115]
	v_mfma_f32_16x16x32_bf16 v[104:107], v[160:163], v[176:179], v[104:107]
	v_mfma_f32_16x16x32_bf16 v[96:99], v[152:155], v[184:187], v[96:99]
	v_mfma_f32_16x16x32_bf16 v[88:91], v[160:163], v[184:187], v[88:91]
	v_mfma_f32_16x16x32_bf16 v[80:83], v[152:155], v[192:195], v[80:83]
	v_mfma_f32_16x16x32_bf16 v[72:75], v[160:163], v[192:195], v[72:75]
	s_nop 0
	s_nop 0
	v_mfma_f32_16x16x32_bf16 v[128:131], v[132:135], v[164:167], v[128:131]
	v_mfma_f32_16x16x32_bf16 v[116:119], v[140:143], v[164:167], v[116:119]
	v_mfma_f32_16x16x32_bf16 v[108:111], v[132:135], v[172:175], v[108:111]
	v_mfma_f32_16x16x32_bf16 v[100:103], v[140:143], v[172:175], v[100:103]
	v_mfma_f32_16x16x32_bf16 v[92:95], v[132:135], v[180:183], v[92:95]
	v_mfma_f32_16x16x32_bf16 v[84:87], v[140:143], v[180:183], v[84:87]
	v_mfma_f32_16x16x32_bf16 v[76:79], v[132:135], v[188:191], v[76:79]
	v_mfma_f32_16x16x32_bf16 v[68:71], v[140:143], v[188:191], v[68:71]
	v_mfma_f32_16x16x32_bf16 v[128:131], v[136:139], v[168:171], v[128:131]
	v_mfma_f32_16x16x32_bf16 v[116:119], v[144:147], v[168:171], v[116:119]
	v_mfma_f32_16x16x32_bf16 v[108:111], v[136:139], v[176:179], v[108:111]
	v_mfma_f32_16x16x32_bf16 v[100:103], v[144:147], v[176:179], v[100:103]
	v_mfma_f32_16x16x32_bf16 v[92:95], v[136:139], v[184:187], v[92:95]
	v_mfma_f32_16x16x32_bf16 v[84:87], v[144:147], v[184:187], v[84:87]
	v_mfma_f32_16x16x32_bf16 v[76:79], v[136:139], v[192:195], v[76:79]
	v_mfma_f32_16x16x32_bf16 v[68:71], v[144:147], v[192:195], v[68:71]
	s_nop 0
	s_barrier
	s_add_i32 s72, s74, s51
	v_lshl_add_u64 v[216:217], s[70:71], 0, v[0:1]
	s_mov_b32 m0, s72
	ds_read_b128 v[188:191], v244 offset:16384
	ds_read_b128 v[192:195], v244 offset:17408
	ds_read_b128 v[180:183], v244 offset:18432
	ds_read_b128 v[184:187], v244 offset:19456
	ds_read_b128 v[172:175], v244 offset:20480
	ds_read_b128 v[176:179], v244 offset:21504
	ds_read_b128 v[164:167], v244 offset:22528
	ds_read_b128 v[168:171], v244 offset:23552
	global_load_lds_dwordx4 v[216:217], off
	s_add_i32 m0, s72, 0x2000
	v_lshl_add_u64 v[218:219], s[70:71], 0, v[202:203]
	s_add_u32 s70, s70, s6
	s_addc_u32 s71, s71, s7
	s_add_i32 s72, s75, s51
	global_load_lds_dwordx4 v[218:219], off
	v_lshl_add_u64 v[220:221], s[70:71], 0, v[0:1]
	s_mov_b32 m0, s72
	v_lshl_add_u64 v[222:223], s[70:71], 0, v[202:203]
	global_load_lds_dwordx4 v[220:221], off
	s_add_i32 m0, s72, 0x2000
	s_and_b64 s[70:71], s[36:37], s[42:43]
	global_load_lds_dwordx4 v[222:223], off
	s_andn2_b64 vcc, exec, s[70:71]
	s_cbranch_vccnz .LBB0_1314
	ds_read_b32 v196, v245
	ds_read_b32 v197, v245 offset:512
	ds_read_b32 v198, v246
	s_waitcnt lgkmcnt(0)
	v_min_u32_e32 v196, 0x41ff, v196
	v_mul_lo_u32 v196, v196, s2
	v_add_lshl_u32 v204, v196, v3, 1
	ds_read_b32 v196, v246 offset:512
	v_min_u32_e32 v197, 0x41ff, v197
	v_mul_lo_u32 v197, v197, s2
	v_add_lshl_u32 v206, v197, v3, 1
	v_min_u32_e32 v197, 0x41ff, v198
	s_waitcnt lgkmcnt(0)
	v_min_u32_e32 v196, 0x41ff, v196
	v_mul_lo_u32 v197, v197, s2
	v_mul_lo_u32 v196, v196, s2
	v_add_lshl_u32 v208, v197, v200, 1
	v_add_lshl_u32 v210, v196, v200, 1
	s_branch .LBB0_1314

; #define LAS __attribute__((address_space(3)))
;     __device__ bool next(int i, Unit& u) const { if (!so.next(i >> 1, u)) return false; u.sel = i & 1; return true; }
;     __device__ bool next(int i, Unit& u) const { const int L = i * nw + r; if (L >= nu) return false; u.pm = L >> 2; u.pn = L & 3; u.pb = u.pn; u.sel = 0; return true; }
; #define PG8_STAGE(bufoff, gbase, voff) do { _Pragma("unroll") for (int _i = 0; _i < 2; ++_i) \
;         __builtin_amdgcn_global_load_lds((const unsigned*)((const char*)(gbase) + (voff)[_i]), (LAS unsigned*)(lds + (bufoff) + ldsw + _i * 8192), 16, 0, 0); } while (0)
; template <class Epi, class Sched>
; __device__ __forceinline__ void gemm_phase(const int tid, LAS unsigned char* lds, const bf16* Aop, const bf16* Bop, const int K_, const Sched& S, const Epi& E, const bf16* Aop1 = nullptr, const bf16* Bop1 = nullptr) {
;     ...
;     for (;;) {
;         const bool has_next = S.next(ui + 1, nxt);
;         if (Epi::GATHER && has_next && wid < 4) E.tok_dma(nxt.pm * 256 + wid * 64, (LAS unsigned*)(lds + 8 * HTB) + ((ui + 1) & 1) * 256 + wid * 64, lane);
;         const char* nA = has_next ? (const char*)((Aop1 && nxt.sel) ? Aop1 : Aop) + (Epi::GATHER ? (size_t)0 : (size_t)nxt.pm * tstep) : cA; const char* nB = has_next ? (const char*)((Bop1 && nxt.sel) ? Bop1 : Bop) + (size_t)nxt.pb * tstep : cB;
;         for (int t = 0; t < nt; t += 2) {
;             const bool last = (t == nt - 2);
;             const char* a1 = cA + (size_t)(t + 1) * kstep;
;             const char* a2 = last ? nA : cA + (size_t)(t + 2) * kstep; const char* b2 = last ? nB : cB + (size_t)(t + 2) * kstep;
;             const char* a3 = a2 + kstep; const char* b3 = b2 + kstep;
;             PG8_LDB(B0, 0, 0); PG8_LDB(B1, 0, 1); PG8_SCHED; PG8_LDA(At, 0, 0); PG8_STAGE_A1(PG8_SA(1, 1), a1);
;             PG8_WAIT_V(8); PG8_WAIT_L(0); PG8_BAR; PG8_MMA(0, 0, At, B0); PG8_MMA(0, 1, At, B1); PG8_BAR; PG8_SCHED;
;             PG8_LDA(At, 0, 1); PG8_STAGE(PG8_SB(0, 0), b2, voffB); PG8_STAGE(PG8_SB(0, 1), b2 + hstep, voffB); if (Epi::GATHER && last && has_next) PG8_GOFFS((ui + 1) & 1); PG8_STAGE(PG8_SA(0, 0), a2, voffA[0]);
;             PG8_WAIT_V(8); PG8_WAIT_L(0); PG8_BAR; PG8_MMA(1, 0, At, B0); PG8_MMA(1, 1, At, B1); PG8_BAR; PG8_SCHED;
;             PG8_LDB(B0, 1, 0); PG8_LDB(B1, 1, 1); PG8_SCHED; PG8_LDA(At, 1, 0); PG8_STAGE_A1(PG8_SA(0, 1), a2);
.LBB0_1398:
	v_mov_b32_e32 v127, 0
	s_andn2_b64 vcc, exec, s[16:17]
	s_cbranch_vccnz .LBB0_1401
	s_add_u32 s34, s34, 0x80
	s_addc_u32 s35, s35, 0
	s_add_u32 s65, s36, 0x100
	s_addc_u32 s66, s37, 0
	s_mov_b32 s36, 0
	s_add_i32 s67, s36, 2
	s_add_u32 s68, s34, 0x80
	s_addc_u32 s37, s35, 0
	s_add_i32 s70, 0, 0x10000
	s_cmp_eq_u32 s58, s36
	s_cselect_b32 s37, s27, s37
	s_cselect_b32 s36, s26, s68
	v_add_u32_e32 v147, s70, v144
	s_cselect_b32 s69, s29, s66
	s_cselect_b32 s68, s28, s65
	s_add_i32 s71, 0, 0x14000
	ds_read_b128 v[148:151], v147
	ds_read_b128 v[152:155], v147 offset:1024
	ds_read_b128 v[156:159], v147 offset:2048
	ds_read_b128 v[160:163], v147 offset:3072
	v_add_u32_e32 v147, s71, v144
	ds_read_b128 v[164:167], v147
	ds_read_b128 v[168:171], v147 offset:1024
	ds_read_b128 v[172:175], v147 offset:2048
	ds_read_b128 v[176:179], v147 offset:3072
	v_lshl_add_u64 v[196:197], s[34:35], 0, v[140:141]
	s_add_i32 m0, s51, 0xc000
	ds_read_b128 v[180:183], v146
	ds_read_b128 v[184:187], v146 offset:1024
	ds_read_b128 v[188:191], v146 offset:2048
	ds_read_b128 v[192:195], v146 offset:3072
	ds_read_b128 v[202:205], v146 offset:4096
	ds_read_b128 v[206:209], v146 offset:5120
	ds_read_b128 v[210:213], v146 offset:6144
	ds_read_b128 v[214:217], v146 offset:7168
	global_load_lds_dwordx4 v[196:197], off
	v_lshl_add_u64 v[196:197], s[34:35], 0, v[142:143]
	s_add_i32 m0, s51, 0xe000
	s_nop 0
	global_load_lds_dwordx4 v[196:197], off
	s_waitcnt vmcnt(8)
	s_waitcnt lgkmcnt(0)
	s_barrier
	s_nop 0
	s_waitcnt lgkmcnt(0)
	v_mfma_f32_16x16x32_bf16 v[124:127], v[148:151], v[180:183], 0
	v_mfma_f32_16x16x32_bf16 v[128:131], v[156:159], v[180:183], 0
	v_mfma_f32_16x16x32_bf16 v[112:115], v[148:151], v[188:191], 0
	v_mfma_f32_16x16x32_bf16 v[108:111], v[156:159], v[188:191], 0
	v_mfma_f32_16x16x32_bf16 v[96:99], v[148:151], v[202:205], 0
	v_mfma_f32_16x16x32_bf16 v[92:95], v[156:159], v[202:205], 0
	v_mfma_f32_16x16x32_bf16 v[80:83], v[148:151], v[210:213], 0
	v_mfma_f32_16x16x32_bf16 v[76:79], v[156:159], v[210:213], 0
	v_mfma_f32_16x16x32_bf16 v[124:127], v[152:155], v[184:187], v[124:127]
	v_mfma_f32_16x16x32_bf16 v[128:131], v[160:163], v[184:187], v[128:131]
	v_mfma_f32_16x16x32_bf16 v[112:115], v[152:155], v[192:195], v[112:115]
	v_mfma_f32_16x16x32_bf16 v[108:111], v[160:163], v[192:195], v[108:111]
	v_mfma_f32_16x16x32_bf16 v[96:99], v[152:155], v[206:209], v[96:99]
	v_mfma_f32_16x16x32_bf16 v[92:95], v[160:163], v[206:209], v[92:95]
	v_mfma_f32_16x16x32_bf16 v[80:83], v[152:155], v[214:217], v[80:83]
	v_mfma_f32_16x16x32_bf16 v[76:79], v[160:163], v[214:217], v[76:79]
	s_nop 0
	s_nop 0
	v_mfma_f32_16x16x32_bf16 v[120:123], v[164:167], v[180:183], 0
	v_mfma_f32_16x16x32_bf16 v[116:119], v[172:175], v[180:183], 0
	v_mfma_f32_16x16x32_bf16 v[104:107], v[164:167], v[188:191], 0
	v_mfma_f32_16x16x32_bf16 v[100:103], v[172:175], v[188:191], 0
	v_mfma_f32_16x16x32_bf16 v[88:91], v[164:167], v[202:205], 0
	v_mfma_f32_16x16x32_bf16 v[84:87], v[172:175], v[202:205], 0
	v_mfma_f32_16x16x32_bf16 v[72:75], v[164:167], v[210:213], 0
	v_mfma_f32_16x16x32_bf16 v[68:71], v[172:175], v[210:213], 0
	v_mfma_f32_16x16x32_bf16 v[120:123], v[168:171], v[184:187], v[120:123]
	v_mfma_f32_16x16x32_bf16 v[116:119], v[176:179], v[184:187], v[116:119]
	v_mfma_f32_16x16x32_bf16 v[104:107], v[168:171], v[192:195], v[104:107]
	v_mfma_f32_16x16x32_bf16 v[100:103], v[176:179], v[192:195], v[100:103]
	v_mfma_f32_16x16x32_bf16 v[88:91], v[168:171], v[206:209], v[88:91]
	v_mfma_f32_16x16x32_bf16 v[84:87], v[176:179], v[206:209], v[84:87]
	v_mfma_f32_16x16x32_bf16 v[72:75], v[168:171], v[214:217], v[72:75]
	v_mfma_f32_16x16x32_bf16 v[68:71], v[176:179], v[214:217], v[68:71]
	s_nop 0
	s_barrier
	s_add_i32 s70, s70, s50
	v_lshl_add_u64 v[196:197], s[68:69], 0, v[134:135]
	s_mov_b32 m0, s70
	ds_read_b128 v[180:183], v146 offset:16384
	ds_read_b128 v[184:187], v146 offset:17408
	ds_read_b128 v[188:191], v146 offset:18432
	ds_read_b128 v[192:195], v146 offset:19456
	ds_read_b128 v[202:205], v146 offset:20480
	ds_read_b128 v[206:209], v146 offset:21504
	ds_read_b128 v[210:213], v146 offset:22528
	ds_read_b128 v[214:217], v146 offset:23552
	global_load_lds_dwordx4 v[196:197], off
	s_add_i32 m0, s70, 0x2000
	v_lshl_add_u64 v[198:199], s[68:69], 0, v[0:1]
	s_add_u32 s68, s68, s6
	s_addc_u32 s69, s69, s7
	s_add_i32 s70, s71, s50
	global_load_lds_dwordx4 v[198:199], off
	v_lshl_add_u64 v[218:219], s[68:69], 0, v[134:135]
	s_mov_b32 m0, s70
	v_lshl_add_u64 v[220:221], s[68:69], 0, v[0:1]
	global_load_lds_dwordx4 v[218:219], off
	s_add_i32 m0, s70, 0x2000
	v_lshl_add_u64 v[222:223], s[36:37], 0, v[136:137]
	global_load_lds_dwordx4 v[220:221], off
	s_mov_b32 m0, s51
	v_lshl_add_u64 v[224:225], s[36:37], 0, v[132:133]
	global_load_lds_dwordx4 v[222:223], off
	s_mov_b32 m0, s52
	s_nop 0
	global_load_lds_dwordx4 v[224:225], off
	s_waitcnt vmcnt(8)
	s_waitcnt lgkmcnt(0)
	s_barrier
; #define PG8_GOFFS(slot_) do { _Pragma("unroll") for (int _i = 0; _i < 2; ++_i) { int R, C; stage_rc(tid * 16 + _i * 8192, R, C); _Pragma("unroll") for (int _h = 0; _h < 2; ++_h) { \
;         unsigned t_ = gtab[(slot_) * 256 + R + 128 * _h]; t_ = t_ < (unsigned)(T - 1) ? t_ : (unsigned)(T - 1); voffA[_h][_i] = (t_ * (unsigned)K + (unsigned)C) * 2u; } } } while (0)
; #define PG8_STAGE(bufoff, gbase, voff) do { _Pragma("unroll") for (int _i = 0; _i < 2; ++_i) \
;         __builtin_amdgcn_global_load_lds((const unsigned*)((const char*)(gbase) + (voff)[_i]), (LAS unsigned*)(lds + (bufoff) + ldsw + _i * 8192), 16, 0, 0); } while (0)
; #define PG8_STAGE_A1(bufoff, gbase) do { if (Epi::GATHER) PG8_STAGE(bufoff, gbase, voffA[1]); else PG8_STAGE(bufoff, (gbase) + hstep, voffA[0]); } while (0)
; #define PG8_LDA(dst, b, h) do { _Pragma("unroll") for (int m = 0; m < 4; ++m) _Pragma("unroll") for (int k = 0; k < 2; ++k) dst[m][k] = *(const LAS bf16x8*)(lds + PG8_SA(b, h) + aoff + m * 2048 + k * 1024); } while (0)
; #define PG8_LDB(dst, b, h) do { _Pragma("unroll") for (int n = 0; n < 2; ++n) _Pragma("unroll") for (int k = 0; k < 2; ++k) dst[n][k] = *(const LAS bf16x8*)(lds + PG8_SB(b, h) + boff + n * 2048 + k * 1024); } while (0)
; #define PG8_WAIT_V(n) asm volatile("s_waitcnt vmcnt(" #n ")" ::: "memory")
; #define PG8_WAIT_L(n) asm volatile("s_waitcnt lgkmcnt(" #n ")" ::: "memory")
; template <class Epi, class Sched>
; __device__ __forceinline__ void gemm_phase(const int tid, LAS unsigned char* lds, const bf16* Aop, const bf16* Bop, const int K_, const Sched& S, const Epi& E, const bf16* Aop1 = nullptr, const bf16* Bop1 = nullptr) {
;     ...
;             PG8_LDA(At, 0, 1); PG8_STAGE(PG8_SB(0, 0), b2, voffB); PG8_STAGE(PG8_SB(0, 1), b2 + hstep, voffB); if (Epi::GATHER && last && has_next) PG8_GOFFS((ui + 1) & 1); PG8_STAGE(PG8_SA(0, 0), a2, voffA[0]);
;             PG8_WAIT_V(8); PG8_WAIT_L(0); PG8_BAR; PG8_MMA(1, 0, At, B0); PG8_MMA(1, 1, At, B1); PG8_BAR; PG8_SCHED;
;             PG8_LDB(B0, 1, 0); PG8_LDB(B1, 1, 1); PG8_SCHED; PG8_LDA(At, 1, 0); PG8_STAGE_A1(PG8_SA(0, 1), a2);
;             PG8_WAIT_V(8); PG8_WAIT_L(0); PG8_BAR; PG8_MMA(0, 0, At, B0); PG8_MMA(0, 1, At, B1); PG8_BAR; PG8_SCHED;
;             PG8_LDA(At, 1, 1); PG8_STAGE(PG8_SB(1, 0), b3, voffB); PG8_STAGE(PG8_SB(1, 1), b3 + hstep, voffB); PG8_STAGE(PG8_SA(1, 0), a3, voffA[0]);
	s_nop 0
	s_waitcnt lgkmcnt(0)
	v_mfma_f32_16x16x32_bf16 v[64:67], v[148:151], v[180:183], 0
	v_mfma_f32_16x16x32_bf16 v[60:63], v[156:159], v[180:183], 0
	v_mfma_f32_16x16x32_bf16 v[48:51], v[148:151], v[188:191], 0
	v_mfma_f32_16x16x32_bf16 v[44:47], v[156:159], v[188:191], 0
	v_mfma_f32_16x16x32_bf16 v[32:35], v[148:151], v[202:205], 0
	v_mfma_f32_16x16x32_bf16 v[28:31], v[156:159], v[202:205], 0
	v_mfma_f32_16x16x32_bf16 v[16:19], v[148:151], v[210:213], 0
	v_mfma_f32_16x16x32_bf16 v[12:15], v[156:159], v[210:213], 0
	v_mfma_f32_16x16x32_bf16 v[64:67], v[152:155], v[184:187], v[64:67]
	v_mfma_f32_16x16x32_bf16 v[60:63], v[160:163], v[184:187], v[60:63]
	v_mfma_f32_16x16x32_bf16 v[48:51], v[152:155], v[192:195], v[48:51]
	v_mfma_f32_16x16x32_bf16 v[44:47], v[160:163], v[192:195], v[44:47]
	v_mfma_f32_16x16x32_bf16 v[32:35], v[152:155], v[206:209], v[32:35]
	v_mfma_f32_16x16x32_bf16 v[28:31], v[160:163], v[206:209], v[28:31]
	v_mfma_f32_16x16x32_bf16 v[16:19], v[152:155], v[214:217], v[16:19]
	v_mfma_f32_16x16x32_bf16 v[12:15], v[160:163], v[214:217], v[12:15]
	s_nop 0
	s_nop 0
	v_mfma_f32_16x16x32_bf16 v[56:59], v[164:167], v[180:183], 0
	v_mfma_f32_16x16x32_bf16 v[52:55], v[172:175], v[180:183], 0
	v_mfma_f32_16x16x32_bf16 v[40:43], v[164:167], v[188:191], 0
	v_mfma_f32_16x16x32_bf16 v[36:39], v[172:175], v[188:191], 0
	v_mfma_f32_16x16x32_bf16 v[24:27], v[164:167], v[202:205], 0
	v_mfma_f32_16x16x32_bf16 v[20:23], v[172:175], v[202:205], 0
	v_mfma_f32_16x16x32_bf16 v[8:11], v[164:167], v[210:213], 0
	v_mfma_f32_16x16x32_bf16 v[4:7], v[172:175], v[210:213], 0
	v_mfma_f32_16x16x32_bf16 v[56:59], v[168:171], v[184:187], v[56:59]
	v_mfma_f32_16x16x32_bf16 v[52:55], v[176:179], v[184:187], v[52:55]
	v_mfma_f32_16x16x32_bf16 v[40:43], v[168:171], v[192:195], v[40:43]
	v_mfma_f32_16x16x32_bf16 v[36:39], v[176:179], v[192:195], v[36:39]
	v_mfma_f32_16x16x32_bf16 v[24:27], v[168:171], v[206:209], v[24:27]
	v_mfma_f32_16x16x32_bf16 v[20:23], v[176:179], v[206:209], v[20:23]
	v_mfma_f32_16x16x32_bf16 v[8:11], v[168:171], v[214:217], v[8:11]
	v_mfma_f32_16x16x32_bf16 v[4:7], v[176:179], v[214:217], v[4:7]
	s_nop 0
	s_barrier
	s_add_i32 s68, 0, 0x18000
	v_add_u32_e32 v147, s68, v144
	s_add_i32 s69, 0, 0x1c000
	ds_read_b128 v[148:151], v147
	ds_read_b128 v[152:155], v147 offset:1024
	ds_read_b128 v[156:159], v147 offset:2048
	ds_read_b128 v[160:163], v147 offset:3072
	v_add_u32_e32 v147, s69, v144
	ds_read_b128 v[164:167], v147
	ds_read_b128 v[168:171], v147 offset:1024
	ds_read_b128 v[172:175], v147 offset:2048
	ds_read_b128 v[176:179], v147 offset:3072
	s_add_u32 s36, s36, s6
	s_addc_u32 s37, s37, s7
	s_mov_b32 m0, s53
	v_lshl_add_u64 v[230:231], s[36:37], 0, v[136:137]
	ds_read_b128 v[180:183], v146 offset:32768
	ds_read_b128 v[184:187], v146 offset:33792
	ds_read_b128 v[188:191], v146 offset:34816
	ds_read_b128 v[192:195], v146 offset:35840
	ds_read_b128 v[202:205], v146 offset:36864
	ds_read_b128 v[206:209], v146 offset:37888
	ds_read_b128 v[210:213], v146 offset:38912
	ds_read_b128 v[214:217], v146 offset:39936
	global_load_lds_dwordx4 v[230:231], off
	v_lshl_add_u64 v[230:231], s[36:37], 0, v[132:133]
	s_mov_b32 m0, s54
	s_nop 0
	global_load_lds_dwordx4 v[230:231], off
	s_waitcnt vmcnt(8)
	s_waitcnt lgkmcnt(0)
	s_barrier
	s_nop 0
	s_waitcnt lgkmcnt(0)
	v_mfma_f32_16x16x32_bf16 v[124:127], v[148:151], v[180:183], v[124:127]
	v_mfma_f32_16x16x32_bf16 v[128:131], v[156:159], v[180:183], v[128:131]
	v_mfma_f32_16x16x32_bf16 v[112:115], v[148:151], v[188:191], v[112:115]
	v_mfma_f32_16x16x32_bf16 v[108:111], v[156:159], v[188:191], v[108:111]
	v_mfma_f32_16x16x32_bf16 v[96:99], v[148:151], v[202:205], v[96:99]
	v_mfma_f32_16x16x32_bf16 v[92:95], v[156:159], v[202:205], v[92:95]
	v_mfma_f32_16x16x32_bf16 v[80:83], v[148:151], v[210:213], v[80:83]
	v_mfma_f32_16x16x32_bf16 v[76:79], v[156:159], v[210:213], v[76:79]
	v_mfma_f32_16x16x32_bf16 v[124:127], v[152:155], v[184:187], v[124:127]
	v_mfma_f32_16x16x32_bf16 v[128:131], v[160:163], v[184:187], v[128:131]
	v_mfma_f32_16x16x32_bf16 v[112:115], v[152:155], v[192:195], v[112:115]
	v_mfma_f32_16x16x32_bf16 v[108:111], v[160:163], v[192:195], v[108:111]
	v_mfma_f32_16x16x32_bf16 v[96:99], v[152:155], v[206:209], v[96:99]
	v_mfma_f32_16x16x32_bf16 v[92:95], v[160:163], v[206:209], v[92:95]
	v_mfma_f32_16x16x32_bf16 v[80:83], v[152:155], v[214:217], v[80:83]
	v_mfma_f32_16x16x32_bf16 v[76:79], v[160:163], v[214:217], v[76:79]
	s_nop 0
	s_nop 0
	v_mfma_f32_16x16x32_bf16 v[120:123], v[164:167], v[180:183], v[120:123]
	v_mfma_f32_16x16x32_bf16 v[116:119], v[172:175], v[180:183], v[116:119]
	v_mfma_f32_16x16x32_bf16 v[104:107], v[164:167], v[188:191], v[104:107]
	v_mfma_f32_16x16x32_bf16 v[100:103], v[172:175], v[188:191], v[100:103]
	v_mfma_f32_16x16x32_bf16 v[88:91], v[164:167], v[202:205], v[88:91]
	v_mfma_f32_16x16x32_bf16 v[84:87], v[172:175], v[202:205], v[84:87]
	v_mfma_f32_16x16x32_bf16 v[72:75], v[164:167], v[210:213], v[72:75]
	v_mfma_f32_16x16x32_bf16 v[68:71], v[172:175], v[210:213], v[68:71]
	v_mfma_f32_16x16x32_bf16 v[120:123], v[168:171], v[184:187], v[120:123]
	v_mfma_f32_16x16x32_bf16 v[116:119], v[176:179], v[184:187], v[116:119]
	v_mfma_f32_16x16x32_bf16 v[104:107], v[168:171], v[192:195], v[104:107]
	v_mfma_f32_16x16x32_bf16 v[100:103], v[176:179], v[192:195], v[100:103]
	v_mfma_f32_16x16x32_bf16 v[88:91], v[168:171], v[206:209], v[88:91]
	v_mfma_f32_16x16x32_bf16 v[84:87], v[176:179], v[206:209], v[84:87]
	v_mfma_f32_16x16x32_bf16 v[72:75], v[168:171], v[214:217], v[72:75]
	v_mfma_f32_16x16x32_bf16 v[68:71], v[176:179], v[214:217], v[68:71]
	s_nop 0
	s_barrier
; #define PG8_STAGE(bufoff, gbase, voff) do { _Pragma("unroll") for (int _i = 0; _i < 2; ++_i) \
;         __builtin_amdgcn_global_load_lds((const unsigned*)((const char*)(gbase) + (voff)[_i]), (LAS unsigned*)(lds + (bufoff) + ldsw + _i * 8192), 16, 0, 0); } while (0)
; #define PG8_STAGE_A1(bufoff, gbase) do { if (Epi::GATHER) PG8_STAGE(bufoff, gbase, voffA[1]); else PG8_STAGE(bufoff, (gbase) + hstep, voffA[0]); } while (0)
; #define PG8_LDA(dst, b, h) do { _Pragma("unroll") for (int m = 0; m < 4; ++m) _Pragma("unroll") for (int k = 0; k < 2; ++k) dst[m][k] = *(const LAS bf16x8*)(lds + PG8_SA(b, h) + aoff + m * 2048 + k * 1024); } while (0)
; #define PG8_LDB(dst, b, h) do { _Pragma("unroll") for (int n = 0; n < 2; ++n) _Pragma("unroll") for (int k = 0; k < 2; ++k) dst[n][k] = *(const LAS bf16x8*)(lds + PG8_SB(b, h) + boff + n * 2048 + k * 1024); } while (0)
; #define PG8_MMA(ai, bj, At, Bt) do { __builtin_amdgcn_s_setprio(1); _Pragma("unroll") for (int m = 0; m < 4; ++m) _Pragma("unroll") for (int n = 0; n < 2; ++n) _Pragma("unroll") for (int k = 0; k < 2; ++k) \
;         acc[ai][bj][m][n] = __builtin_amdgcn_mfma_f32_16x16x32_bf16(Bt[n][k], At[m][k], acc[ai][bj][m][n], 0, 0, 0); __builtin_amdgcn_s_setprio(0); } while (0)
; #define PG8_WAIT_V(n) asm volatile("s_waitcnt vmcnt(" #n ")" ::: "memory")
; #define PG8_WAIT_L(n) asm volatile("s_waitcnt lgkmcnt(" #n ")" ::: "memory")
; #define PG8_BAR __builtin_amdgcn_s_barrier()
; #define PG8_SCHED __builtin_amdgcn_sched_barrier(0)
; template <class Epi, class Sched>
; __device__ __forceinline__ void gemm_phase(const int tid, LAS unsigned char* lds, const bf16* Aop, const bf16* Bop, const int K_, const Sched& S, const Epi& E, const bf16* Aop1 = nullptr, const bf16* Bop1 = nullptr) {
;     ...
;             PG8_LDB(B0, 1, 0); PG8_LDB(B1, 1, 1); PG8_SCHED; PG8_LDA(At, 1, 0); PG8_STAGE_A1(PG8_SA(0, 1), a2);
;             PG8_WAIT_V(8); PG8_WAIT_L(0); PG8_BAR; PG8_MMA(0, 0, At, B0); PG8_MMA(0, 1, At, B1); PG8_BAR; PG8_SCHED;
;             PG8_LDA(At, 1, 1); PG8_STAGE(PG8_SB(1, 0), b3, voffB); PG8_STAGE(PG8_SB(1, 1), b3 + hstep, voffB); PG8_STAGE(PG8_SA(1, 0), a3, voffA[0]);
;             PG8_WAIT_V(8); PG8_WAIT_L(0); PG8_BAR; PG8_MMA(1, 0, At, B0); PG8_MMA(1, 1, At, B1); PG8_BAR; PG8_SCHED;
;         }
	s_add_i32 s36, s68, s50
	v_lshl_add_u64 v[196:197], v[196:197], 0, s[20:21]
	s_mov_b32 m0, s36
	ds_read_b128 v[180:183], v146 offset:49152
	ds_read_b128 v[184:187], v146 offset:50176
	ds_read_b128 v[188:191], v146 offset:51200
	ds_read_b128 v[192:195], v146 offset:52224
	ds_read_b128 v[202:205], v146 offset:53248
	ds_read_b128 v[206:209], v146 offset:54272
	ds_read_b128 v[210:213], v146 offset:55296
	ds_read_b128 v[214:217], v146 offset:56320
	global_load_lds_dwordx4 v[196:197], off
	v_lshl_add_u64 v[196:197], v[198:199], 0, s[20:21]
	s_add_i32 m0, s36, 0x2000
	s_add_i32 s36, s69, s50
	global_load_lds_dwordx4 v[196:197], off
	v_lshl_add_u64 v[196:197], v[218:219], 0, s[20:21]
	s_mov_b32 m0, s36
	s_nop 0
	global_load_lds_dwordx4 v[196:197], off
	v_lshl_add_u64 v[196:197], v[220:221], 0, s[20:21]
	s_add_i32 m0, s36, 0x2000
	s_nop 0
	global_load_lds_dwordx4 v[196:197], off
	v_lshl_add_u64 v[196:197], v[222:223], 0, s[20:21]
	s_mov_b32 m0, s56
	s_nop 0
	global_load_lds_dwordx4 v[196:197], off
	v_lshl_add_u64 v[196:197], v[224:225], 0, s[20:21]
	s_mov_b32 m0, s57
	s_nop 0
	global_load_lds_dwordx4 v[196:197], off
	s_waitcnt vmcnt(8)
	s_waitcnt lgkmcnt(0)
	s_barrier
	s_nop 0
	s_waitcnt lgkmcnt(0)
	v_mfma_f32_16x16x32_bf16 v[64:67], v[148:151], v[180:183], v[64:67]
	v_mfma_f32_16x16x32_bf16 v[60:63], v[156:159], v[180:183], v[60:63]
	v_mfma_f32_16x16x32_bf16 v[48:51], v[148:151], v[188:191], v[48:51]
	v_mfma_f32_16x16x32_bf16 v[44:47], v[156:159], v[188:191], v[44:47]
	v_mfma_f32_16x16x32_bf16 v[32:35], v[148:151], v[202:205], v[32:35]
	v_mfma_f32_16x16x32_bf16 v[28:31], v[156:159], v[202:205], v[28:31]
	v_mfma_f32_16x16x32_bf16 v[16:19], v[148:151], v[210:213], v[16:19]
	v_mfma_f32_16x16x32_bf16 v[12:15], v[156:159], v[210:213], v[12:15]
	v_mfma_f32_16x16x32_bf16 v[64:67], v[152:155], v[184:187], v[64:67]
	v_mfma_f32_16x16x32_bf16 v[60:63], v[160:163], v[184:187], v[60:63]
	v_mfma_f32_16x16x32_bf16 v[48:51], v[152:155], v[192:195], v[48:51]
	v_mfma_f32_16x16x32_bf16 v[44:47], v[160:163], v[192:195], v[44:47]
	v_mfma_f32_16x16x32_bf16 v[32:35], v[152:155], v[206:209], v[32:35]
	v_mfma_f32_16x16x32_bf16 v[28:31], v[160:163], v[206:209], v[28:31]
	v_mfma_f32_16x16x32_bf16 v[16:19], v[152:155], v[214:217], v[16:19]
	v_mfma_f32_16x16x32_bf16 v[12:15], v[160:163], v[214:217], v[12:15]
	s_nop 0
	s_nop 0
	v_mfma_f32_16x16x32_bf16 v[56:59], v[164:167], v[180:183], v[56:59]
	v_mfma_f32_16x16x32_bf16 v[52:55], v[172:175], v[180:183], v[52:55]
	v_mfma_f32_16x16x32_bf16 v[40:43], v[164:167], v[188:191], v[40:43]
	v_mfma_f32_16x16x32_bf16 v[36:39], v[172:175], v[188:191], v[36:39]
	v_mfma_f32_16x16x32_bf16 v[24:27], v[164:167], v[202:205], v[24:27]
	v_mfma_f32_16x16x32_bf16 v[20:23], v[172:175], v[202:205], v[20:23]
	v_mfma_f32_16x16x32_bf16 v[8:11], v[164:167], v[210:213], v[8:11]
	v_mfma_f32_16x16x32_bf16 v[4:7], v[172:175], v[210:213], v[4:7]
	v_mfma_f32_16x16x32_bf16 v[56:59], v[168:171], v[184:187], v[56:59]
	v_mfma_f32_16x16x32_bf16 v[52:55], v[176:179], v[184:187], v[52:55]
	v_mfma_f32_16x16x32_bf16 v[40:43], v[168:171], v[192:195], v[40:43]
	v_mfma_f32_16x16x32_bf16 v[36:39], v[176:179], v[192:195], v[36:39]
	v_mfma_f32_16x16x32_bf16 v[24:27], v[168:171], v[206:209], v[24:27]
	v_mfma_f32_16x16x32_bf16 v[20:23], v[176:179], v[206:209], v[20:23]
	v_mfma_f32_16x16x32_bf16 v[8:11], v[168:171], v[214:217], v[8:11]
	v_mfma_f32_16x16x32_bf16 v[4:7], v[176:179], v[214:217], v[4:7]
	s_nop 0
	s_barrier
	s_add_u32 s34, s34, 0x100
	s_addc_u32 s35, s35, 0
	s_add_u32 s65, s65, 0x100
	s_addc_u32 s66, s66, 0
	s_cmp_ge_i32 s67, s55
	s_mov_b32 s36, s67
	s_cbranch_scc0 .LBB0_1400
	s_branch .LBB0_1401
.LBB0_1400:
	s_add_i32 s67, s36, 2
	s_add_u32 s68, s34, 0x80
	s_addc_u32 s37, s35, 0
	s_add_i32 s70, 0, 0x10000
	s_cmp_eq_u32 s58, s36
	s_cselect_b32 s37, s27, s37
	s_cselect_b32 s36, s26, s68
	v_add_u32_e32 v147, s70, v144
	s_cselect_b32 s69, s29, s66
	s_cselect_b32 s68, s28, s65
	s_add_i32 s71, 0, 0x14000
	ds_read_b128 v[148:151], v147
	ds_read_b128 v[152:155], v147 offset:1024
	ds_read_b128 v[156:159], v147 offset:2048
	ds_read_b128 v[160:163], v147 offset:3072
	v_add_u32_e32 v147, s71, v144
	ds_read_b128 v[164:167], v147
	ds_read_b128 v[168:171], v147 offset:1024
	ds_read_b128 v[172:175], v147 offset:2048
	ds_read_b128 v[176:179], v147 offset:3072
	v_lshl_add_u64 v[196:197], s[34:35], 0, v[140:141]
	s_add_i32 m0, s51, 0xc000
	ds_read_b128 v[180:183], v146
	ds_read_b128 v[184:187], v146 offset:1024
	ds_read_b128 v[188:191], v146 offset:2048
	ds_read_b128 v[192:195], v146 offset:3072
	ds_read_b128 v[202:205], v146 offset:4096
	ds_read_b128 v[206:209], v146 offset:5120
	ds_read_b128 v[210:213], v146 offset:6144
	ds_read_b128 v[214:217], v146 offset:7168
	global_load_lds_dwordx4 v[196:197], off
	v_lshl_add_u64 v[196:197], s[34:35], 0, v[142:143]
	s_add_i32 m0, s51, 0xe000
	s_nop 0
	global_load_lds_dwordx4 v[196:197], off
	s_waitcnt vmcnt(8)
	s_waitcnt lgkmcnt(0)
	s_barrier
; #define PG8_GOFFS(slot_) do { _Pragma("unroll") for (int _i = 0; _i < 2; ++_i) { int R, C; stage_rc(tid * 16 + _i * 8192, R, C); _Pragma("unroll") for (int _h = 0; _h < 2; ++_h) { \
;         unsigned t_ = gtab[(slot_) * 256 + R + 128 * _h]; t_ = t_ < (unsigned)(T - 1) ? t_ : (unsigned)(T - 1); voffA[_h][_i] = (t_ * (unsigned)K + (unsigned)C) * 2u; } } } while (0)
; #define PG8_STAGE(bufoff, gbase, voff) do { _Pragma("unroll") for (int _i = 0; _i < 2; ++_i) \
;         __builtin_amdgcn_global_load_lds((const unsigned*)((const char*)(gbase) + (voff)[_i]), (LAS unsigned*)(lds + (bufoff) + ldsw + _i * 8192), 16, 0, 0); } while (0)
; #define PG8_STAGE_A1(bufoff, gbase) do { if (Epi::GATHER) PG8_STAGE(bufoff, gbase, voffA[1]); else PG8_STAGE(bufoff, (gbase) + hstep, voffA[0]); } while (0)
; #define PG8_LDA(dst, b, h) do { _Pragma("unroll") for (int m = 0; m < 4; ++m) _Pragma("unroll") for (int k = 0; k < 2; ++k) dst[m][k] = *(const LAS bf16x8*)(lds + PG8_SA(b, h) + aoff + m * 2048 + k * 1024); } while (0)
; #define PG8_WAIT_V(n) asm volatile("s_waitcnt vmcnt(" #n ")" ::: "memory")
; #define PG8_WAIT_L(n) asm volatile("s_waitcnt lgkmcnt(" #n ")" ::: "memory")
; template <class Epi, class Sched>
; __device__ __forceinline__ void gemm_phase(const int tid, LAS unsigned char* lds, const bf16* Aop, const bf16* Bop, const int K_, const Sched& S, const Epi& E, const bf16* Aop1 = nullptr, const bf16* Bop1 = nullptr) {
;     ...
;             PG8_LDB(B0, 0, 0); PG8_LDB(B1, 0, 1); PG8_SCHED; PG8_LDA(At, 0, 0); PG8_STAGE_A1(PG8_SA(1, 1), a1);
;             PG8_WAIT_V(8); PG8_WAIT_L(0); PG8_BAR; PG8_MMA(0, 0, At, B0); PG8_MMA(0, 1, At, B1); PG8_BAR; PG8_SCHED;
;             PG8_LDA(At, 0, 1); PG8_STAGE(PG8_SB(0, 0), b2, voffB); PG8_STAGE(PG8_SB(0, 1), b2 + hstep, voffB); if (Epi::GATHER && last && has_next) PG8_GOFFS((ui + 1) & 1); PG8_STAGE(PG8_SA(0, 0), a2, voffA[0]);
;             PG8_WAIT_V(8); PG8_WAIT_L(0); PG8_BAR; PG8_MMA(1, 0, At, B0); PG8_MMA(1, 1, At, B1); PG8_BAR; PG8_SCHED;
;             PG8_LDB(B0, 1, 0); PG8_LDB(B1, 1, 1); PG8_SCHED; PG8_LDA(At, 1, 0); PG8_STAGE_A1(PG8_SA(0, 1), a2);
;             PG8_WAIT_V(8); PG8_WAIT_L(0); PG8_BAR; PG8_MMA(0, 0, At, B0); PG8_MMA(0, 1, At, B1); PG8_BAR; PG8_SCHED;
;             PG8_LDA(At, 1, 1); PG8_STAGE(PG8_SB(1, 0), b3, voffB); PG8_STAGE(PG8_SB(1, 1), b3 + hstep, voffB); PG8_STAGE(PG8_SA(1, 0), a3, voffA[0]);
	s_nop 0
	s_waitcnt lgkmcnt(0)
	v_mfma_f32_16x16x32_bf16 v[124:127], v[148:151], v[180:183], v[124:127]
	v_mfma_f32_16x16x32_bf16 v[128:131], v[156:159], v[180:183], v[128:131]
	v_mfma_f32_16x16x32_bf16 v[112:115], v[148:151], v[188:191], v[112:115]
	v_mfma_f32_16x16x32_bf16 v[108:111], v[156:159], v[188:191], v[108:111]
	v_mfma_f32_16x16x32_bf16 v[96:99], v[148:151], v[202:205], v[96:99]
	v_mfma_f32_16x16x32_bf16 v[92:95], v[156:159], v[202:205], v[92:95]
	v_mfma_f32_16x16x32_bf16 v[80:83], v[148:151], v[210:213], v[80:83]
	v_mfma_f32_16x16x32_bf16 v[76:79], v[156:159], v[210:213], v[76:79]
	v_mfma_f32_16x16x32_bf16 v[124:127], v[152:155], v[184:187], v[124:127]
	v_mfma_f32_16x16x32_bf16 v[128:131], v[160:163], v[184:187], v[128:131]
	v_mfma_f32_16x16x32_bf16 v[112:115], v[152:155], v[192:195], v[112:115]
	v_mfma_f32_16x16x32_bf16 v[108:111], v[160:163], v[192:195], v[108:111]
	v_mfma_f32_16x16x32_bf16 v[96:99], v[152:155], v[206:209], v[96:99]
	v_mfma_f32_16x16x32_bf16 v[92:95], v[160:163], v[206:209], v[92:95]
	v_mfma_f32_16x16x32_bf16 v[80:83], v[152:155], v[214:217], v[80:83]
	v_mfma_f32_16x16x32_bf16 v[76:79], v[160:163], v[214:217], v[76:79]
	s_nop 0
	s_nop 0
	v_mfma_f32_16x16x32_bf16 v[120:123], v[164:167], v[180:183], v[120:123]
	v_mfma_f32_16x16x32_bf16 v[116:119], v[172:175], v[180:183], v[116:119]
	v_mfma_f32_16x16x32_bf16 v[104:107], v[164:167], v[188:191], v[104:107]
	v_mfma_f32_16x16x32_bf16 v[100:103], v[172:175], v[188:191], v[100:103]
	v_mfma_f32_16x16x32_bf16 v[88:91], v[164:167], v[202:205], v[88:91]
	v_mfma_f32_16x16x32_bf16 v[84:87], v[172:175], v[202:205], v[84:87]
	v_mfma_f32_16x16x32_bf16 v[72:75], v[164:167], v[210:213], v[72:75]
	v_mfma_f32_16x16x32_bf16 v[68:71], v[172:175], v[210:213], v[68:71]
	v_mfma_f32_16x16x32_bf16 v[120:123], v[168:171], v[184:187], v[120:123]
	v_mfma_f32_16x16x32_bf16 v[116:119], v[176:179], v[184:187], v[116:119]
	v_mfma_f32_16x16x32_bf16 v[104:107], v[168:171], v[192:195], v[104:107]
	v_mfma_f32_16x16x32_bf16 v[100:103], v[176:179], v[192:195], v[100:103]
	v_mfma_f32_16x16x32_bf16 v[88:91], v[168:171], v[206:209], v[88:91]
	v_mfma_f32_16x16x32_bf16 v[84:87], v[176:179], v[206:209], v[84:87]
	v_mfma_f32_16x16x32_bf16 v[72:75], v[168:171], v[214:217], v[72:75]
	v_mfma_f32_16x16x32_bf16 v[68:71], v[176:179], v[214:217], v[68:71]
	s_nop 0
	s_barrier
	s_add_i32 s70, s70, s50
	v_lshl_add_u64 v[196:197], s[68:69], 0, v[134:135]
	s_mov_b32 m0, s70
	ds_read_b128 v[180:183], v146 offset:16384
	ds_read_b128 v[184:187], v146 offset:17408
	ds_read_b128 v[188:191], v146 offset:18432
	ds_read_b128 v[192:195], v146 offset:19456
	ds_read_b128 v[202:205], v146 offset:20480
	ds_read_b128 v[206:209], v146 offset:21504
	ds_read_b128 v[210:213], v146 offset:22528
	ds_read_b128 v[214:217], v146 offset:23552
	global_load_lds_dwordx4 v[196:197], off
	s_add_i32 m0, s70, 0x2000
	v_lshl_add_u64 v[198:199], s[68:69], 0, v[0:1]
	s_add_u32 s68, s68, s6
	s_addc_u32 s69, s69, s7
	s_add_i32 s70, s71, s50
	global_load_lds_dwordx4 v[198:199], off
	v_lshl_add_u64 v[218:219], s[68:69], 0, v[134:135]
	s_mov_b32 m0, s70
	v_lshl_add_u64 v[220:221], s[68:69], 0, v[0:1]
	global_load_lds_dwordx4 v[218:219], off
	s_add_i32 m0, s70, 0x2000
	v_lshl_add_u64 v[222:223], s[36:37], 0, v[136:137]
	global_load_lds_dwordx4 v[220:221], off
	s_mov_b32 m0, s51
	v_lshl_add_u64 v[224:225], s[36:37], 0, v[132:133]
	global_load_lds_dwordx4 v[222:223], off
	s_mov_b32 m0, s52
	s_nop 0
	global_load_lds_dwordx4 v[224:225], off
	s_waitcnt vmcnt(8)
	s_waitcnt lgkmcnt(0)
	s_barrier
	s_nop 0
	s_waitcnt lgkmcnt(0)
	v_mfma_f32_16x16x32_bf16 v[64:67], v[148:151], v[180:183], v[64:67]
	v_mfma_f32_16x16x32_bf16 v[60:63], v[156:159], v[180:183], v[60:63]
	v_mfma_f32_16x16x32_bf16 v[48:51], v[148:151], v[188:191], v[48:51]
	v_mfma_f32_16x16x32_bf16 v[44:47], v[156:159], v[188:191], v[44:47]
	v_mfma_f32_16x16x32_bf16 v[32:35], v[148:151], v[202:205], v[32:35]
	v_mfma_f32_16x16x32_bf16 v[28:31], v[156:159], v[202:205], v[28:31]
	v_mfma_f32_16x16x32_bf16 v[16:19], v[148:151], v[210:213], v[16:19]
	v_mfma_f32_16x16x32_bf16 v[12:15], v[156:159], v[210:213], v[12:15]
	v_mfma_f32_16x16x32_bf16 v[64:67], v[152:155], v[184:187], v[64:67]
	v_mfma_f32_16x16x32_bf16 v[60:63], v[160:163], v[184:187], v[60:63]
	v_mfma_f32_16x16x32_bf16 v[48:51], v[152:155], v[192:195], v[48:51]
	v_mfma_f32_16x16x32_bf16 v[44:47], v[160:163], v[192:195], v[44:47]
	v_mfma_f32_16x16x32_bf16 v[32:35], v[152:155], v[206:209], v[32:35]
	v_mfma_f32_16x16x32_bf16 v[28:31], v[160:163], v[206:209], v[28:31]
	v_mfma_f32_16x16x32_bf16 v[16:19], v[152:155], v[214:217], v[16:19]
	v_mfma_f32_16x16x32_bf16 v[12:15], v[160:163], v[214:217], v[12:15]
	s_nop 0
	s_nop 0
	v_mfma_f32_16x16x32_bf16 v[56:59], v[164:167], v[180:183], v[56:59]
	v_mfma_f32_16x16x32_bf16 v[52:55], v[172:175], v[180:183], v[52:55]
	v_mfma_f32_16x16x32_bf16 v[40:43], v[164:167], v[188:191], v[40:43]
	v_mfma_f32_16x16x32_bf16 v[36:39], v[172:175], v[188:191], v[36:39]
	v_mfma_f32_16x16x32_bf16 v[24:27], v[164:167], v[202:205], v[24:27]
	v_mfma_f32_16x16x32_bf16 v[20:23], v[172:175], v[202:205], v[20:23]
	v_mfma_f32_16x16x32_bf16 v[8:11], v[164:167], v[210:213], v[8:11]
	v_mfma_f32_16x16x32_bf16 v[4:7], v[172:175], v[210:213], v[4:7]
	v_mfma_f32_16x16x32_bf16 v[56:59], v[168:171], v[184:187], v[56:59]
	v_mfma_f32_16x16x32_bf16 v[52:55], v[176:179], v[184:187], v[52:55]
	v_mfma_f32_16x16x32_bf16 v[40:43], v[168:171], v[192:195], v[40:43]
	v_mfma_f32_16x16x32_bf16 v[36:39], v[176:179], v[192:195], v[36:39]
	v_mfma_f32_16x16x32_bf16 v[24:27], v[168:171], v[206:209], v[24:27]
	v_mfma_f32_16x16x32_bf16 v[20:23], v[176:179], v[206:209], v[20:23]
	v_mfma_f32_16x16x32_bf16 v[8:11], v[168:171], v[214:217], v[8:11]
	v_mfma_f32_16x16x32_bf16 v[4:7], v[176:179], v[214:217], v[4:7]
	s_nop 0
	s_barrier
; #define PG8_STAGE(bufoff, gbase, voff) do { _Pragma("unroll") for (int _i = 0; _i < 2; ++_i) \
;         __builtin_amdgcn_global_load_lds((const unsigned*)((const char*)(gbase) + (voff)[_i]), (LAS unsigned*)(lds + (bufoff) + ldsw + _i * 8192), 16, 0, 0); } while (0)
; #define PG8_STAGE_A1(bufoff, gbase) do { if (Epi::GATHER) PG8_STAGE(bufoff, gbase, voffA[1]); else PG8_STAGE(bufoff, (gbase) + hstep, voffA[0]); } while (0)
; #define PG8_LDA(dst, b, h) do { _Pragma("unroll") for (int m = 0; m < 4; ++m) _Pragma("unroll") for (int k = 0; k < 2; ++k) dst[m][k] = *(const LAS bf16x8*)(lds + PG8_SA(b, h) + aoff + m * 2048 + k * 1024); } while (0)
; #define PG8_LDB(dst, b, h) do { _Pragma("unroll") for (int n = 0; n < 2; ++n) _Pragma("unroll") for (int k = 0; k < 2; ++k) dst[n][k] = *(const LAS bf16x8*)(lds + PG8_SB(b, h) + boff + n * 2048 + k * 1024); } while (0)
; #define PG8_MMA(ai, bj, At, Bt) do { __builtin_amdgcn_s_setprio(1); _Pragma("unroll") for (int m = 0; m < 4; ++m) _Pragma("unroll") for (int n = 0; n < 2; ++n) _Pragma("unroll") for (int k = 0; k < 2; ++k) \
;         acc[ai][bj][m][n] = __builtin_amdgcn_mfma_f32_16x16x32_bf16(Bt[n][k], At[m][k], acc[ai][bj][m][n], 0, 0, 0); __builtin_amdgcn_s_setprio(0); } while (0)
; #define PG8_WAIT_V(n) asm volatile("s_waitcnt vmcnt(" #n ")" ::: "memory")
; #define PG8_WAIT_L(n) asm volatile("s_waitcnt lgkmcnt(" #n ")" ::: "memory")
; #define PG8_BAR __builtin_amdgcn_s_barrier()
; #define PG8_SCHED __builtin_amdgcn_sched_barrier(0)
; template <class Epi, class Sched>
; __device__ __forceinline__ void gemm_phase(const int tid, LAS unsigned char* lds, const bf16* Aop, const bf16* Bop, const int K_, const Sched& S, const Epi& E, const bf16* Aop1 = nullptr, const bf16* Bop1 = nullptr) {
;     ...
;             PG8_LDB(B0, 1, 0); PG8_LDB(B1, 1, 1); PG8_SCHED; PG8_LDA(At, 1, 0); PG8_STAGE_A1(PG8_SA(0, 1), a2);
;             PG8_WAIT_V(8); PG8_WAIT_L(0); PG8_BAR; PG8_MMA(0, 0, At, B0); PG8_MMA(0, 1, At, B1); PG8_BAR; PG8_SCHED;
;             PG8_LDA(At, 1, 1); PG8_STAGE(PG8_SB(1, 0), b3, voffB); PG8_STAGE(PG8_SB(1, 1), b3 + hstep, voffB); PG8_STAGE(PG8_SA(1, 0), a3, voffA[0]);
;             PG8_WAIT_V(8); PG8_WAIT_L(0); PG8_BAR; PG8_MMA(1, 0, At, B0); PG8_MMA(1, 1, At, B1); PG8_BAR; PG8_SCHED;
	s_add_i32 s68, 0, 0x18000
	v_add_u32_e32 v147, s68, v144
	s_add_i32 s69, 0, 0x1c000
	ds_read_b128 v[148:151], v147
	ds_read_b128 v[152:155], v147 offset:1024
	ds_read_b128 v[156:159], v147 offset:2048
	ds_read_b128 v[160:163], v147 offset:3072
	v_add_u32_e32 v147, s69, v144
	ds_read_b128 v[164:167], v147
	ds_read_b128 v[168:171], v147 offset:1024
	ds_read_b128 v[172:175], v147 offset:2048
	ds_read_b128 v[176:179], v147 offset:3072
	s_add_u32 s36, s36, s6
	s_addc_u32 s37, s37, s7
	s_mov_b32 m0, s53
	v_lshl_add_u64 v[230:231], s[36:37], 0, v[136:137]
	ds_read_b128 v[180:183], v146 offset:32768
	ds_read_b128 v[184:187], v146 offset:33792
	ds_read_b128 v[188:191], v146 offset:34816
	ds_read_b128 v[192:195], v146 offset:35840
	ds_read_b128 v[202:205], v146 offset:36864
	ds_read_b128 v[206:209], v146 offset:37888
	ds_read_b128 v[210:213], v146 offset:38912
	ds_read_b128 v[214:217], v146 offset:39936
	global_load_lds_dwordx4 v[230:231], off
	v_lshl_add_u64 v[230:231], s[36:37], 0, v[132:133]
	s_mov_b32 m0, s54
	s_nop 0
	global_load_lds_dwordx4 v[230:231], off
	s_waitcnt vmcnt(8)
	s_waitcnt lgkmcnt(0)
	s_barrier
	s_nop 0
	s_waitcnt lgkmcnt(0)
	v_mfma_f32_16x16x32_bf16 v[124:127], v[148:151], v[180:183], v[124:127]
	v_mfma_f32_16x16x32_bf16 v[128:131], v[156:159], v[180:183], v[128:131]
	v_mfma_f32_16x16x32_bf16 v[112:115], v[148:151], v[188:191], v[112:115]
	v_mfma_f32_16x16x32_bf16 v[108:111], v[156:159], v[188:191], v[108:111]
	v_mfma_f32_16x16x32_bf16 v[96:99], v[148:151], v[202:205], v[96:99]
	v_mfma_f32_16x16x32_bf16 v[92:95], v[156:159], v[202:205], v[92:95]
	v_mfma_f32_16x16x32_bf16 v[80:83], v[148:151], v[210:213], v[80:83]
	v_mfma_f32_16x16x32_bf16 v[76:79], v[156:159], v[210:213], v[76:79]
	v_mfma_f32_16x16x32_bf16 v[124:127], v[152:155], v[184:187], v[124:127]
	v_mfma_f32_16x16x32_bf16 v[128:131], v[160:163], v[184:187], v[128:131]
	v_mfma_f32_16x16x32_bf16 v[112:115], v[152:155], v[192:195], v[112:115]
	v_mfma_f32_16x16x32_bf16 v[108:111], v[160:163], v[192:195], v[108:111]
	v_mfma_f32_16x16x32_bf16 v[96:99], v[152:155], v[206:209], v[96:99]
	v_mfma_f32_16x16x32_bf16 v[92:95], v[160:163], v[206:209], v[92:95]
	v_mfma_f32_16x16x32_bf16 v[80:83], v[152:155], v[214:217], v[80:83]
	v_mfma_f32_16x16x32_bf16 v[76:79], v[160:163], v[214:217], v[76:79]
	s_nop 0
	s_nop 0
	v_mfma_f32_16x16x32_bf16 v[120:123], v[164:167], v[180:183], v[120:123]
	v_mfma_f32_16x16x32_bf16 v[116:119], v[172:175], v[180:183], v[116:119]
	v_mfma_f32_16x16x32_bf16 v[104:107], v[164:167], v[188:191], v[104:107]
	v_mfma_f32_16x16x32_bf16 v[100:103], v[172:175], v[188:191], v[100:103]
	v_mfma_f32_16x16x32_bf16 v[88:91], v[164:167], v[202:205], v[88:91]
	v_mfma_f32_16x16x32_bf16 v[84:87], v[172:175], v[202:205], v[84:87]
	v_mfma_f32_16x16x32_bf16 v[72:75], v[164:167], v[210:213], v[72:75]
	v_mfma_f32_16x16x32_bf16 v[68:71], v[172:175], v[210:213], v[68:71]
	v_mfma_f32_16x16x32_bf16 v[120:123], v[168:171], v[184:187], v[120:123]
	v_mfma_f32_16x16x32_bf16 v[116:119], v[176:179], v[184:187], v[116:119]
	v_mfma_f32_16x16x32_bf16 v[104:107], v[168:171], v[192:195], v[104:107]
	v_mfma_f32_16x16x32_bf16 v[100:103], v[176:179], v[192:195], v[100:103]
	v_mfma_f32_16x16x32_bf16 v[88:91], v[168:171], v[206:209], v[88:91]
	v_mfma_f32_16x16x32_bf16 v[84:87], v[176:179], v[206:209], v[84:87]
	v_mfma_f32_16x16x32_bf16 v[72:75], v[168:171], v[214:217], v[72:75]
	v_mfma_f32_16x16x32_bf16 v[68:71], v[176:179], v[214:217], v[68:71]
	s_nop 0
	s_barrier
; #define PG8_STAGE(bufoff, gbase, voff) do { _Pragma("unroll") for (int _i = 0; _i < 2; ++_i) \
;         __builtin_amdgcn_global_load_lds((const unsigned*)((const char*)(gbase) + (voff)[_i]), (LAS unsigned*)(lds + (bufoff) + ldsw + _i * 8192), 16, 0, 0); } while (0)
; #define PG8_STAGE_A1(bufoff, gbase) do { if (Epi::GATHER) PG8_STAGE(bufoff, gbase, voffA[1]); else PG8_STAGE(bufoff, (gbase) + hstep, voffA[0]); } while (0)
; #define PG8_LDA(dst, b, h) do { _Pragma("unroll") for (int m = 0; m < 4; ++m) _Pragma("unroll") for (int k = 0; k < 2; ++k) dst[m][k] = *(const LAS bf16x8*)(lds + PG8_SA(b, h) + aoff + m * 2048 + k * 1024); } while (0)
; #define PG8_LDB(dst, b, h) do { _Pragma("unroll") for (int n = 0; n < 2; ++n) _Pragma("unroll") for (int k = 0; k < 2; ++k) dst[n][k] = *(const LAS bf16x8*)(lds + PG8_SB(b, h) + boff + n * 2048 + k * 1024); } while (0)
; #define PG8_MMA(ai, bj, At, Bt) do { __builtin_amdgcn_s_setprio(1); _Pragma("unroll") for (int m = 0; m < 4; ++m) _Pragma("unroll") for (int n = 0; n < 2; ++n) _Pragma("unroll") for (int k = 0; k < 2; ++k) \
;         acc[ai][bj][m][n] = __builtin_amdgcn_mfma_f32_16x16x32_bf16(Bt[n][k], At[m][k], acc[ai][bj][m][n], 0, 0, 0); __builtin_amdgcn_s_setprio(0); } while (0)
; #define PG8_WAIT_V(n) asm volatile("s_waitcnt vmcnt(" #n ")" ::: "memory")
; #define PG8_WAIT_L(n) asm volatile("s_waitcnt lgkmcnt(" #n ")" ::: "memory")
; #define PG8_BAR __builtin_amdgcn_s_barrier()
; #define PG8_SCHED __builtin_amdgcn_sched_barrier(0)
; template <class Epi, class Sched>
; __device__ __forceinline__ void gemm_phase(const int tid, LAS unsigned char* lds, const bf16* Aop, const bf16* Bop, const int K_, const Sched& S, const Epi& E, const bf16* Aop1 = nullptr, const bf16* Bop1 = nullptr) {
;     ...
;             PG8_LDB(B0, 1, 0); PG8_LDB(B1, 1, 1); PG8_SCHED; PG8_LDA(At, 1, 0); PG8_STAGE_A1(PG8_SA(0, 1), a2);
;             PG8_WAIT_V(8); PG8_WAIT_L(0); PG8_BAR; PG8_MMA(0, 0, At, B0); PG8_MMA(0, 1, At, B1); PG8_BAR; PG8_SCHED;
;             PG8_LDA(At, 1, 1); PG8_STAGE(PG8_SB(1, 0), b3, voffB); PG8_STAGE(PG8_SB(1, 1), b3 + hstep, voffB); PG8_STAGE(PG8_SA(1, 0), a3, voffA[0]);
;             PG8_WAIT_V(8); PG8_WAIT_L(0); PG8_BAR; PG8_MMA(1, 0, At, B0); PG8_MMA(1, 1, At, B1); PG8_BAR; PG8_SCHED;
;         }
	s_add_i32 s36, s68, s50
	v_lshl_add_u64 v[196:197], v[196:197], 0, s[20:21]
	s_mov_b32 m0, s36
	ds_read_b128 v[180:183], v146 offset:49152
	ds_read_b128 v[184:187], v146 offset:50176
	ds_read_b128 v[188:191], v146 offset:51200
	ds_read_b128 v[192:195], v146 offset:52224
	ds_read_b128 v[202:205], v146 offset:53248
	ds_read_b128 v[206:209], v146 offset:54272
	ds_read_b128 v[210:213], v146 offset:55296
	ds_read_b128 v[214:217], v146 offset:56320
	global_load_lds_dwordx4 v[196:197], off
	v_lshl_add_u64 v[196:197], v[198:199], 0, s[20:21]
	s_add_i32 m0, s36, 0x2000
	s_add_i32 s36, s69, s50
	global_load_lds_dwordx4 v[196:197], off
	v_lshl_add_u64 v[196:197], v[218:219], 0, s[20:21]
	s_mov_b32 m0, s36
	s_nop 0
	global_load_lds_dwordx4 v[196:197], off
	v_lshl_add_u64 v[196:197], v[220:221], 0, s[20:21]
	s_add_i32 m0, s36, 0x2000
	s_nop 0
	global_load_lds_dwordx4 v[196:197], off
	v_lshl_add_u64 v[196:197], v[222:223], 0, s[20:21]
	s_mov_b32 m0, s56
	s_nop 0
	global_load_lds_dwordx4 v[196:197], off
	v_lshl_add_u64 v[196:197], v[224:225], 0, s[20:21]
	s_mov_b32 m0, s57
	s_nop 0
	global_load_lds_dwordx4 v[196:197], off
	s_waitcnt vmcnt(8)
	s_waitcnt lgkmcnt(0)
	s_barrier
	s_nop 0
	s_waitcnt lgkmcnt(0)
	v_mfma_f32_16x16x32_bf16 v[64:67], v[148:151], v[180:183], v[64:67]
	v_mfma_f32_16x16x32_bf16 v[60:63], v[156:159], v[180:183], v[60:63]
	v_mfma_f32_16x16x32_bf16 v[48:51], v[148:151], v[188:191], v[48:51]
	v_mfma_f32_16x16x32_bf16 v[44:47], v[156:159], v[188:191], v[44:47]
	v_mfma_f32_16x16x32_bf16 v[32:35], v[148:151], v[202:205], v[32:35]
	v_mfma_f32_16x16x32_bf16 v[28:31], v[156:159], v[202:205], v[28:31]
	v_mfma_f32_16x16x32_bf16 v[16:19], v[148:151], v[210:213], v[16:19]
	v_mfma_f32_16x16x32_bf16 v[12:15], v[156:159], v[210:213], v[12:15]
	v_mfma_f32_16x16x32_bf16 v[64:67], v[152:155], v[184:187], v[64:67]
	v_mfma_f32_16x16x32_bf16 v[60:63], v[160:163], v[184:187], v[60:63]
	v_mfma_f32_16x16x32_bf16 v[48:51], v[152:155], v[192:195], v[48:51]
	v_mfma_f32_16x16x32_bf16 v[44:47], v[160:163], v[192:195], v[44:47]
	v_mfma_f32_16x16x32_bf16 v[32:35], v[152:155], v[206:209], v[32:35]
	v_mfma_f32_16x16x32_bf16 v[28:31], v[160:163], v[206:209], v[28:31]
	v_mfma_f32_16x16x32_bf16 v[16:19], v[152:155], v[214:217], v[16:19]
	v_mfma_f32_16x16x32_bf16 v[12:15], v[160:163], v[214:217], v[12:15]
	s_nop 0
	s_nop 0
	v_mfma_f32_16x16x32_bf16 v[56:59], v[164:167], v[180:183], v[56:59]
	v_mfma_f32_16x16x32_bf16 v[52:55], v[172:175], v[180:183], v[52:55]
	v_mfma_f32_16x16x32_bf16 v[40:43], v[164:167], v[188:191], v[40:43]
	v_mfma_f32_16x16x32_bf16 v[36:39], v[172:175], v[188:191], v[36:39]
	v_mfma_f32_16x16x32_bf16 v[24:27], v[164:167], v[202:205], v[24:27]
	v_mfma_f32_16x16x32_bf16 v[20:23], v[172:175], v[202:205], v[20:23]
	v_mfma_f32_16x16x32_bf16 v[8:11], v[164:167], v[210:213], v[8:11]
	v_mfma_f32_16x16x32_bf16 v[4:7], v[172:175], v[210:213], v[4:7]
	v_mfma_f32_16x16x32_bf16 v[56:59], v[168:171], v[184:187], v[56:59]
	v_mfma_f32_16x16x32_bf16 v[52:55], v[176:179], v[184:187], v[52:55]
	v_mfma_f32_16x16x32_bf16 v[40:43], v[168:171], v[192:195], v[40:43]
	v_mfma_f32_16x16x32_bf16 v[36:39], v[176:179], v[192:195], v[36:39]
	v_mfma_f32_16x16x32_bf16 v[24:27], v[168:171], v[206:209], v[24:27]
	v_mfma_f32_16x16x32_bf16 v[20:23], v[176:179], v[206:209], v[20:23]
	v_mfma_f32_16x16x32_bf16 v[8:11], v[168:171], v[214:217], v[8:11]
	v_mfma_f32_16x16x32_bf16 v[4:7], v[176:179], v[214:217], v[4:7]
	s_nop 0
	s_barrier
	s_add_u32 s34, s34, 0x100
	s_addc_u32 s35, s35, 0
	s_add_u32 s65, s65, 0x100
	s_addc_u32 s66, s66, 0
	s_cmp_ge_i32 s67, s55
	s_mov_b32 s36, s67
	s_cbranch_scc0 .LBB0_1400

; #define LAS __attribute__((address_space(3)))
;     __device__ bool next(int i, Unit& u) const { if (!so.next(i >> 1, u)) return false; u.sel = i & 1; return true; }
;     __device__ bool next(int i, Unit& u) const { const int L = i * nw + r; if (L >= nu) return false; u.pm = L >> 2; u.pn = L & 3; u.pb = u.pn; u.sel = 0; return true; }
; #define PG8_STAGE(bufoff, gbase, voff) do { _Pragma("unroll") for (int _i = 0; _i < 2; ++_i) \
;         __builtin_amdgcn_global_load_lds((const unsigned*)((const char*)(gbase) + (voff)[_i]), (LAS unsigned*)(lds + (bufoff) + ldsw + _i * 8192), 16, 0, 0); } while (0)
; template <class Epi, class Sched>
; __device__ __forceinline__ void gemm_phase(const int tid, LAS unsigned char* lds, const bf16* Aop, const bf16* Bop, const int K_, const Sched& S, const Epi& E, const bf16* Aop1 = nullptr, const bf16* Bop1 = nullptr) {
;     ...
;     for (;;) {
;         const bool has_next = S.next(ui + 1, nxt);
;         if (Epi::GATHER && has_next && wid < 4) E.tok_dma(nxt.pm * 256 + wid * 64, (LAS unsigned*)(lds + 8 * HTB) + ((ui + 1) & 1) * 256 + wid * 64, lane);
;         const char* nA = has_next ? (const char*)((Aop1 && nxt.sel) ? Aop1 : Aop) + (Epi::GATHER ? (size_t)0 : (size_t)nxt.pm * tstep) : cA; const char* nB = has_next ? (const char*)((Bop1 && nxt.sel) ? Bop1 : Bop) + (size_t)nxt.pb * tstep : cB;
;         for (int t = 0; t < nt; t += 2) {
;             const bool last = (t == nt - 2);
;             const char* a1 = cA + (size_t)(t + 1) * kstep;
;             const char* a2 = last ? nA : cA + (size_t)(t + 2) * kstep; const char* b2 = last ? nB : cB + (size_t)(t + 2) * kstep;
;             const char* a3 = a2 + kstep; const char* b3 = b2 + kstep;
;             PG8_LDB(B0, 0, 0); PG8_LDB(B1, 0, 1); PG8_SCHED; PG8_LDA(At, 0, 0); PG8_STAGE_A1(PG8_SA(1, 1), a1);
;             PG8_WAIT_V(8); PG8_WAIT_L(0); PG8_BAR; PG8_MMA(0, 0, At, B0); PG8_MMA(0, 1, At, B1); PG8_BAR; PG8_SCHED;
;             PG8_LDA(At, 0, 1); PG8_STAGE(PG8_SB(0, 0), b2, voffB); PG8_STAGE(PG8_SB(0, 1), b2 + hstep, voffB); if (Epi::GATHER && last && has_next) PG8_GOFFS((ui + 1) & 1); PG8_STAGE(PG8_SA(0, 0), a2, voffA[0]);
;             PG8_WAIT_V(8); PG8_WAIT_L(0); PG8_BAR; PG8_MMA(1, 0, At, B0); PG8_MMA(1, 1, At, B1); PG8_BAR; PG8_SCHED;
;             PG8_LDB(B0, 1, 0); PG8_LDB(B1, 1, 1); PG8_SCHED; PG8_LDA(At, 1, 0); PG8_STAGE_A1(PG8_SA(0, 1), a2);
.LBB0_1418:
	v_mov_b32_e32 v127, 0
	s_andn2_b64 vcc, exec, s[16:17]
	s_cbranch_vccnz .LBB0_1421
	s_add_u32 s34, s34, 0x80
	s_addc_u32 s35, s35, 0
	s_add_u32 s15, s36, 0x100
	s_addc_u32 s67, s37, 0
	s_mov_b32 s36, 0
	s_add_i32 s68, s36, 2
	s_add_u32 s69, s34, 0x80
	s_addc_u32 s37, s35, 0
	s_add_i32 s72, 0, 0x10000
	s_cmp_eq_u32 s61, s36
	s_cselect_b32 s37, s27, s37
	s_cselect_b32 s36, s26, s69
	s_cselect_b32 s71, s29, s67
	s_cselect_b32 s70, s28, s15
	s_add_i32 s69, 0, 0x14000
	v_add_u32_e32 v158, s72, v3
	v_add_u32_e32 v174, s69, v3
	ds_read_b128 v[146:149], v158
	ds_read_b128 v[150:153], v158 offset:1024
	ds_read_b128 v[154:157], v158 offset:2048
	ds_read_b128 v[158:161], v158 offset:3072
	ds_read_b128 v[162:165], v174
	ds_read_b128 v[166:169], v174 offset:1024
	ds_read_b128 v[170:173], v174 offset:2048
	ds_read_b128 v[174:177], v174 offset:3072
	v_lshl_add_u64 v[194:195], s[34:35], 0, v[140:141]
	s_add_i32 m0, s53, 0xc000
	ds_read_b128 v[178:181], v144
	ds_read_b128 v[182:185], v144 offset:1024
	ds_read_b128 v[186:189], v144 offset:2048
	ds_read_b128 v[190:193], v144 offset:3072
	ds_read_b128 v[202:205], v144 offset:4096
	ds_read_b128 v[206:209], v144 offset:5120
	ds_read_b128 v[210:213], v144 offset:6144
	ds_read_b128 v[214:217], v144 offset:7168
	global_load_lds_dwordx4 v[194:195], off
	v_lshl_add_u64 v[194:195], s[34:35], 0, v[142:143]
	s_add_i32 m0, s53, 0xe000
	s_nop 0
	global_load_lds_dwordx4 v[194:195], off
	s_waitcnt vmcnt(8)
	s_waitcnt lgkmcnt(0)
	s_barrier
	s_nop 0
	s_waitcnt lgkmcnt(0)
	v_mfma_f32_16x16x32_bf16 v[124:127], v[146:149], v[178:181], 0
	v_mfma_f32_16x16x32_bf16 v[128:131], v[154:157], v[178:181], 0
	v_mfma_f32_16x16x32_bf16 v[112:115], v[146:149], v[186:189], 0
	v_mfma_f32_16x16x32_bf16 v[108:111], v[154:157], v[186:189], 0
	v_mfma_f32_16x16x32_bf16 v[96:99], v[146:149], v[202:205], 0
	v_mfma_f32_16x16x32_bf16 v[92:95], v[154:157], v[202:205], 0
	v_mfma_f32_16x16x32_bf16 v[80:83], v[146:149], v[210:213], 0
	v_mfma_f32_16x16x32_bf16 v[76:79], v[154:157], v[210:213], 0
	v_mfma_f32_16x16x32_bf16 v[124:127], v[150:153], v[182:185], v[124:127]
	v_mfma_f32_16x16x32_bf16 v[128:131], v[158:161], v[182:185], v[128:131]
	v_mfma_f32_16x16x32_bf16 v[112:115], v[150:153], v[190:193], v[112:115]
	v_mfma_f32_16x16x32_bf16 v[108:111], v[158:161], v[190:193], v[108:111]
	v_mfma_f32_16x16x32_bf16 v[96:99], v[150:153], v[206:209], v[96:99]
	v_mfma_f32_16x16x32_bf16 v[92:95], v[158:161], v[206:209], v[92:95]
	v_mfma_f32_16x16x32_bf16 v[80:83], v[150:153], v[214:217], v[80:83]
	v_mfma_f32_16x16x32_bf16 v[76:79], v[158:161], v[214:217], v[76:79]
	s_nop 0
	s_nop 0
	v_mfma_f32_16x16x32_bf16 v[120:123], v[162:165], v[178:181], 0
	v_mfma_f32_16x16x32_bf16 v[116:119], v[170:173], v[178:181], 0
	v_mfma_f32_16x16x32_bf16 v[104:107], v[162:165], v[186:189], 0
	v_mfma_f32_16x16x32_bf16 v[100:103], v[170:173], v[186:189], 0
	v_mfma_f32_16x16x32_bf16 v[88:91], v[162:165], v[202:205], 0
	v_mfma_f32_16x16x32_bf16 v[84:87], v[170:173], v[202:205], 0
	v_mfma_f32_16x16x32_bf16 v[72:75], v[162:165], v[210:213], 0
	v_mfma_f32_16x16x32_bf16 v[68:71], v[170:173], v[210:213], 0
	v_mfma_f32_16x16x32_bf16 v[120:123], v[166:169], v[182:185], v[120:123]
	v_mfma_f32_16x16x32_bf16 v[116:119], v[174:177], v[182:185], v[116:119]
	v_mfma_f32_16x16x32_bf16 v[104:107], v[166:169], v[190:193], v[104:107]
	v_mfma_f32_16x16x32_bf16 v[100:103], v[174:177], v[190:193], v[100:103]
	v_mfma_f32_16x16x32_bf16 v[88:91], v[166:169], v[206:209], v[88:91]
	v_mfma_f32_16x16x32_bf16 v[84:87], v[174:177], v[206:209], v[84:87]
	v_mfma_f32_16x16x32_bf16 v[72:75], v[166:169], v[214:217], v[72:75]
	v_mfma_f32_16x16x32_bf16 v[68:71], v[174:177], v[214:217], v[68:71]
	s_nop 0
	s_barrier
	s_add_i32 s72, s72, s52
	v_lshl_add_u64 v[194:195], s[70:71], 0, v[134:135]
	s_mov_b32 m0, s72
	ds_read_b128 v[178:181], v144 offset:16384
	ds_read_b128 v[182:185], v144 offset:17408
	ds_read_b128 v[186:189], v144 offset:18432
	ds_read_b128 v[190:193], v144 offset:19456
	ds_read_b128 v[202:205], v144 offset:20480
	ds_read_b128 v[206:209], v144 offset:21504
	ds_read_b128 v[210:213], v144 offset:22528
	ds_read_b128 v[214:217], v144 offset:23552
	global_load_lds_dwordx4 v[194:195], off
	s_add_i32 m0, s72, 0x2000
	v_lshl_add_u64 v[196:197], s[70:71], 0, v[0:1]
	s_add_u32 s70, s70, s6
	s_addc_u32 s71, s71, s7
	s_add_i32 s69, s69, s52
	global_load_lds_dwordx4 v[196:197], off
	v_lshl_add_u64 v[198:199], s[70:71], 0, v[134:135]
	s_mov_b32 m0, s69
	v_lshl_add_u64 v[218:219], s[70:71], 0, v[0:1]
	global_load_lds_dwordx4 v[198:199], off
	s_add_i32 m0, s69, 0x2000
	v_lshl_add_u64 v[220:221], s[36:37], 0, v[136:137]
	global_load_lds_dwordx4 v[218:219], off
	s_mov_b32 m0, s53
	v_lshl_add_u64 v[222:223], s[36:37], 0, v[132:133]
	global_load_lds_dwordx4 v[220:221], off
	s_mov_b32 m0, s54
	s_nop 0
	global_load_lds_dwordx4 v[222:223], off
	s_waitcnt vmcnt(8)
	s_waitcnt lgkmcnt(0)
	s_barrier
; #define PG8_GOFFS(slot_) do { _Pragma("unroll") for (int _i = 0; _i < 2; ++_i) { int R, C; stage_rc(tid * 16 + _i * 8192, R, C); _Pragma("unroll") for (int _h = 0; _h < 2; ++_h) { \
;         unsigned t_ = gtab[(slot_) * 256 + R + 128 * _h]; t_ = t_ < (unsigned)(T - 1) ? t_ : (unsigned)(T - 1); voffA[_h][_i] = (t_ * (unsigned)K + (unsigned)C) * 2u; } } } while (0)
; #define PG8_STAGE(bufoff, gbase, voff) do { _Pragma("unroll") for (int _i = 0; _i < 2; ++_i) \
;         __builtin_amdgcn_global_load_lds((const unsigned*)((const char*)(gbase) + (voff)[_i]), (LAS unsigned*)(lds + (bufoff) + ldsw + _i * 8192), 16, 0, 0); } while (0)
; #define PG8_STAGE_A1(bufoff, gbase) do { if (Epi::GATHER) PG8_STAGE(bufoff, gbase, voffA[1]); else PG8_STAGE(bufoff, (gbase) + hstep, voffA[0]); } while (0)
; #define PG8_LDA(dst, b, h) do { _Pragma("unroll") for (int m = 0; m < 4; ++m) _Pragma("unroll") for (int k = 0; k < 2; ++k) dst[m][k] = *(const LAS bf16x8*)(lds + PG8_SA(b, h) + aoff + m * 2048 + k * 1024); } while (0)
; #define PG8_LDB(dst, b, h) do { _Pragma("unroll") for (int n = 0; n < 2; ++n) _Pragma("unroll") for (int k = 0; k < 2; ++k) dst[n][k] = *(const LAS bf16x8*)(lds + PG8_SB(b, h) + boff + n * 2048 + k * 1024); } while (0)
; #define PG8_WAIT_V(n) asm volatile("s_waitcnt vmcnt(" #n ")" ::: "memory")
; #define PG8_WAIT_L(n) asm volatile("s_waitcnt lgkmcnt(" #n ")" ::: "memory")
; template <class Epi, class Sched>
; __device__ __forceinline__ void gemm_phase(const int tid, LAS unsigned char* lds, const bf16* Aop, const bf16* Bop, const int K_, const Sched& S, const Epi& E, const bf16* Aop1 = nullptr, const bf16* Bop1 = nullptr) {
;     ...
;             PG8_LDA(At, 0, 1); PG8_STAGE(PG8_SB(0, 0), b2, voffB); PG8_STAGE(PG8_SB(0, 1), b2 + hstep, voffB); if (Epi::GATHER && last && has_next) PG8_GOFFS((ui + 1) & 1); PG8_STAGE(PG8_SA(0, 0), a2, voffA[0]);
;             PG8_WAIT_V(8); PG8_WAIT_L(0); PG8_BAR; PG8_MMA(1, 0, At, B0); PG8_MMA(1, 1, At, B1); PG8_BAR; PG8_SCHED;
;             PG8_LDB(B0, 1, 0); PG8_LDB(B1, 1, 1); PG8_SCHED; PG8_LDA(At, 1, 0); PG8_STAGE_A1(PG8_SA(0, 1), a2);
;             PG8_WAIT_V(8); PG8_WAIT_L(0); PG8_BAR; PG8_MMA(0, 0, At, B0); PG8_MMA(0, 1, At, B1); PG8_BAR; PG8_SCHED;
;             PG8_LDA(At, 1, 1); PG8_STAGE(PG8_SB(1, 0), b3, voffB); PG8_STAGE(PG8_SB(1, 1), b3 + hstep, voffB); PG8_STAGE(PG8_SA(1, 0), a3, voffA[0]);
	s_nop 0
	s_waitcnt lgkmcnt(0)
	v_mfma_f32_16x16x32_bf16 v[64:67], v[146:149], v[178:181], 0
	v_mfma_f32_16x16x32_bf16 v[60:63], v[154:157], v[178:181], 0
	v_mfma_f32_16x16x32_bf16 v[48:51], v[146:149], v[186:189], 0
	v_mfma_f32_16x16x32_bf16 v[44:47], v[154:157], v[186:189], 0
	v_mfma_f32_16x16x32_bf16 v[32:35], v[146:149], v[202:205], 0
	v_mfma_f32_16x16x32_bf16 v[28:31], v[154:157], v[202:205], 0
	v_mfma_f32_16x16x32_bf16 v[16:19], v[146:149], v[210:213], 0
	v_mfma_f32_16x16x32_bf16 v[12:15], v[154:157], v[210:213], 0
	v_mfma_f32_16x16x32_bf16 v[64:67], v[150:153], v[182:185], v[64:67]
	v_mfma_f32_16x16x32_bf16 v[60:63], v[158:161], v[182:185], v[60:63]
	v_mfma_f32_16x16x32_bf16 v[48:51], v[150:153], v[190:193], v[48:51]
	v_mfma_f32_16x16x32_bf16 v[44:47], v[158:161], v[190:193], v[44:47]
	v_mfma_f32_16x16x32_bf16 v[32:35], v[150:153], v[206:209], v[32:35]
	v_mfma_f32_16x16x32_bf16 v[28:31], v[158:161], v[206:209], v[28:31]
	v_mfma_f32_16x16x32_bf16 v[16:19], v[150:153], v[214:217], v[16:19]
	v_mfma_f32_16x16x32_bf16 v[12:15], v[158:161], v[214:217], v[12:15]
	s_nop 0
	s_nop 0
	v_mfma_f32_16x16x32_bf16 v[56:59], v[162:165], v[178:181], 0
	v_mfma_f32_16x16x32_bf16 v[52:55], v[170:173], v[178:181], 0
	v_mfma_f32_16x16x32_bf16 v[40:43], v[162:165], v[186:189], 0
	v_mfma_f32_16x16x32_bf16 v[36:39], v[170:173], v[186:189], 0
	v_mfma_f32_16x16x32_bf16 v[24:27], v[162:165], v[202:205], 0
	v_mfma_f32_16x16x32_bf16 v[20:23], v[170:173], v[202:205], 0
	v_mfma_f32_16x16x32_bf16 v[8:11], v[162:165], v[210:213], 0
	v_mfma_f32_16x16x32_bf16 v[4:7], v[170:173], v[210:213], 0
	v_mfma_f32_16x16x32_bf16 v[56:59], v[166:169], v[182:185], v[56:59]
	v_mfma_f32_16x16x32_bf16 v[52:55], v[174:177], v[182:185], v[52:55]
	v_mfma_f32_16x16x32_bf16 v[40:43], v[166:169], v[190:193], v[40:43]
	v_mfma_f32_16x16x32_bf16 v[36:39], v[174:177], v[190:193], v[36:39]
	v_mfma_f32_16x16x32_bf16 v[24:27], v[166:169], v[206:209], v[24:27]
	v_mfma_f32_16x16x32_bf16 v[20:23], v[174:177], v[206:209], v[20:23]
	v_mfma_f32_16x16x32_bf16 v[8:11], v[166:169], v[214:217], v[8:11]
	v_mfma_f32_16x16x32_bf16 v[4:7], v[174:177], v[214:217], v[4:7]
	s_nop 0
	s_barrier
	s_add_i32 s69, 0, 0x18000
	s_add_i32 s70, 0, 0x1c000
	v_add_u32_e32 v158, s69, v3
	v_add_u32_e32 v174, s70, v3
	ds_read_b128 v[146:149], v158
	ds_read_b128 v[150:153], v158 offset:1024
	ds_read_b128 v[154:157], v158 offset:2048
	ds_read_b128 v[158:161], v158 offset:3072
	ds_read_b128 v[162:165], v174
	ds_read_b128 v[166:169], v174 offset:1024
	ds_read_b128 v[170:173], v174 offset:2048
	ds_read_b128 v[174:177], v174 offset:3072
	s_add_u32 s36, s36, s6
	s_addc_u32 s37, s37, s7
	s_mov_b32 m0, s55
	v_lshl_add_u64 v[224:225], s[36:37], 0, v[136:137]
	ds_read_b128 v[178:181], v144 offset:32768
	ds_read_b128 v[182:185], v144 offset:33792
	ds_read_b128 v[186:189], v144 offset:34816
	ds_read_b128 v[190:193], v144 offset:35840
	ds_read_b128 v[202:205], v144 offset:36864
	ds_read_b128 v[206:209], v144 offset:37888
	ds_read_b128 v[210:213], v144 offset:38912
	ds_read_b128 v[214:217], v144 offset:39936
	global_load_lds_dwordx4 v[224:225], off
	v_lshl_add_u64 v[224:225], s[36:37], 0, v[132:133]
	s_mov_b32 m0, s56
	s_nop 0
	global_load_lds_dwordx4 v[224:225], off
	s_waitcnt vmcnt(8)
	s_waitcnt lgkmcnt(0)
	s_barrier
	s_nop 0
	s_waitcnt lgkmcnt(0)
	v_mfma_f32_16x16x32_bf16 v[124:127], v[146:149], v[178:181], v[124:127]
	v_mfma_f32_16x16x32_bf16 v[128:131], v[154:157], v[178:181], v[128:131]
	v_mfma_f32_16x16x32_bf16 v[112:115], v[146:149], v[186:189], v[112:115]
	v_mfma_f32_16x16x32_bf16 v[108:111], v[154:157], v[186:189], v[108:111]
	v_mfma_f32_16x16x32_bf16 v[96:99], v[146:149], v[202:205], v[96:99]
	v_mfma_f32_16x16x32_bf16 v[92:95], v[154:157], v[202:205], v[92:95]
	v_mfma_f32_16x16x32_bf16 v[80:83], v[146:149], v[210:213], v[80:83]
	v_mfma_f32_16x16x32_bf16 v[76:79], v[154:157], v[210:213], v[76:79]
	v_mfma_f32_16x16x32_bf16 v[124:127], v[150:153], v[182:185], v[124:127]
	v_mfma_f32_16x16x32_bf16 v[128:131], v[158:161], v[182:185], v[128:131]
	v_mfma_f32_16x16x32_bf16 v[112:115], v[150:153], v[190:193], v[112:115]
	v_mfma_f32_16x16x32_bf16 v[108:111], v[158:161], v[190:193], v[108:111]
	v_mfma_f32_16x16x32_bf16 v[96:99], v[150:153], v[206:209], v[96:99]
	v_mfma_f32_16x16x32_bf16 v[92:95], v[158:161], v[206:209], v[92:95]
	v_mfma_f32_16x16x32_bf16 v[80:83], v[150:153], v[214:217], v[80:83]
	v_mfma_f32_16x16x32_bf16 v[76:79], v[158:161], v[214:217], v[76:79]
	s_nop 0
	s_nop 0
	v_mfma_f32_16x16x32_bf16 v[120:123], v[162:165], v[178:181], v[120:123]
	v_mfma_f32_16x16x32_bf16 v[116:119], v[170:173], v[178:181], v[116:119]
	v_mfma_f32_16x16x32_bf16 v[104:107], v[162:165], v[186:189], v[104:107]
	v_mfma_f32_16x16x32_bf16 v[100:103], v[170:173], v[186:189], v[100:103]
	v_mfma_f32_16x16x32_bf16 v[88:91], v[162:165], v[202:205], v[88:91]
	v_mfma_f32_16x16x32_bf16 v[84:87], v[170:173], v[202:205], v[84:87]
	v_mfma_f32_16x16x32_bf16 v[72:75], v[162:165], v[210:213], v[72:75]
	v_mfma_f32_16x16x32_bf16 v[68:71], v[170:173], v[210:213], v[68:71]
	v_mfma_f32_16x16x32_bf16 v[120:123], v[166:169], v[182:185], v[120:123]
	v_mfma_f32_16x16x32_bf16 v[116:119], v[174:177], v[182:185], v[116:119]
	v_mfma_f32_16x16x32_bf16 v[104:107], v[166:169], v[190:193], v[104:107]
	v_mfma_f32_16x16x32_bf16 v[100:103], v[174:177], v[190:193], v[100:103]
	v_mfma_f32_16x16x32_bf16 v[88:91], v[166:169], v[206:209], v[88:91]
	v_mfma_f32_16x16x32_bf16 v[84:87], v[174:177], v[206:209], v[84:87]
	v_mfma_f32_16x16x32_bf16 v[72:75], v[166:169], v[214:217], v[72:75]
	v_mfma_f32_16x16x32_bf16 v[68:71], v[174:177], v[214:217], v[68:71]
	s_nop 0
	s_barrier
; #define PG8_STAGE(bufoff, gbase, voff) do { _Pragma("unroll") for (int _i = 0; _i < 2; ++_i) \
;         __builtin_amdgcn_global_load_lds((const unsigned*)((const char*)(gbase) + (voff)[_i]), (LAS unsigned*)(lds + (bufoff) + ldsw + _i * 8192), 16, 0, 0); } while (0)
; #define PG8_STAGE_A1(bufoff, gbase) do { if (Epi::GATHER) PG8_STAGE(bufoff, gbase, voffA[1]); else PG8_STAGE(bufoff, (gbase) + hstep, voffA[0]); } while (0)
; #define PG8_LDA(dst, b, h) do { _Pragma("unroll") for (int m = 0; m < 4; ++m) _Pragma("unroll") for (int k = 0; k < 2; ++k) dst[m][k] = *(const LAS bf16x8*)(lds + PG8_SA(b, h) + aoff + m * 2048 + k * 1024); } while (0)
; #define PG8_LDB(dst, b, h) do { _Pragma("unroll") for (int n = 0; n < 2; ++n) _Pragma("unroll") for (int k = 0; k < 2; ++k) dst[n][k] = *(const LAS bf16x8*)(lds + PG8_SB(b, h) + boff + n * 2048 + k * 1024); } while (0)
; #define PG8_MMA(ai, bj, At, Bt) do { __builtin_amdgcn_s_setprio(1); _Pragma("unroll") for (int m = 0; m < 4; ++m) _Pragma("unroll") for (int n = 0; n < 2; ++n) _Pragma("unroll") for (int k = 0; k < 2; ++k) \
;         acc[ai][bj][m][n] = __builtin_amdgcn_mfma_f32_16x16x32_bf16(Bt[n][k], At[m][k], acc[ai][bj][m][n], 0, 0, 0); __builtin_amdgcn_s_setprio(0); } while (0)
; #define PG8_WAIT_V(n) asm volatile("s_waitcnt vmcnt(" #n ")" ::: "memory")
; #define PG8_WAIT_L(n) asm volatile("s_waitcnt lgkmcnt(" #n ")" ::: "memory")
; #define PG8_BAR __builtin_amdgcn_s_barrier()
; #define PG8_SCHED __builtin_amdgcn_sched_barrier(0)
; template <class Epi, class Sched>
; __device__ __forceinline__ void gemm_phase(const int tid, LAS unsigned char* lds, const bf16* Aop, const bf16* Bop, const int K_, const Sched& S, const Epi& E, const bf16* Aop1 = nullptr, const bf16* Bop1 = nullptr) {
;     ...
;             PG8_LDB(B0, 1, 0); PG8_LDB(B1, 1, 1); PG8_SCHED; PG8_LDA(At, 1, 0); PG8_STAGE_A1(PG8_SA(0, 1), a2);
;             PG8_WAIT_V(8); PG8_WAIT_L(0); PG8_BAR; PG8_MMA(0, 0, At, B0); PG8_MMA(0, 1, At, B1); PG8_BAR; PG8_SCHED;
;             PG8_LDA(At, 1, 1); PG8_STAGE(PG8_SB(1, 0), b3, voffB); PG8_STAGE(PG8_SB(1, 1), b3 + hstep, voffB); PG8_STAGE(PG8_SA(1, 0), a3, voffA[0]);
;             PG8_WAIT_V(8); PG8_WAIT_L(0); PG8_BAR; PG8_MMA(1, 0, At, B0); PG8_MMA(1, 1, At, B1); PG8_BAR; PG8_SCHED;
;         }
	s_add_i32 s36, s69, s52
	v_lshl_add_u64 v[194:195], v[194:195], 0, s[20:21]
	s_mov_b32 m0, s36
	ds_read_b128 v[178:181], v144 offset:49152
	ds_read_b128 v[182:185], v144 offset:50176
	ds_read_b128 v[186:189], v144 offset:51200
	ds_read_b128 v[190:193], v144 offset:52224
	ds_read_b128 v[202:205], v144 offset:53248
	ds_read_b128 v[206:209], v144 offset:54272
	ds_read_b128 v[210:213], v144 offset:55296
	ds_read_b128 v[214:217], v144 offset:56320
	global_load_lds_dwordx4 v[194:195], off
	v_lshl_add_u64 v[194:195], v[196:197], 0, s[20:21]
	s_add_i32 m0, s36, 0x2000
	s_add_i32 s36, s70, s52
	global_load_lds_dwordx4 v[194:195], off
	v_lshl_add_u64 v[194:195], v[198:199], 0, s[20:21]
	s_mov_b32 m0, s36
	s_nop 0
	global_load_lds_dwordx4 v[194:195], off
	v_lshl_add_u64 v[194:195], v[218:219], 0, s[20:21]
	s_add_i32 m0, s36, 0x2000
	s_nop 0
	global_load_lds_dwordx4 v[194:195], off
	v_lshl_add_u64 v[194:195], v[220:221], 0, s[20:21]
	s_mov_b32 m0, s59
	s_nop 0
	global_load_lds_dwordx4 v[194:195], off
	v_lshl_add_u64 v[194:195], v[222:223], 0, s[20:21]
	s_mov_b32 m0, s60
	s_nop 0
	global_load_lds_dwordx4 v[194:195], off
	s_waitcnt vmcnt(8)
	s_waitcnt lgkmcnt(0)
	s_barrier
	s_nop 0
	s_waitcnt lgkmcnt(0)
	v_mfma_f32_16x16x32_bf16 v[64:67], v[146:149], v[178:181], v[64:67]
	v_mfma_f32_16x16x32_bf16 v[60:63], v[154:157], v[178:181], v[60:63]
	v_mfma_f32_16x16x32_bf16 v[48:51], v[146:149], v[186:189], v[48:51]
	v_mfma_f32_16x16x32_bf16 v[44:47], v[154:157], v[186:189], v[44:47]
	v_mfma_f32_16x16x32_bf16 v[32:35], v[146:149], v[202:205], v[32:35]
	v_mfma_f32_16x16x32_bf16 v[28:31], v[154:157], v[202:205], v[28:31]
	v_mfma_f32_16x16x32_bf16 v[16:19], v[146:149], v[210:213], v[16:19]
	v_mfma_f32_16x16x32_bf16 v[12:15], v[154:157], v[210:213], v[12:15]
	v_mfma_f32_16x16x32_bf16 v[64:67], v[150:153], v[182:185], v[64:67]
	v_mfma_f32_16x16x32_bf16 v[60:63], v[158:161], v[182:185], v[60:63]
	v_mfma_f32_16x16x32_bf16 v[48:51], v[150:153], v[190:193], v[48:51]
	v_mfma_f32_16x16x32_bf16 v[44:47], v[158:161], v[190:193], v[44:47]
	v_mfma_f32_16x16x32_bf16 v[32:35], v[150:153], v[206:209], v[32:35]
	v_mfma_f32_16x16x32_bf16 v[28:31], v[158:161], v[206:209], v[28:31]
	v_mfma_f32_16x16x32_bf16 v[16:19], v[150:153], v[214:217], v[16:19]
	v_mfma_f32_16x16x32_bf16 v[12:15], v[158:161], v[214:217], v[12:15]
	s_nop 0
	s_nop 0
	v_mfma_f32_16x16x32_bf16 v[56:59], v[162:165], v[178:181], v[56:59]
	v_mfma_f32_16x16x32_bf16 v[52:55], v[170:173], v[178:181], v[52:55]
	v_mfma_f32_16x16x32_bf16 v[40:43], v[162:165], v[186:189], v[40:43]
	v_mfma_f32_16x16x32_bf16 v[36:39], v[170:173], v[186:189], v[36:39]
	v_mfma_f32_16x16x32_bf16 v[24:27], v[162:165], v[202:205], v[24:27]
	v_mfma_f32_16x16x32_bf16 v[20:23], v[170:173], v[202:205], v[20:23]
	v_mfma_f32_16x16x32_bf16 v[8:11], v[162:165], v[210:213], v[8:11]
	v_mfma_f32_16x16x32_bf16 v[4:7], v[170:173], v[210:213], v[4:7]
	v_mfma_f32_16x16x32_bf16 v[56:59], v[166:169], v[182:185], v[56:59]
	v_mfma_f32_16x16x32_bf16 v[52:55], v[174:177], v[182:185], v[52:55]
	v_mfma_f32_16x16x32_bf16 v[40:43], v[166:169], v[190:193], v[40:43]
	v_mfma_f32_16x16x32_bf16 v[36:39], v[174:177], v[190:193], v[36:39]
	v_mfma_f32_16x16x32_bf16 v[24:27], v[166:169], v[206:209], v[24:27]
	v_mfma_f32_16x16x32_bf16 v[20:23], v[174:177], v[206:209], v[20:23]
	v_mfma_f32_16x16x32_bf16 v[8:11], v[166:169], v[214:217], v[8:11]
	v_mfma_f32_16x16x32_bf16 v[4:7], v[174:177], v[214:217], v[4:7]
	s_nop 0
	s_barrier
	s_add_u32 s34, s34, 0x100
	s_addc_u32 s35, s35, 0
	s_add_u32 s15, s15, 0x100
	s_addc_u32 s67, s67, 0
	s_cmp_ge_i32 s68, s58
	s_mov_b32 s36, s68
	s_cbranch_scc0 .LBB0_1420
	s_branch .LBB0_1421
.LBB0_1420:
	s_add_i32 s68, s36, 2
	s_add_u32 s69, s34, 0x80
	s_addc_u32 s37, s35, 0
	s_add_i32 s72, 0, 0x10000
	s_cmp_eq_u32 s61, s36
	s_cselect_b32 s37, s27, s37
	s_cselect_b32 s36, s26, s69
	s_cselect_b32 s71, s29, s67
	s_cselect_b32 s70, s28, s15
	s_add_i32 s69, 0, 0x14000
	v_add_u32_e32 v158, s72, v3
	v_add_u32_e32 v174, s69, v3
	ds_read_b128 v[146:149], v158
	ds_read_b128 v[150:153], v158 offset:1024
	ds_read_b128 v[154:157], v158 offset:2048
	ds_read_b128 v[158:161], v158 offset:3072
	ds_read_b128 v[162:165], v174
	ds_read_b128 v[166:169], v174 offset:1024
	ds_read_b128 v[170:173], v174 offset:2048
	ds_read_b128 v[174:177], v174 offset:3072
	v_lshl_add_u64 v[194:195], s[34:35], 0, v[140:141]
	s_add_i32 m0, s53, 0xc000
	ds_read_b128 v[178:181], v144
	ds_read_b128 v[182:185], v144 offset:1024
	ds_read_b128 v[186:189], v144 offset:2048
	ds_read_b128 v[190:193], v144 offset:3072
	ds_read_b128 v[202:205], v144 offset:4096
	ds_read_b128 v[206:209], v144 offset:5120
	ds_read_b128 v[210:213], v144 offset:6144
	ds_read_b128 v[214:217], v144 offset:7168
	global_load_lds_dwordx4 v[194:195], off
	v_lshl_add_u64 v[194:195], s[34:35], 0, v[142:143]
	s_add_i32 m0, s53, 0xe000
	s_nop 0
	global_load_lds_dwordx4 v[194:195], off
	s_waitcnt vmcnt(8)
	s_waitcnt lgkmcnt(0)
	s_barrier
; #define PG8_GOFFS(slot_) do { _Pragma("unroll") for (int _i = 0; _i < 2; ++_i) { int R, C; stage_rc(tid * 16 + _i * 8192, R, C); _Pragma("unroll") for (int _h = 0; _h < 2; ++_h) { \
;         unsigned t_ = gtab[(slot_) * 256 + R + 128 * _h]; t_ = t_ < (unsigned)(T - 1) ? t_ : (unsigned)(T - 1); voffA[_h][_i] = (t_ * (unsigned)K + (unsigned)C) * 2u; } } } while (0)
; #define PG8_STAGE(bufoff, gbase, voff) do { _Pragma("unroll") for (int _i = 0; _i < 2; ++_i) \
;         __builtin_amdgcn_global_load_lds((const unsigned*)((const char*)(gbase) + (voff)[_i]), (LAS unsigned*)(lds + (bufoff) + ldsw + _i * 8192), 16, 0, 0); } while (0)
; #define PG8_STAGE_A1(bufoff, gbase) do { if (Epi::GATHER) PG8_STAGE(bufoff, gbase, voffA[1]); else PG8_STAGE(bufoff, (gbase) + hstep, voffA[0]); } while (0)
; #define PG8_LDA(dst, b, h) do { _Pragma("unroll") for (int m = 0; m < 4; ++m) _Pragma("unroll") for (int k = 0; k < 2; ++k) dst[m][k] = *(const LAS bf16x8*)(lds + PG8_SA(b, h) + aoff + m * 2048 + k * 1024); } while (0)
; #define PG8_WAIT_V(n) asm volatile("s_waitcnt vmcnt(" #n ")" ::: "memory")
; #define PG8_WAIT_L(n) asm volatile("s_waitcnt lgkmcnt(" #n ")" ::: "memory")
; template <class Epi, class Sched>
; __device__ __forceinline__ void gemm_phase(const int tid, LAS unsigned char* lds, const bf16* Aop, const bf16* Bop, const int K_, const Sched& S, const Epi& E, const bf16* Aop1 = nullptr, const bf16* Bop1 = nullptr) {
;     ...
;             PG8_LDB(B0, 0, 0); PG8_LDB(B1, 0, 1); PG8_SCHED; PG8_LDA(At, 0, 0); PG8_STAGE_A1(PG8_SA(1, 1), a1);
;             PG8_WAIT_V(8); PG8_WAIT_L(0); PG8_BAR; PG8_MMA(0, 0, At, B0); PG8_MMA(0, 1, At, B1); PG8_BAR; PG8_SCHED;
;             PG8_LDA(At, 0, 1); PG8_STAGE(PG8_SB(0, 0), b2, voffB); PG8_STAGE(PG8_SB(0, 1), b2 + hstep, voffB); if (Epi::GATHER && last && has_next) PG8_GOFFS((ui + 1) & 1); PG8_STAGE(PG8_SA(0, 0), a2, voffA[0]);
;             PG8_WAIT_V(8); PG8_WAIT_L(0); PG8_BAR; PG8_MMA(1, 0, At, B0); PG8_MMA(1, 1, At, B1); PG8_BAR; PG8_SCHED;
;             PG8_LDB(B0, 1, 0); PG8_LDB(B1, 1, 1); PG8_SCHED; PG8_LDA(At, 1, 0); PG8_STAGE_A1(PG8_SA(0, 1), a2);
;             PG8_WAIT_V(8); PG8_WAIT_L(0); PG8_BAR; PG8_MMA(0, 0, At, B0); PG8_MMA(0, 1, At, B1); PG8_BAR; PG8_SCHED;
;             PG8_LDA(At, 1, 1); PG8_STAGE(PG8_SB(1, 0), b3, voffB); PG8_STAGE(PG8_SB(1, 1), b3 + hstep, voffB); PG8_STAGE(PG8_SA(1, 0), a3, voffA[0]);
	s_nop 0
	s_waitcnt lgkmcnt(0)
	v_mfma_f32_16x16x32_bf16 v[124:127], v[146:149], v[178:181], v[124:127]
	v_mfma_f32_16x16x32_bf16 v[128:131], v[154:157], v[178:181], v[128:131]
	v_mfma_f32_16x16x32_bf16 v[112:115], v[146:149], v[186:189], v[112:115]
	v_mfma_f32_16x16x32_bf16 v[108:111], v[154:157], v[186:189], v[108:111]
	v_mfma_f32_16x16x32_bf16 v[96:99], v[146:149], v[202:205], v[96:99]
	v_mfma_f32_16x16x32_bf16 v[92:95], v[154:157], v[202:205], v[92:95]
	v_mfma_f32_16x16x32_bf16 v[80:83], v[146:149], v[210:213], v[80:83]
	v_mfma_f32_16x16x32_bf16 v[76:79], v[154:157], v[210:213], v[76:79]
	v_mfma_f32_16x16x32_bf16 v[124:127], v[150:153], v[182:185], v[124:127]
	v_mfma_f32_16x16x32_bf16 v[128:131], v[158:161], v[182:185], v[128:131]
	v_mfma_f32_16x16x32_bf16 v[112:115], v[150:153], v[190:193], v[112:115]
	v_mfma_f32_16x16x32_bf16 v[108:111], v[158:161], v[190:193], v[108:111]
	v_mfma_f32_16x16x32_bf16 v[96:99], v[150:153], v[206:209], v[96:99]
	v_mfma_f32_16x16x32_bf16 v[92:95], v[158:161], v[206:209], v[92:95]
	v_mfma_f32_16x16x32_bf16 v[80:83], v[150:153], v[214:217], v[80:83]
	v_mfma_f32_16x16x32_bf16 v[76:79], v[158:161], v[214:217], v[76:79]
	s_nop 0
	s_nop 0
	v_mfma_f32_16x16x32_bf16 v[120:123], v[162:165], v[178:181], v[120:123]
	v_mfma_f32_16x16x32_bf16 v[116:119], v[170:173], v[178:181], v[116:119]
	v_mfma_f32_16x16x32_bf16 v[104:107], v[162:165], v[186:189], v[104:107]
	v_mfma_f32_16x16x32_bf16 v[100:103], v[170:173], v[186:189], v[100:103]
	v_mfma_f32_16x16x32_bf16 v[88:91], v[162:165], v[202:205], v[88:91]
	v_mfma_f32_16x16x32_bf16 v[84:87], v[170:173], v[202:205], v[84:87]
	v_mfma_f32_16x16x32_bf16 v[72:75], v[162:165], v[210:213], v[72:75]
	v_mfma_f32_16x16x32_bf16 v[68:71], v[170:173], v[210:213], v[68:71]
	v_mfma_f32_16x16x32_bf16 v[120:123], v[166:169], v[182:185], v[120:123]
	v_mfma_f32_16x16x32_bf16 v[116:119], v[174:177], v[182:185], v[116:119]
	v_mfma_f32_16x16x32_bf16 v[104:107], v[166:169], v[190:193], v[104:107]
	v_mfma_f32_16x16x32_bf16 v[100:103], v[174:177], v[190:193], v[100:103]
	v_mfma_f32_16x16x32_bf16 v[88:91], v[166:169], v[206:209], v[88:91]
	v_mfma_f32_16x16x32_bf16 v[84:87], v[174:177], v[206:209], v[84:87]
	v_mfma_f32_16x16x32_bf16 v[72:75], v[166:169], v[214:217], v[72:75]
	v_mfma_f32_16x16x32_bf16 v[68:71], v[174:177], v[214:217], v[68:71]
	s_nop 0
	s_barrier
	s_add_i32 s72, s72, s52
	v_lshl_add_u64 v[194:195], s[70:71], 0, v[134:135]
	s_mov_b32 m0, s72
	ds_read_b128 v[178:181], v144 offset:16384
	ds_read_b128 v[182:185], v144 offset:17408
	ds_read_b128 v[186:189], v144 offset:18432
	ds_read_b128 v[190:193], v144 offset:19456
	ds_read_b128 v[202:205], v144 offset:20480
	ds_read_b128 v[206:209], v144 offset:21504
	ds_read_b128 v[210:213], v144 offset:22528
	ds_read_b128 v[214:217], v144 offset:23552
	global_load_lds_dwordx4 v[194:195], off
	s_add_i32 m0, s72, 0x2000
	v_lshl_add_u64 v[196:197], s[70:71], 0, v[0:1]
	s_add_u32 s70, s70, s6
	s_addc_u32 s71, s71, s7
	s_add_i32 s69, s69, s52
	global_load_lds_dwordx4 v[196:197], off
	v_lshl_add_u64 v[198:199], s[70:71], 0, v[134:135]
	s_mov_b32 m0, s69
	v_lshl_add_u64 v[218:219], s[70:71], 0, v[0:1]
	global_load_lds_dwordx4 v[198:199], off
	s_add_i32 m0, s69, 0x2000
	v_lshl_add_u64 v[220:221], s[36:37], 0, v[136:137]
	global_load_lds_dwordx4 v[218:219], off
	s_mov_b32 m0, s53
	v_lshl_add_u64 v[222:223], s[36:37], 0, v[132:133]
	global_load_lds_dwordx4 v[220:221], off
	s_mov_b32 m0, s54
	s_nop 0
	global_load_lds_dwordx4 v[222:223], off
	s_waitcnt vmcnt(8)
	s_waitcnt lgkmcnt(0)
	s_barrier
	s_nop 0
	s_waitcnt lgkmcnt(0)
	v_mfma_f32_16x16x32_bf16 v[64:67], v[146:149], v[178:181], v[64:67]
	v_mfma_f32_16x16x32_bf16 v[60:63], v[154:157], v[178:181], v[60:63]
	v_mfma_f32_16x16x32_bf16 v[48:51], v[146:149], v[186:189], v[48:51]
	v_mfma_f32_16x16x32_bf16 v[44:47], v[154:157], v[186:189], v[44:47]
	v_mfma_f32_16x16x32_bf16 v[32:35], v[146:149], v[202:205], v[32:35]
	v_mfma_f32_16x16x32_bf16 v[28:31], v[154:157], v[202:205], v[28:31]
	v_mfma_f32_16x16x32_bf16 v[16:19], v[146:149], v[210:213], v[16:19]
	v_mfma_f32_16x16x32_bf16 v[12:15], v[154:157], v[210:213], v[12:15]
	v_mfma_f32_16x16x32_bf16 v[64:67], v[150:153], v[182:185], v[64:67]
	v_mfma_f32_16x16x32_bf16 v[60:63], v[158:161], v[182:185], v[60:63]
	v_mfma_f32_16x16x32_bf16 v[48:51], v[150:153], v[190:193], v[48:51]
	v_mfma_f32_16x16x32_bf16 v[44:47], v[158:161], v[190:193], v[44:47]
	v_mfma_f32_16x16x32_bf16 v[32:35], v[150:153], v[206:209], v[32:35]
	v_mfma_f32_16x16x32_bf16 v[28:31], v[158:161], v[206:209], v[28:31]
	v_mfma_f32_16x16x32_bf16 v[16:19], v[150:153], v[214:217], v[16:19]
	v_mfma_f32_16x16x32_bf16 v[12:15], v[158:161], v[214:217], v[12:15]
	s_nop 0
	s_nop 0
	v_mfma_f32_16x16x32_bf16 v[56:59], v[162:165], v[178:181], v[56:59]
	v_mfma_f32_16x16x32_bf16 v[52:55], v[170:173], v[178:181], v[52:55]
	v_mfma_f32_16x16x32_bf16 v[40:43], v[162:165], v[186:189], v[40:43]
	v_mfma_f32_16x16x32_bf16 v[36:39], v[170:173], v[186:189], v[36:39]
	v_mfma_f32_16x16x32_bf16 v[24:27], v[162:165], v[202:205], v[24:27]
	v_mfma_f32_16x16x32_bf16 v[20:23], v[170:173], v[202:205], v[20:23]
	v_mfma_f32_16x16x32_bf16 v[8:11], v[162:165], v[210:213], v[8:11]
	v_mfma_f32_16x16x32_bf16 v[4:7], v[170:173], v[210:213], v[4:7]
	v_mfma_f32_16x16x32_bf16 v[56:59], v[166:169], v[182:185], v[56:59]
	v_mfma_f32_16x16x32_bf16 v[52:55], v[174:177], v[182:185], v[52:55]
	v_mfma_f32_16x16x32_bf16 v[40:43], v[166:169], v[190:193], v[40:43]
	v_mfma_f32_16x16x32_bf16 v[36:39], v[174:177], v[190:193], v[36:39]
	v_mfma_f32_16x16x32_bf16 v[24:27], v[166:169], v[206:209], v[24:27]
	v_mfma_f32_16x16x32_bf16 v[20:23], v[174:177], v[206:209], v[20:23]
	v_mfma_f32_16x16x32_bf16 v[8:11], v[166:169], v[214:217], v[8:11]
	v_mfma_f32_16x16x32_bf16 v[4:7], v[174:177], v[214:217], v[4:7]
	s_nop 0
	s_barrier
; #define PG8_STAGE(bufoff, gbase, voff) do { _Pragma("unroll") for (int _i = 0; _i < 2; ++_i) \
;         __builtin_amdgcn_global_load_lds((const unsigned*)((const char*)(gbase) + (voff)[_i]), (LAS unsigned*)(lds + (bufoff) + ldsw + _i * 8192), 16, 0, 0); } while (0)
; #define PG8_STAGE_A1(bufoff, gbase) do { if (Epi::GATHER) PG8_STAGE(bufoff, gbase, voffA[1]); else PG8_STAGE(bufoff, (gbase) + hstep, voffA[0]); } while (0)
; #define PG8_LDA(dst, b, h) do { _Pragma("unroll") for (int m = 0; m < 4; ++m) _Pragma("unroll") for (int k = 0; k < 2; ++k) dst[m][k] = *(const LAS bf16x8*)(lds + PG8_SA(b, h) + aoff + m * 2048 + k * 1024); } while (0)
; #define PG8_LDB(dst, b, h) do { _Pragma("unroll") for (int n = 0; n < 2; ++n) _Pragma("unroll") for (int k = 0; k < 2; ++k) dst[n][k] = *(const LAS bf16x8*)(lds + PG8_SB(b, h) + boff + n * 2048 + k * 1024); } while (0)
; #define PG8_MMA(ai, bj, At, Bt) do { __builtin_amdgcn_s_setprio(1); _Pragma("unroll") for (int m = 0; m < 4; ++m) _Pragma("unroll") for (int n = 0; n < 2; ++n) _Pragma("unroll") for (int k = 0; k < 2; ++k) \
;         acc[ai][bj][m][n] = __builtin_amdgcn_mfma_f32_16x16x32_bf16(Bt[n][k], At[m][k], acc[ai][bj][m][n], 0, 0, 0); __builtin_amdgcn_s_setprio(0); } while (0)
; #define PG8_WAIT_V(n) asm volatile("s_waitcnt vmcnt(" #n ")" ::: "memory")
; #define PG8_WAIT_L(n) asm volatile("s_waitcnt lgkmcnt(" #n ")" ::: "memory")
; #define PG8_BAR __builtin_amdgcn_s_barrier()
; #define PG8_SCHED __builtin_amdgcn_sched_barrier(0)
; template <class Epi, class Sched>
; __device__ __forceinline__ void gemm_phase(const int tid, LAS unsigned char* lds, const bf16* Aop, const bf16* Bop, const int K_, const Sched& S, const Epi& E, const bf16* Aop1 = nullptr, const bf16* Bop1 = nullptr) {
;     ...
;             PG8_LDB(B0, 1, 0); PG8_LDB(B1, 1, 1); PG8_SCHED; PG8_LDA(At, 1, 0); PG8_STAGE_A1(PG8_SA(0, 1), a2);
;             PG8_WAIT_V(8); PG8_WAIT_L(0); PG8_BAR; PG8_MMA(0, 0, At, B0); PG8_MMA(0, 1, At, B1); PG8_BAR; PG8_SCHED;
;             PG8_LDA(At, 1, 1); PG8_STAGE(PG8_SB(1, 0), b3, voffB); PG8_STAGE(PG8_SB(1, 1), b3 + hstep, voffB); PG8_STAGE(PG8_SA(1, 0), a3, voffA[0]);
;             PG8_WAIT_V(8); PG8_WAIT_L(0); PG8_BAR; PG8_MMA(1, 0, At, B0); PG8_MMA(1, 1, At, B1); PG8_BAR; PG8_SCHED;
	s_add_i32 s69, 0, 0x18000
	s_add_i32 s70, 0, 0x1c000
	v_add_u32_e32 v158, s69, v3
	v_add_u32_e32 v174, s70, v3
	ds_read_b128 v[146:149], v158
	ds_read_b128 v[150:153], v158 offset:1024
	ds_read_b128 v[154:157], v158 offset:2048
	ds_read_b128 v[158:161], v158 offset:3072
	ds_read_b128 v[162:165], v174
	ds_read_b128 v[166:169], v174 offset:1024
	ds_read_b128 v[170:173], v174 offset:2048
	ds_read_b128 v[174:177], v174 offset:3072
	s_add_u32 s36, s36, s6
	s_addc_u32 s37, s37, s7
	s_mov_b32 m0, s55
	v_lshl_add_u64 v[224:225], s[36:37], 0, v[136:137]
	ds_read_b128 v[178:181], v144 offset:32768
	ds_read_b128 v[182:185], v144 offset:33792
	ds_read_b128 v[186:189], v144 offset:34816
	ds_read_b128 v[190:193], v144 offset:35840
	ds_read_b128 v[202:205], v144 offset:36864
	ds_read_b128 v[206:209], v144 offset:37888
	ds_read_b128 v[210:213], v144 offset:38912
	ds_read_b128 v[214:217], v144 offset:39936
	global_load_lds_dwordx4 v[224:225], off
	v_lshl_add_u64 v[224:225], s[36:37], 0, v[132:133]
	s_mov_b32 m0, s56
	s_nop 0
	global_load_lds_dwordx4 v[224:225], off
	s_waitcnt vmcnt(8)
	s_waitcnt lgkmcnt(0)
	s_barrier
	s_nop 0
	s_waitcnt lgkmcnt(0)
	v_mfma_f32_16x16x32_bf16 v[124:127], v[146:149], v[178:181], v[124:127]
	v_mfma_f32_16x16x32_bf16 v[128:131], v[154:157], v[178:181], v[128:131]
	v_mfma_f32_16x16x32_bf16 v[112:115], v[146:149], v[186:189], v[112:115]
	v_mfma_f32_16x16x32_bf16 v[108:111], v[154:157], v[186:189], v[108:111]
	v_mfma_f32_16x16x32_bf16 v[96:99], v[146:149], v[202:205], v[96:99]
	v_mfma_f32_16x16x32_bf16 v[92:95], v[154:157], v[202:205], v[92:95]
	v_mfma_f32_16x16x32_bf16 v[80:83], v[146:149], v[210:213], v[80:83]
	v_mfma_f32_16x16x32_bf16 v[76:79], v[154:157], v[210:213], v[76:79]
	v_mfma_f32_16x16x32_bf16 v[124:127], v[150:153], v[182:185], v[124:127]
	v_mfma_f32_16x16x32_bf16 v[128:131], v[158:161], v[182:185], v[128:131]
	v_mfma_f32_16x16x32_bf16 v[112:115], v[150:153], v[190:193], v[112:115]
	v_mfma_f32_16x16x32_bf16 v[108:111], v[158:161], v[190:193], v[108:111]
	v_mfma_f32_16x16x32_bf16 v[96:99], v[150:153], v[206:209], v[96:99]
	v_mfma_f32_16x16x32_bf16 v[92:95], v[158:161], v[206:209], v[92:95]
	v_mfma_f32_16x16x32_bf16 v[80:83], v[150:153], v[214:217], v[80:83]
	v_mfma_f32_16x16x32_bf16 v[76:79], v[158:161], v[214:217], v[76:79]
	s_nop 0
	s_nop 0
	v_mfma_f32_16x16x32_bf16 v[120:123], v[162:165], v[178:181], v[120:123]
	v_mfma_f32_16x16x32_bf16 v[116:119], v[170:173], v[178:181], v[116:119]
	v_mfma_f32_16x16x32_bf16 v[104:107], v[162:165], v[186:189], v[104:107]
	v_mfma_f32_16x16x32_bf16 v[100:103], v[170:173], v[186:189], v[100:103]
	v_mfma_f32_16x16x32_bf16 v[88:91], v[162:165], v[202:205], v[88:91]
	v_mfma_f32_16x16x32_bf16 v[84:87], v[170:173], v[202:205], v[84:87]
	v_mfma_f32_16x16x32_bf16 v[72:75], v[162:165], v[210:213], v[72:75]
	v_mfma_f32_16x16x32_bf16 v[68:71], v[170:173], v[210:213], v[68:71]
	v_mfma_f32_16x16x32_bf16 v[120:123], v[166:169], v[182:185], v[120:123]
	v_mfma_f32_16x16x32_bf16 v[116:119], v[174:177], v[182:185], v[116:119]
	v_mfma_f32_16x16x32_bf16 v[104:107], v[166:169], v[190:193], v[104:107]
	v_mfma_f32_16x16x32_bf16 v[100:103], v[174:177], v[190:193], v[100:103]
	v_mfma_f32_16x16x32_bf16 v[88:91], v[166:169], v[206:209], v[88:91]
	v_mfma_f32_16x16x32_bf16 v[84:87], v[174:177], v[206:209], v[84:87]
	v_mfma_f32_16x16x32_bf16 v[72:75], v[166:169], v[214:217], v[72:75]
	v_mfma_f32_16x16x32_bf16 v[68:71], v[174:177], v[214:217], v[68:71]
	s_nop 0
	s_barrier
; #define PG8_STAGE(bufoff, gbase, voff) do { _Pragma("unroll") for (int _i = 0; _i < 2; ++_i) \
;         __builtin_amdgcn_global_load_lds((const unsigned*)((const char*)(gbase) + (voff)[_i]), (LAS unsigned*)(lds + (bufoff) + ldsw + _i * 8192), 16, 0, 0); } while (0)
; #define PG8_STAGE_A1(bufoff, gbase) do { if (Epi::GATHER) PG8_STAGE(bufoff, gbase, voffA[1]); else PG8_STAGE(bufoff, (gbase) + hstep, voffA[0]); } while (0)
; #define PG8_LDA(dst, b, h) do { _Pragma("unroll") for (int m = 0; m < 4; ++m) _Pragma("unroll") for (int k = 0; k < 2; ++k) dst[m][k] = *(const LAS bf16x8*)(lds + PG8_SA(b, h) + aoff + m * 2048 + k * 1024); } while (0)
; #define PG8_LDB(dst, b, h) do { _Pragma("unroll") for (int n = 0; n < 2; ++n) _Pragma("unroll") for (int k = 0; k < 2; ++k) dst[n][k] = *(const LAS bf16x8*)(lds + PG8_SB(b, h) + boff + n * 2048 + k * 1024); } while (0)
; #define PG8_MMA(ai, bj, At, Bt) do { __builtin_amdgcn_s_setprio(1); _Pragma("unroll") for (int m = 0; m < 4; ++m) _Pragma("unroll") for (int n = 0; n < 2; ++n) _Pragma("unroll") for (int k = 0; k < 2; ++k) \
;         acc[ai][bj][m][n] = __builtin_amdgcn_mfma_f32_16x16x32_bf16(Bt[n][k], At[m][k], acc[ai][bj][m][n], 0, 0, 0); __builtin_amdgcn_s_setprio(0); } while (0)
; #define PG8_WAIT_V(n) asm volatile("s_waitcnt vmcnt(" #n ")" ::: "memory")
; #define PG8_WAIT_L(n) asm volatile("s_waitcnt lgkmcnt(" #n ")" ::: "memory")
; #define PG8_BAR __builtin_amdgcn_s_barrier()
; #define PG8_SCHED __builtin_amdgcn_sched_barrier(0)
; template <class Epi, class Sched>
; __device__ __forceinline__ void gemm_phase(const int tid, LAS unsigned char* lds, const bf16* Aop, const bf16* Bop, const int K_, const Sched& S, const Epi& E, const bf16* Aop1 = nullptr, const bf16* Bop1 = nullptr) {
;     ...
;             PG8_LDB(B0, 1, 0); PG8_LDB(B1, 1, 1); PG8_SCHED; PG8_LDA(At, 1, 0); PG8_STAGE_A1(PG8_SA(0, 1), a2);
;             PG8_WAIT_V(8); PG8_WAIT_L(0); PG8_BAR; PG8_MMA(0, 0, At, B0); PG8_MMA(0, 1, At, B1); PG8_BAR; PG8_SCHED;
;             PG8_LDA(At, 1, 1); PG8_STAGE(PG8_SB(1, 0), b3, voffB); PG8_STAGE(PG8_SB(1, 1), b3 + hstep, voffB); PG8_STAGE(PG8_SA(1, 0), a3, voffA[0]);
;             PG8_WAIT_V(8); PG8_WAIT_L(0); PG8_BAR; PG8_MMA(1, 0, At, B0); PG8_MMA(1, 1, At, B1); PG8_BAR; PG8_SCHED;
;         }
	s_add_i32 s36, s69, s52
	v_lshl_add_u64 v[194:195], v[194:195], 0, s[20:21]
	s_mov_b32 m0, s36
	ds_read_b128 v[178:181], v144 offset:49152
	ds_read_b128 v[182:185], v144 offset:50176
	ds_read_b128 v[186:189], v144 offset:51200
	ds_read_b128 v[190:193], v144 offset:52224
	ds_read_b128 v[202:205], v144 offset:53248
	ds_read_b128 v[206:209], v144 offset:54272
	ds_read_b128 v[210:213], v144 offset:55296
	ds_read_b128 v[214:217], v144 offset:56320
	global_load_lds_dwordx4 v[194:195], off
	v_lshl_add_u64 v[194:195], v[196:197], 0, s[20:21]
	s_add_i32 m0, s36, 0x2000
	s_add_i32 s36, s70, s52
	global_load_lds_dwordx4 v[194:195], off
	v_lshl_add_u64 v[194:195], v[198:199], 0, s[20:21]
	s_mov_b32 m0, s36
	s_nop 0
	global_load_lds_dwordx4 v[194:195], off
	v_lshl_add_u64 v[194:195], v[218:219], 0, s[20:21]
	s_add_i32 m0, s36, 0x2000
	s_nop 0
	global_load_lds_dwordx4 v[194:195], off
	v_lshl_add_u64 v[194:195], v[220:221], 0, s[20:21]
	s_mov_b32 m0, s59
	s_nop 0
	global_load_lds_dwordx4 v[194:195], off
	v_lshl_add_u64 v[194:195], v[222:223], 0, s[20:21]
	s_mov_b32 m0, s60
	s_nop 0
	global_load_lds_dwordx4 v[194:195], off
	s_waitcnt vmcnt(8)
	s_waitcnt lgkmcnt(0)
	s_barrier
	s_nop 0
	s_waitcnt lgkmcnt(0)
	v_mfma_f32_16x16x32_bf16 v[64:67], v[146:149], v[178:181], v[64:67]
	v_mfma_f32_16x16x32_bf16 v[60:63], v[154:157], v[178:181], v[60:63]
	v_mfma_f32_16x16x32_bf16 v[48:51], v[146:149], v[186:189], v[48:51]
	v_mfma_f32_16x16x32_bf16 v[44:47], v[154:157], v[186:189], v[44:47]
	v_mfma_f32_16x16x32_bf16 v[32:35], v[146:149], v[202:205], v[32:35]
	v_mfma_f32_16x16x32_bf16 v[28:31], v[154:157], v[202:205], v[28:31]
	v_mfma_f32_16x16x32_bf16 v[16:19], v[146:149], v[210:213], v[16:19]
	v_mfma_f32_16x16x32_bf16 v[12:15], v[154:157], v[210:213], v[12:15]
	v_mfma_f32_16x16x32_bf16 v[64:67], v[150:153], v[182:185], v[64:67]
	v_mfma_f32_16x16x32_bf16 v[60:63], v[158:161], v[182:185], v[60:63]
	v_mfma_f32_16x16x32_bf16 v[48:51], v[150:153], v[190:193], v[48:51]
	v_mfma_f32_16x16x32_bf16 v[44:47], v[158:161], v[190:193], v[44:47]
	v_mfma_f32_16x16x32_bf16 v[32:35], v[150:153], v[206:209], v[32:35]
	v_mfma_f32_16x16x32_bf16 v[28:31], v[158:161], v[206:209], v[28:31]
	v_mfma_f32_16x16x32_bf16 v[16:19], v[150:153], v[214:217], v[16:19]
	v_mfma_f32_16x16x32_bf16 v[12:15], v[158:161], v[214:217], v[12:15]
	s_nop 0
	s_nop 0
	v_mfma_f32_16x16x32_bf16 v[56:59], v[162:165], v[178:181], v[56:59]
	v_mfma_f32_16x16x32_bf16 v[52:55], v[170:173], v[178:181], v[52:55]
	v_mfma_f32_16x16x32_bf16 v[40:43], v[162:165], v[186:189], v[40:43]
	v_mfma_f32_16x16x32_bf16 v[36:39], v[170:173], v[186:189], v[36:39]
	v_mfma_f32_16x16x32_bf16 v[24:27], v[162:165], v[202:205], v[24:27]
	v_mfma_f32_16x16x32_bf16 v[20:23], v[170:173], v[202:205], v[20:23]
	v_mfma_f32_16x16x32_bf16 v[8:11], v[162:165], v[210:213], v[8:11]
	v_mfma_f32_16x16x32_bf16 v[4:7], v[170:173], v[210:213], v[4:7]
	v_mfma_f32_16x16x32_bf16 v[56:59], v[166:169], v[182:185], v[56:59]
	v_mfma_f32_16x16x32_bf16 v[52:55], v[174:177], v[182:185], v[52:55]
	v_mfma_f32_16x16x32_bf16 v[40:43], v[166:169], v[190:193], v[40:43]
	v_mfma_f32_16x16x32_bf16 v[36:39], v[174:177], v[190:193], v[36:39]
	v_mfma_f32_16x16x32_bf16 v[24:27], v[166:169], v[206:209], v[24:27]
	v_mfma_f32_16x16x32_bf16 v[20:23], v[174:177], v[206:209], v[20:23]
	v_mfma_f32_16x16x32_bf16 v[8:11], v[166:169], v[214:217], v[8:11]
	v_mfma_f32_16x16x32_bf16 v[4:7], v[174:177], v[214:217], v[4:7]
	s_nop 0
	s_barrier
	s_add_u32 s34, s34, 0x100
	s_addc_u32 s35, s35, 0
	s_add_u32 s15, s15, 0x100
	s_addc_u32 s67, s67, 0
	s_cmp_ge_i32 s68, s58
	s_mov_b32 s36, s68
	s_cbranch_scc0 .LBB0_1420

; #define LAS __attribute__((address_space(3)))
;     __device__ bool next(int i, Unit& u) const { if (!so.next(i >> 1, u)) return false; u.sel = i & 1; return true; }
;     __device__ bool next(int i, Unit& u) const { const int L = i * nw + r; if (L >= nu) return false; u.pm = L >> 2; u.pn = L & 3; u.pb = u.pn; u.sel = 0; return true; }
; #define PG8_STAGE(bufoff, gbase, voff) do { _Pragma("unroll") for (int _i = 0; _i < 2; ++_i) \
;         __builtin_amdgcn_global_load_lds((const unsigned*)((const char*)(gbase) + (voff)[_i]), (LAS unsigned*)(lds + (bufoff) + ldsw + _i * 8192), 16, 0, 0); } while (0)
; template <class Epi, class Sched>
; __device__ __forceinline__ void gemm_phase(const int tid, LAS unsigned char* lds, const bf16* Aop, const bf16* Bop, const int K_, const Sched& S, const Epi& E, const bf16* Aop1 = nullptr, const bf16* Bop1 = nullptr) {
;     ...
;     for (;;) {
;         const bool has_next = S.next(ui + 1, nxt);
;         if (Epi::GATHER && has_next && wid < 4) E.tok_dma(nxt.pm * 256 + wid * 64, (LAS unsigned*)(lds + 8 * HTB) + ((ui + 1) & 1) * 256 + wid * 64, lane);
;         const char* nA = has_next ? (const char*)((Aop1 && nxt.sel) ? Aop1 : Aop) + (Epi::GATHER ? (size_t)0 : (size_t)nxt.pm * tstep) : cA; const char* nB = has_next ? (const char*)((Bop1 && nxt.sel) ? Bop1 : Bop) + (size_t)nxt.pb * tstep : cB;
;         for (int t = 0; t < nt; t += 2) {
;             const bool last = (t == nt - 2);
;             const char* a1 = cA + (size_t)(t + 1) * kstep;
;             const char* a2 = last ? nA : cA + (size_t)(t + 2) * kstep; const char* b2 = last ? nB : cB + (size_t)(t + 2) * kstep;
;             const char* a3 = a2 + kstep; const char* b3 = b2 + kstep;
;             PG8_LDB(B0, 0, 0); PG8_LDB(B1, 0, 1); PG8_SCHED; PG8_LDA(At, 0, 0); PG8_STAGE_A1(PG8_SA(1, 1), a1);
;             PG8_WAIT_V(8); PG8_WAIT_L(0); PG8_BAR; PG8_MMA(0, 0, At, B0); PG8_MMA(0, 1, At, B1); PG8_BAR; PG8_SCHED;
;             PG8_LDA(At, 0, 1); PG8_STAGE(PG8_SB(0, 0), b2, voffB); PG8_STAGE(PG8_SB(0, 1), b2 + hstep, voffB); if (Epi::GATHER && last && has_next) PG8_GOFFS((ui + 1) & 1); PG8_STAGE(PG8_SA(0, 0), a2, voffA[0]);
;             PG8_WAIT_V(8); PG8_WAIT_L(0); PG8_BAR; PG8_MMA(1, 0, At, B0); PG8_MMA(1, 1, At, B1); PG8_BAR; PG8_SCHED;
;             PG8_LDB(B0, 1, 0); PG8_LDB(B1, 1, 1); PG8_SCHED; PG8_LDA(At, 1, 0); PG8_STAGE_A1(PG8_SA(0, 1), a2);
.LBB0_1595:
	v_mov_b32_e32 v131, 0
	s_andn2_b64 vcc, exec, s[64:65]
	s_cbranch_vccnz .LBB0_1598
	s_add_u32 s2, s2, 0x80
	s_addc_u32 s3, s3, 0
	s_add_u32 s6, s4, 0x100
	s_addc_u32 s7, s5, 0
	s_mov_b32 s4, 0
	s_add_i32 s72, s4, 2
	s_add_u32 s73, s2, 0x80
	s_addc_u32 s5, s3, 0
	s_add_i32 s76, 0, 0x10000
	s_cmp_eq_u32 s37, s4
	s_cselect_b32 s5, s41, s5
	s_cselect_b32 s4, s40, s73
	v_add_u32_e32 v158, s76, v160
	s_cselect_b32 s75, s69, s7
	s_cselect_b32 s74, s68, s6
	s_add_i32 s73, 0, 0x14000
	ds_read_b128 v[132:135], v158
	ds_read_b128 v[136:139], v158 offset:1024
	ds_read_b128 v[154:157], v158 offset:2048
	ds_read_b128 v[164:167], v158 offset:3072
	v_add_u32_e32 v158, s73, v160
	ds_read_b128 v[168:171], v158
	ds_read_b128 v[172:175], v158 offset:1024
	ds_read_b128 v[176:179], v158 offset:2048
	ds_read_b128 v[180:183], v158 offset:3072
	v_lshl_add_u64 v[158:159], s[2:3], 0, v[150:151]
	s_add_i32 m0, s17, 0xc000
	ds_read_b128 v[184:187], v162
	ds_read_b128 v[188:191], v162 offset:1024
	ds_read_b128 v[192:195], v162 offset:2048
	ds_read_b128 v[202:205], v162 offset:3072
	ds_read_b128 v[206:209], v162 offset:4096
	ds_read_b128 v[210:213], v162 offset:5120
	ds_read_b128 v[214:217], v162 offset:6144
	ds_read_b128 v[218:221], v162 offset:7168
	global_load_lds_dwordx4 v[158:159], off
	v_lshl_add_u64 v[158:159], s[2:3], 0, v[152:153]
	s_add_i32 m0, s17, 0xe000
	s_nop 0
	global_load_lds_dwordx4 v[158:159], off
	s_waitcnt vmcnt(8)
	s_waitcnt lgkmcnt(0)
	s_barrier
	s_nop 0
	s_waitcnt lgkmcnt(0)
	v_mfma_f32_16x16x32_bf16 v[128:131], v[132:135], v[184:187], 0
	v_mfma_f32_16x16x32_bf16 v[124:127], v[154:157], v[184:187], 0
	v_mfma_f32_16x16x32_bf16 v[112:115], v[132:135], v[192:195], 0
	v_mfma_f32_16x16x32_bf16 v[108:111], v[154:157], v[192:195], 0
	v_mfma_f32_16x16x32_bf16 v[96:99], v[132:135], v[206:209], 0
	v_mfma_f32_16x16x32_bf16 v[92:95], v[154:157], v[206:209], 0
	v_mfma_f32_16x16x32_bf16 v[80:83], v[132:135], v[214:217], 0
	v_mfma_f32_16x16x32_bf16 v[76:79], v[154:157], v[214:217], 0
	v_mfma_f32_16x16x32_bf16 v[128:131], v[136:139], v[188:191], v[128:131]
	v_mfma_f32_16x16x32_bf16 v[124:127], v[164:167], v[188:191], v[124:127]
	v_mfma_f32_16x16x32_bf16 v[112:115], v[136:139], v[202:205], v[112:115]
	v_mfma_f32_16x16x32_bf16 v[108:111], v[164:167], v[202:205], v[108:111]
	v_mfma_f32_16x16x32_bf16 v[96:99], v[136:139], v[210:213], v[96:99]
	v_mfma_f32_16x16x32_bf16 v[92:95], v[164:167], v[210:213], v[92:95]
	v_mfma_f32_16x16x32_bf16 v[80:83], v[136:139], v[218:221], v[80:83]
	v_mfma_f32_16x16x32_bf16 v[76:79], v[164:167], v[218:221], v[76:79]
	s_nop 0
	s_nop 0
	v_mfma_f32_16x16x32_bf16 v[120:123], v[168:171], v[184:187], 0
	v_mfma_f32_16x16x32_bf16 v[116:119], v[176:179], v[184:187], 0
	v_mfma_f32_16x16x32_bf16 v[104:107], v[168:171], v[192:195], 0
	v_mfma_f32_16x16x32_bf16 v[100:103], v[176:179], v[192:195], 0
	v_mfma_f32_16x16x32_bf16 v[88:91], v[168:171], v[206:209], 0
	v_mfma_f32_16x16x32_bf16 v[84:87], v[176:179], v[206:209], 0
	v_mfma_f32_16x16x32_bf16 v[72:75], v[168:171], v[214:217], 0
	v_mfma_f32_16x16x32_bf16 v[68:71], v[176:179], v[214:217], 0
	v_mfma_f32_16x16x32_bf16 v[120:123], v[172:175], v[188:191], v[120:123]
	v_mfma_f32_16x16x32_bf16 v[116:119], v[180:183], v[188:191], v[116:119]
	v_mfma_f32_16x16x32_bf16 v[104:107], v[172:175], v[202:205], v[104:107]
	v_mfma_f32_16x16x32_bf16 v[100:103], v[180:183], v[202:205], v[100:103]
	v_mfma_f32_16x16x32_bf16 v[88:91], v[172:175], v[210:213], v[88:91]
	v_mfma_f32_16x16x32_bf16 v[84:87], v[180:183], v[210:213], v[84:87]
	v_mfma_f32_16x16x32_bf16 v[72:75], v[172:175], v[218:221], v[72:75]
	v_mfma_f32_16x16x32_bf16 v[68:71], v[180:183], v[218:221], v[68:71]
	s_nop 0
	s_barrier
	s_add_i32 s76, s76, s16
	v_lshl_add_u64 v[158:159], s[74:75], 0, v[142:143]
	s_mov_b32 m0, s76
	ds_read_b128 v[184:187], v162 offset:16384
	ds_read_b128 v[188:191], v162 offset:17408
	ds_read_b128 v[192:195], v162 offset:18432
	ds_read_b128 v[202:205], v162 offset:19456
	ds_read_b128 v[206:209], v162 offset:20480
	ds_read_b128 v[210:213], v162 offset:21504
	ds_read_b128 v[214:217], v162 offset:22528
	ds_read_b128 v[218:221], v162 offset:23552
	global_load_lds_dwordx4 v[158:159], off
	s_add_i32 m0, s76, 0x2000
	v_lshl_add_u64 v[196:197], s[74:75], 0, v[146:147]
	s_add_u32 s74, s74, s58
	s_addc_u32 s75, s75, s59
	s_add_i32 s73, s73, s16
	global_load_lds_dwordx4 v[196:197], off
	v_lshl_add_u64 v[198:199], s[74:75], 0, v[142:143]
	s_mov_b32 m0, s73
	v_lshl_add_u64 v[222:223], s[74:75], 0, v[146:147]
	global_load_lds_dwordx4 v[198:199], off
	s_add_i32 m0, s73, 0x2000
	v_lshl_add_u64 v[224:225], s[4:5], 0, v[140:141]
	global_load_lds_dwordx4 v[222:223], off
	s_mov_b32 m0, s17
	v_lshl_add_u64 v[230:231], s[4:5], 0, v[144:145]
	global_load_lds_dwordx4 v[224:225], off
	s_mov_b32 m0, s28
	s_nop 0
	global_load_lds_dwordx4 v[230:231], off
	s_waitcnt vmcnt(8)
	s_waitcnt lgkmcnt(0)
	s_barrier
; #define PG8_GOFFS(slot_) do { _Pragma("unroll") for (int _i = 0; _i < 2; ++_i) { int R, C; stage_rc(tid * 16 + _i * 8192, R, C); _Pragma("unroll") for (int _h = 0; _h < 2; ++_h) { \
;         unsigned t_ = gtab[(slot_) * 256 + R + 128 * _h]; t_ = t_ < (unsigned)(T - 1) ? t_ : (unsigned)(T - 1); voffA[_h][_i] = (t_ * (unsigned)K + (unsigned)C) * 2u; } } } while (0)
; #define PG8_STAGE(bufoff, gbase, voff) do { _Pragma("unroll") for (int _i = 0; _i < 2; ++_i) \
;         __builtin_amdgcn_global_load_lds((const unsigned*)((const char*)(gbase) + (voff)[_i]), (LAS unsigned*)(lds + (bufoff) + ldsw + _i * 8192), 16, 0, 0); } while (0)
; #define PG8_STAGE_A1(bufoff, gbase) do { if (Epi::GATHER) PG8_STAGE(bufoff, gbase, voffA[1]); else PG8_STAGE(bufoff, (gbase) + hstep, voffA[0]); } while (0)
; #define PG8_LDA(dst, b, h) do { _Pragma("unroll") for (int m = 0; m < 4; ++m) _Pragma("unroll") for (int k = 0; k < 2; ++k) dst[m][k] = *(const LAS bf16x8*)(lds + PG8_SA(b, h) + aoff + m * 2048 + k * 1024); } while (0)
; #define PG8_LDB(dst, b, h) do { _Pragma("unroll") for (int n = 0; n < 2; ++n) _Pragma("unroll") for (int k = 0; k < 2; ++k) dst[n][k] = *(const LAS bf16x8*)(lds + PG8_SB(b, h) + boff + n * 2048 + k * 1024); } while (0)
; #define PG8_WAIT_V(n) asm volatile("s_waitcnt vmcnt(" #n ")" ::: "memory")
; #define PG8_WAIT_L(n) asm volatile("s_waitcnt lgkmcnt(" #n ")" ::: "memory")
; template <class Epi, class Sched>
; __device__ __forceinline__ void gemm_phase(const int tid, LAS unsigned char* lds, const bf16* Aop, const bf16* Bop, const int K_, const Sched& S, const Epi& E, const bf16* Aop1 = nullptr, const bf16* Bop1 = nullptr) {
;     ...
;             PG8_LDA(At, 0, 1); PG8_STAGE(PG8_SB(0, 0), b2, voffB); PG8_STAGE(PG8_SB(0, 1), b2 + hstep, voffB); if (Epi::GATHER && last && has_next) PG8_GOFFS((ui + 1) & 1); PG8_STAGE(PG8_SA(0, 0), a2, voffA[0]);
;             PG8_WAIT_V(8); PG8_WAIT_L(0); PG8_BAR; PG8_MMA(1, 0, At, B0); PG8_MMA(1, 1, At, B1); PG8_BAR; PG8_SCHED;
;             PG8_LDB(B0, 1, 0); PG8_LDB(B1, 1, 1); PG8_SCHED; PG8_LDA(At, 1, 0); PG8_STAGE_A1(PG8_SA(0, 1), a2);
;             PG8_WAIT_V(8); PG8_WAIT_L(0); PG8_BAR; PG8_MMA(0, 0, At, B0); PG8_MMA(0, 1, At, B1); PG8_BAR; PG8_SCHED;
;             PG8_LDA(At, 1, 1); PG8_STAGE(PG8_SB(1, 0), b3, voffB); PG8_STAGE(PG8_SB(1, 1), b3 + hstep, voffB); PG8_STAGE(PG8_SA(1, 0), a3, voffA[0]);
	s_nop 0
	s_waitcnt lgkmcnt(0)
	v_mfma_f32_16x16x32_bf16 v[64:67], v[132:135], v[184:187], 0
	v_mfma_f32_16x16x32_bf16 v[60:63], v[154:157], v[184:187], 0
	v_mfma_f32_16x16x32_bf16 v[48:51], v[132:135], v[192:195], 0
	v_mfma_f32_16x16x32_bf16 v[44:47], v[154:157], v[192:195], 0
	v_mfma_f32_16x16x32_bf16 v[32:35], v[132:135], v[206:209], 0
	v_mfma_f32_16x16x32_bf16 v[28:31], v[154:157], v[206:209], 0
	v_mfma_f32_16x16x32_bf16 v[16:19], v[132:135], v[214:217], 0
	v_mfma_f32_16x16x32_bf16 v[12:15], v[154:157], v[214:217], 0
	v_mfma_f32_16x16x32_bf16 v[64:67], v[136:139], v[188:191], v[64:67]
	v_mfma_f32_16x16x32_bf16 v[60:63], v[164:167], v[188:191], v[60:63]
	v_mfma_f32_16x16x32_bf16 v[48:51], v[136:139], v[202:205], v[48:51]
	v_mfma_f32_16x16x32_bf16 v[44:47], v[164:167], v[202:205], v[44:47]
	v_mfma_f32_16x16x32_bf16 v[32:35], v[136:139], v[210:213], v[32:35]
	v_mfma_f32_16x16x32_bf16 v[28:31], v[164:167], v[210:213], v[28:31]
	v_mfma_f32_16x16x32_bf16 v[16:19], v[136:139], v[218:221], v[16:19]
	v_mfma_f32_16x16x32_bf16 v[12:15], v[164:167], v[218:221], v[12:15]
	s_nop 0
	s_nop 0
	v_mfma_f32_16x16x32_bf16 v[56:59], v[168:171], v[184:187], 0
	v_mfma_f32_16x16x32_bf16 v[52:55], v[176:179], v[184:187], 0
	v_mfma_f32_16x16x32_bf16 v[40:43], v[168:171], v[192:195], 0
	v_mfma_f32_16x16x32_bf16 v[36:39], v[176:179], v[192:195], 0
	v_mfma_f32_16x16x32_bf16 v[24:27], v[168:171], v[206:209], 0
	v_mfma_f32_16x16x32_bf16 v[20:23], v[176:179], v[206:209], 0
	v_mfma_f32_16x16x32_bf16 v[8:11], v[168:171], v[214:217], 0
	v_mfma_f32_16x16x32_bf16 v[4:7], v[176:179], v[214:217], 0
	v_mfma_f32_16x16x32_bf16 v[56:59], v[172:175], v[188:191], v[56:59]
	v_mfma_f32_16x16x32_bf16 v[52:55], v[180:183], v[188:191], v[52:55]
	v_mfma_f32_16x16x32_bf16 v[40:43], v[172:175], v[202:205], v[40:43]
	v_mfma_f32_16x16x32_bf16 v[36:39], v[180:183], v[202:205], v[36:39]
	v_mfma_f32_16x16x32_bf16 v[24:27], v[172:175], v[210:213], v[24:27]
	v_mfma_f32_16x16x32_bf16 v[20:23], v[180:183], v[210:213], v[20:23]
	v_mfma_f32_16x16x32_bf16 v[8:11], v[172:175], v[218:221], v[8:11]
	v_mfma_f32_16x16x32_bf16 v[4:7], v[180:183], v[218:221], v[4:7]
	s_nop 0
	s_barrier
	s_add_i32 s73, 0, 0x18000
	v_add_u32_e32 v163, s73, v160
	s_add_i32 s74, 0, 0x1c000
	ds_read_b128 v[132:135], v163
	ds_read_b128 v[136:139], v163 offset:1024
	ds_read_b128 v[154:157], v163 offset:2048
	ds_read_b128 v[164:167], v163 offset:3072
	v_add_u32_e32 v163, s74, v160
	ds_read_b128 v[168:171], v163
	ds_read_b128 v[172:175], v163 offset:1024
	ds_read_b128 v[176:179], v163 offset:2048
	ds_read_b128 v[180:183], v163 offset:3072
	s_add_u32 s4, s4, s58
	s_addc_u32 s5, s5, s59
	s_mov_b32 m0, s29
	v_lshl_add_u64 v[232:233], s[4:5], 0, v[140:141]
	ds_read_b128 v[184:187], v162 offset:32768
	ds_read_b128 v[188:191], v162 offset:33792
	ds_read_b128 v[192:195], v162 offset:34816
	ds_read_b128 v[202:205], v162 offset:35840
	ds_read_b128 v[206:209], v162 offset:36864
	ds_read_b128 v[210:213], v162 offset:37888
	ds_read_b128 v[214:217], v162 offset:38912
	ds_read_b128 v[218:221], v162 offset:39936
	global_load_lds_dwordx4 v[232:233], off
	v_lshl_add_u64 v[232:233], s[4:5], 0, v[144:145]
	s_mov_b32 m0, s34
	s_nop 0
	global_load_lds_dwordx4 v[232:233], off
	s_waitcnt vmcnt(8)
	s_waitcnt lgkmcnt(0)
	s_barrier
	s_nop 0
	s_waitcnt lgkmcnt(0)
	v_mfma_f32_16x16x32_bf16 v[128:131], v[132:135], v[184:187], v[128:131]
	v_mfma_f32_16x16x32_bf16 v[124:127], v[154:157], v[184:187], v[124:127]
	v_mfma_f32_16x16x32_bf16 v[112:115], v[132:135], v[192:195], v[112:115]
	v_mfma_f32_16x16x32_bf16 v[108:111], v[154:157], v[192:195], v[108:111]
	v_mfma_f32_16x16x32_bf16 v[96:99], v[132:135], v[206:209], v[96:99]
	v_mfma_f32_16x16x32_bf16 v[92:95], v[154:157], v[206:209], v[92:95]
	v_mfma_f32_16x16x32_bf16 v[80:83], v[132:135], v[214:217], v[80:83]
	v_mfma_f32_16x16x32_bf16 v[76:79], v[154:157], v[214:217], v[76:79]
	v_mfma_f32_16x16x32_bf16 v[128:131], v[136:139], v[188:191], v[128:131]
	v_mfma_f32_16x16x32_bf16 v[124:127], v[164:167], v[188:191], v[124:127]
	v_mfma_f32_16x16x32_bf16 v[112:115], v[136:139], v[202:205], v[112:115]
	v_mfma_f32_16x16x32_bf16 v[108:111], v[164:167], v[202:205], v[108:111]
	v_mfma_f32_16x16x32_bf16 v[96:99], v[136:139], v[210:213], v[96:99]
	v_mfma_f32_16x16x32_bf16 v[92:95], v[164:167], v[210:213], v[92:95]
	v_mfma_f32_16x16x32_bf16 v[80:83], v[136:139], v[218:221], v[80:83]
	v_mfma_f32_16x16x32_bf16 v[76:79], v[164:167], v[218:221], v[76:79]
	s_nop 0
	s_nop 0
	v_mfma_f32_16x16x32_bf16 v[120:123], v[168:171], v[184:187], v[120:123]
	v_mfma_f32_16x16x32_bf16 v[116:119], v[176:179], v[184:187], v[116:119]
	v_mfma_f32_16x16x32_bf16 v[104:107], v[168:171], v[192:195], v[104:107]
	v_mfma_f32_16x16x32_bf16 v[100:103], v[176:179], v[192:195], v[100:103]
	v_mfma_f32_16x16x32_bf16 v[88:91], v[168:171], v[206:209], v[88:91]
	v_mfma_f32_16x16x32_bf16 v[84:87], v[176:179], v[206:209], v[84:87]
	v_mfma_f32_16x16x32_bf16 v[72:75], v[168:171], v[214:217], v[72:75]
	v_mfma_f32_16x16x32_bf16 v[68:71], v[176:179], v[214:217], v[68:71]
	v_mfma_f32_16x16x32_bf16 v[120:123], v[172:175], v[188:191], v[120:123]
	v_mfma_f32_16x16x32_bf16 v[116:119], v[180:183], v[188:191], v[116:119]
	v_mfma_f32_16x16x32_bf16 v[104:107], v[172:175], v[202:205], v[104:107]
	v_mfma_f32_16x16x32_bf16 v[100:103], v[180:183], v[202:205], v[100:103]
	v_mfma_f32_16x16x32_bf16 v[88:91], v[172:175], v[210:213], v[88:91]
	v_mfma_f32_16x16x32_bf16 v[84:87], v[180:183], v[210:213], v[84:87]
	v_mfma_f32_16x16x32_bf16 v[72:75], v[172:175], v[218:221], v[72:75]
	v_mfma_f32_16x16x32_bf16 v[68:71], v[180:183], v[218:221], v[68:71]
	s_nop 0
	s_barrier
; #define PG8_STAGE(bufoff, gbase, voff) do { _Pragma("unroll") for (int _i = 0; _i < 2; ++_i) \
;         __builtin_amdgcn_global_load_lds((const unsigned*)((const char*)(gbase) + (voff)[_i]), (LAS unsigned*)(lds + (bufoff) + ldsw + _i * 8192), 16, 0, 0); } while (0)
; #define PG8_STAGE_A1(bufoff, gbase) do { if (Epi::GATHER) PG8_STAGE(bufoff, gbase, voffA[1]); else PG8_STAGE(bufoff, (gbase) + hstep, voffA[0]); } while (0)
; #define PG8_LDA(dst, b, h) do { _Pragma("unroll") for (int m = 0; m < 4; ++m) _Pragma("unroll") for (int k = 0; k < 2; ++k) dst[m][k] = *(const LAS bf16x8*)(lds + PG8_SA(b, h) + aoff + m * 2048 + k * 1024); } while (0)
; #define PG8_LDB(dst, b, h) do { _Pragma("unroll") for (int n = 0; n < 2; ++n) _Pragma("unroll") for (int k = 0; k < 2; ++k) dst[n][k] = *(const LAS bf16x8*)(lds + PG8_SB(b, h) + boff + n * 2048 + k * 1024); } while (0)
; #define PG8_MMA(ai, bj, At, Bt) do { __builtin_amdgcn_s_setprio(1); _Pragma("unroll") for (int m = 0; m < 4; ++m) _Pragma("unroll") for (int n = 0; n < 2; ++n) _Pragma("unroll") for (int k = 0; k < 2; ++k) \
;         acc[ai][bj][m][n] = __builtin_amdgcn_mfma_f32_16x16x32_bf16(Bt[n][k], At[m][k], acc[ai][bj][m][n], 0, 0, 0); __builtin_amdgcn_s_setprio(0); } while (0)
; #define PG8_WAIT_V(n) asm volatile("s_waitcnt vmcnt(" #n ")" ::: "memory")
; #define PG8_WAIT_L(n) asm volatile("s_waitcnt lgkmcnt(" #n ")" ::: "memory")
; #define PG8_BAR __builtin_amdgcn_s_barrier()
; #define PG8_SCHED __builtin_amdgcn_sched_barrier(0)
; template <class Epi, class Sched>
; __device__ __forceinline__ void gemm_phase(const int tid, LAS unsigned char* lds, const bf16* Aop, const bf16* Bop, const int K_, const Sched& S, const Epi& E, const bf16* Aop1 = nullptr, const bf16* Bop1 = nullptr) {
;     ...
;             PG8_LDB(B0, 1, 0); PG8_LDB(B1, 1, 1); PG8_SCHED; PG8_LDA(At, 1, 0); PG8_STAGE_A1(PG8_SA(0, 1), a2);
;             PG8_WAIT_V(8); PG8_WAIT_L(0); PG8_BAR; PG8_MMA(0, 0, At, B0); PG8_MMA(0, 1, At, B1); PG8_BAR; PG8_SCHED;
;             PG8_LDA(At, 1, 1); PG8_STAGE(PG8_SB(1, 0), b3, voffB); PG8_STAGE(PG8_SB(1, 1), b3 + hstep, voffB); PG8_STAGE(PG8_SA(1, 0), a3, voffA[0]);
;             PG8_WAIT_V(8); PG8_WAIT_L(0); PG8_BAR; PG8_MMA(1, 0, At, B0); PG8_MMA(1, 1, At, B1); PG8_BAR; PG8_SCHED;
;         }
	s_add_i32 s4, s73, s16
	v_lshl_add_u64 v[158:159], v[158:159], 0, s[20:21]
	s_mov_b32 m0, s4
	ds_read_b128 v[184:187], v162 offset:49152
	ds_read_b128 v[188:191], v162 offset:50176
	ds_read_b128 v[192:195], v162 offset:51200
	ds_read_b128 v[202:205], v162 offset:52224
	ds_read_b128 v[206:209], v162 offset:53248
	ds_read_b128 v[210:213], v162 offset:54272
	ds_read_b128 v[214:217], v162 offset:55296
	ds_read_b128 v[218:221], v162 offset:56320
	global_load_lds_dwordx4 v[158:159], off
	v_lshl_add_u64 v[158:159], v[196:197], 0, s[20:21]
	s_add_i32 m0, s4, 0x2000
	s_add_i32 s4, s74, s16
	global_load_lds_dwordx4 v[158:159], off
	v_lshl_add_u64 v[158:159], v[198:199], 0, s[20:21]
	s_mov_b32 m0, s4
	s_nop 0
	global_load_lds_dwordx4 v[158:159], off
	v_lshl_add_u64 v[158:159], v[222:223], 0, s[20:21]
	s_add_i32 m0, s4, 0x2000
	s_nop 0
	global_load_lds_dwordx4 v[158:159], off
	v_lshl_add_u64 v[158:159], v[224:225], 0, s[20:21]
	s_mov_b32 m0, s35
	s_nop 0
	global_load_lds_dwordx4 v[158:159], off
	v_lshl_add_u64 v[158:159], v[230:231], 0, s[20:21]
	s_mov_b32 m0, s36
	s_nop 0
	global_load_lds_dwordx4 v[158:159], off
	s_waitcnt vmcnt(8)
	s_waitcnt lgkmcnt(0)
	s_barrier
	s_nop 0
	s_waitcnt lgkmcnt(0)
	v_mfma_f32_16x16x32_bf16 v[64:67], v[132:135], v[184:187], v[64:67]
	v_mfma_f32_16x16x32_bf16 v[60:63], v[154:157], v[184:187], v[60:63]
	v_mfma_f32_16x16x32_bf16 v[48:51], v[132:135], v[192:195], v[48:51]
	v_mfma_f32_16x16x32_bf16 v[44:47], v[154:157], v[192:195], v[44:47]
	v_mfma_f32_16x16x32_bf16 v[32:35], v[132:135], v[206:209], v[32:35]
	v_mfma_f32_16x16x32_bf16 v[28:31], v[154:157], v[206:209], v[28:31]
	v_mfma_f32_16x16x32_bf16 v[16:19], v[132:135], v[214:217], v[16:19]
	v_mfma_f32_16x16x32_bf16 v[12:15], v[154:157], v[214:217], v[12:15]
	v_mfma_f32_16x16x32_bf16 v[64:67], v[136:139], v[188:191], v[64:67]
	v_mfma_f32_16x16x32_bf16 v[60:63], v[164:167], v[188:191], v[60:63]
	v_mfma_f32_16x16x32_bf16 v[48:51], v[136:139], v[202:205], v[48:51]
	v_mfma_f32_16x16x32_bf16 v[44:47], v[164:167], v[202:205], v[44:47]
	v_mfma_f32_16x16x32_bf16 v[32:35], v[136:139], v[210:213], v[32:35]
	v_mfma_f32_16x16x32_bf16 v[28:31], v[164:167], v[210:213], v[28:31]
	v_mfma_f32_16x16x32_bf16 v[16:19], v[136:139], v[218:221], v[16:19]
	v_mfma_f32_16x16x32_bf16 v[12:15], v[164:167], v[218:221], v[12:15]
	s_nop 0
	s_nop 0
	v_mfma_f32_16x16x32_bf16 v[56:59], v[168:171], v[184:187], v[56:59]
	v_mfma_f32_16x16x32_bf16 v[52:55], v[176:179], v[184:187], v[52:55]
	v_mfma_f32_16x16x32_bf16 v[40:43], v[168:171], v[192:195], v[40:43]
	v_mfma_f32_16x16x32_bf16 v[36:39], v[176:179], v[192:195], v[36:39]
	v_mfma_f32_16x16x32_bf16 v[24:27], v[168:171], v[206:209], v[24:27]
	v_mfma_f32_16x16x32_bf16 v[20:23], v[176:179], v[206:209], v[20:23]
	v_mfma_f32_16x16x32_bf16 v[8:11], v[168:171], v[214:217], v[8:11]
	v_mfma_f32_16x16x32_bf16 v[4:7], v[176:179], v[214:217], v[4:7]
	v_mfma_f32_16x16x32_bf16 v[56:59], v[172:175], v[188:191], v[56:59]
	v_mfma_f32_16x16x32_bf16 v[52:55], v[180:183], v[188:191], v[52:55]
	v_mfma_f32_16x16x32_bf16 v[40:43], v[172:175], v[202:205], v[40:43]
	v_mfma_f32_16x16x32_bf16 v[36:39], v[180:183], v[202:205], v[36:39]
	v_mfma_f32_16x16x32_bf16 v[24:27], v[172:175], v[210:213], v[24:27]
	v_mfma_f32_16x16x32_bf16 v[20:23], v[180:183], v[210:213], v[20:23]
	v_mfma_f32_16x16x32_bf16 v[8:11], v[172:175], v[218:221], v[8:11]
	v_mfma_f32_16x16x32_bf16 v[4:7], v[180:183], v[218:221], v[4:7]
	s_nop 0
	s_barrier
	s_add_u32 s2, s2, 0x100
	s_addc_u32 s3, s3, 0
	s_add_u32 s6, s6, 0x100
	s_addc_u32 s7, s7, 0
	s_cmp_ge_i32 s72, s8
	s_mov_b32 s4, s72
	s_cbranch_scc0 .LBB0_1597
	s_branch .LBB0_1598
.LBB0_1597:
	s_add_i32 s72, s4, 2
	s_add_u32 s73, s2, 0x80
	s_addc_u32 s5, s3, 0
	s_add_i32 s76, 0, 0x10000
	s_cmp_eq_u32 s37, s4
	s_cselect_b32 s5, s41, s5
	s_cselect_b32 s4, s40, s73
	v_add_u32_e32 v158, s76, v160
	s_cselect_b32 s75, s69, s7
	s_cselect_b32 s74, s68, s6
	s_add_i32 s73, 0, 0x14000
	ds_read_b128 v[132:135], v158
	ds_read_b128 v[136:139], v158 offset:1024
	ds_read_b128 v[154:157], v158 offset:2048
	ds_read_b128 v[164:167], v158 offset:3072
	v_add_u32_e32 v158, s73, v160
	ds_read_b128 v[168:171], v158
	ds_read_b128 v[172:175], v158 offset:1024
	ds_read_b128 v[176:179], v158 offset:2048
	ds_read_b128 v[180:183], v158 offset:3072
	v_lshl_add_u64 v[158:159], s[2:3], 0, v[150:151]
	s_add_i32 m0, s17, 0xc000
	ds_read_b128 v[184:187], v162
	ds_read_b128 v[188:191], v162 offset:1024
	ds_read_b128 v[192:195], v162 offset:2048
	ds_read_b128 v[202:205], v162 offset:3072
	ds_read_b128 v[206:209], v162 offset:4096
	ds_read_b128 v[210:213], v162 offset:5120
	ds_read_b128 v[214:217], v162 offset:6144
	ds_read_b128 v[218:221], v162 offset:7168
	global_load_lds_dwordx4 v[158:159], off
	v_lshl_add_u64 v[158:159], s[2:3], 0, v[152:153]
	s_add_i32 m0, s17, 0xe000
	s_nop 0
	global_load_lds_dwordx4 v[158:159], off
	s_waitcnt vmcnt(8)
	s_waitcnt lgkmcnt(0)
	s_barrier
; #define PG8_GOFFS(slot_) do { _Pragma("unroll") for (int _i = 0; _i < 2; ++_i) { int R, C; stage_rc(tid * 16 + _i * 8192, R, C); _Pragma("unroll") for (int _h = 0; _h < 2; ++_h) { \
;         unsigned t_ = gtab[(slot_) * 256 + R + 128 * _h]; t_ = t_ < (unsigned)(T - 1) ? t_ : (unsigned)(T - 1); voffA[_h][_i] = (t_ * (unsigned)K + (unsigned)C) * 2u; } } } while (0)
; #define PG8_STAGE(bufoff, gbase, voff) do { _Pragma("unroll") for (int _i = 0; _i < 2; ++_i) \
;         __builtin_amdgcn_global_load_lds((const unsigned*)((const char*)(gbase) + (voff)[_i]), (LAS unsigned*)(lds + (bufoff) + ldsw + _i * 8192), 16, 0, 0); } while (0)
; #define PG8_STAGE_A1(bufoff, gbase) do { if (Epi::GATHER) PG8_STAGE(bufoff, gbase, voffA[1]); else PG8_STAGE(bufoff, (gbase) + hstep, voffA[0]); } while (0)
; #define PG8_LDA(dst, b, h) do { _Pragma("unroll") for (int m = 0; m < 4; ++m) _Pragma("unroll") for (int k = 0; k < 2; ++k) dst[m][k] = *(const LAS bf16x8*)(lds + PG8_SA(b, h) + aoff + m * 2048 + k * 1024); } while (0)
; #define PG8_WAIT_V(n) asm volatile("s_waitcnt vmcnt(" #n ")" ::: "memory")
; #define PG8_WAIT_L(n) asm volatile("s_waitcnt lgkmcnt(" #n ")" ::: "memory")
; template <class Epi, class Sched>
; __device__ __forceinline__ void gemm_phase(const int tid, LAS unsigned char* lds, const bf16* Aop, const bf16* Bop, const int K_, const Sched& S, const Epi& E, const bf16* Aop1 = nullptr, const bf16* Bop1 = nullptr) {
;     ...
;             PG8_LDB(B0, 0, 0); PG8_LDB(B1, 0, 1); PG8_SCHED; PG8_LDA(At, 0, 0); PG8_STAGE_A1(PG8_SA(1, 1), a1);
;             PG8_WAIT_V(8); PG8_WAIT_L(0); PG8_BAR; PG8_MMA(0, 0, At, B0); PG8_MMA(0, 1, At, B1); PG8_BAR; PG8_SCHED;
;             PG8_LDA(At, 0, 1); PG8_STAGE(PG8_SB(0, 0), b2, voffB); PG8_STAGE(PG8_SB(0, 1), b2 + hstep, voffB); if (Epi::GATHER && last && has_next) PG8_GOFFS((ui + 1) & 1); PG8_STAGE(PG8_SA(0, 0), a2, voffA[0]);
;             PG8_WAIT_V(8); PG8_WAIT_L(0); PG8_BAR; PG8_MMA(1, 0, At, B0); PG8_MMA(1, 1, At, B1); PG8_BAR; PG8_SCHED;
;             PG8_LDB(B0, 1, 0); PG8_LDB(B1, 1, 1); PG8_SCHED; PG8_LDA(At, 1, 0); PG8_STAGE_A1(PG8_SA(0, 1), a2);
;             PG8_WAIT_V(8); PG8_WAIT_L(0); PG8_BAR; PG8_MMA(0, 0, At, B0); PG8_MMA(0, 1, At, B1); PG8_BAR; PG8_SCHED;
;             PG8_LDA(At, 1, 1); PG8_STAGE(PG8_SB(1, 0), b3, voffB); PG8_STAGE(PG8_SB(1, 1), b3 + hstep, voffB); PG8_STAGE(PG8_SA(1, 0), a3, voffA[0]);
	s_nop 0
	s_waitcnt lgkmcnt(0)
	v_mfma_f32_16x16x32_bf16 v[128:131], v[132:135], v[184:187], v[128:131]
	v_mfma_f32_16x16x32_bf16 v[124:127], v[154:157], v[184:187], v[124:127]
	v_mfma_f32_16x16x32_bf16 v[112:115], v[132:135], v[192:195], v[112:115]
	v_mfma_f32_16x16x32_bf16 v[108:111], v[154:157], v[192:195], v[108:111]
	v_mfma_f32_16x16x32_bf16 v[96:99], v[132:135], v[206:209], v[96:99]
	v_mfma_f32_16x16x32_bf16 v[92:95], v[154:157], v[206:209], v[92:95]
	v_mfma_f32_16x16x32_bf16 v[80:83], v[132:135], v[214:217], v[80:83]
	v_mfma_f32_16x16x32_bf16 v[76:79], v[154:157], v[214:217], v[76:79]
	v_mfma_f32_16x16x32_bf16 v[128:131], v[136:139], v[188:191], v[128:131]
	v_mfma_f32_16x16x32_bf16 v[124:127], v[164:167], v[188:191], v[124:127]
	v_mfma_f32_16x16x32_bf16 v[112:115], v[136:139], v[202:205], v[112:115]
	v_mfma_f32_16x16x32_bf16 v[108:111], v[164:167], v[202:205], v[108:111]
	v_mfma_f32_16x16x32_bf16 v[96:99], v[136:139], v[210:213], v[96:99]
	v_mfma_f32_16x16x32_bf16 v[92:95], v[164:167], v[210:213], v[92:95]
	v_mfma_f32_16x16x32_bf16 v[80:83], v[136:139], v[218:221], v[80:83]
	v_mfma_f32_16x16x32_bf16 v[76:79], v[164:167], v[218:221], v[76:79]
	s_nop 0
	s_nop 0
	v_mfma_f32_16x16x32_bf16 v[120:123], v[168:171], v[184:187], v[120:123]
	v_mfma_f32_16x16x32_bf16 v[116:119], v[176:179], v[184:187], v[116:119]
	v_mfma_f32_16x16x32_bf16 v[104:107], v[168:171], v[192:195], v[104:107]
	v_mfma_f32_16x16x32_bf16 v[100:103], v[176:179], v[192:195], v[100:103]
	v_mfma_f32_16x16x32_bf16 v[88:91], v[168:171], v[206:209], v[88:91]
	v_mfma_f32_16x16x32_bf16 v[84:87], v[176:179], v[206:209], v[84:87]
	v_mfma_f32_16x16x32_bf16 v[72:75], v[168:171], v[214:217], v[72:75]
	v_mfma_f32_16x16x32_bf16 v[68:71], v[176:179], v[214:217], v[68:71]
	v_mfma_f32_16x16x32_bf16 v[120:123], v[172:175], v[188:191], v[120:123]
	v_mfma_f32_16x16x32_bf16 v[116:119], v[180:183], v[188:191], v[116:119]
	v_mfma_f32_16x16x32_bf16 v[104:107], v[172:175], v[202:205], v[104:107]
	v_mfma_f32_16x16x32_bf16 v[100:103], v[180:183], v[202:205], v[100:103]
	v_mfma_f32_16x16x32_bf16 v[88:91], v[172:175], v[210:213], v[88:91]
	v_mfma_f32_16x16x32_bf16 v[84:87], v[180:183], v[210:213], v[84:87]
	v_mfma_f32_16x16x32_bf16 v[72:75], v[172:175], v[218:221], v[72:75]
	v_mfma_f32_16x16x32_bf16 v[68:71], v[180:183], v[218:221], v[68:71]
	s_nop 0
	s_barrier
	s_add_i32 s76, s76, s16
	v_lshl_add_u64 v[158:159], s[74:75], 0, v[142:143]
	s_mov_b32 m0, s76
	ds_read_b128 v[184:187], v162 offset:16384
	ds_read_b128 v[188:191], v162 offset:17408
	ds_read_b128 v[192:195], v162 offset:18432
	ds_read_b128 v[202:205], v162 offset:19456
	ds_read_b128 v[206:209], v162 offset:20480
	ds_read_b128 v[210:213], v162 offset:21504
	ds_read_b128 v[214:217], v162 offset:22528
	ds_read_b128 v[218:221], v162 offset:23552
	global_load_lds_dwordx4 v[158:159], off
	s_add_i32 m0, s76, 0x2000
	v_lshl_add_u64 v[196:197], s[74:75], 0, v[146:147]
	s_add_u32 s74, s74, s58
	s_addc_u32 s75, s75, s59
	s_add_i32 s73, s73, s16
	global_load_lds_dwordx4 v[196:197], off
	v_lshl_add_u64 v[198:199], s[74:75], 0, v[142:143]
	s_mov_b32 m0, s73
	v_lshl_add_u64 v[222:223], s[74:75], 0, v[146:147]
	global_load_lds_dwordx4 v[198:199], off
	s_add_i32 m0, s73, 0x2000
	v_lshl_add_u64 v[224:225], s[4:5], 0, v[140:141]
	global_load_lds_dwordx4 v[222:223], off
	s_mov_b32 m0, s17
	v_lshl_add_u64 v[230:231], s[4:5], 0, v[144:145]
	global_load_lds_dwordx4 v[224:225], off
	s_mov_b32 m0, s28
	s_nop 0
	global_load_lds_dwordx4 v[230:231], off
	s_waitcnt vmcnt(8)
	s_waitcnt lgkmcnt(0)
	s_barrier
	s_nop 0
	s_waitcnt lgkmcnt(0)
	v_mfma_f32_16x16x32_bf16 v[64:67], v[132:135], v[184:187], v[64:67]
	v_mfma_f32_16x16x32_bf16 v[60:63], v[154:157], v[184:187], v[60:63]
	v_mfma_f32_16x16x32_bf16 v[48:51], v[132:135], v[192:195], v[48:51]
	v_mfma_f32_16x16x32_bf16 v[44:47], v[154:157], v[192:195], v[44:47]
	v_mfma_f32_16x16x32_bf16 v[32:35], v[132:135], v[206:209], v[32:35]
	v_mfma_f32_16x16x32_bf16 v[28:31], v[154:157], v[206:209], v[28:31]
	v_mfma_f32_16x16x32_bf16 v[16:19], v[132:135], v[214:217], v[16:19]
	v_mfma_f32_16x16x32_bf16 v[12:15], v[154:157], v[214:217], v[12:15]
	v_mfma_f32_16x16x32_bf16 v[64:67], v[136:139], v[188:191], v[64:67]
	v_mfma_f32_16x16x32_bf16 v[60:63], v[164:167], v[188:191], v[60:63]
	v_mfma_f32_16x16x32_bf16 v[48:51], v[136:139], v[202:205], v[48:51]
	v_mfma_f32_16x16x32_bf16 v[44:47], v[164:167], v[202:205], v[44:47]
	v_mfma_f32_16x16x32_bf16 v[32:35], v[136:139], v[210:213], v[32:35]
	v_mfma_f32_16x16x32_bf16 v[28:31], v[164:167], v[210:213], v[28:31]
	v_mfma_f32_16x16x32_bf16 v[16:19], v[136:139], v[218:221], v[16:19]
	v_mfma_f32_16x16x32_bf16 v[12:15], v[164:167], v[218:221], v[12:15]
	s_nop 0
	s_nop 0
	v_mfma_f32_16x16x32_bf16 v[56:59], v[168:171], v[184:187], v[56:59]
	v_mfma_f32_16x16x32_bf16 v[52:55], v[176:179], v[184:187], v[52:55]
	v_mfma_f32_16x16x32_bf16 v[40:43], v[168:171], v[192:195], v[40:43]
	v_mfma_f32_16x16x32_bf16 v[36:39], v[176:179], v[192:195], v[36:39]
	v_mfma_f32_16x16x32_bf16 v[24:27], v[168:171], v[206:209], v[24:27]
	v_mfma_f32_16x16x32_bf16 v[20:23], v[176:179], v[206:209], v[20:23]
	v_mfma_f32_16x16x32_bf16 v[8:11], v[168:171], v[214:217], v[8:11]
	v_mfma_f32_16x16x32_bf16 v[4:7], v[176:179], v[214:217], v[4:7]
	v_mfma_f32_16x16x32_bf16 v[56:59], v[172:175], v[188:191], v[56:59]
	v_mfma_f32_16x16x32_bf16 v[52:55], v[180:183], v[188:191], v[52:55]
	v_mfma_f32_16x16x32_bf16 v[40:43], v[172:175], v[202:205], v[40:43]
	v_mfma_f32_16x16x32_bf16 v[36:39], v[180:183], v[202:205], v[36:39]
	v_mfma_f32_16x16x32_bf16 v[24:27], v[172:175], v[210:213], v[24:27]
	v_mfma_f32_16x16x32_bf16 v[20:23], v[180:183], v[210:213], v[20:23]
	v_mfma_f32_16x16x32_bf16 v[8:11], v[172:175], v[218:221], v[8:11]
	v_mfma_f32_16x16x32_bf16 v[4:7], v[180:183], v[218:221], v[4:7]
	s_nop 0
	s_barrier
; #define PG8_STAGE(bufoff, gbase, voff) do { _Pragma("unroll") for (int _i = 0; _i < 2; ++_i) \
;         __builtin_amdgcn_global_load_lds((const unsigned*)((const char*)(gbase) + (voff)[_i]), (LAS unsigned*)(lds + (bufoff) + ldsw + _i * 8192), 16, 0, 0); } while (0)
; #define PG8_STAGE_A1(bufoff, gbase) do { if (Epi::GATHER) PG8_STAGE(bufoff, gbase, voffA[1]); else PG8_STAGE(bufoff, (gbase) + hstep, voffA[0]); } while (0)
; #define PG8_LDA(dst, b, h) do { _Pragma("unroll") for (int m = 0; m < 4; ++m) _Pragma("unroll") for (int k = 0; k < 2; ++k) dst[m][k] = *(const LAS bf16x8*)(lds + PG8_SA(b, h) + aoff + m * 2048 + k * 1024); } while (0)
; #define PG8_LDB(dst, b, h) do { _Pragma("unroll") for (int n = 0; n < 2; ++n) _Pragma("unroll") for (int k = 0; k < 2; ++k) dst[n][k] = *(const LAS bf16x8*)(lds + PG8_SB(b, h) + boff + n * 2048 + k * 1024); } while (0)
; #define PG8_MMA(ai, bj, At, Bt) do { __builtin_amdgcn_s_setprio(1); _Pragma("unroll") for (int m = 0; m < 4; ++m) _Pragma("unroll") for (int n = 0; n < 2; ++n) _Pragma("unroll") for (int k = 0; k < 2; ++k) \
;         acc[ai][bj][m][n] = __builtin_amdgcn_mfma_f32_16x16x32_bf16(Bt[n][k], At[m][k], acc[ai][bj][m][n], 0, 0, 0); __builtin_amdgcn_s_setprio(0); } while (0)
; #define PG8_WAIT_V(n) asm volatile("s_waitcnt vmcnt(" #n ")" ::: "memory")
; #define PG8_WAIT_L(n) asm volatile("s_waitcnt lgkmcnt(" #n ")" ::: "memory")
; #define PG8_BAR __builtin_amdgcn_s_barrier()
; #define PG8_SCHED __builtin_amdgcn_sched_barrier(0)
; template <class Epi, class Sched>
; __device__ __forceinline__ void gemm_phase(const int tid, LAS unsigned char* lds, const bf16* Aop, const bf16* Bop, const int K_, const Sched& S, const Epi& E, const bf16* Aop1 = nullptr, const bf16* Bop1 = nullptr) {
;     ...
;             PG8_LDB(B0, 1, 0); PG8_LDB(B1, 1, 1); PG8_SCHED; PG8_LDA(At, 1, 0); PG8_STAGE_A1(PG8_SA(0, 1), a2);
;             PG8_WAIT_V(8); PG8_WAIT_L(0); PG8_BAR; PG8_MMA(0, 0, At, B0); PG8_MMA(0, 1, At, B1); PG8_BAR; PG8_SCHED;
;             PG8_LDA(At, 1, 1); PG8_STAGE(PG8_SB(1, 0), b3, voffB); PG8_STAGE(PG8_SB(1, 1), b3 + hstep, voffB); PG8_STAGE(PG8_SA(1, 0), a3, voffA[0]);
;             PG8_WAIT_V(8); PG8_WAIT_L(0); PG8_BAR; PG8_MMA(1, 0, At, B0); PG8_MMA(1, 1, At, B1); PG8_BAR; PG8_SCHED;
	s_add_i32 s73, 0, 0x18000
	v_add_u32_e32 v163, s73, v160
	s_add_i32 s74, 0, 0x1c000
	ds_read_b128 v[132:135], v163
	ds_read_b128 v[136:139], v163 offset:1024
	ds_read_b128 v[154:157], v163 offset:2048
	ds_read_b128 v[164:167], v163 offset:3072
	v_add_u32_e32 v163, s74, v160
	ds_read_b128 v[168:171], v163
	ds_read_b128 v[172:175], v163 offset:1024
	ds_read_b128 v[176:179], v163 offset:2048
	ds_read_b128 v[180:183], v163 offset:3072
	s_add_u32 s4, s4, s58
	s_addc_u32 s5, s5, s59
	s_mov_b32 m0, s29
	v_lshl_add_u64 v[232:233], s[4:5], 0, v[140:141]
	ds_read_b128 v[184:187], v162 offset:32768
	ds_read_b128 v[188:191], v162 offset:33792
	ds_read_b128 v[192:195], v162 offset:34816
	ds_read_b128 v[202:205], v162 offset:35840
	ds_read_b128 v[206:209], v162 offset:36864
	ds_read_b128 v[210:213], v162 offset:37888
	ds_read_b128 v[214:217], v162 offset:38912
	ds_read_b128 v[218:221], v162 offset:39936
	global_load_lds_dwordx4 v[232:233], off
	v_lshl_add_u64 v[232:233], s[4:5], 0, v[144:145]
	s_mov_b32 m0, s34
	s_nop 0
	global_load_lds_dwordx4 v[232:233], off
	s_waitcnt vmcnt(8)
	s_waitcnt lgkmcnt(0)
	s_barrier
	s_nop 0
	s_waitcnt lgkmcnt(0)
	v_mfma_f32_16x16x32_bf16 v[128:131], v[132:135], v[184:187], v[128:131]
	v_mfma_f32_16x16x32_bf16 v[124:127], v[154:157], v[184:187], v[124:127]
	v_mfma_f32_16x16x32_bf16 v[112:115], v[132:135], v[192:195], v[112:115]
	v_mfma_f32_16x16x32_bf16 v[108:111], v[154:157], v[192:195], v[108:111]
	v_mfma_f32_16x16x32_bf16 v[96:99], v[132:135], v[206:209], v[96:99]
	v_mfma_f32_16x16x32_bf16 v[92:95], v[154:157], v[206:209], v[92:95]
	v_mfma_f32_16x16x32_bf16 v[80:83], v[132:135], v[214:217], v[80:83]
	v_mfma_f32_16x16x32_bf16 v[76:79], v[154:157], v[214:217], v[76:79]
	v_mfma_f32_16x16x32_bf16 v[128:131], v[136:139], v[188:191], v[128:131]
	v_mfma_f32_16x16x32_bf16 v[124:127], v[164:167], v[188:191], v[124:127]
	v_mfma_f32_16x16x32_bf16 v[112:115], v[136:139], v[202:205], v[112:115]
	v_mfma_f32_16x16x32_bf16 v[108:111], v[164:167], v[202:205], v[108:111]
	v_mfma_f32_16x16x32_bf16 v[96:99], v[136:139], v[210:213], v[96:99]
	v_mfma_f32_16x16x32_bf16 v[92:95], v[164:167], v[210:213], v[92:95]
	v_mfma_f32_16x16x32_bf16 v[80:83], v[136:139], v[218:221], v[80:83]
	v_mfma_f32_16x16x32_bf16 v[76:79], v[164:167], v[218:221], v[76:79]
	s_nop 0
	s_nop 0
	v_mfma_f32_16x16x32_bf16 v[120:123], v[168:171], v[184:187], v[120:123]
	v_mfma_f32_16x16x32_bf16 v[116:119], v[176:179], v[184:187], v[116:119]
	v_mfma_f32_16x16x32_bf16 v[104:107], v[168:171], v[192:195], v[104:107]
	v_mfma_f32_16x16x32_bf16 v[100:103], v[176:179], v[192:195], v[100:103]
	v_mfma_f32_16x16x32_bf16 v[88:91], v[168:171], v[206:209], v[88:91]
	v_mfma_f32_16x16x32_bf16 v[84:87], v[176:179], v[206:209], v[84:87]
	v_mfma_f32_16x16x32_bf16 v[72:75], v[168:171], v[214:217], v[72:75]
	v_mfma_f32_16x16x32_bf16 v[68:71], v[176:179], v[214:217], v[68:71]
	v_mfma_f32_16x16x32_bf16 v[120:123], v[172:175], v[188:191], v[120:123]
	v_mfma_f32_16x16x32_bf16 v[116:119], v[180:183], v[188:191], v[116:119]
	v_mfma_f32_16x16x32_bf16 v[104:107], v[172:175], v[202:205], v[104:107]
	v_mfma_f32_16x16x32_bf16 v[100:103], v[180:183], v[202:205], v[100:103]
	v_mfma_f32_16x16x32_bf16 v[88:91], v[172:175], v[210:213], v[88:91]
	v_mfma_f32_16x16x32_bf16 v[84:87], v[180:183], v[210:213], v[84:87]
	v_mfma_f32_16x16x32_bf16 v[72:75], v[172:175], v[218:221], v[72:75]
	v_mfma_f32_16x16x32_bf16 v[68:71], v[180:183], v[218:221], v[68:71]
	s_nop 0
	s_barrier
; #define PG8_STAGE(bufoff, gbase, voff) do { _Pragma("unroll") for (int _i = 0; _i < 2; ++_i) \
;         __builtin_amdgcn_global_load_lds((const unsigned*)((const char*)(gbase) + (voff)[_i]), (LAS unsigned*)(lds + (bufoff) + ldsw + _i * 8192), 16, 0, 0); } while (0)
; #define PG8_STAGE_A1(bufoff, gbase) do { if (Epi::GATHER) PG8_STAGE(bufoff, gbase, voffA[1]); else PG8_STAGE(bufoff, (gbase) + hstep, voffA[0]); } while (0)
; #define PG8_LDA(dst, b, h) do { _Pragma("unroll") for (int m = 0; m < 4; ++m) _Pragma("unroll") for (int k = 0; k < 2; ++k) dst[m][k] = *(const LAS bf16x8*)(lds + PG8_SA(b, h) + aoff + m * 2048 + k * 1024); } while (0)
; #define PG8_LDB(dst, b, h) do { _Pragma("unroll") for (int n = 0; n < 2; ++n) _Pragma("unroll") for (int k = 0; k < 2; ++k) dst[n][k] = *(const LAS bf16x8*)(lds + PG8_SB(b, h) + boff + n * 2048 + k * 1024); } while (0)
; #define PG8_MMA(ai, bj, At, Bt) do { __builtin_amdgcn_s_setprio(1); _Pragma("unroll") for (int m = 0; m < 4; ++m) _Pragma("unroll") for (int n = 0; n < 2; ++n) _Pragma("unroll") for (int k = 0; k < 2; ++k) \
;         acc[ai][bj][m][n] = __builtin_amdgcn_mfma_f32_16x16x32_bf16(Bt[n][k], At[m][k], acc[ai][bj][m][n], 0, 0, 0); __builtin_amdgcn_s_setprio(0); } while (0)
; #define PG8_WAIT_V(n) asm volatile("s_waitcnt vmcnt(" #n ")" ::: "memory")
; #define PG8_WAIT_L(n) asm volatile("s_waitcnt lgkmcnt(" #n ")" ::: "memory")
; #define PG8_BAR __builtin_amdgcn_s_barrier()
; #define PG8_SCHED __builtin_amdgcn_sched_barrier(0)
; template <class Epi, class Sched>
; __device__ __forceinline__ void gemm_phase(const int tid, LAS unsigned char* lds, const bf16* Aop, const bf16* Bop, const int K_, const Sched& S, const Epi& E, const bf16* Aop1 = nullptr, const bf16* Bop1 = nullptr) {
;     ...
;             PG8_LDB(B0, 1, 0); PG8_LDB(B1, 1, 1); PG8_SCHED; PG8_LDA(At, 1, 0); PG8_STAGE_A1(PG8_SA(0, 1), a2);
;             PG8_WAIT_V(8); PG8_WAIT_L(0); PG8_BAR; PG8_MMA(0, 0, At, B0); PG8_MMA(0, 1, At, B1); PG8_BAR; PG8_SCHED;
;             PG8_LDA(At, 1, 1); PG8_STAGE(PG8_SB(1, 0), b3, voffB); PG8_STAGE(PG8_SB(1, 1), b3 + hstep, voffB); PG8_STAGE(PG8_SA(1, 0), a3, voffA[0]);
;             PG8_WAIT_V(8); PG8_WAIT_L(0); PG8_BAR; PG8_MMA(1, 0, At, B0); PG8_MMA(1, 1, At, B1); PG8_BAR; PG8_SCHED;
;         }
	s_add_i32 s4, s73, s16
	v_lshl_add_u64 v[158:159], v[158:159], 0, s[20:21]
	s_mov_b32 m0, s4
	ds_read_b128 v[184:187], v162 offset:49152
	ds_read_b128 v[188:191], v162 offset:50176
	ds_read_b128 v[192:195], v162 offset:51200
	ds_read_b128 v[202:205], v162 offset:52224
	ds_read_b128 v[206:209], v162 offset:53248
	ds_read_b128 v[210:213], v162 offset:54272
	ds_read_b128 v[214:217], v162 offset:55296
	ds_read_b128 v[218:221], v162 offset:56320
	global_load_lds_dwordx4 v[158:159], off
	v_lshl_add_u64 v[158:159], v[196:197], 0, s[20:21]
	s_add_i32 m0, s4, 0x2000
	s_add_i32 s4, s74, s16
	global_load_lds_dwordx4 v[158:159], off
	v_lshl_add_u64 v[158:159], v[198:199], 0, s[20:21]
	s_mov_b32 m0, s4
	s_nop 0
	global_load_lds_dwordx4 v[158:159], off
	v_lshl_add_u64 v[158:159], v[222:223], 0, s[20:21]
	s_add_i32 m0, s4, 0x2000
	s_nop 0
	global_load_lds_dwordx4 v[158:159], off
	v_lshl_add_u64 v[158:159], v[224:225], 0, s[20:21]
	s_mov_b32 m0, s35
	s_nop 0
	global_load_lds_dwordx4 v[158:159], off
	v_lshl_add_u64 v[158:159], v[230:231], 0, s[20:21]
	s_mov_b32 m0, s36
	s_nop 0
	global_load_lds_dwordx4 v[158:159], off
	s_waitcnt vmcnt(8)
	s_waitcnt lgkmcnt(0)
	s_barrier
	s_nop 0
	s_waitcnt lgkmcnt(0)
	v_mfma_f32_16x16x32_bf16 v[64:67], v[132:135], v[184:187], v[64:67]
	v_mfma_f32_16x16x32_bf16 v[60:63], v[154:157], v[184:187], v[60:63]
	v_mfma_f32_16x16x32_bf16 v[48:51], v[132:135], v[192:195], v[48:51]
	v_mfma_f32_16x16x32_bf16 v[44:47], v[154:157], v[192:195], v[44:47]
	v_mfma_f32_16x16x32_bf16 v[32:35], v[132:135], v[206:209], v[32:35]
	v_mfma_f32_16x16x32_bf16 v[28:31], v[154:157], v[206:209], v[28:31]
	v_mfma_f32_16x16x32_bf16 v[16:19], v[132:135], v[214:217], v[16:19]
	v_mfma_f32_16x16x32_bf16 v[12:15], v[154:157], v[214:217], v[12:15]
	v_mfma_f32_16x16x32_bf16 v[64:67], v[136:139], v[188:191], v[64:67]
	v_mfma_f32_16x16x32_bf16 v[60:63], v[164:167], v[188:191], v[60:63]
	v_mfma_f32_16x16x32_bf16 v[48:51], v[136:139], v[202:205], v[48:51]
	v_mfma_f32_16x16x32_bf16 v[44:47], v[164:167], v[202:205], v[44:47]
	v_mfma_f32_16x16x32_bf16 v[32:35], v[136:139], v[210:213], v[32:35]
	v_mfma_f32_16x16x32_bf16 v[28:31], v[164:167], v[210:213], v[28:31]
	v_mfma_f32_16x16x32_bf16 v[16:19], v[136:139], v[218:221], v[16:19]
	v_mfma_f32_16x16x32_bf16 v[12:15], v[164:167], v[218:221], v[12:15]
	s_nop 0
	s_nop 0
	v_mfma_f32_16x16x32_bf16 v[56:59], v[168:171], v[184:187], v[56:59]
	v_mfma_f32_16x16x32_bf16 v[52:55], v[176:179], v[184:187], v[52:55]
	v_mfma_f32_16x16x32_bf16 v[40:43], v[168:171], v[192:195], v[40:43]
	v_mfma_f32_16x16x32_bf16 v[36:39], v[176:179], v[192:195], v[36:39]
	v_mfma_f32_16x16x32_bf16 v[24:27], v[168:171], v[206:209], v[24:27]
	v_mfma_f32_16x16x32_bf16 v[20:23], v[176:179], v[206:209], v[20:23]
	v_mfma_f32_16x16x32_bf16 v[8:11], v[168:171], v[214:217], v[8:11]
	v_mfma_f32_16x16x32_bf16 v[4:7], v[176:179], v[214:217], v[4:7]
	v_mfma_f32_16x16x32_bf16 v[56:59], v[172:175], v[188:191], v[56:59]
	v_mfma_f32_16x16x32_bf16 v[52:55], v[180:183], v[188:191], v[52:55]
	v_mfma_f32_16x16x32_bf16 v[40:43], v[172:175], v[202:205], v[40:43]
	v_mfma_f32_16x16x32_bf16 v[36:39], v[180:183], v[202:205], v[36:39]
	v_mfma_f32_16x16x32_bf16 v[24:27], v[172:175], v[210:213], v[24:27]
	v_mfma_f32_16x16x32_bf16 v[20:23], v[180:183], v[210:213], v[20:23]
	v_mfma_f32_16x16x32_bf16 v[8:11], v[172:175], v[218:221], v[8:11]
	v_mfma_f32_16x16x32_bf16 v[4:7], v[180:183], v[218:221], v[4:7]
	s_nop 0
	s_barrier
	s_add_u32 s2, s2, 0x100
	s_addc_u32 s3, s3, 0
	s_add_u32 s6, s6, 0x100
	s_addc_u32 s7, s7, 0
	s_cmp_ge_i32 s72, s8
	s_mov_b32 s4, s72
	s_cbranch_scc0 .LBB0_1597
